# attention inner loop rewritten (8-slot LDS fragment ring, ALiBi folded into MFMA C-init, separate diagonal path) + GEMM loops: rebalanced LDS reads + SGPR-base LDS-DMA
# speedup vs baseline: 1.0282x; 1.0282x over previous
; #define PG8_STAGE(bufoff, gbase, voff) do { _Pragma("unroll") for (int _i = 0; _i < 2; ++_i) \
;         __builtin_amdgcn_global_load_lds((const unsigned*)((const char*)(gbase) + (voff)[_i]), (LAS unsigned*)(lds + (bufoff) + ldsw + _i * 8192), 16, 0, 0); } while (0)
; #define PG8_LDA(dst, b, h) do { _Pragma("unroll") for (int m = 0; m < 4; ++m) _Pragma("unroll") for (int k = 0; k < 2; ++k) dst[m][k] = *(const LAS bf16x8*)(lds + PG8_SA(b, h) + aoff + m * 2048 + k * 1024); } while (0)
; #define PG8_LDB(dst, b, h) do { _Pragma("unroll") for (int n = 0; n < 2; ++n) _Pragma("unroll") for (int k = 0; k < 2; ++k) dst[n][k] = *(const LAS bf16x8*)(lds + PG8_SB(b, h) + boff + n * 2048 + k * 1024); } while (0)
; #define PG8_MMA(ai, bj, At, Bt) do { __builtin_amdgcn_s_setprio(1); _Pragma("unroll") for (int m = 0; m < 4; ++m) _Pragma("unroll") for (int n = 0; n < 2; ++n) _Pragma("unroll") for (int k = 0; k < 2; ++k) \
;         acc[ai][bj][m][n] = __builtin_amdgcn_mfma_f32_16x16x32_bf16(Bt[n][k], At[m][k], acc[ai][bj][m][n], 0, 0, 0); __builtin_amdgcn_s_setprio(0); } while (0)
; template <class Epi>
; __device__ __forceinline__ void gemm_phase(LAS unsigned char* lds, const Gemm g, const StaticOrder& S, const Epi& E, int wv) {
;     ...
;         const bool has_next = S.next(ui + 1, nxt);
;         const char* nA = has_next ? (const char*)g.A + (size_t)nxt.pm * tstepA + ((g.adiag & 1) ? (size_t)(nxt.pn >> 1) * K * 2 : 0) + kbeg : cA;
;         const char* nB = has_next ? (const char*)g.Bt + (size_t)nxt.pn * tstepB + kbeg : cB;
;         for (int t = 0; t < nt; t += 2) {
;             const bool last = (t == nt - 2);
;             const char* a1 = cA + (ptrdiff_t)(t + 1) * kstep;
;             const char* a2 = last ? nA : cA + (ptrdiff_t)(t + 2) * kstep; const char* b2 = last ? nB : cB + (ptrdiff_t)(t + 2) * kstep;
;             const char* a3 = a2 + kstep; const char* b3 = b2 + kstep;
;             PG8_LDB(B0, 0, 0); PG8_SCHED; PG8_LDA(At, 0, 0); PG8_STAGE(PG8_SA(1, 1), a1 + hstepA, voffA);
;             PG8_WAIT_L(8); PG8_BAR; PG8_WAIT_L(0); PG8_MMA(0, 0, At, B0); PG8_BAR; PG8_SCHED;
;     ...
; #pragma unroll
;         for (int a = 0; a < 2; ++a)
; #pragma unroll
;             for (int b = 0; b < 2; ++b)
; #pragma unroll
;                 for (int m = 0; m < 4; ++m)
; #pragma unroll
;                     for (int n = 0; n < 2; ++n) acc[a][b][m][n] = (f32x4){0.f, 0.f, 0.f, 0.f};
.LBB0_207:
	s_ashr_i32 s63, s62, 31
	s_lshl_b64 s[30:31], s[62:63], 20
	v_cmp_lt_i64_e32 vcc, s[64:65], v[148:149]
	s_add_u32 s64, s5, s30
	s_addc_u32 s65, s6, s31
	s_and_b64 s[30:31], vcc, exec
	s_cselect_b32 s21, s65, s71
	s_cselect_b32 s30, s64, s70
	s_ashr_i32 s61, s60, 31
	s_lshl_b64 s[34:35], s[60:61], 20
	s_add_u32 s66, s7, s34
	s_addc_u32 s67, s8, s35
	s_and_b64 s[34:35], vcc, exec
	s_cselect_b32 s31, s67, s73
	s_cselect_b32 s33, s66, s72
	s_add_u32 s70, s70, 0x80080
	s_addc_u32 s71, s71, 0
	s_add_u32 s34, s72, 0x100
	v_mov_b32_e32 v0, 0
	s_addc_u32 s35, s73, 0
	s_mov_b32 s38, -2
	v_mov_b32_e32 v1, v0
	v_mov_b32_e32 v2, v0
	v_mov_b32_e32 v3, v0
	v_mov_b32_e32 v4, v0
	v_mov_b32_e32 v5, v0
	v_mov_b32_e32 v6, v0
	v_mov_b32_e32 v7, v0
	v_mov_b32_e32 v16, v0
	v_mov_b32_e32 v17, v0
	v_mov_b32_e32 v18, v0
	v_mov_b32_e32 v19, v0
	v_mov_b32_e32 v20, v0
	v_mov_b32_e32 v21, v0
	v_mov_b32_e32 v22, v0
	v_mov_b32_e32 v23, v0
	v_mov_b32_e32 v32, v0
	v_mov_b32_e32 v33, v0
	v_mov_b32_e32 v34, v0
	v_mov_b32_e32 v35, v0
	v_mov_b32_e32 v36, v0
	v_mov_b32_e32 v37, v0
	v_mov_b32_e32 v38, v0
	v_mov_b32_e32 v39, v0
	v_mov_b32_e32 v48, v0
	v_mov_b32_e32 v49, v0
	v_mov_b32_e32 v50, v0
	v_mov_b32_e32 v51, v0
	v_mov_b32_e32 v52, v0
	v_mov_b32_e32 v53, v0
	v_mov_b32_e32 v54, v0
	v_mov_b32_e32 v55, v0
	v_mov_b32_e32 v8, v0
	v_mov_b32_e32 v9, v0
	v_mov_b32_e32 v10, v0
	v_mov_b32_e32 v11, v0
	v_mov_b32_e32 v12, v0
	v_mov_b32_e32 v13, v0
	v_mov_b32_e32 v14, v0
	v_mov_b32_e32 v15, v0
	v_mov_b32_e32 v24, v0
	v_mov_b32_e32 v25, v0
	v_mov_b32_e32 v26, v0
	v_mov_b32_e32 v27, v0
	v_mov_b32_e32 v28, v0
	v_mov_b32_e32 v29, v0
	v_mov_b32_e32 v30, v0
	v_mov_b32_e32 v31, v0
	v_mov_b32_e32 v40, v0
	v_mov_b32_e32 v41, v0
	v_mov_b32_e32 v42, v0
	v_mov_b32_e32 v43, v0
	v_mov_b32_e32 v44, v0
	v_mov_b32_e32 v45, v0
	v_mov_b32_e32 v46, v0
	v_mov_b32_e32 v47, v0
	v_mov_b32_e32 v56, v0
	v_mov_b32_e32 v57, v0
	v_mov_b32_e32 v58, v0
	v_mov_b32_e32 v59, v0
	v_mov_b32_e32 v60, v0
	v_mov_b32_e32 v61, v0
	v_mov_b32_e32 v62, v0
	v_mov_b32_e32 v63, v0
	v_mov_b32_e32 v64, v0
	v_mov_b32_e32 v65, v0
	v_mov_b32_e32 v66, v0
	v_mov_b32_e32 v67, v0
	v_mov_b32_e32 v68, v0
	v_mov_b32_e32 v69, v0
	v_mov_b32_e32 v70, v0
	v_mov_b32_e32 v71, v0
	v_mov_b32_e32 v80, v0
	v_mov_b32_e32 v81, v0
	v_mov_b32_e32 v82, v0
	v_mov_b32_e32 v83, v0
	v_mov_b32_e32 v84, v0
	v_mov_b32_e32 v85, v0
	v_mov_b32_e32 v86, v0
	v_mov_b32_e32 v87, v0
	v_mov_b32_e32 v96, v0
	v_mov_b32_e32 v97, v0
	v_mov_b32_e32 v98, v0
	v_mov_b32_e32 v99, v0
	v_mov_b32_e32 v100, v0
	v_mov_b32_e32 v101, v0
	v_mov_b32_e32 v102, v0
	v_mov_b32_e32 v103, v0
	v_mov_b32_e32 v112, v0
	v_mov_b32_e32 v113, v0
	v_mov_b32_e32 v114, v0
	v_mov_b32_e32 v115, v0
	v_mov_b32_e32 v116, v0
	v_mov_b32_e32 v117, v0
	v_mov_b32_e32 v118, v0
	v_mov_b32_e32 v119, v0
	v_mov_b32_e32 v72, v0
	v_mov_b32_e32 v73, v0
	v_mov_b32_e32 v74, v0
	v_mov_b32_e32 v75, v0
	v_mov_b32_e32 v76, v0
	v_mov_b32_e32 v77, v0
	v_mov_b32_e32 v78, v0
	v_mov_b32_e32 v79, v0
	v_mov_b32_e32 v88, v0
	v_mov_b32_e32 v89, v0
	v_mov_b32_e32 v90, v0
	v_mov_b32_e32 v91, v0
	v_mov_b32_e32 v92, v0
	v_mov_b32_e32 v93, v0
	v_mov_b32_e32 v94, v0
	v_mov_b32_e32 v95, v0
	v_mov_b32_e32 v104, v0
	v_mov_b32_e32 v105, v0
	v_mov_b32_e32 v106, v0
	v_mov_b32_e32 v107, v0
	v_mov_b32_e32 v108, v0
	v_mov_b32_e32 v109, v0
	v_mov_b32_e32 v110, v0
	v_mov_b32_e32 v111, v0
	v_mov_b32_e32 v120, v0
	v_mov_b32_e32 v121, v0
	v_mov_b32_e32 v122, v0
	v_mov_b32_e32 v123, v0
	v_mov_b32_e32 v124, v0
	v_mov_b32_e32 v125, v0
	v_mov_b32_e32 v126, v0
	v_mov_b32_e32 v127, v0
	ds_read_b128 v[128:131], v190
	ds_read_b128 v[132:135], v190 offset:1024
	ds_read_b128 v[152:155], v190 offset:2048
	ds_read_b128 v[156:159], v190 offset:3072
.LBB0_208:
	s_add_u32 s39, s70, 0xfff80080
	s_addc_u32 s40, s71, -1
	s_cmp_eq_u32 s38, 28
	s_cselect_b32 s75, s21, s40
	s_cselect_b32 s74, s30, s39
	s_cselect_b32 s73, s31, s35
	s_cselect_b32 s72, s33, s34
	s_add_i32 m0, s10, 0xc000
	ds_read_b128 v[160:163], v191
	ds_read_b128 v[164:167], v191 offset:1024
	ds_read_b128 v[168:171], v191 offset:2048
	ds_read_b128 v[172:175], v191 offset:3072
	ds_read_b128 v[176:179], v191 offset:4096
	ds_read_b128 v[198:201], v191 offset:5120
	ds_read_b128 v[202:205], v191 offset:6144
	ds_read_b128 v[206:209], v191 offset:7168
	global_load_lds_dwordx4 v144, s[70:71]
	s_add_i32 m0, s10, 0xe000
	s_nop 0
	global_load_lds_dwordx4 v146, s[70:71]
	s_waitcnt lgkmcnt(8)
	s_barrier
	s_waitcnt lgkmcnt(0)
	s_setprio 1
	s_waitcnt lgkmcnt(0)
	v_mfma_f32_16x16x32_bf16 v[124:127], v[128:131], v[160:163], v[124:127]
	v_mfma_f32_16x16x32_bf16 v[120:123], v[152:155], v[160:163], v[120:123]
	v_mfma_f32_16x16x32_bf16 v[108:111], v[128:131], v[168:171], v[108:111]
	v_mfma_f32_16x16x32_bf16 v[104:107], v[152:155], v[168:171], v[104:107]
	v_mfma_f32_16x16x32_bf16 v[92:95], v[128:131], v[176:179], v[92:95]
	v_mfma_f32_16x16x32_bf16 v[88:91], v[152:155], v[176:179], v[88:91]
	v_mfma_f32_16x16x32_bf16 v[76:79], v[128:131], v[202:205], v[76:79]
	v_mfma_f32_16x16x32_bf16 v[72:75], v[152:155], v[202:205], v[72:75]
	v_mfma_f32_16x16x32_bf16 v[124:127], v[132:135], v[164:167], v[124:127]
	v_mfma_f32_16x16x32_bf16 v[120:123], v[156:159], v[164:167], v[120:123]
	v_mfma_f32_16x16x32_bf16 v[108:111], v[132:135], v[172:175], v[108:111]
	v_mfma_f32_16x16x32_bf16 v[104:107], v[156:159], v[172:175], v[104:107]
	v_mfma_f32_16x16x32_bf16 v[92:95], v[132:135], v[198:201], v[92:95]
	v_mfma_f32_16x16x32_bf16 v[88:91], v[156:159], v[198:201], v[88:91]
	v_mfma_f32_16x16x32_bf16 v[76:79], v[132:135], v[206:209], v[76:79]
	v_mfma_f32_16x16x32_bf16 v[72:75], v[156:159], v[206:209], v[72:75]
	s_setprio 0
	s_barrier
; #define PG8_STAGE(bufoff, gbase, voff) do { _Pragma("unroll") for (int _i = 0; _i < 2; ++_i) \
;         __builtin_amdgcn_global_load_lds((const unsigned*)((const char*)(gbase) + (voff)[_i]), (LAS unsigned*)(lds + (bufoff) + ldsw + _i * 8192), 16, 0, 0); } while (0)
; #define PG8_LDA(dst, b, h) do { _Pragma("unroll") for (int m = 0; m < 4; ++m) _Pragma("unroll") for (int k = 0; k < 2; ++k) dst[m][k] = *(const LAS bf16x8*)(lds + PG8_SA(b, h) + aoff + m * 2048 + k * 1024); } while (0)
; #define PG8_LDB(dst, b, h) do { _Pragma("unroll") for (int n = 0; n < 2; ++n) _Pragma("unroll") for (int k = 0; k < 2; ++k) dst[n][k] = *(const LAS bf16x8*)(lds + PG8_SB(b, h) + boff + n * 2048 + k * 1024); } while (0)
; #define PG8_MMA(ai, bj, At, Bt) do { __builtin_amdgcn_s_setprio(1); _Pragma("unroll") for (int m = 0; m < 4; ++m) _Pragma("unroll") for (int n = 0; n < 2; ++n) _Pragma("unroll") for (int k = 0; k < 2; ++k) \
;         acc[ai][bj][m][n] = __builtin_amdgcn_mfma_f32_16x16x32_bf16(Bt[n][k], At[m][k], acc[ai][bj][m][n], 0, 0, 0); __builtin_amdgcn_s_setprio(0); } while (0)
; #define PG8_WAIT_V(n) asm volatile("s_waitcnt vmcnt(" #n ")" ::: "memory")
; #define PG8_WAIT_L(n) asm volatile("s_waitcnt lgkmcnt(" #n ")" ::: "memory")
; #define PG8_BAR __builtin_amdgcn_s_barrier()
; #define PG8_SCHED __builtin_amdgcn_sched_barrier(0)
; template <class Epi>
; __device__ __forceinline__ void gemm_phase(LAS unsigned char* lds, const Gemm g, const StaticOrder& S, const Epi& E, int wv) {
;     ...
;             PG8_LDB(B1, 0, 1); PG8_STAGE(PG8_SB(0, 0), b2, voffB);
;             PG8_BAR; PG8_WAIT_L(0); PG8_MMA(0, 1, At, B1); PG8_BAR;
;             PG8_LDA(At, 0, 1); PG8_STAGE(PG8_SA(0, 0), a2, voffA);
;             PG8_BAR; PG8_WAIT_L(0); PG8_MMA(1, 0, At, B0); PG8_BAR; PG8_SCHED;
;             PG8_STAGE(PG8_SB(0, 1), b2 + hstepB, voffB);
;             PG8_WAIT_V(6); PG8_BAR; PG8_MMA(1, 1, At, B1); PG8_BAR;
;             PG8_LDB(B0, 1, 0); PG8_SCHED; PG8_LDA(At, 1, 0); PG8_STAGE(PG8_SA(0, 1), a2 + hstepA, voffA);
;             PG8_WAIT_L(8); PG8_BAR; PG8_WAIT_L(0); PG8_MMA(0, 0, At, B0); PG8_BAR; PG8_SCHED;
	s_add_i32 s39, s23, s9
	s_add_u32 s98, s72, s58
	s_addc_u32 s99, s73, s59
	s_mov_b32 m0, s39
	ds_read_b128 v[210:213], v192
	ds_read_b128 v[214:217], v192 offset:1024
	ds_read_b128 v[218:221], v192 offset:2048
	ds_read_b128 v[222:225], v192 offset:3072
	global_load_lds_dwordx4 v138, s[72:73]
	s_add_i32 m0, s39, 0x2000
	s_nop 0
	global_load_lds_dwordx4 v142, s[72:73]
	s_barrier
	s_waitcnt lgkmcnt(0)
	s_setprio 1
	s_waitcnt lgkmcnt(0)
	v_mfma_f32_16x16x32_bf16 v[116:119], v[210:213], v[160:163], v[116:119]
	v_mfma_f32_16x16x32_bf16 v[112:115], v[218:221], v[160:163], v[112:115]
	v_mfma_f32_16x16x32_bf16 v[100:103], v[210:213], v[168:171], v[100:103]
	v_mfma_f32_16x16x32_bf16 v[96:99], v[218:221], v[168:171], v[96:99]
	v_mfma_f32_16x16x32_bf16 v[84:87], v[210:213], v[176:179], v[84:87]
	v_mfma_f32_16x16x32_bf16 v[80:83], v[218:221], v[176:179], v[80:83]
	v_mfma_f32_16x16x32_bf16 v[68:71], v[210:213], v[202:205], v[68:71]
	v_mfma_f32_16x16x32_bf16 v[64:67], v[218:221], v[202:205], v[64:67]
	v_mfma_f32_16x16x32_bf16 v[116:119], v[214:217], v[164:167], v[116:119]
	v_mfma_f32_16x16x32_bf16 v[112:115], v[222:225], v[164:167], v[112:115]
	v_mfma_f32_16x16x32_bf16 v[100:103], v[214:217], v[172:175], v[100:103]
	v_mfma_f32_16x16x32_bf16 v[96:99], v[222:225], v[172:175], v[96:99]
	v_mfma_f32_16x16x32_bf16 v[84:87], v[214:217], v[198:201], v[84:87]
	v_mfma_f32_16x16x32_bf16 v[80:83], v[222:225], v[198:201], v[80:83]
	v_mfma_f32_16x16x32_bf16 v[68:71], v[214:217], v[206:209], v[68:71]
	v_mfma_f32_16x16x32_bf16 v[64:67], v[222:225], v[206:209], v[64:67]
	s_setprio 0
	s_mov_b32 m0, s10
	s_add_u32 s100, s74, s58
	s_addc_u32 s101, s75, s59
	s_barrier
	ds_read_b128 v[160:163], v191 offset:16384
	ds_read_b128 v[164:167], v191 offset:17408
	ds_read_b128 v[168:171], v191 offset:18432
	ds_read_b128 v[172:175], v191 offset:19456
	ds_read_b128 v[176:179], v191 offset:20480
	ds_read_b128 v[198:201], v191 offset:21504
	ds_read_b128 v[202:205], v191 offset:22528
	ds_read_b128 v[206:209], v191 offset:23552
	global_load_lds_dwordx4 v136, s[74:75]
	s_mov_b32 m0, s11
	s_nop 0
	global_load_lds_dwordx4 v140, s[74:75]
	s_waitcnt vmcnt(10)
	s_barrier
	s_waitcnt lgkmcnt(0)
	s_setprio 1
	s_waitcnt lgkmcnt(0)
	v_mfma_f32_16x16x32_bf16 v[60:63], v[128:131], v[160:163], v[60:63]
	v_mfma_f32_16x16x32_bf16 v[56:59], v[152:155], v[160:163], v[56:59]
	v_mfma_f32_16x16x32_bf16 v[44:47], v[128:131], v[168:171], v[44:47]
	v_mfma_f32_16x16x32_bf16 v[40:43], v[152:155], v[168:171], v[40:43]
	v_mfma_f32_16x16x32_bf16 v[28:31], v[128:131], v[176:179], v[28:31]
	v_mfma_f32_16x16x32_bf16 v[24:27], v[152:155], v[176:179], v[24:27]
	v_mfma_f32_16x16x32_bf16 v[12:15], v[128:131], v[202:205], v[12:15]
	v_mfma_f32_16x16x32_bf16 v[8:11], v[152:155], v[202:205], v[8:11]
	v_mfma_f32_16x16x32_bf16 v[60:63], v[132:135], v[164:167], v[60:63]
	v_mfma_f32_16x16x32_bf16 v[56:59], v[156:159], v[164:167], v[56:59]
	v_mfma_f32_16x16x32_bf16 v[44:47], v[132:135], v[172:175], v[44:47]
	v_mfma_f32_16x16x32_bf16 v[40:43], v[156:159], v[172:175], v[40:43]
	v_mfma_f32_16x16x32_bf16 v[28:31], v[132:135], v[198:201], v[28:31]
	v_mfma_f32_16x16x32_bf16 v[24:27], v[156:159], v[198:201], v[24:27]
	v_mfma_f32_16x16x32_bf16 v[12:15], v[132:135], v[206:209], v[12:15]
	v_mfma_f32_16x16x32_bf16 v[8:11], v[156:159], v[206:209], v[8:11]
	s_setprio 0
	s_barrier
	s_add_u32 s40, s72, 0x80000
	s_addc_u32 s41, s73, 0
	s_add_i32 s39, s24, s9
	s_mov_b32 m0, s39
	s_nop 0
	global_load_lds_dwordx4 v138, s[40:41]
	s_add_i32 m0, s39, 0x2000
	s_nop 0
	global_load_lds_dwordx4 v142, s[40:41]
	s_add_i32 s39, 0, 0x18000
	v_add_u32_e32 v156, s39, v184
	ds_read_b128 v[128:131], v156
	ds_read_b128 v[132:135], v156 offset:1024
	ds_read_b128 v[152:155], v156 offset:2048
	ds_read_b128 v[156:159], v156 offset:3072
	s_waitcnt vmcnt(6)
	s_barrier
	s_setprio 1
	v_mfma_f32_16x16x32_bf16 v[52:55], v[210:213], v[160:163], v[52:55]
	v_mfma_f32_16x16x32_bf16 v[48:51], v[218:221], v[160:163], v[48:51]
	v_mfma_f32_16x16x32_bf16 v[36:39], v[210:213], v[168:171], v[36:39]
	v_mfma_f32_16x16x32_bf16 v[32:35], v[218:221], v[168:171], v[32:35]
	v_mfma_f32_16x16x32_bf16 v[20:23], v[210:213], v[176:179], v[20:23]
	v_mfma_f32_16x16x32_bf16 v[16:19], v[218:221], v[176:179], v[16:19]
	v_mfma_f32_16x16x32_bf16 v[4:7], v[210:213], v[202:205], v[4:7]
	v_mfma_f32_16x16x32_bf16 v[0:3], v[218:221], v[202:205], v[0:3]
	v_mfma_f32_16x16x32_bf16 v[52:55], v[214:217], v[164:167], v[52:55]
	v_mfma_f32_16x16x32_bf16 v[48:51], v[222:225], v[164:167], v[48:51]
	v_mfma_f32_16x16x32_bf16 v[36:39], v[214:217], v[172:175], v[36:39]
	v_mfma_f32_16x16x32_bf16 v[32:35], v[222:225], v[172:175], v[32:35]
	v_mfma_f32_16x16x32_bf16 v[20:23], v[214:217], v[198:201], v[20:23]
	v_mfma_f32_16x16x32_bf16 v[16:19], v[222:225], v[198:201], v[16:19]
	v_mfma_f32_16x16x32_bf16 v[4:7], v[214:217], v[206:209], v[4:7]
	v_mfma_f32_16x16x32_bf16 v[0:3], v[222:225], v[206:209], v[0:3]
	s_setprio 0
	s_waitcnt lgkmcnt(0)
	s_barrier
	s_add_u32 s40, s74, 0x80000
	s_addc_u32 s41, s75, 0
	s_mov_b32 m0, s12
	ds_read_b128 v[160:163], v191 offset:32768
	ds_read_b128 v[164:167], v191 offset:33792
	ds_read_b128 v[168:171], v191 offset:34816
	ds_read_b128 v[172:175], v191 offset:35840
	ds_read_b128 v[176:179], v191 offset:36864
	ds_read_b128 v[198:201], v191 offset:37888
	ds_read_b128 v[202:205], v191 offset:38912
	ds_read_b128 v[206:209], v191 offset:39936
	global_load_lds_dwordx4 v136, s[40:41]
	s_mov_b32 m0, s13
	s_nop 0
	global_load_lds_dwordx4 v140, s[40:41]
	s_waitcnt lgkmcnt(8)
	s_barrier
; #define PG8_STAGE(bufoff, gbase, voff) do { _Pragma("unroll") for (int _i = 0; _i < 2; ++_i) \
;         __builtin_amdgcn_global_load_lds((const unsigned*)((const char*)(gbase) + (voff)[_i]), (LAS unsigned*)(lds + (bufoff) + ldsw + _i * 8192), 16, 0, 0); } while (0)
; #define PG8_LDA(dst, b, h) do { _Pragma("unroll") for (int m = 0; m < 4; ++m) _Pragma("unroll") for (int k = 0; k < 2; ++k) dst[m][k] = *(const LAS bf16x8*)(lds + PG8_SA(b, h) + aoff + m * 2048 + k * 1024); } while (0)
; #define PG8_LDB(dst, b, h) do { _Pragma("unroll") for (int n = 0; n < 2; ++n) _Pragma("unroll") for (int k = 0; k < 2; ++k) dst[n][k] = *(const LAS bf16x8*)(lds + PG8_SB(b, h) + boff + n * 2048 + k * 1024); } while (0)
; #define PG8_MMA(ai, bj, At, Bt) do { __builtin_amdgcn_s_setprio(1); _Pragma("unroll") for (int m = 0; m < 4; ++m) _Pragma("unroll") for (int n = 0; n < 2; ++n) _Pragma("unroll") for (int k = 0; k < 2; ++k) \
;         acc[ai][bj][m][n] = __builtin_amdgcn_mfma_f32_16x16x32_bf16(Bt[n][k], At[m][k], acc[ai][bj][m][n], 0, 0, 0); __builtin_amdgcn_s_setprio(0); } while (0)
; #define PG8_WAIT_L(n) asm volatile("s_waitcnt lgkmcnt(" #n ")" ::: "memory")
; #define PG8_BAR __builtin_amdgcn_s_barrier()
; #define PG8_SCHED __builtin_amdgcn_sched_barrier(0)
; template <class Epi>
; __device__ __forceinline__ void gemm_phase(LAS unsigned char* lds, const Gemm g, const StaticOrder& S, const Epi& E, int wv) {
;     ...
;             PG8_WAIT_L(8); PG8_BAR; PG8_WAIT_L(0); PG8_MMA(0, 0, At, B0); PG8_BAR; PG8_SCHED;
;             PG8_LDB(B1, 1, 1); PG8_STAGE(PG8_SB(1, 0), b3, voffB);
;             PG8_BAR; PG8_WAIT_L(0); PG8_MMA(0, 1, At, B1); PG8_BAR;
;             PG8_LDA(At, 1, 1); PG8_STAGE(PG8_SA(1, 0), a3, voffA);
;             PG8_BAR; PG8_WAIT_L(0); PG8_MMA(1, 0, At, B0); PG8_BAR; PG8_SCHED;
;             PG8_STAGE(PG8_SB(1, 1), b3 + hstepB, voffB);
	s_waitcnt lgkmcnt(0)
	s_setprio 1
	s_waitcnt lgkmcnt(0)
	v_mfma_f32_16x16x32_bf16 v[124:127], v[128:131], v[160:163], v[124:127]
	v_mfma_f32_16x16x32_bf16 v[120:123], v[152:155], v[160:163], v[120:123]
	v_mfma_f32_16x16x32_bf16 v[108:111], v[128:131], v[168:171], v[108:111]
	v_mfma_f32_16x16x32_bf16 v[104:107], v[152:155], v[168:171], v[104:107]
	v_mfma_f32_16x16x32_bf16 v[92:95], v[128:131], v[176:179], v[92:95]
	v_mfma_f32_16x16x32_bf16 v[88:91], v[152:155], v[176:179], v[88:91]
	v_mfma_f32_16x16x32_bf16 v[76:79], v[128:131], v[202:205], v[76:79]
	v_mfma_f32_16x16x32_bf16 v[72:75], v[152:155], v[202:205], v[72:75]
	v_mfma_f32_16x16x32_bf16 v[124:127], v[132:135], v[164:167], v[124:127]
	v_mfma_f32_16x16x32_bf16 v[120:123], v[156:159], v[164:167], v[120:123]
	v_mfma_f32_16x16x32_bf16 v[108:111], v[132:135], v[172:175], v[108:111]
	v_mfma_f32_16x16x32_bf16 v[104:107], v[156:159], v[172:175], v[104:107]
	v_mfma_f32_16x16x32_bf16 v[92:95], v[132:135], v[198:201], v[92:95]
	v_mfma_f32_16x16x32_bf16 v[88:91], v[156:159], v[198:201], v[88:91]
	v_mfma_f32_16x16x32_bf16 v[76:79], v[132:135], v[206:209], v[76:79]
	v_mfma_f32_16x16x32_bf16 v[72:75], v[156:159], v[206:209], v[72:75]
	s_setprio 0
	s_barrier
	s_add_i32 s42, 0, 0x1c000
	s_add_i32 s39, s39, s9
	v_add_u32_e32 v197, s42, v184
	s_mov_b32 m0, s39
	ds_read_b128 v[210:213], v197
	ds_read_b128 v[214:217], v197 offset:1024
	ds_read_b128 v[218:221], v197 offset:2048
	ds_read_b128 v[222:225], v197 offset:3072
	global_load_lds_dwordx4 v138, s[98:99]
	s_add_i32 m0, s39, 0x2000
	s_nop 0
	global_load_lds_dwordx4 v142, s[98:99]
	s_barrier
	s_waitcnt lgkmcnt(0)
	s_setprio 1
	s_waitcnt lgkmcnt(0)
	v_mfma_f32_16x16x32_bf16 v[116:119], v[210:213], v[160:163], v[116:119]
	v_mfma_f32_16x16x32_bf16 v[112:115], v[218:221], v[160:163], v[112:115]
	v_mfma_f32_16x16x32_bf16 v[100:103], v[210:213], v[168:171], v[100:103]
	v_mfma_f32_16x16x32_bf16 v[96:99], v[218:221], v[168:171], v[96:99]
	v_mfma_f32_16x16x32_bf16 v[84:87], v[210:213], v[176:179], v[84:87]
	v_mfma_f32_16x16x32_bf16 v[80:83], v[218:221], v[176:179], v[80:83]
	v_mfma_f32_16x16x32_bf16 v[68:71], v[210:213], v[202:205], v[68:71]
	v_mfma_f32_16x16x32_bf16 v[64:67], v[218:221], v[202:205], v[64:67]
	v_mfma_f32_16x16x32_bf16 v[116:119], v[214:217], v[164:167], v[116:119]
	v_mfma_f32_16x16x32_bf16 v[112:115], v[222:225], v[164:167], v[112:115]
	v_mfma_f32_16x16x32_bf16 v[100:103], v[214:217], v[172:175], v[100:103]
	v_mfma_f32_16x16x32_bf16 v[96:99], v[222:225], v[172:175], v[96:99]
	v_mfma_f32_16x16x32_bf16 v[84:87], v[214:217], v[198:201], v[84:87]
	v_mfma_f32_16x16x32_bf16 v[80:83], v[222:225], v[198:201], v[80:83]
	v_mfma_f32_16x16x32_bf16 v[68:71], v[214:217], v[206:209], v[68:71]
	v_mfma_f32_16x16x32_bf16 v[64:67], v[222:225], v[206:209], v[64:67]
	s_setprio 0
	s_mov_b32 m0, s15
	s_barrier
	ds_read_b128 v[160:163], v191 offset:49152
	ds_read_b128 v[164:167], v191 offset:50176
	ds_read_b128 v[168:171], v191 offset:51200
	ds_read_b128 v[172:175], v191 offset:52224
	ds_read_b128 v[176:179], v191 offset:53248
	ds_read_b128 v[198:201], v191 offset:54272
	ds_read_b128 v[202:205], v191 offset:55296
	ds_read_b128 v[206:209], v191 offset:56320
	global_load_lds_dwordx4 v136, s[100:101]
	s_mov_b32 m0, s22
	s_nop 0
	global_load_lds_dwordx4 v140, s[100:101]
	s_waitcnt vmcnt(10)
	s_barrier
	s_waitcnt lgkmcnt(0)
	s_setprio 1
	s_waitcnt lgkmcnt(0)
	v_mfma_f32_16x16x32_bf16 v[60:63], v[128:131], v[160:163], v[60:63]
	v_mfma_f32_16x16x32_bf16 v[56:59], v[152:155], v[160:163], v[56:59]
	v_mfma_f32_16x16x32_bf16 v[44:47], v[128:131], v[168:171], v[44:47]
	v_mfma_f32_16x16x32_bf16 v[40:43], v[152:155], v[168:171], v[40:43]
	v_mfma_f32_16x16x32_bf16 v[28:31], v[128:131], v[176:179], v[28:31]
	v_mfma_f32_16x16x32_bf16 v[24:27], v[152:155], v[176:179], v[24:27]
	v_mfma_f32_16x16x32_bf16 v[12:15], v[128:131], v[202:205], v[12:15]
	v_mfma_f32_16x16x32_bf16 v[8:11], v[152:155], v[202:205], v[8:11]
	v_mfma_f32_16x16x32_bf16 v[60:63], v[132:135], v[164:167], v[60:63]
	v_mfma_f32_16x16x32_bf16 v[56:59], v[156:159], v[164:167], v[56:59]
	v_mfma_f32_16x16x32_bf16 v[44:47], v[132:135], v[172:175], v[44:47]
	v_mfma_f32_16x16x32_bf16 v[40:43], v[156:159], v[172:175], v[40:43]
	v_mfma_f32_16x16x32_bf16 v[28:31], v[132:135], v[198:201], v[28:31]
	v_mfma_f32_16x16x32_bf16 v[24:27], v[156:159], v[198:201], v[24:27]
	v_mfma_f32_16x16x32_bf16 v[12:15], v[132:135], v[206:209], v[12:15]
	v_mfma_f32_16x16x32_bf16 v[8:11], v[156:159], v[206:209], v[8:11]
	s_setprio 0
	s_barrier
; __device__ __forceinline__ float ss_fix(float raw) { return (float)__float_as_uint(raw) * (1.0f / 256.0f); }
; #define PG8_STAGE(bufoff, gbase, voff) do { _Pragma("unroll") for (int _i = 0; _i < 2; ++_i) \
;         __builtin_amdgcn_global_load_lds((const unsigned*)((const char*)(gbase) + (voff)[_i]), (LAS unsigned*)(lds + (bufoff) + ldsw + _i * 8192), 16, 0, 0); } while (0)
; #define PG8_LDA(dst, b, h) do { _Pragma("unroll") for (int m = 0; m < 4; ++m) _Pragma("unroll") for (int k = 0; k < 2; ++k) dst[m][k] = *(const LAS bf16x8*)(lds + PG8_SA(b, h) + aoff + m * 2048 + k * 1024); } while (0)
; #define PG8_WAIT_V(n) asm volatile("s_waitcnt vmcnt(" #n ")" ::: "memory")
; template <class Epi>
; __device__ __forceinline__ void gemm_phase(LAS unsigned char* lds, const Gemm g, const StaticOrder& S, const Epi& E, int wv) {
;     ...
;             PG8_LDA(At, 1, 1); PG8_STAGE(PG8_SA(1, 0), a3, voffA);
;             PG8_BAR; PG8_WAIT_L(0); PG8_MMA(1, 0, At, B0); PG8_BAR; PG8_SCHED;
;             PG8_STAGE(PG8_SB(1, 1), b3 + hstepB, voffB);
;             PG8_WAIT_V(6); PG8_BAR; PG8_MMA(1, 1, At, B1); PG8_BAR;
;     __device__ __forceinline__ void operator()(const f32x4 (&acc)[2][2][4][2], const Unit& u, int wr, int wc, int fr, int fq) const {
;         const int row0 = u.pm * BM + wr * 64 + fr, col0 = u.pn * BM + wc * 32 + 8 * fq;
;         const bool isq = u.pn < 8;
;         const float* gp = (isq ? gq : gk) + wc * 32 + 8 * fq;
;         const float qs = isq ? 0.08838834764831845f * LOG2E : 1.0f;
;         const f32x4 g0 = *(const f32x4*)gp * qs, g1 = *(const f32x4*)(gp + 4) * qs;
;         float rsv[8];
; #pragma unroll
;         for (int it = 0; it < 8; ++it) rsv[it] = __builtin_amdgcn_rsqf(ss_fix(ss[row0 + (it >> 2) * HALF + (it & 3) * 16]) * (1.0f / DM) + EPS);
; #pragma unroll
;         for (int it = 0; it < 8; ++it) { const int ai = it >> 2, m = it & 3; const float rs = rsv[it];
; #pragma unroll
;             for (int bj = 0; bj < 2; ++bj) { const f32x4 v0 = acc[ai][bj][m][0] * rs, v1 = acc[ai][bj][m][1] * rs;
;                 float sq = (v0[0] * v0[0] + v0[1] * v0[1]) + (v0[2] * v0[2] + v0[3] * v0[3]) + (v1[0] * v1[0] + v1[1] * v1[1]) + (v1[2] * v1[2] + v1[3] * v1[3]);
;                 sq += __shfl_xor(sq, 16); sq += __shfl_xor(sq, 32);
;                 if (fq == 0) P[((ai * HALF + wr * 64 + m * 16 + fr) * 2 + bj) * 4 + wc] = sq; } }
	s_add_u32 s40, s72, 0x80080
	s_addc_u32 s41, s73, 0
	s_add_i32 s39, s42, s9
	s_mov_b32 m0, s39
	s_nop 0
	global_load_lds_dwordx4 v138, s[40:41]
	s_add_i32 m0, s39, 0x2000
	s_nop 0
	global_load_lds_dwordx4 v142, s[40:41]
	ds_read_b128 v[128:131], v190
	ds_read_b128 v[132:135], v190 offset:1024
	ds_read_b128 v[152:155], v190 offset:2048
	ds_read_b128 v[156:159], v190 offset:3072
	s_waitcnt vmcnt(6)
	s_barrier
	s_setprio 1
	v_mfma_f32_16x16x32_bf16 v[52:55], v[210:213], v[160:163], v[52:55]
	v_mfma_f32_16x16x32_bf16 v[48:51], v[218:221], v[160:163], v[48:51]
	v_mfma_f32_16x16x32_bf16 v[36:39], v[210:213], v[168:171], v[36:39]
	v_mfma_f32_16x16x32_bf16 v[32:35], v[218:221], v[168:171], v[32:35]
	v_mfma_f32_16x16x32_bf16 v[20:23], v[210:213], v[176:179], v[20:23]
	v_mfma_f32_16x16x32_bf16 v[16:19], v[218:221], v[176:179], v[16:19]
	v_mfma_f32_16x16x32_bf16 v[4:7], v[210:213], v[202:205], v[4:7]
	v_mfma_f32_16x16x32_bf16 v[0:3], v[218:221], v[202:205], v[0:3]
	v_mfma_f32_16x16x32_bf16 v[52:55], v[214:217], v[164:167], v[52:55]
	v_mfma_f32_16x16x32_bf16 v[48:51], v[222:225], v[164:167], v[48:51]
	v_mfma_f32_16x16x32_bf16 v[36:39], v[214:217], v[172:175], v[36:39]
	v_mfma_f32_16x16x32_bf16 v[32:35], v[222:225], v[172:175], v[32:35]
	v_mfma_f32_16x16x32_bf16 v[20:23], v[214:217], v[198:201], v[20:23]
	v_mfma_f32_16x16x32_bf16 v[16:19], v[222:225], v[198:201], v[16:19]
	v_mfma_f32_16x16x32_bf16 v[4:7], v[214:217], v[206:209], v[4:7]
	v_mfma_f32_16x16x32_bf16 v[0:3], v[222:225], v[206:209], v[0:3]
	s_setprio 0
	s_waitcnt lgkmcnt(0)
	s_add_i32 s38, s38, 2
	s_add_u32 s70, s70, 0x100
	s_addc_u32 s71, s71, 0
	s_add_u32 s34, s34, 0x100
	s_addc_u32 s35, s35, 0
	s_cmp_gt_u32 s38, 29
	s_barrier
	s_cbranch_scc0 .LBB0_208
	v_lshl_add_u32 v168, s20, 8, v183
	v_ashrrev_i32_e32 v169, 31, v168
	v_lshl_add_u64 v[128:129], v[168:169], 2, s[50:51]
	global_load_dword v159, v[128:129], off
	s_cmp_lt_i32 s68, 8
	s_cselect_b64 vcc, -1, 0
	global_load_dword v158, v[128:129], off offset:64
	global_load_dword v157, v[128:129], off offset:128
	global_load_dword v156, v[128:129], off offset:192
	global_load_dword v155, v[128:129], off offset:512
	global_load_dword v154, v[128:129], off offset:576
	global_load_dword v153, v[128:129], off offset:640
	global_load_dword v152, v[128:129], off offset:704
	s_and_b64 s[20:21], vcc, exec
	s_cselect_b32 s20, s52, s54
	s_cselect_b32 s21, s53, s55
	s_add_u32 s20, s20, s25
	s_addc_u32 s21, s21, 0
	global_load_dwordx4 v[128:131], v193, s[20:21] offset:16
	global_load_dwordx4 v[132:135], v193, s[20:21]
	v_and_b32_e32 v161, 64, v195
	v_xor_b32_e32 v160, 16, v195
	v_add_u32_e32 v167, 64, v161
	v_cmp_lt_i32_e64 s[20:21], v160, v167
	s_waitcnt vmcnt(0)
	v_cvt_f32_u32_e32 v159, v159
	v_mul_f32_e32 v159, 0x3b800000, v159
	v_fmamk_f32 v159, v159, 0x3a000000, v194
	v_rsq_f32_e32 v166, v159
	v_cndmask_b32_e64 v159, v195, v160, s[20:21]
	v_lshlrev_b32_e32 v170, 2, v159
	v_pk_mul_f32 v[160:161], v[126:127], v[166:167] op_sel_hi:[1,0]
	v_pk_mul_f32 v[162:163], v[124:125], v[166:167] op_sel_hi:[1,0]
	v_pk_mul_f32 v[172:173], v[120:121], v[166:167] op_sel_hi:[1,0]
	v_mul_f32_e32 v159, v163, v163
	v_mul_f32_e32 v161, v161, v161
	v_pk_mul_f32 v[164:165], v[122:123], v[166:167] op_sel_hi:[1,0]
	v_mul_f32_e32 v163, v173, v173
	v_fmac_f32_e32 v159, v162, v162
	v_fmac_f32_e32 v161, v160, v160
	v_mul_f32_e32 v165, v165, v165
	v_fmac_f32_e32 v163, v172, v172
	v_add_f32_e32 v159, v159, v161
	v_add_f32_e32 v159, v163, v159
	v_fmac_f32_e32 v165, v164, v164
	v_add_f32_e32 v159, v165, v159
	ds_bpermute_b32 v160, v170, v159
	v_xor_b32_e32 v161, 32, v195
	v_cmp_lt_i32_e64 s[20:21], v161, v167
	s_waitcnt lgkmcnt(0)
	v_add_f32_e32 v159, v159, v160
	v_cndmask_b32_e64 v161, v195, v161, s[20:21]
	v_lshlrev_b32_e32 v171, 2, v161
	ds_bpermute_b32 v160, v171, v159
	s_and_saveexec_b64 s[20:21], s[16:17]
	s_cbranch_execz .LBB0_211
	s_waitcnt lgkmcnt(0)
	v_add_f32_e32 v159, v159, v160
	ds_write_b32 v186, v159

; #define PG8_STAGE(bufoff, gbase, voff) do { _Pragma("unroll") for (int _i = 0; _i < 2; ++_i) \
;         __builtin_amdgcn_global_load_lds((const unsigned*)((const char*)(gbase) + (voff)[_i]), (LAS unsigned*)(lds + (bufoff) + ldsw + _i * 8192), 16, 0, 0); } while (0)
; #define PG8_LDA(dst, b, h) do { _Pragma("unroll") for (int m = 0; m < 4; ++m) _Pragma("unroll") for (int k = 0; k < 2; ++k) dst[m][k] = *(const LAS bf16x8*)(lds + PG8_SA(b, h) + aoff + m * 2048 + k * 1024); } while (0)
; #define PG8_LDB(dst, b, h) do { _Pragma("unroll") for (int n = 0; n < 2; ++n) _Pragma("unroll") for (int k = 0; k < 2; ++k) dst[n][k] = *(const LAS bf16x8*)(lds + PG8_SB(b, h) + boff + n * 2048 + k * 1024); } while (0)
; #define PG8_MMA(ai, bj, At, Bt) do { __builtin_amdgcn_s_setprio(1); _Pragma("unroll") for (int m = 0; m < 4; ++m) _Pragma("unroll") for (int n = 0; n < 2; ++n) _Pragma("unroll") for (int k = 0; k < 2; ++k) \
;         acc[ai][bj][m][n] = __builtin_amdgcn_mfma_f32_16x16x32_bf16(Bt[n][k], At[m][k], acc[ai][bj][m][n], 0, 0, 0); __builtin_amdgcn_s_setprio(0); } while (0)
; template <class Epi>
; __device__ __forceinline__ void gemm_phase(LAS unsigned char* lds, const Gemm g, const StaticOrder& S, const Epi& E, int wv) {
;     ...
;         const bool has_next = S.next(ui + 1, nxt);
;         const char* nA = has_next ? (const char*)g.A + (size_t)nxt.pm * tstepA + ((g.adiag & 1) ? (size_t)(nxt.pn >> 1) * K * 2 : 0) + kbeg : cA;
;         const char* nB = has_next ? (const char*)g.Bt + (size_t)nxt.pn * tstepB + kbeg : cB;
;         for (int t = 0; t < nt; t += 2) {
;             const bool last = (t == nt - 2);
;             const char* a1 = cA + (ptrdiff_t)(t + 1) * kstep;
;             const char* a2 = last ? nA : cA + (ptrdiff_t)(t + 2) * kstep; const char* b2 = last ? nB : cB + (ptrdiff_t)(t + 2) * kstep;
;             const char* a3 = a2 + kstep; const char* b3 = b2 + kstep;
;             PG8_LDB(B0, 0, 0); PG8_SCHED; PG8_LDA(At, 0, 0); PG8_STAGE(PG8_SA(1, 1), a1 + hstepA, voffA);
;             PG8_WAIT_L(8); PG8_BAR; PG8_WAIT_L(0); PG8_MMA(0, 0, At, B0); PG8_BAR; PG8_SCHED;
;     ...
; #pragma unroll
;         for (int a = 0; a < 2; ++a)
; #pragma unroll
;             for (int b = 0; b < 2; ++b)
; #pragma unroll
;                 for (int m = 0; m < 4; ++m)
; #pragma unroll
;                     for (int n = 0; n < 2; ++n) acc[a][b][m][n] = (f32x4){0.f, 0.f, 0.f, 0.f};
.LBB0_258:
	s_ashr_i32 s59, s58, 31
	s_lshl_b64 s[34:35], s[58:59], 20
	v_cmp_lt_i64_e32 vcc, s[60:61], v[142:143]
	s_add_u32 s60, s5, s34
	s_addc_u32 s61, s6, s35
	s_and_b64 s[34:35], vcc, exec
	s_cselect_b32 s34, s61, s67
	s_cselect_b32 s35, s60, s66
	s_ashr_i32 s57, s56, 31
	s_lshl_b64 s[38:39], s[56:57], 20
	s_add_u32 s62, s7, s38
	s_addc_u32 s63, s8, s39
	s_and_b64 s[38:39], vcc, exec
	s_cselect_b32 s38, s63, s69
	s_cselect_b32 s39, s62, s68
	s_add_u32 s66, s66, 0x80080
	s_addc_u32 s67, s67, 0
	s_add_u32 s40, s68, 0x100
	v_mov_b32_e32 v0, 0
	s_addc_u32 s41, s69, 0
	s_mov_b32 s42, -2
	v_mov_b32_e32 v1, v0
	v_mov_b32_e32 v2, v0
	v_mov_b32_e32 v3, v0
	v_mov_b32_e32 v4, v0
	v_mov_b32_e32 v5, v0
	v_mov_b32_e32 v6, v0
	v_mov_b32_e32 v7, v0
	v_mov_b32_e32 v8, v0
	v_mov_b32_e32 v9, v0
	v_mov_b32_e32 v10, v0
	v_mov_b32_e32 v11, v0
	v_mov_b32_e32 v16, v0
	v_mov_b32_e32 v17, v0
	v_mov_b32_e32 v18, v0
	v_mov_b32_e32 v19, v0
	v_mov_b32_e32 v24, v0
	v_mov_b32_e32 v25, v0
	v_mov_b32_e32 v26, v0
	v_mov_b32_e32 v27, v0
	v_mov_b32_e32 v32, v0
	v_mov_b32_e32 v33, v0
	v_mov_b32_e32 v34, v0
	v_mov_b32_e32 v35, v0
	v_mov_b32_e32 v40, v0
	v_mov_b32_e32 v41, v0
	v_mov_b32_e32 v42, v0
	v_mov_b32_e32 v43, v0
	v_mov_b32_e32 v48, v0
	v_mov_b32_e32 v49, v0
	v_mov_b32_e32 v50, v0
	v_mov_b32_e32 v51, v0
	v_mov_b32_e32 v12, v0
	v_mov_b32_e32 v13, v0
	v_mov_b32_e32 v14, v0
	v_mov_b32_e32 v15, v0
	v_mov_b32_e32 v20, v0
	v_mov_b32_e32 v21, v0
	v_mov_b32_e32 v22, v0
	v_mov_b32_e32 v23, v0
	v_mov_b32_e32 v28, v0
	v_mov_b32_e32 v29, v0
	v_mov_b32_e32 v30, v0
	v_mov_b32_e32 v31, v0
	v_mov_b32_e32 v36, v0
	v_mov_b32_e32 v37, v0
	v_mov_b32_e32 v38, v0
	v_mov_b32_e32 v39, v0
	v_mov_b32_e32 v44, v0
	v_mov_b32_e32 v45, v0
	v_mov_b32_e32 v46, v0
	v_mov_b32_e32 v47, v0
	v_mov_b32_e32 v52, v0
	v_mov_b32_e32 v53, v0
	v_mov_b32_e32 v54, v0
	v_mov_b32_e32 v55, v0
	v_mov_b32_e32 v56, v0
	v_mov_b32_e32 v57, v0
	v_mov_b32_e32 v58, v0
	v_mov_b32_e32 v59, v0
	v_mov_b32_e32 v60, v0
	v_mov_b32_e32 v61, v0
	v_mov_b32_e32 v62, v0
	v_mov_b32_e32 v63, v0
	v_mov_b32_e32 v64, v0
	v_mov_b32_e32 v65, v0
	v_mov_b32_e32 v66, v0
	v_mov_b32_e32 v67, v0
	v_mov_b32_e32 v68, v0
	v_mov_b32_e32 v69, v0
	v_mov_b32_e32 v70, v0
	v_mov_b32_e32 v71, v0
	v_mov_b32_e32 v76, v0
	v_mov_b32_e32 v77, v0
	v_mov_b32_e32 v78, v0
	v_mov_b32_e32 v79, v0
	v_mov_b32_e32 v84, v0
	v_mov_b32_e32 v85, v0
	v_mov_b32_e32 v86, v0
	v_mov_b32_e32 v87, v0
	v_mov_b32_e32 v92, v0
	v_mov_b32_e32 v93, v0
	v_mov_b32_e32 v94, v0
	v_mov_b32_e32 v95, v0
	v_mov_b32_e32 v100, v0
	v_mov_b32_e32 v101, v0
	v_mov_b32_e32 v102, v0
	v_mov_b32_e32 v103, v0
	v_mov_b32_e32 v108, v0
	v_mov_b32_e32 v109, v0
	v_mov_b32_e32 v110, v0
	v_mov_b32_e32 v111, v0
	v_mov_b32_e32 v116, v0
	v_mov_b32_e32 v117, v0
	v_mov_b32_e32 v118, v0
	v_mov_b32_e32 v119, v0
	v_mov_b32_e32 v72, v0
	v_mov_b32_e32 v73, v0
	v_mov_b32_e32 v74, v0
	v_mov_b32_e32 v75, v0
	v_mov_b32_e32 v80, v0
	v_mov_b32_e32 v81, v0
	v_mov_b32_e32 v82, v0
	v_mov_b32_e32 v83, v0
	v_mov_b32_e32 v88, v0
	v_mov_b32_e32 v89, v0
	v_mov_b32_e32 v90, v0
	v_mov_b32_e32 v91, v0
	v_mov_b32_e32 v96, v0
	v_mov_b32_e32 v97, v0
	v_mov_b32_e32 v98, v0
	v_mov_b32_e32 v99, v0
	v_mov_b32_e32 v104, v0
	v_mov_b32_e32 v105, v0
	v_mov_b32_e32 v106, v0
	v_mov_b32_e32 v107, v0
	v_mov_b32_e32 v112, v0
	v_mov_b32_e32 v113, v0
	v_mov_b32_e32 v114, v0
	v_mov_b32_e32 v115, v0
	v_mov_b32_e32 v120, v0
	v_mov_b32_e32 v121, v0
	v_mov_b32_e32 v122, v0
	v_mov_b32_e32 v123, v0
	v_mov_b32_e32 v124, v0
	v_mov_b32_e32 v125, v0
	v_mov_b32_e32 v126, v0
	v_mov_b32_e32 v127, v0
	ds_read_b128 v[146:149], v167
	ds_read_b128 v[150:153], v167 offset:1024
	ds_read_b128 v[154:157], v167 offset:2048
	ds_read_b128 v[158:161], v167 offset:3072
.LBB0_259:
	s_add_u32 s43, s66, 0xfff80080
	s_addc_u32 s44, s67, -1
	s_cmp_eq_u32 s42, 28
	s_cselect_b32 s71, s34, s44
	s_cselect_b32 s70, s35, s43
	s_cselect_b32 s69, s38, s41
	s_cselect_b32 s68, s39, s40
	s_add_i32 m0, s10, 0xc000
	ds_read_b128 v[172:175], v168
	ds_read_b128 v[176:179], v168 offset:1024
	ds_read_b128 v[184:187], v168 offset:2048
	ds_read_b128 v[188:191], v168 offset:3072
	ds_read_b128 v[192:195], v168 offset:4096
	ds_read_b128 v[196:199], v168 offset:5120
	ds_read_b128 v[200:203], v168 offset:6144
	ds_read_b128 v[204:207], v168 offset:7168
	global_load_lds_dwordx4 v138, s[66:67]
	s_add_i32 m0, s10, 0xe000
	s_nop 0
	global_load_lds_dwordx4 v140, s[66:67]
	s_waitcnt lgkmcnt(8)
	s_barrier
	s_waitcnt lgkmcnt(0)
	s_setprio 1
	s_waitcnt lgkmcnt(0)
	v_mfma_f32_16x16x32_bf16 v[124:127], v[146:149], v[172:175], v[124:127]
	v_mfma_f32_16x16x32_bf16 v[120:123], v[154:157], v[172:175], v[120:123]
	v_mfma_f32_16x16x32_bf16 v[112:115], v[146:149], v[184:187], v[112:115]
	v_mfma_f32_16x16x32_bf16 v[104:107], v[154:157], v[184:187], v[104:107]
	v_mfma_f32_16x16x32_bf16 v[96:99], v[146:149], v[192:195], v[96:99]
	v_mfma_f32_16x16x32_bf16 v[88:91], v[154:157], v[192:195], v[88:91]
	v_mfma_f32_16x16x32_bf16 v[80:83], v[146:149], v[200:203], v[80:83]
	v_mfma_f32_16x16x32_bf16 v[72:75], v[154:157], v[200:203], v[72:75]
	v_mfma_f32_16x16x32_bf16 v[124:127], v[150:153], v[176:179], v[124:127]
	v_mfma_f32_16x16x32_bf16 v[120:123], v[158:161], v[176:179], v[120:123]
	v_mfma_f32_16x16x32_bf16 v[112:115], v[150:153], v[188:191], v[112:115]
	v_mfma_f32_16x16x32_bf16 v[104:107], v[158:161], v[188:191], v[104:107]
	v_mfma_f32_16x16x32_bf16 v[96:99], v[150:153], v[196:199], v[96:99]
	v_mfma_f32_16x16x32_bf16 v[88:91], v[158:161], v[196:199], v[88:91]
	v_mfma_f32_16x16x32_bf16 v[80:83], v[150:153], v[204:207], v[80:83]
	v_mfma_f32_16x16x32_bf16 v[72:75], v[158:161], v[204:207], v[72:75]
	s_setprio 0
	s_barrier
; #define PG8_STAGE(bufoff, gbase, voff) do { _Pragma("unroll") for (int _i = 0; _i < 2; ++_i) \
;         __builtin_amdgcn_global_load_lds((const unsigned*)((const char*)(gbase) + (voff)[_i]), (LAS unsigned*)(lds + (bufoff) + ldsw + _i * 8192), 16, 0, 0); } while (0)
; #define PG8_LDA(dst, b, h) do { _Pragma("unroll") for (int m = 0; m < 4; ++m) _Pragma("unroll") for (int k = 0; k < 2; ++k) dst[m][k] = *(const LAS bf16x8*)(lds + PG8_SA(b, h) + aoff + m * 2048 + k * 1024); } while (0)
; #define PG8_LDB(dst, b, h) do { _Pragma("unroll") for (int n = 0; n < 2; ++n) _Pragma("unroll") for (int k = 0; k < 2; ++k) dst[n][k] = *(const LAS bf16x8*)(lds + PG8_SB(b, h) + boff + n * 2048 + k * 1024); } while (0)
; #define PG8_MMA(ai, bj, At, Bt) do { __builtin_amdgcn_s_setprio(1); _Pragma("unroll") for (int m = 0; m < 4; ++m) _Pragma("unroll") for (int n = 0; n < 2; ++n) _Pragma("unroll") for (int k = 0; k < 2; ++k) \
;         acc[ai][bj][m][n] = __builtin_amdgcn_mfma_f32_16x16x32_bf16(Bt[n][k], At[m][k], acc[ai][bj][m][n], 0, 0, 0); __builtin_amdgcn_s_setprio(0); } while (0)
; #define PG8_WAIT_V(n) asm volatile("s_waitcnt vmcnt(" #n ")" ::: "memory")
; #define PG8_WAIT_L(n) asm volatile("s_waitcnt lgkmcnt(" #n ")" ::: "memory")
; #define PG8_BAR __builtin_amdgcn_s_barrier()
; #define PG8_SCHED __builtin_amdgcn_sched_barrier(0)
; template <class Epi>
; __device__ __forceinline__ void gemm_phase(LAS unsigned char* lds, const Gemm g, const StaticOrder& S, const Epi& E, int wv) {
;     ...
;             PG8_LDB(B1, 0, 1); PG8_STAGE(PG8_SB(0, 0), b2, voffB);
;             PG8_BAR; PG8_WAIT_L(0); PG8_MMA(0, 1, At, B1); PG8_BAR;
;             PG8_LDA(At, 0, 1); PG8_STAGE(PG8_SA(0, 0), a2, voffA);
;             PG8_BAR; PG8_WAIT_L(0); PG8_MMA(1, 0, At, B0); PG8_BAR; PG8_SCHED;
;             PG8_STAGE(PG8_SB(0, 1), b2 + hstepB, voffB);
;             PG8_WAIT_V(6); PG8_BAR; PG8_MMA(1, 1, At, B1); PG8_BAR;
;             PG8_LDB(B0, 1, 0); PG8_SCHED; PG8_LDA(At, 1, 0); PG8_STAGE(PG8_SA(0, 1), a2 + hstepA, voffA);
;             PG8_WAIT_L(8); PG8_BAR; PG8_WAIT_L(0); PG8_MMA(0, 0, At, B0); PG8_BAR; PG8_SCHED;
	s_add_i32 s43, s23, s9
	s_add_u32 s98, s68, s20
	s_addc_u32 s99, s69, s21
	s_mov_b32 m0, s43
	ds_read_b128 v[208:211], v169
	ds_read_b128 v[212:215], v169 offset:1024
	ds_read_b128 v[216:219], v169 offset:2048
	ds_read_b128 v[220:223], v169 offset:3072
	global_load_lds_dwordx4 v130, s[68:69]
	s_add_i32 m0, s43, 0x2000
	s_nop 0
	global_load_lds_dwordx4 v134, s[68:69]
	s_barrier
	s_waitcnt lgkmcnt(0)
	s_setprio 1
	s_waitcnt lgkmcnt(0)
	v_mfma_f32_16x16x32_bf16 v[116:119], v[208:211], v[172:175], v[116:119]
	v_mfma_f32_16x16x32_bf16 v[108:111], v[216:219], v[172:175], v[108:111]
	v_mfma_f32_16x16x32_bf16 v[100:103], v[208:211], v[184:187], v[100:103]
	v_mfma_f32_16x16x32_bf16 v[92:95], v[216:219], v[184:187], v[92:95]
	v_mfma_f32_16x16x32_bf16 v[84:87], v[208:211], v[192:195], v[84:87]
	v_mfma_f32_16x16x32_bf16 v[76:79], v[216:219], v[192:195], v[76:79]
	v_mfma_f32_16x16x32_bf16 v[68:71], v[208:211], v[200:203], v[68:71]
	v_mfma_f32_16x16x32_bf16 v[64:67], v[216:219], v[200:203], v[64:67]
	v_mfma_f32_16x16x32_bf16 v[116:119], v[212:215], v[176:179], v[116:119]
	v_mfma_f32_16x16x32_bf16 v[108:111], v[220:223], v[176:179], v[108:111]
	v_mfma_f32_16x16x32_bf16 v[100:103], v[212:215], v[188:191], v[100:103]
	v_mfma_f32_16x16x32_bf16 v[92:95], v[220:223], v[188:191], v[92:95]
	v_mfma_f32_16x16x32_bf16 v[84:87], v[212:215], v[196:199], v[84:87]
	v_mfma_f32_16x16x32_bf16 v[76:79], v[220:223], v[196:199], v[76:79]
	v_mfma_f32_16x16x32_bf16 v[68:71], v[212:215], v[204:207], v[68:71]
	v_mfma_f32_16x16x32_bf16 v[64:67], v[220:223], v[204:207], v[64:67]
	s_setprio 0
	s_mov_b32 m0, s10
	s_add_u32 s100, s70, s20
	s_addc_u32 s101, s71, s21
	s_barrier
	ds_read_b128 v[172:175], v168 offset:16384
	ds_read_b128 v[176:179], v168 offset:17408
	ds_read_b128 v[184:187], v168 offset:18432
	ds_read_b128 v[188:191], v168 offset:19456
	ds_read_b128 v[192:195], v168 offset:20480
	ds_read_b128 v[196:199], v168 offset:21504
	ds_read_b128 v[200:203], v168 offset:22528
	ds_read_b128 v[204:207], v168 offset:23552
	global_load_lds_dwordx4 v128, s[70:71]
	s_mov_b32 m0, s11
	s_nop 0
	global_load_lds_dwordx4 v132, s[70:71]
	s_waitcnt vmcnt(10)
	s_barrier
	s_waitcnt lgkmcnt(0)
	s_setprio 1
	s_waitcnt lgkmcnt(0)
	v_mfma_f32_16x16x32_bf16 v[60:63], v[146:149], v[172:175], v[60:63]
	v_mfma_f32_16x16x32_bf16 v[56:59], v[154:157], v[172:175], v[56:59]
	v_mfma_f32_16x16x32_bf16 v[52:55], v[146:149], v[184:187], v[52:55]
	v_mfma_f32_16x16x32_bf16 v[44:47], v[154:157], v[184:187], v[44:47]
	v_mfma_f32_16x16x32_bf16 v[36:39], v[146:149], v[192:195], v[36:39]
	v_mfma_f32_16x16x32_bf16 v[28:31], v[154:157], v[192:195], v[28:31]
	v_mfma_f32_16x16x32_bf16 v[20:23], v[146:149], v[200:203], v[20:23]
	v_mfma_f32_16x16x32_bf16 v[12:15], v[154:157], v[200:203], v[12:15]
	v_mfma_f32_16x16x32_bf16 v[60:63], v[150:153], v[176:179], v[60:63]
	v_mfma_f32_16x16x32_bf16 v[56:59], v[158:161], v[176:179], v[56:59]
	v_mfma_f32_16x16x32_bf16 v[52:55], v[150:153], v[188:191], v[52:55]
	v_mfma_f32_16x16x32_bf16 v[44:47], v[158:161], v[188:191], v[44:47]
	v_mfma_f32_16x16x32_bf16 v[36:39], v[150:153], v[196:199], v[36:39]
	v_mfma_f32_16x16x32_bf16 v[28:31], v[158:161], v[196:199], v[28:31]
	v_mfma_f32_16x16x32_bf16 v[20:23], v[150:153], v[204:207], v[20:23]
	v_mfma_f32_16x16x32_bf16 v[12:15], v[158:161], v[204:207], v[12:15]
	s_setprio 0
	s_barrier
	s_add_u32 s44, s68, 0x80000
	s_addc_u32 s45, s69, 0
	s_add_i32 s43, s24, s9
	s_mov_b32 m0, s43
	s_nop 0
	global_load_lds_dwordx4 v130, s[44:45]
	s_add_i32 m0, s43, 0x2000
	s_nop 0
	global_load_lds_dwordx4 v134, s[44:45]
	s_add_i32 s43, 0, 0x18000
	v_add_u32_e32 v158, s43, v165
	ds_read_b128 v[146:149], v158
	ds_read_b128 v[150:153], v158 offset:1024
	ds_read_b128 v[154:157], v158 offset:2048
	ds_read_b128 v[158:161], v158 offset:3072
	s_waitcnt vmcnt(6)
	s_barrier
	s_setprio 1
	v_mfma_f32_16x16x32_bf16 v[48:51], v[208:211], v[172:175], v[48:51]
	v_mfma_f32_16x16x32_bf16 v[40:43], v[216:219], v[172:175], v[40:43]
	v_mfma_f32_16x16x32_bf16 v[32:35], v[208:211], v[184:187], v[32:35]
	v_mfma_f32_16x16x32_bf16 v[24:27], v[216:219], v[184:187], v[24:27]
	v_mfma_f32_16x16x32_bf16 v[16:19], v[208:211], v[192:195], v[16:19]
	v_mfma_f32_16x16x32_bf16 v[8:11], v[216:219], v[192:195], v[8:11]
	v_mfma_f32_16x16x32_bf16 v[4:7], v[208:211], v[200:203], v[4:7]
	v_mfma_f32_16x16x32_bf16 v[0:3], v[216:219], v[200:203], v[0:3]
	v_mfma_f32_16x16x32_bf16 v[48:51], v[212:215], v[176:179], v[48:51]
	v_mfma_f32_16x16x32_bf16 v[40:43], v[220:223], v[176:179], v[40:43]
	v_mfma_f32_16x16x32_bf16 v[32:35], v[212:215], v[188:191], v[32:35]
	v_mfma_f32_16x16x32_bf16 v[24:27], v[220:223], v[188:191], v[24:27]
	v_mfma_f32_16x16x32_bf16 v[16:19], v[212:215], v[196:199], v[16:19]
	v_mfma_f32_16x16x32_bf16 v[8:11], v[220:223], v[196:199], v[8:11]
	v_mfma_f32_16x16x32_bf16 v[4:7], v[212:215], v[204:207], v[4:7]
	v_mfma_f32_16x16x32_bf16 v[0:3], v[220:223], v[204:207], v[0:3]
	s_setprio 0
	s_waitcnt lgkmcnt(0)
	s_barrier
	s_add_u32 s44, s70, 0x80000
	s_addc_u32 s45, s71, 0
	s_mov_b32 m0, s12
	ds_read_b128 v[172:175], v168 offset:32768
	ds_read_b128 v[176:179], v168 offset:33792
	ds_read_b128 v[184:187], v168 offset:34816
	ds_read_b128 v[188:191], v168 offset:35840
	ds_read_b128 v[192:195], v168 offset:36864
	ds_read_b128 v[196:199], v168 offset:37888
	ds_read_b128 v[200:203], v168 offset:38912
	ds_read_b128 v[204:207], v168 offset:39936
	global_load_lds_dwordx4 v128, s[44:45]
	s_mov_b32 m0, s13
	s_nop 0
	global_load_lds_dwordx4 v132, s[44:45]
	s_waitcnt lgkmcnt(8)
	s_barrier
; #define PG8_STAGE(bufoff, gbase, voff) do { _Pragma("unroll") for (int _i = 0; _i < 2; ++_i) \
;         __builtin_amdgcn_global_load_lds((const unsigned*)((const char*)(gbase) + (voff)[_i]), (LAS unsigned*)(lds + (bufoff) + ldsw + _i * 8192), 16, 0, 0); } while (0)
; #define PG8_LDA(dst, b, h) do { _Pragma("unroll") for (int m = 0; m < 4; ++m) _Pragma("unroll") for (int k = 0; k < 2; ++k) dst[m][k] = *(const LAS bf16x8*)(lds + PG8_SA(b, h) + aoff + m * 2048 + k * 1024); } while (0)
; #define PG8_LDB(dst, b, h) do { _Pragma("unroll") for (int n = 0; n < 2; ++n) _Pragma("unroll") for (int k = 0; k < 2; ++k) dst[n][k] = *(const LAS bf16x8*)(lds + PG8_SB(b, h) + boff + n * 2048 + k * 1024); } while (0)
; #define PG8_MMA(ai, bj, At, Bt) do { __builtin_amdgcn_s_setprio(1); _Pragma("unroll") for (int m = 0; m < 4; ++m) _Pragma("unroll") for (int n = 0; n < 2; ++n) _Pragma("unroll") for (int k = 0; k < 2; ++k) \
;         acc[ai][bj][m][n] = __builtin_amdgcn_mfma_f32_16x16x32_bf16(Bt[n][k], At[m][k], acc[ai][bj][m][n], 0, 0, 0); __builtin_amdgcn_s_setprio(0); } while (0)
; #define PG8_WAIT_V(n) asm volatile("s_waitcnt vmcnt(" #n ")" ::: "memory")
; #define PG8_WAIT_L(n) asm volatile("s_waitcnt lgkmcnt(" #n ")" ::: "memory")
; #define PG8_BAR __builtin_amdgcn_s_barrier()
; #define PG8_SCHED __builtin_amdgcn_sched_barrier(0)
; template <class Epi>
; __device__ __forceinline__ void gemm_phase(LAS unsigned char* lds, const Gemm g, const StaticOrder& S, const Epi& E, int wv) {
;     ...
;             PG8_WAIT_L(8); PG8_BAR; PG8_WAIT_L(0); PG8_MMA(0, 0, At, B0); PG8_BAR; PG8_SCHED;
;             PG8_LDB(B1, 1, 1); PG8_STAGE(PG8_SB(1, 0), b3, voffB);
;             PG8_BAR; PG8_WAIT_L(0); PG8_MMA(0, 1, At, B1); PG8_BAR;
;             PG8_LDA(At, 1, 1); PG8_STAGE(PG8_SA(1, 0), a3, voffA);
;             PG8_BAR; PG8_WAIT_L(0); PG8_MMA(1, 0, At, B0); PG8_BAR; PG8_SCHED;
;             PG8_STAGE(PG8_SB(1, 1), b3 + hstepB, voffB);
;             PG8_WAIT_V(6); PG8_BAR; PG8_MMA(1, 1, At, B1); PG8_BAR;
	s_waitcnt lgkmcnt(0)
	s_setprio 1
	s_waitcnt lgkmcnt(0)
	v_mfma_f32_16x16x32_bf16 v[124:127], v[146:149], v[172:175], v[124:127]
	v_mfma_f32_16x16x32_bf16 v[120:123], v[154:157], v[172:175], v[120:123]
	v_mfma_f32_16x16x32_bf16 v[112:115], v[146:149], v[184:187], v[112:115]
	v_mfma_f32_16x16x32_bf16 v[104:107], v[154:157], v[184:187], v[104:107]
	v_mfma_f32_16x16x32_bf16 v[96:99], v[146:149], v[192:195], v[96:99]
	v_mfma_f32_16x16x32_bf16 v[88:91], v[154:157], v[192:195], v[88:91]
	v_mfma_f32_16x16x32_bf16 v[80:83], v[146:149], v[200:203], v[80:83]
	v_mfma_f32_16x16x32_bf16 v[72:75], v[154:157], v[200:203], v[72:75]
	v_mfma_f32_16x16x32_bf16 v[124:127], v[150:153], v[176:179], v[124:127]
	v_mfma_f32_16x16x32_bf16 v[120:123], v[158:161], v[176:179], v[120:123]
	v_mfma_f32_16x16x32_bf16 v[112:115], v[150:153], v[188:191], v[112:115]
	v_mfma_f32_16x16x32_bf16 v[104:107], v[158:161], v[188:191], v[104:107]
	v_mfma_f32_16x16x32_bf16 v[96:99], v[150:153], v[196:199], v[96:99]
	v_mfma_f32_16x16x32_bf16 v[88:91], v[158:161], v[196:199], v[88:91]
	v_mfma_f32_16x16x32_bf16 v[80:83], v[150:153], v[204:207], v[80:83]
	v_mfma_f32_16x16x32_bf16 v[72:75], v[158:161], v[204:207], v[72:75]
	s_setprio 0
	s_barrier
	s_add_i32 s46, 0, 0x1c000
	s_add_i32 s43, s43, s9
	v_add_u32_e32 v171, s46, v165
	s_mov_b32 m0, s43
	ds_read_b128 v[208:211], v171
	ds_read_b128 v[212:215], v171 offset:1024
	ds_read_b128 v[216:219], v171 offset:2048
	ds_read_b128 v[220:223], v171 offset:3072
	global_load_lds_dwordx4 v130, s[98:99]
	s_add_i32 m0, s43, 0x2000
	s_nop 0
	global_load_lds_dwordx4 v134, s[98:99]
	s_barrier
	s_waitcnt lgkmcnt(0)
	s_setprio 1
	s_waitcnt lgkmcnt(0)
	v_mfma_f32_16x16x32_bf16 v[116:119], v[208:211], v[172:175], v[116:119]
	v_mfma_f32_16x16x32_bf16 v[108:111], v[216:219], v[172:175], v[108:111]
	v_mfma_f32_16x16x32_bf16 v[100:103], v[208:211], v[184:187], v[100:103]
	v_mfma_f32_16x16x32_bf16 v[92:95], v[216:219], v[184:187], v[92:95]
	v_mfma_f32_16x16x32_bf16 v[84:87], v[208:211], v[192:195], v[84:87]
	v_mfma_f32_16x16x32_bf16 v[76:79], v[216:219], v[192:195], v[76:79]
	v_mfma_f32_16x16x32_bf16 v[68:71], v[208:211], v[200:203], v[68:71]
	v_mfma_f32_16x16x32_bf16 v[64:67], v[216:219], v[200:203], v[64:67]
	v_mfma_f32_16x16x32_bf16 v[116:119], v[212:215], v[176:179], v[116:119]
	v_mfma_f32_16x16x32_bf16 v[108:111], v[220:223], v[176:179], v[108:111]
	v_mfma_f32_16x16x32_bf16 v[100:103], v[212:215], v[188:191], v[100:103]
	v_mfma_f32_16x16x32_bf16 v[92:95], v[220:223], v[188:191], v[92:95]
	v_mfma_f32_16x16x32_bf16 v[84:87], v[212:215], v[196:199], v[84:87]
	v_mfma_f32_16x16x32_bf16 v[76:79], v[220:223], v[196:199], v[76:79]
	v_mfma_f32_16x16x32_bf16 v[68:71], v[212:215], v[204:207], v[68:71]
	v_mfma_f32_16x16x32_bf16 v[64:67], v[220:223], v[204:207], v[64:67]
	s_setprio 0
	s_mov_b32 m0, s15
	s_barrier
	ds_read_b128 v[172:175], v168 offset:49152
	ds_read_b128 v[176:179], v168 offset:50176
	ds_read_b128 v[184:187], v168 offset:51200
	ds_read_b128 v[188:191], v168 offset:52224
	ds_read_b128 v[192:195], v168 offset:53248
	ds_read_b128 v[196:199], v168 offset:54272
	ds_read_b128 v[200:203], v168 offset:55296
	ds_read_b128 v[204:207], v168 offset:56320
	global_load_lds_dwordx4 v128, s[100:101]
	s_mov_b32 m0, s22
	s_nop 0
	global_load_lds_dwordx4 v132, s[100:101]
	s_waitcnt vmcnt(10)
	s_barrier
	s_waitcnt lgkmcnt(0)
	s_setprio 1
	s_waitcnt lgkmcnt(0)
	v_mfma_f32_16x16x32_bf16 v[60:63], v[146:149], v[172:175], v[60:63]
	v_mfma_f32_16x16x32_bf16 v[56:59], v[154:157], v[172:175], v[56:59]
	v_mfma_f32_16x16x32_bf16 v[52:55], v[146:149], v[184:187], v[52:55]
	v_mfma_f32_16x16x32_bf16 v[44:47], v[154:157], v[184:187], v[44:47]
	v_mfma_f32_16x16x32_bf16 v[36:39], v[146:149], v[192:195], v[36:39]
	v_mfma_f32_16x16x32_bf16 v[28:31], v[154:157], v[192:195], v[28:31]
	v_mfma_f32_16x16x32_bf16 v[20:23], v[146:149], v[200:203], v[20:23]
	v_mfma_f32_16x16x32_bf16 v[12:15], v[154:157], v[200:203], v[12:15]
	v_mfma_f32_16x16x32_bf16 v[60:63], v[150:153], v[176:179], v[60:63]
	v_mfma_f32_16x16x32_bf16 v[56:59], v[158:161], v[176:179], v[56:59]
	v_mfma_f32_16x16x32_bf16 v[52:55], v[150:153], v[188:191], v[52:55]
	v_mfma_f32_16x16x32_bf16 v[44:47], v[158:161], v[188:191], v[44:47]
	v_mfma_f32_16x16x32_bf16 v[36:39], v[150:153], v[196:199], v[36:39]
	v_mfma_f32_16x16x32_bf16 v[28:31], v[158:161], v[196:199], v[28:31]
	v_mfma_f32_16x16x32_bf16 v[20:23], v[150:153], v[204:207], v[20:23]
	v_mfma_f32_16x16x32_bf16 v[12:15], v[158:161], v[204:207], v[12:15]
	s_setprio 0
	s_barrier
	s_add_u32 s44, s68, 0x80080
	s_addc_u32 s45, s69, 0
	s_add_i32 s43, s46, s9
	s_mov_b32 m0, s43
	s_nop 0
	global_load_lds_dwordx4 v130, s[44:45]
	s_add_i32 m0, s43, 0x2000
	s_nop 0
	global_load_lds_dwordx4 v134, s[44:45]
	ds_read_b128 v[146:149], v167
	ds_read_b128 v[150:153], v167 offset:1024
	ds_read_b128 v[154:157], v167 offset:2048
	ds_read_b128 v[158:161], v167 offset:3072
	s_waitcnt vmcnt(6)
	s_barrier
	s_setprio 1
	v_mfma_f32_16x16x32_bf16 v[48:51], v[208:211], v[172:175], v[48:51]
	v_mfma_f32_16x16x32_bf16 v[40:43], v[216:219], v[172:175], v[40:43]
	v_mfma_f32_16x16x32_bf16 v[32:35], v[208:211], v[184:187], v[32:35]
	v_mfma_f32_16x16x32_bf16 v[24:27], v[216:219], v[184:187], v[24:27]
	v_mfma_f32_16x16x32_bf16 v[16:19], v[208:211], v[192:195], v[16:19]
	v_mfma_f32_16x16x32_bf16 v[8:11], v[216:219], v[192:195], v[8:11]
	v_mfma_f32_16x16x32_bf16 v[4:7], v[208:211], v[200:203], v[4:7]
	v_mfma_f32_16x16x32_bf16 v[0:3], v[216:219], v[200:203], v[0:3]
	v_mfma_f32_16x16x32_bf16 v[48:51], v[212:215], v[176:179], v[48:51]
	v_mfma_f32_16x16x32_bf16 v[40:43], v[220:223], v[176:179], v[40:43]
	v_mfma_f32_16x16x32_bf16 v[32:35], v[212:215], v[188:191], v[32:35]
	v_mfma_f32_16x16x32_bf16 v[24:27], v[220:223], v[188:191], v[24:27]
	v_mfma_f32_16x16x32_bf16 v[16:19], v[212:215], v[196:199], v[16:19]
	v_mfma_f32_16x16x32_bf16 v[8:11], v[220:223], v[196:199], v[8:11]
	v_mfma_f32_16x16x32_bf16 v[4:7], v[212:215], v[204:207], v[4:7]
	v_mfma_f32_16x16x32_bf16 v[0:3], v[220:223], v[204:207], v[0:3]
	s_setprio 0
	s_waitcnt lgkmcnt(0)
	s_add_i32 s42, s42, 2
	s_add_u32 s66, s66, 0x100
	s_addc_u32 s67, s67, 0
	s_add_u32 s40, s40, 0x100
	s_addc_u32 s41, s41, 0
	s_cmp_gt_u32 s42, 29
	s_barrier
; __device__ __forceinline__ float fast_sigmoid(float x) { return __builtin_amdgcn_rcpf(1.0f + __builtin_amdgcn_exp2f(-x * LOG2E)); }
; __device__ __forceinline__ float ss_fix(float raw) { return (float)__float_as_uint(raw) * (1.0f / 256.0f); }
;     __device__ __forceinline__ void operator()(const f32x4 (&acc)[2][2][4][2], const Unit& u, int wr, int wc, int fr, int fq) const {
;     ...
;         if (SM == 2) {
; #pragma unroll
;             for (int bj = 0; bj < 2; ++bj)
; #pragma unroll
;                 for (int n = 0; n < 2; ++n) { const f32x4 s = *(const f32x4*)(ss + u.pn * BM + wc * 32 + 8 * fq + bj * HALF + 4 * n);
; #pragma unroll
;                     for (int j = 0; j < 4; ++j) cs[bj][n][j] = __builtin_amdgcn_rsqf(ss_fix(s[j]) * (1.0f / DM) + EPS); }
;         }
;         float rsv[8];
; #pragma unroll
;         for (int it = 0; it < 8; ++it) rsv[it] = (SM == 1) ? ss[row0 + (it >> 2) * HALF + (it & 3) * 16] : 1.0f;
; #pragma unroll
;         for (int ai = 0; ai < 2; ++ai)
; #pragma unroll
;             for (int m = 0; m < 4; ++m) { const int row = row0 + ai * HALF + m * 16; float rs = 1.0f; if (SM == 1) rs = __builtin_amdgcn_rsqf(ss_fix(rsv[ai * 4 + m]) * (1.0f / DM) + EPS);
;                 bf16_t* rowp = base + (size_t)row * ldc + col0;
; #pragma unroll
;                 for (int bj = 0; bj < 2; ++bj) { f32x4 v0 = acc[ai][bj][m][0], v1 = acc[ai][bj][m][1];
;                     if (SM == 1) { v0 *= rs; v1 *= rs; }
;                     if (SM == 2) { v0 *= cs[bj][0]; v1 *= cs[bj][1]; }
;                     if (ACT == 1) {
; #pragma unroll
;                         for (int j = 0; j < 4; ++j) { const float a = fmaxf(v0[j], 0.f), b = fmaxf(v1[j], 0.f); v0[j] = a * a; v1[j] = b * b; } }
;                     if (ACT == 2) { if (tsel == 0) {
; #pragma unroll
;                         for (int j = 0; j < 4; ++j) { const float a = v0[j], b = v1[j];
;                             v0[j] = a * fast_sigmoid(1.5957691216057308f * (a + 0.044715f * a * a * a)); v1[j] = b * fast_sigmoid(1.5957691216057308f * (b + 0.044715f * b * b * b)); } } }
;                     u32x4 w; w.x = pk_bf16(v0[0], v0[1]); w.y = pk_bf16(v0[2], v0[3]); w.z = pk_bf16(v1[0], v1[1]); w.w = pk_bf16(v1[2], v1[3]);
;                     *(u32x4*)(rowp + bj * HALF) = w; } }
	s_cbranch_scc0 .LBB0_259
	s_lshl_b32 s34, s33, 8
	s_ashr_i32 s35, s34, 31
	v_lshl_add_u64 v[146:147], s[34:35], 2, v[136:137]
	global_load_dwordx4 v[148:151], v[146:147], off
	global_load_dwordx4 v[152:155], v[146:147], off offset:16
	global_load_dwordx4 v[156:159], v[146:147], off offset:512
	global_load_dwordx4 v[160:163], v[146:147], off offset:528
	v_lshl_add_u32 v172, s64, 8, v164
	v_or_b32_e32 v146, s34, v166
	v_ashrrev_i32_e32 v173, 31, v172
	v_ashrrev_i32_e32 v147, 31, v146
	v_lshlrev_b64 v[174:175], 15, v[172:173]
	v_lshl_add_u64 v[176:177], v[146:147], 1, s[18:19]
	v_lshl_add_u64 v[146:147], v[176:177], 0, v[174:175]
	s_mov_b32 s33, 0x400000
	s_mov_b64 s[34:35], 0x400000
	s_mov_b32 s64, s58
	s_mov_b64 s[68:69], s[62:63]
	s_mov_b64 s[66:67], s[60:61]
	s_waitcnt vmcnt(0)
	v_cvt_f32_u32_e32 v148, v148
	v_cvt_f32_u32_e32 v149, v149
	v_cvt_f32_u32_e32 v150, v150
	v_cvt_f32_u32_e32 v151, v151
	v_cvt_f32_u32_e32 v152, v152
	v_cvt_f32_u32_e32 v153, v153
	v_cvt_f32_u32_e32 v154, v154
	v_cvt_f32_u32_e32 v155, v155
	v_cvt_f32_u32_e32 v156, v156
	v_cvt_f32_u32_e32 v157, v157
	v_cvt_f32_u32_e32 v158, v158
	v_cvt_f32_u32_e32 v159, v159
	v_cvt_f32_u32_e32 v160, v160
	v_cvt_f32_u32_e32 v161, v161
	v_cvt_f32_u32_e32 v162, v162
	v_cvt_f32_u32_e32 v163, v163
	v_mul_f32_e32 v148, 0x3b800000, v148
	v_mul_f32_e32 v149, 0x3b800000, v149
	v_mul_f32_e32 v150, 0x3b800000, v150
	v_mul_f32_e32 v151, 0x3b800000, v151
	v_mul_f32_e32 v152, 0x3b800000, v152
	v_mul_f32_e32 v153, 0x3b800000, v153
	v_mul_f32_e32 v154, 0x3b800000, v154
	v_mul_f32_e32 v155, 0x3b800000, v155
	v_mul_f32_e32 v156, 0x3b800000, v156
	v_mul_f32_e32 v157, 0x3b800000, v157
	v_mul_f32_e32 v158, 0x3b800000, v158
	v_mul_f32_e32 v159, 0x3b800000, v159
	v_mul_f32_e32 v160, 0x3b800000, v160
	v_mul_f32_e32 v161, 0x3b800000, v161
	v_mul_f32_e32 v162, 0x3b800000, v162
	v_mul_f32_e32 v163, 0x3b800000, v163
	v_fmamk_f32 v148, v148, 0x3a000000, v170
	v_fmamk_f32 v149, v149, 0x3a000000, v170
	v_fmamk_f32 v150, v150, 0x3a000000, v170
	v_fmamk_f32 v151, v151, 0x3a000000, v170
	v_fmamk_f32 v152, v152, 0x3a000000, v170
	v_fmamk_f32 v153, v153, 0x3a000000, v170
	v_fmamk_f32 v154, v154, 0x3a000000, v170
	v_fmamk_f32 v155, v155, 0x3a000000, v170
	v_fmamk_f32 v171, v156, 0x3a000000, v170
	v_fmamk_f32 v173, v157, 0x3a000000, v170
	v_fmamk_f32 v174, v158, 0x3a000000, v170
	v_fmamk_f32 v175, v159, 0x3a000000, v170
	v_fmamk_f32 v178, v160, 0x3a000000, v170
	v_fmamk_f32 v179, v161, 0x3a000000, v170
	v_fmamk_f32 v180, v162, 0x3a000000, v170
	v_fmamk_f32 v181, v163, 0x3a000000, v170
	v_rsq_f32_e32 v158, v148
	v_rsq_f32_e32 v159, v149
	v_rsq_f32_e32 v162, v150
	v_rsq_f32_e32 v163, v151
	v_rsq_f32_e32 v156, v152
	v_rsq_f32_e32 v157, v153
	v_rsq_f32_e32 v160, v154
	v_rsq_f32_e32 v161, v155
	v_rsq_f32_e32 v150, v171
	v_rsq_f32_e32 v151, v173
	v_rsq_f32_e32 v154, v174
	v_rsq_f32_e32 v155, v175
	v_rsq_f32_e32 v148, v178
	v_rsq_f32_e32 v149, v179
	v_rsq_f32_e32 v152, v180
	v_rsq_f32_e32 v153, v181
	v_pk_mul_f32 v[126:127], v[126:127], v[162:163]
	v_pk_mul_f32 v[124:125], v[124:125], v[158:159]
	v_pk_mul_f32 v[122:123], v[122:123], v[160:161]
	v_pk_mul_f32 v[120:121], v[120:121], v[156:157]
	v_pk_mul_f32 v[118:119], v[118:119], v[154:155]
	v_pk_mul_f32 v[116:117], v[116:117], v[150:151]
	v_pk_mul_f32 v[174:175], v[110:111], v[152:153]
	v_pk_mul_f32 v[178:179], v[108:109], v[148:149]
	v_cvt_pk_bf16_f32 v108, v124, v125
	v_cvt_pk_bf16_f32 v109, v126, v127
	v_cvt_pk_bf16_f32 v110, v120, v121
	v_cvt_pk_bf16_f32 v111, v122, v123
	v_cvt_pk_bf16_f32 v116, v116, v117
	v_cvt_pk_bf16_f32 v117, v118, v119
	v_cvt_pk_bf16_f32 v118, v178, v179
	v_cvt_pk_bf16_f32 v119, v174, v175
	global_store_dwordx4 v[146:147], v[108:111], off
	global_store_dwordx4 v[146:147], v[116:119], off offset:256
	v_pk_mul_f32 v[112:113], v[112:113], v[158:159]
	v_or_b32_e32 v108, 16, v172
	v_ashrrev_i32_e32 v109, 31, v108
	v_lshlrev_b64 v[108:109], 15, v[108:109]
	v_pk_mul_f32 v[110:111], v[114:115], v[162:163]
	v_pk_mul_f32 v[114:115], v[106:107], v[160:161]
	v_pk_mul_f32 v[106:107], v[104:105], v[156:157]
	v_lshl_add_u64 v[108:109], v[176:177], 0, v[108:109]
	v_cvt_pk_bf16_f32 v104, v112, v113
	v_cvt_pk_bf16_f32 v105, v110, v111
	v_cvt_pk_bf16_f32 v106, v106, v107
	v_cvt_pk_bf16_f32 v107, v114, v115
	global_store_dwordx4 v[108:109], v[104:107], off
	v_pk_mul_f32 v[102:103], v[102:103], v[154:155]
	v_pk_mul_f32 v[100:101], v[100:101], v[150:151]
	v_pk_mul_f32 v[104:105], v[94:95], v[152:153]
	v_pk_mul_f32 v[94:95], v[92:93], v[148:149]
	v_cvt_pk_bf16_f32 v92, v100, v101
	v_cvt_pk_bf16_f32 v93, v102, v103
	v_cvt_pk_bf16_f32 v94, v94, v95
	v_cvt_pk_bf16_f32 v95, v104, v105
	global_store_dwordx4 v[108:109], v[92:95], off offset:256
	v_pk_mul_f32 v[96:97], v[96:97], v[158:159]
	v_pk_mul_f32 v[86:87], v[86:87], v[154:155]
	v_or_b32_e32 v92, 32, v172
	v_ashrrev_i32_e32 v93, 31, v92
	v_lshlrev_b64 v[92:93], 15, v[92:93]
	v_pk_mul_f32 v[94:95], v[98:99], v[162:163]
	v_pk_mul_f32 v[98:99], v[90:91], v[160:161]
	v_pk_mul_f32 v[90:91], v[88:89], v[156:157]
; __device__ __forceinline__ float fast_sigmoid(float x) { return __builtin_amdgcn_rcpf(1.0f + __builtin_amdgcn_exp2f(-x * LOG2E)); }
; __device__ __forceinline__ float ss_fix(float raw) { return (float)__float_as_uint(raw) * (1.0f / 256.0f); }
; #define PG8_WAIT_V(n) asm volatile("s_waitcnt vmcnt(" #n ")" ::: "memory")
; template <class Epi>
; __device__ __forceinline__ void gemm_phase(LAS unsigned char* lds, const Gemm g, const StaticOrder& S, const Epi& E, int wv) {
;     ...
;         if (!has_next) break;
; #pragma unroll
;         for (int a = 0; a < 2; ++a)
; #pragma unroll
;             for (int b = 0; b < 2; ++b)
; #pragma unroll
;                 for (int m = 0; m < 4; ++m)
; #pragma unroll
;                     for (int n = 0; n < 2; ++n) acc[a][b][m][n] = (f32x4){0.f, 0.f, 0.f, 0.f};
;         cur = nxt; cA = nA; cB = nB; ++ui;
;     }
;     PG8_WAIT_V(0);
;     if (wr == 0) PG8_BAR;
;     PG8_BAR;
;     __device__ __forceinline__ void operator()(const f32x4 (&acc)[2][2][4][2], const Unit& u, int wr, int wc, int fr, int fq) const {
;     ...
;         for (int ai = 0; ai < 2; ++ai)
; #pragma unroll
;             for (int m = 0; m < 4; ++m) { const int row = row0 + ai * HALF + m * 16; float rs = 1.0f; if (SM == 1) rs = __builtin_amdgcn_rsqf(ss_fix(rsv[ai * 4 + m]) * (1.0f / DM) + EPS);
;                 bf16_t* rowp = base + (size_t)row * ldc + col0;
; #pragma unroll
;                 for (int bj = 0; bj < 2; ++bj) { f32x4 v0 = acc[ai][bj][m][0], v1 = acc[ai][bj][m][1];
;                     if (SM == 1) { v0 *= rs; v1 *= rs; }
;                     if (SM == 2) { v0 *= cs[bj][0]; v1 *= cs[bj][1]; }
;                     if (ACT == 1) {
; #pragma unroll
;                         for (int j = 0; j < 4; ++j) { const float a = fmaxf(v0[j], 0.f), b = fmaxf(v1[j], 0.f); v0[j] = a * a; v1[j] = b * b; } }
;                     if (ACT == 2) { if (tsel == 0) {
; #pragma unroll
;                         for (int j = 0; j < 4; ++j) { const float a = v0[j], b = v1[j];
;                             v0[j] = a * fast_sigmoid(1.5957691216057308f * (a + 0.044715f * a * a * a)); v1[j] = b * fast_sigmoid(1.5957691216057308f * (b + 0.044715f * b * b * b)); } } }
;                     u32x4 w; w.x = pk_bf16(v0[0], v0[1]); w.y = pk_bf16(v0[2], v0[3]); w.z = pk_bf16(v1[0], v1[1]); w.w = pk_bf16(v1[2], v1[3]);
;                     *(u32x4*)(rowp + bj * HALF) = w; } }
	v_lshl_add_u64 v[92:93], v[176:177], 0, v[92:93]
	v_cvt_pk_bf16_f32 v88, v96, v97
	v_cvt_pk_bf16_f32 v89, v94, v95
	v_cvt_pk_bf16_f32 v90, v90, v91
	v_cvt_pk_bf16_f32 v91, v98, v99
	global_store_dwordx4 v[92:93], v[88:91], off
	v_pk_mul_f32 v[84:85], v[84:85], v[150:151]
	v_pk_mul_f32 v[80:81], v[80:81], v[158:159]
	v_pk_mul_f32 v[88:89], v[78:79], v[152:153]
	v_pk_mul_f32 v[78:79], v[76:77], v[148:149]
	v_cvt_pk_bf16_f32 v76, v84, v85
	v_cvt_pk_bf16_f32 v77, v86, v87
	v_cvt_pk_bf16_f32 v78, v78, v79
	v_cvt_pk_bf16_f32 v79, v88, v89
	global_store_dwordx4 v[92:93], v[76:79], off offset:256
	v_pk_mul_f32 v[70:71], v[70:71], v[154:155]
	v_pk_mul_f32 v[68:69], v[68:69], v[150:151]
	v_or_b32_e32 v76, 48, v172
	v_ashrrev_i32_e32 v77, 31, v76
	v_lshlrev_b64 v[76:77], 15, v[76:77]
	v_pk_mul_f32 v[78:79], v[82:83], v[162:163]
	v_pk_mul_f32 v[82:83], v[74:75], v[160:161]
	v_pk_mul_f32 v[74:75], v[72:73], v[156:157]
	v_lshl_add_u64 v[76:77], v[176:177], 0, v[76:77]
	v_cvt_pk_bf16_f32 v72, v80, v81
	v_cvt_pk_bf16_f32 v73, v78, v79
	v_cvt_pk_bf16_f32 v74, v74, v75
	v_cvt_pk_bf16_f32 v75, v82, v83
	global_store_dwordx4 v[76:77], v[72:75], off
	v_pk_mul_f32 v[60:61], v[60:61], v[158:159]
	v_pk_mul_f32 v[62:63], v[62:63], v[162:163]
	v_pk_mul_f32 v[72:73], v[66:67], v[152:153]
	v_pk_mul_f32 v[66:67], v[64:65], v[148:149]
	v_cvt_pk_bf16_f32 v64, v68, v69
	v_cvt_pk_bf16_f32 v65, v70, v71
	v_cvt_pk_bf16_f32 v66, v66, v67
	v_cvt_pk_bf16_f32 v67, v72, v73
	global_store_dwordx4 v[76:77], v[64:67], off offset:256
	v_pk_mul_f32 v[50:51], v[50:51], v[154:155]
	v_pk_mul_f32 v[48:49], v[48:49], v[150:151]
	v_pk_mul_f32 v[66:67], v[58:59], v[160:161]
	v_pk_mul_f32 v[58:59], v[56:57], v[156:157]
	v_cvt_pk_bf16_f32 v56, v60, v61
	v_add_co_u32_e32 v60, vcc, s33, v146
	v_cvt_pk_bf16_f32 v57, v62, v63
	v_cvt_pk_bf16_f32 v58, v58, v59
	v_cvt_pk_bf16_f32 v59, v66, v67
	v_addc_co_u32_e32 v61, vcc, 0, v147, vcc
	global_store_dwordx4 v[60:61], v[56:59], off
	v_lshl_add_u64 v[64:65], v[146:147], 0, s[34:35]
	v_pk_mul_f32 v[44:45], v[44:45], v[156:157]
	v_pk_mul_f32 v[56:57], v[42:43], v[152:153]
	v_pk_mul_f32 v[42:43], v[40:41], v[148:149]
	v_cvt_pk_bf16_f32 v40, v48, v49
	v_cvt_pk_bf16_f32 v41, v50, v51
	v_cvt_pk_bf16_f32 v42, v42, v43
	v_cvt_pk_bf16_f32 v43, v56, v57
	global_store_dwordx4 v[64:65], v[40:43], off offset:256
	v_pk_mul_f32 v[46:47], v[46:47], v[160:161]
	v_pk_mul_f32 v[34:35], v[34:35], v[154:155]
	v_pk_mul_f32 v[42:43], v[54:55], v[162:163]
	v_pk_mul_f32 v[40:41], v[52:53], v[158:159]
	v_pk_mul_f32 v[32:33], v[32:33], v[150:151]
	v_cvt_pk_bf16_f32 v40, v40, v41
	v_cvt_pk_bf16_f32 v41, v42, v43
	v_cvt_pk_bf16_f32 v42, v44, v45
	v_add_co_u32_e32 v44, vcc, s25, v146
	v_cvt_pk_bf16_f32 v43, v46, v47
	s_nop 0
	v_addc_co_u32_e32 v45, vcc, 0, v147, vcc
	global_store_dwordx4 v[44:45], v[40:43], off
	v_lshl_add_u64 v[48:49], v[146:147], 0, s[50:51]
	v_pk_mul_f32 v[28:29], v[28:29], v[156:157]
	v_pk_mul_f32 v[40:41], v[26:27], v[152:153]
	v_pk_mul_f32 v[26:27], v[24:25], v[148:149]
	v_cvt_pk_bf16_f32 v24, v32, v33
	v_cvt_pk_bf16_f32 v25, v34, v35
	v_cvt_pk_bf16_f32 v26, v26, v27
	v_cvt_pk_bf16_f32 v27, v40, v41
	global_store_dwordx4 v[48:49], v[24:27], off offset:256
	v_pk_mul_f32 v[30:31], v[30:31], v[160:161]
	v_pk_mul_f32 v[18:19], v[18:19], v[154:155]
	v_pk_mul_f32 v[26:27], v[38:39], v[162:163]
	v_pk_mul_f32 v[24:25], v[36:37], v[158:159]
	v_pk_mul_f32 v[16:17], v[16:17], v[150:151]
	v_cvt_pk_bf16_f32 v24, v24, v25
	v_cvt_pk_bf16_f32 v25, v26, v27
	v_cvt_pk_bf16_f32 v26, v28, v29
	v_add_co_u32_e32 v28, vcc, s30, v146
	v_cvt_pk_bf16_f32 v27, v30, v31
	s_nop 0
	v_addc_co_u32_e32 v29, vcc, 0, v147, vcc
	global_store_dwordx4 v[28:29], v[24:27], off
	v_lshl_add_u64 v[32:33], v[146:147], 0, s[52:53]
	v_pk_mul_f32 v[12:13], v[12:13], v[156:157]
	v_pk_mul_f32 v[24:25], v[10:11], v[152:153]
	v_pk_mul_f32 v[10:11], v[8:9], v[148:149]
	v_cvt_pk_bf16_f32 v8, v16, v17
	v_cvt_pk_bf16_f32 v9, v18, v19
	v_cvt_pk_bf16_f32 v10, v10, v11
	v_cvt_pk_bf16_f32 v11, v24, v25
	global_store_dwordx4 v[32:33], v[8:11], off offset:256
	v_pk_mul_f32 v[14:15], v[14:15], v[160:161]
	v_pk_mul_f32 v[6:7], v[6:7], v[154:155]
	v_pk_mul_f32 v[10:11], v[22:23], v[162:163]
	v_pk_mul_f32 v[8:9], v[20:21], v[158:159]
	v_pk_mul_f32 v[4:5], v[4:5], v[150:151]
	v_cvt_pk_bf16_f32 v8, v8, v9
	v_cvt_pk_bf16_f32 v9, v10, v11
	v_cvt_pk_bf16_f32 v10, v12, v13
	v_add_co_u32_e32 v12, vcc, s31, v146
	v_cvt_pk_bf16_f32 v11, v14, v15
	s_nop 0
	v_addc_co_u32_e32 v13, vcc, 0, v147, vcc
	global_store_dwordx4 v[12:13], v[8:11], off
	v_lshl_add_u64 v[16:17], v[146:147], 0, s[54:55]
	s_and_b64 vcc, exec, s[16:17]
	v_pk_mul_f32 v[8:9], v[2:3], v[152:153]
	v_pk_mul_f32 v[2:3], v[0:1], v[148:149]
	v_cvt_pk_bf16_f32 v0, v4, v5
	v_cvt_pk_bf16_f32 v1, v6, v7
	v_cvt_pk_bf16_f32 v2, v2, v3
	v_cvt_pk_bf16_f32 v3, v8, v9
	s_mov_b32 s33, s56
	global_store_dwordx4 v[16:17], v[0:3], off offset:256
	s_cbranch_vccz .LBB0_252
	s_waitcnt vmcnt(0)
	s_cmpk_gt_u32 s4, 0xff
	s_cbranch_scc1 .LBB0_263
	s_barrier

; #define LAS __attribute__((address_space(3)))
; #define MFMA32(a, b, c) __builtin_amdgcn_mfma_f32_32x32x16_bf16((a), (b), (c), 0, 0, 0)
; __device__ __forceinline__ void attn_phase(LAS unsigned char* lds, const KArgs& P, int G, int c, int wv) {
;     ...
;             const int k0 = kt * 64;
;             if (k0 <= qw + 31) {
;                 const int rz = lz & 31, hz = lz >> 5, prz = (rz & 19) | ((rz & 4) << 1) | ((rz & 8) >> 1);
;                 const LAS unsigned char* kb = lds + (kt & 1) * 65536 + sub * 16384 + prz * 256;
;                 const int kx = (hz ^ (prz & 15)) * 16;
;                 const LAS unsigned char* vb = lds + (kt & 1) * 65536 + 32768 + rz * 128;
;                 const int vx = (hz ^ ((rz >> 1) & 7)) * 16;
;                 const int rel0 = k0 + 8 * hz - (qw + rz);
;                 const float tb = sl2 * (float)rel0 - Mb;
;                 const bool diag = (k0 + 63 > qw);
; #pragma unroll
;                 for (int half = 0; half < 2; ++half) {
;     ...
;                     f32x16 s;
; #pragma unroll
;                     for (int i = 0; i < 16; ++i) s[i] = 0.f;
;                     bf16x8 fr4[2];
;                     fr4[0] = KREAD(0);
;                     __builtin_amdgcn_sched_barrier(0);
; #pragma unroll
;                     for (int ks = 0; ks < 8; ++ks) {
;                         if (ks + 1 < 8) fr4[(ks + 1) & 1] = KREAD(ks + 1);
;                         s = MFMA32(fr4[ks & 1], qf[ks], s);
;                         __builtin_amdgcn_sched_barrier(0);
;                     }
;                     bf16x8 pf0, pf1;
;                     { float pv[8];
; #pragma unroll
;                       for (int j = 0; j < 8; ++j) { const int cc = 32 * half + j;
;                           float p = __builtin_amdgcn_exp2f(s[j] + (tb + sl2 * (float)cc));
;                           if (diag && (rel0 + cc > 0)) p = 0.f;
;                           pv[j] = p; lsum += p; }
;                       u32x4 w; w.x = pk_bf16(pv[0], pv[1]); w.y = pk_bf16(pv[2], pv[3]); w.z = pk_bf16(pv[4], pv[5]); w.w = pk_bf16(pv[6], pv[7]);
;                       pf0 = __builtin_bit_cast(bf16x8, w); }
.LBB0_366:
	s_sub_i32 s50, s90, 63
	s_cmp_gt_u32 s50, s11
	s_cbranch_scc1 .LBB0_358
	v_and_b32_e32 v128, 31, v130
	v_ashrrev_i32_e32 v129, 5, v130
	v_and_b32_e32 v131, 19, v130
	v_lshlrev_b32_e32 v132, 1, v130
	v_lshrrev_b32_e32 v130, 1, v130
	s_and_b32 s50, s25, 0x10000
	v_and_b32_e32 v132, 8, v132
	v_and_b32_e32 v133, 4, v130
	s_add_i32 s50, s50, 0
	v_or3_b32 v131, v132, v131, v133
	s_add_i32 s76, s50, s46
	v_lshl_add_u32 v224, v131, 8, s76
	v_bitop3_b32 v131, v131, v129, 15 bitop3:0x6c
	v_bitop3_b32 v130, v130, v129, 7 bitop3:0x6c
	v_lshlrev_b32_e32 v129, 3, v129
	v_lshl_add_u32 v178, v128, 7, s50
	v_sub_u32_e32 v128, v129, v128
	s_add_i32 s50, s6, s90
	v_add_u32_e32 v128, s50, v128
	v_subrev_u32_e32 v214, 63, v128
	v_cvt_f32_i32_e32 v128, v214
	v_lshlrev_b32_e32 v225, 4, v131
	v_add_u32_e32 v226, v224, v225
	v_lshlrev_b32_e32 v213, 4, v130
	v_fma_f32 v215, v180, v128, -v248
	v_add_u32_e32 v235, v178, v213
	v_xad_u32 v233, v213, 32, v178
	v_xad_u32 v252, v213, 64, v178
	v_xad_u32 v234, v213, s80, v178
	v_xad_u32 v227, v225, 32, v224
	v_xad_u32 v228, v225, 64, v224
	v_xad_u32 v229, v225, s80, v224
	v_xad_u32 v230, v225, s39, v224
	s_movk_i32 s50, 0xa0
	v_xad_u32 v231, v225, s50, v224
	s_movk_i32 s50, 0xc0
	v_xad_u32 v232, v225, s50, v224
	s_movk_i32 s50, 0xe0
	v_xad_u32 v253, v225, s50, v224
	s_cmp_gt_u32 s90, s81
	s_cbranch_scc1 .Lattn_diag_path
	ds_read_b128 v[216:219], v226
	ds_read_b128 v[220:223], v227
	ds_read_b128 v[236:239], v228
	ds_read_b128 v[240:243], v229
	ds_read_b128 v[184:187], v230
	ds_read_b128 v[188:191], v231
	ds_read_b128 v[192:195], v232
	ds_read_b128 v[196:199], v253
	v_mov_b32_e32 v128, v215
	v_fmamk_f32 v129, v180, 0x3f800000, v215
	v_fmamk_f32 v130, v180, 0x40000000, v215
	v_fmamk_f32 v131, v180, 0x40400000, v215
	v_fmamk_f32 v132, v180, 0x40800000, v215
	v_fmamk_f32 v133, v180, 0x40a00000, v215
	v_fmamk_f32 v134, v180, 0x40c00000, v215
	v_fmamk_f32 v135, v180, 0x40e00000, v215
	v_fmamk_f32 v136, v180, 0x41800000, v215
	v_fmamk_f32 v137, v180, 0x41880000, v215
	v_fmamk_f32 v138, v180, 0x41900000, v215
	v_fmamk_f32 v139, v180, 0x41980000, v215
	v_fmamk_f32 v140, v180, 0x41a00000, v215
	v_fmamk_f32 v141, v180, 0x41a80000, v215
	v_fmamk_f32 v142, v180, 0x41b00000, v215
	v_fmamk_f32 v143, v180, 0x41b80000, v215
	s_nop 1
	s_waitcnt lgkmcnt(7)
	v_mfma_f32_32x32x16_bf16 v[128:143], v[216:219], v[144:147], v[128:143]
	ds_read_b128 v[216:219], v235 offset:32768
	s_waitcnt lgkmcnt(7)
	v_mfma_f32_32x32x16_bf16 v[128:143], v[220:223], v[148:151], v[128:143]
	ds_read_b128 v[220:223], v235 offset:36864
	s_waitcnt lgkmcnt(7)
	v_mfma_f32_32x32x16_bf16 v[128:143], v[236:239], v[152:155], v[128:143]
	ds_read_b128 v[236:239], v235 offset:40960
	s_waitcnt lgkmcnt(7)
	v_mfma_f32_32x32x16_bf16 v[128:143], v[240:243], v[156:159], v[128:143]
	ds_read_b128 v[240:243], v235 offset:45056
	s_waitcnt lgkmcnt(7)
	v_mfma_f32_32x32x16_bf16 v[128:143], v[184:187], v[160:163], v[128:143]
	ds_read_b128 v[184:187], v235 offset:49152
	s_waitcnt lgkmcnt(7)
	v_mfma_f32_32x32x16_bf16 v[128:143], v[188:191], v[164:167], v[128:143]
	ds_read_b128 v[188:191], v235 offset:53248
	s_waitcnt lgkmcnt(7)
	v_mfma_f32_32x32x16_bf16 v[128:143], v[192:195], v[168:171], v[128:143]
	ds_read_b128 v[192:195], v235 offset:57344
	s_waitcnt lgkmcnt(7)
	v_mfma_f32_32x32x16_bf16 v[128:143], v[196:199], v[172:175], v[128:143]
	ds_read_b128 v[196:199], v235 offset:61440
	s_nop 11
	v_exp_f32_e32 v128, v128
	v_exp_f32_e32 v129, v129
	v_exp_f32_e32 v130, v130
	v_exp_f32_e32 v131, v131
	v_exp_f32_e32 v132, v132
	v_exp_f32_e32 v133, v133
	v_exp_f32_e32 v134, v134
	v_exp_f32_e32 v135, v135
	v_cvt_pk_bf16_f32 v200, v128, v129
	v_cvt_pk_bf16_f32 v201, v130, v131
	v_cvt_pk_bf16_f32 v202, v132, v133
	v_cvt_pk_bf16_f32 v203, v134, v135
	v_add_f32_e32 v183, v128, v129
	v_add_f32_e32 v208, v130, v131
	v_add_f32_e32 v209, v132, v133
	v_add_f32_e32 v210, v134, v135
	v_add_f32_e32 v183, v183, v208
	v_add_f32_e32 v209, v209, v210
	v_add_f32_e32 v183, v183, v209
	v_add_f32_e32 v212, v212, v183
	s_waitcnt lgkmcnt(7)
	v_mfma_f32_32x32x16_bf16 v[112:127], v[216:219], v[200:203], v[112:127]
	ds_read_b128 v[216:219], v233 offset:32768
	v_exp_f32_e32 v136, v136
	s_waitcnt lgkmcnt(7)
	v_mfma_f32_32x32x16_bf16 v[96:111], v[220:223], v[200:203], v[96:111]
	ds_read_b128 v[220:223], v233 offset:36864
	v_exp_f32_e32 v137, v137
	s_nop 0
	v_cvt_pk_bf16_f32 v204, v136, v137
	v_add_f32_e32 v183, v136, v137
	s_waitcnt lgkmcnt(7)
	v_mfma_f32_32x32x16_bf16 v[80:95], v[236:239], v[200:203], v[80:95]
	ds_read_b128 v[236:239], v233 offset:40960
	v_exp_f32_e32 v138, v138
	s_waitcnt lgkmcnt(7)
	v_mfma_f32_32x32x16_bf16 v[64:79], v[240:243], v[200:203], v[64:79]
	ds_read_b128 v[240:243], v233 offset:45056
	v_exp_f32_e32 v139, v139
	s_nop 0
	v_cvt_pk_bf16_f32 v205, v138, v139
	v_add_f32_e32 v208, v138, v139
	s_waitcnt lgkmcnt(7)
	v_mfma_f32_32x32x16_bf16 v[48:63], v[184:187], v[200:203], v[48:63]
	ds_read_b128 v[184:187], v233 offset:49152
	v_exp_f32_e32 v140, v140
	s_waitcnt lgkmcnt(7)
	v_mfma_f32_32x32x16_bf16 v[32:47], v[188:191], v[200:203], v[32:47]
	ds_read_b128 v[188:191], v233 offset:53248
	v_exp_f32_e32 v141, v141
	s_nop 0
	v_cvt_pk_bf16_f32 v206, v140, v141
	v_add_f32_e32 v209, v140, v141
	s_waitcnt lgkmcnt(7)
	v_mfma_f32_32x32x16_bf16 v[16:31], v[192:195], v[200:203], v[16:31]
	ds_read_b128 v[192:195], v233 offset:57344
	v_exp_f32_e32 v142, v142
	s_waitcnt lgkmcnt(7)
	v_mfma_f32_32x32x16_bf16 v[0:15], v[196:199], v[200:203], v[0:15]
	ds_read_b128 v[196:199], v233 offset:61440
	v_exp_f32_e32 v143, v143
	s_nop 0
	v_cvt_pk_bf16_f32 v207, v142, v143
	v_add_f32_e32 v210, v142, v143
	v_add_f32_e32 v183, v183, v208
	v_add_f32_e32 v209, v209, v210
	v_add_f32_e32 v183, v183, v209
	v_add_f32_e32 v212, v212, v183
	s_waitcnt lgkmcnt(7)
; #define MFMA32(a, b, c) __builtin_amdgcn_mfma_f32_32x32x16_bf16((a), (b), (c), 0, 0, 0)
; __device__ __forceinline__ void attn_phase(LAS unsigned char* lds, const KArgs& P, int G, int c, int wv) {
;     ...
;                 for (int half = 0; half < 2; ++half) {
;     ...
;                     f32x16 s;
; #pragma unroll
;                     for (int i = 0; i < 16; ++i) s[i] = 0.f;
;                     bf16x8 fr4[2];
;                     fr4[0] = KREAD(0);
;                     __builtin_amdgcn_sched_barrier(0);
; #pragma unroll
;                     for (int ks = 0; ks < 8; ++ks) {
;                         if (ks + 1 < 8) fr4[(ks + 1) & 1] = KREAD(ks + 1);
;                         s = MFMA32(fr4[ks & 1], qf[ks], s);
;                         __builtin_amdgcn_sched_barrier(0);
;                     }
;                     bf16x8 pf0, pf1;
;                     { float pv[8];
; #pragma unroll
;                       for (int j = 0; j < 8; ++j) { const int cc = 32 * half + j;
;                           float p = __builtin_amdgcn_exp2f(s[j] + (tb + sl2 * (float)cc));
;                           if (diag && (rel0 + cc > 0)) p = 0.f;
;                           pv[j] = p; lsum += p; }
;                       u32x4 w; w.x = pk_bf16(pv[0], pv[1]); w.y = pk_bf16(pv[2], pv[3]); w.z = pk_bf16(pv[4], pv[5]); w.w = pk_bf16(pv[6], pv[7]);
;                       pf0 = __builtin_bit_cast(bf16x8, w); }
;                     __builtin_amdgcn_sched_barrier(0);
;                     u32x4 w1; float pe = 0.f;
; #pragma unroll
;                     for (int d = 0; d < 8; ++d) {
;                         O[d] = MFMA32(VREAD(2 * d), pf0, O[d]);
;                         { const int cc = 32 * half + 16 + d;
;                           float p = __builtin_amdgcn_exp2f(s[8 + d] + (tb + sl2 * (float)cc));
;                           if (diag && (rel0 + cc > 0)) p = 0.f;
;                           lsum += p;
;                           if (d & 1) w1[d >> 1] = pk_bf16(pe, p); else pe = p; }
;                         __builtin_amdgcn_sched_barrier(0);
;                     }
;                     pf1 = __builtin_bit_cast(bf16x8, w1);
; #pragma unroll
;                     for (int d = 0; d < 8; ++d) {
;                         O[d] = MFMA32(VREAD(2 * d + 1), pf1, O[d]);
;                         __builtin_amdgcn_sched_barrier(0);
;                     }
	v_mfma_f32_32x32x16_bf16 v[112:127], v[216:219], v[204:207], v[112:127]
	ds_read_b128 v[216:219], v226 offset:8192
	v_fmamk_f32 v128, v180, 0x42000000, v215
	v_fmamk_f32 v129, v180, 0x42040000, v215
	s_waitcnt lgkmcnt(7)
	v_mfma_f32_32x32x16_bf16 v[96:111], v[220:223], v[204:207], v[96:111]
	ds_read_b128 v[220:223], v227 offset:8192
	v_fmamk_f32 v130, v180, 0x42080000, v215
	v_fmamk_f32 v131, v180, 0x420c0000, v215
	s_waitcnt lgkmcnt(7)
	v_mfma_f32_32x32x16_bf16 v[80:95], v[236:239], v[204:207], v[80:95]
	ds_read_b128 v[236:239], v228 offset:8192
	v_fmamk_f32 v132, v180, 0x42100000, v215
	v_fmamk_f32 v133, v180, 0x42140000, v215
	s_waitcnt lgkmcnt(7)
	v_mfma_f32_32x32x16_bf16 v[64:79], v[240:243], v[204:207], v[64:79]
	ds_read_b128 v[240:243], v229 offset:8192
	v_fmamk_f32 v134, v180, 0x42180000, v215
	v_fmamk_f32 v135, v180, 0x421c0000, v215
	s_waitcnt lgkmcnt(7)
	v_mfma_f32_32x32x16_bf16 v[48:63], v[184:187], v[204:207], v[48:63]
	ds_read_b128 v[184:187], v230 offset:8192
	v_fmamk_f32 v136, v180, 0x42400000, v215
	v_fmamk_f32 v137, v180, 0x42440000, v215
	s_waitcnt lgkmcnt(7)
	v_mfma_f32_32x32x16_bf16 v[32:47], v[188:191], v[204:207], v[32:47]
	ds_read_b128 v[188:191], v231 offset:8192
	v_fmamk_f32 v138, v180, 0x42480000, v215
	v_fmamk_f32 v139, v180, 0x424c0000, v215
	s_waitcnt lgkmcnt(7)
	v_mfma_f32_32x32x16_bf16 v[16:31], v[192:195], v[204:207], v[16:31]
	ds_read_b128 v[192:195], v232 offset:8192
	v_fmamk_f32 v140, v180, 0x42500000, v215
	v_fmamk_f32 v141, v180, 0x42540000, v215
	s_waitcnt lgkmcnt(7)
	v_mfma_f32_32x32x16_bf16 v[0:15], v[196:199], v[204:207], v[0:15]
	ds_read_b128 v[196:199], v253 offset:8192
	v_fmamk_f32 v142, v180, 0x42580000, v215
	v_fmamk_f32 v143, v180, 0x425c0000, v215
	s_nop 1
	s_waitcnt lgkmcnt(7)
	v_mfma_f32_32x32x16_bf16 v[128:143], v[216:219], v[144:147], v[128:143]
	ds_read_b128 v[216:219], v252 offset:32768
	s_waitcnt lgkmcnt(7)
	v_mfma_f32_32x32x16_bf16 v[128:143], v[220:223], v[148:151], v[128:143]
	ds_read_b128 v[220:223], v252 offset:36864
	s_waitcnt lgkmcnt(7)
	v_mfma_f32_32x32x16_bf16 v[128:143], v[236:239], v[152:155], v[128:143]
	ds_read_b128 v[236:239], v252 offset:40960
	s_waitcnt lgkmcnt(7)
	v_mfma_f32_32x32x16_bf16 v[128:143], v[240:243], v[156:159], v[128:143]
	ds_read_b128 v[240:243], v252 offset:45056
	s_waitcnt lgkmcnt(7)
	v_mfma_f32_32x32x16_bf16 v[128:143], v[184:187], v[160:163], v[128:143]
	ds_read_b128 v[184:187], v252 offset:49152
	s_waitcnt lgkmcnt(7)
	v_mfma_f32_32x32x16_bf16 v[128:143], v[188:191], v[164:167], v[128:143]
	ds_read_b128 v[188:191], v252 offset:53248
	s_waitcnt lgkmcnt(7)
	v_mfma_f32_32x32x16_bf16 v[128:143], v[192:195], v[168:171], v[128:143]
	ds_read_b128 v[192:195], v252 offset:57344
	s_waitcnt lgkmcnt(7)
	v_mfma_f32_32x32x16_bf16 v[128:143], v[196:199], v[172:175], v[128:143]
	ds_read_b128 v[196:199], v252 offset:61440
	s_nop 11
	v_exp_f32_e32 v128, v128
	v_exp_f32_e32 v129, v129
	v_exp_f32_e32 v130, v130
	v_exp_f32_e32 v131, v131
	v_exp_f32_e32 v132, v132
	v_exp_f32_e32 v133, v133
	v_exp_f32_e32 v134, v134
	v_exp_f32_e32 v135, v135
	v_cvt_pk_bf16_f32 v200, v128, v129
	v_cvt_pk_bf16_f32 v201, v130, v131
	v_cvt_pk_bf16_f32 v202, v132, v133
	v_cvt_pk_bf16_f32 v203, v134, v135
	v_add_f32_e32 v183, v128, v129
	v_add_f32_e32 v208, v130, v131
	v_add_f32_e32 v209, v132, v133
	v_add_f32_e32 v210, v134, v135
	v_add_f32_e32 v183, v183, v208
	v_add_f32_e32 v209, v209, v210
	v_add_f32_e32 v183, v183, v209
	v_add_f32_e32 v212, v212, v183
	s_waitcnt lgkmcnt(7)
	v_mfma_f32_32x32x16_bf16 v[112:127], v[216:219], v[200:203], v[112:127]
	ds_read_b128 v[216:219], v234 offset:32768
	v_exp_f32_e32 v136, v136
	s_waitcnt lgkmcnt(7)
	v_mfma_f32_32x32x16_bf16 v[96:111], v[220:223], v[200:203], v[96:111]
	ds_read_b128 v[220:223], v234 offset:36864
	v_exp_f32_e32 v137, v137
	s_nop 0
	v_cvt_pk_bf16_f32 v204, v136, v137
	v_add_f32_e32 v183, v136, v137
	s_waitcnt lgkmcnt(7)
	v_mfma_f32_32x32x16_bf16 v[80:95], v[236:239], v[200:203], v[80:95]
	ds_read_b128 v[236:239], v234 offset:40960
	v_exp_f32_e32 v138, v138
	s_waitcnt lgkmcnt(7)
	v_mfma_f32_32x32x16_bf16 v[64:79], v[240:243], v[200:203], v[64:79]
	ds_read_b128 v[240:243], v234 offset:45056
	v_exp_f32_e32 v139, v139
	s_nop 0
	v_cvt_pk_bf16_f32 v205, v138, v139
	v_add_f32_e32 v208, v138, v139
	s_waitcnt lgkmcnt(7)
	v_mfma_f32_32x32x16_bf16 v[48:63], v[184:187], v[200:203], v[48:63]
	ds_read_b128 v[184:187], v234 offset:49152
	v_exp_f32_e32 v140, v140
	s_waitcnt lgkmcnt(7)
	v_mfma_f32_32x32x16_bf16 v[32:47], v[188:191], v[200:203], v[32:47]
	ds_read_b128 v[188:191], v234 offset:53248
	v_exp_f32_e32 v141, v141
	s_nop 0
	v_cvt_pk_bf16_f32 v206, v140, v141
	v_add_f32_e32 v209, v140, v141
	s_waitcnt lgkmcnt(7)
	v_mfma_f32_32x32x16_bf16 v[16:31], v[192:195], v[200:203], v[16:31]
	ds_read_b128 v[192:195], v234 offset:57344
	v_exp_f32_e32 v142, v142
	s_waitcnt lgkmcnt(7)
	v_mfma_f32_32x32x16_bf16 v[0:15], v[196:199], v[200:203], v[0:15]
	ds_read_b128 v[196:199], v234 offset:61440
	v_exp_f32_e32 v143, v143
	s_nop 0
	v_cvt_pk_bf16_f32 v207, v142, v143
	v_add_f32_e32 v210, v142, v143
	v_add_f32_e32 v183, v183, v208
	v_add_f32_e32 v209, v209, v210
	v_add_f32_e32 v183, v183, v209
	v_add_f32_e32 v212, v212, v183
	s_waitcnt lgkmcnt(7)
	v_mfma_f32_32x32x16_bf16 v[112:127], v[216:219], v[204:207], v[112:127]
	s_waitcnt lgkmcnt(6)
	v_mfma_f32_32x32x16_bf16 v[96:111], v[220:223], v[204:207], v[96:111]
	s_waitcnt lgkmcnt(5)
	v_mfma_f32_32x32x16_bf16 v[80:95], v[236:239], v[204:207], v[80:95]
	s_waitcnt lgkmcnt(4)
	v_mfma_f32_32x32x16_bf16 v[64:79], v[240:243], v[204:207], v[64:79]
	s_waitcnt lgkmcnt(3)
	v_mfma_f32_32x32x16_bf16 v[48:63], v[184:187], v[204:207], v[48:63]
	s_waitcnt lgkmcnt(2)
	v_mfma_f32_32x32x16_bf16 v[32:47], v[188:191], v[204:207], v[32:47]
	s_waitcnt lgkmcnt(1)
	v_mfma_f32_32x32x16_bf16 v[16:31], v[192:195], v[204:207], v[16:31]
	s_waitcnt lgkmcnt(0)
	v_mfma_f32_32x32x16_bf16 v[0:15], v[196:199], v[204:207], v[0:15]
	s_branch .LBB0_358
; #define MFMA32(a, b, c) __builtin_amdgcn_mfma_f32_32x32x16_bf16((a), (b), (c), 0, 0, 0)
; __device__ __forceinline__ void attn_phase(LAS unsigned char* lds, const KArgs& P, int G, int c, int wv) {
;     ...
;                 const bool diag = (k0 + 63 > qw);
; #pragma unroll
;                 for (int half = 0; half < 2; ++half) {
;     ...
;                     f32x16 s;
; #pragma unroll
;                     for (int i = 0; i < 16; ++i) s[i] = 0.f;
;                     bf16x8 fr4[2];
;                     fr4[0] = KREAD(0);
;                     __builtin_amdgcn_sched_barrier(0);
; #pragma unroll
;                     for (int ks = 0; ks < 8; ++ks) {
;                         if (ks + 1 < 8) fr4[(ks + 1) & 1] = KREAD(ks + 1);
;                         s = MFMA32(fr4[ks & 1], qf[ks], s);
;                         __builtin_amdgcn_sched_barrier(0);
;                     }
;                     bf16x8 pf0, pf1;
;                     { float pv[8];
; #pragma unroll
;                       for (int j = 0; j < 8; ++j) { const int cc = 32 * half + j;
;                           float p = __builtin_amdgcn_exp2f(s[j] + (tb + sl2 * (float)cc));
;                           if (diag && (rel0 + cc > 0)) p = 0.f;
;                           pv[j] = p; lsum += p; }
;                       u32x4 w; w.x = pk_bf16(pv[0], pv[1]); w.y = pk_bf16(pv[2], pv[3]); w.z = pk_bf16(pv[4], pv[5]); w.w = pk_bf16(pv[6], pv[7]);
;                       pf0 = __builtin_bit_cast(bf16x8, w); }
.Lattn_diag_path:
	v_sub_u32_e32 v182, 0, v214
	v_mov_b32_e32 v181, 0xf149f2ca
	ds_read_b128 v[216:219], v226
	ds_read_b128 v[220:223], v227
	ds_read_b128 v[236:239], v228
	ds_read_b128 v[240:243], v229
	ds_read_b128 v[184:187], v230
	ds_read_b128 v[188:191], v231
	ds_read_b128 v[192:195], v232
	ds_read_b128 v[196:199], v253
	v_mov_b32_e32 v128, v215
	v_fmamk_f32 v129, v180, 0x3f800000, v215
	v_fmamk_f32 v130, v180, 0x40000000, v215
	v_fmamk_f32 v131, v180, 0x40400000, v215
	v_fmamk_f32 v132, v180, 0x40800000, v215
	v_fmamk_f32 v133, v180, 0x40a00000, v215
	v_fmamk_f32 v134, v180, 0x40c00000, v215
	v_fmamk_f32 v135, v180, 0x40e00000, v215
	v_fmamk_f32 v136, v180, 0x41800000, v215
	v_fmamk_f32 v137, v180, 0x41880000, v215
	v_fmamk_f32 v138, v180, 0x41900000, v215
	v_fmamk_f32 v139, v180, 0x41980000, v215
	v_fmamk_f32 v140, v180, 0x41a00000, v215
	v_fmamk_f32 v141, v180, 0x41a80000, v215
	v_fmamk_f32 v142, v180, 0x41b00000, v215
	v_fmamk_f32 v143, v180, 0x41b80000, v215
	v_cmp_gt_i32_e32 vcc, 0, v182
	s_nop 1
	v_cndmask_b32_e32 v128, v128, v181, vcc
	v_cmp_gt_i32_e32 vcc, 1, v182
	s_nop 1
	v_cndmask_b32_e32 v129, v129, v181, vcc
	v_cmp_gt_i32_e32 vcc, 2, v182
	s_nop 1
	v_cndmask_b32_e32 v130, v130, v181, vcc
	v_cmp_gt_i32_e32 vcc, 3, v182
	s_nop 1
	v_cndmask_b32_e32 v131, v131, v181, vcc
	v_cmp_gt_i32_e32 vcc, 4, v182
	s_nop 1
	v_cndmask_b32_e32 v132, v132, v181, vcc
	v_cmp_gt_i32_e32 vcc, 5, v182
	s_nop 1
	v_cndmask_b32_e32 v133, v133, v181, vcc
	v_cmp_gt_i32_e32 vcc, 6, v182
	s_nop 1
	v_cndmask_b32_e32 v134, v134, v181, vcc
	v_cmp_gt_i32_e32 vcc, 7, v182
	s_nop 1
	v_cndmask_b32_e32 v135, v135, v181, vcc
	v_cmp_gt_i32_e32 vcc, 16, v182
	s_nop 1
	v_cndmask_b32_e32 v136, v136, v181, vcc
	v_cmp_gt_i32_e32 vcc, 17, v182
	s_nop 1
	v_cndmask_b32_e32 v137, v137, v181, vcc
	v_cmp_gt_i32_e32 vcc, 18, v182
	s_nop 1
	v_cndmask_b32_e32 v138, v138, v181, vcc
	v_cmp_gt_i32_e32 vcc, 19, v182
	s_nop 1
	v_cndmask_b32_e32 v139, v139, v181, vcc
	v_cmp_gt_i32_e32 vcc, 20, v182
	s_nop 1
	v_cndmask_b32_e32 v140, v140, v181, vcc
	v_cmp_gt_i32_e32 vcc, 21, v182
	s_nop 1
	v_cndmask_b32_e32 v141, v141, v181, vcc
	v_cmp_gt_i32_e32 vcc, 22, v182
	s_nop 1
	v_cndmask_b32_e32 v142, v142, v181, vcc
	v_cmp_gt_i32_e32 vcc, 23, v182
	s_nop 1
	v_cndmask_b32_e32 v143, v143, v181, vcc
	s_nop 1
	s_waitcnt lgkmcnt(7)
	v_mfma_f32_32x32x16_bf16 v[128:143], v[216:219], v[144:147], v[128:143]
	ds_read_b128 v[216:219], v235 offset:32768
	s_waitcnt lgkmcnt(7)
	v_mfma_f32_32x32x16_bf16 v[128:143], v[220:223], v[148:151], v[128:143]
	ds_read_b128 v[220:223], v235 offset:36864
	s_waitcnt lgkmcnt(7)
	v_mfma_f32_32x32x16_bf16 v[128:143], v[236:239], v[152:155], v[128:143]
	ds_read_b128 v[236:239], v235 offset:40960
	s_waitcnt lgkmcnt(7)
	v_mfma_f32_32x32x16_bf16 v[128:143], v[240:243], v[156:159], v[128:143]
	ds_read_b128 v[240:243], v235 offset:45056
	s_waitcnt lgkmcnt(7)
	v_mfma_f32_32x32x16_bf16 v[128:143], v[184:187], v[160:163], v[128:143]
	ds_read_b128 v[184:187], v235 offset:49152
	s_waitcnt lgkmcnt(7)
	v_mfma_f32_32x32x16_bf16 v[128:143], v[188:191], v[164:167], v[128:143]
	ds_read_b128 v[188:191], v235 offset:53248
	s_waitcnt lgkmcnt(7)
	v_mfma_f32_32x32x16_bf16 v[128:143], v[192:195], v[168:171], v[128:143]
	ds_read_b128 v[192:195], v235 offset:57344
	s_waitcnt lgkmcnt(7)
	v_mfma_f32_32x32x16_bf16 v[128:143], v[196:199], v[172:175], v[128:143]
	ds_read_b128 v[196:199], v235 offset:61440
	s_nop 11
	v_exp_f32_e32 v128, v128
	v_exp_f32_e32 v129, v129
	v_exp_f32_e32 v130, v130
	v_exp_f32_e32 v131, v131
	v_exp_f32_e32 v132, v132
	v_exp_f32_e32 v133, v133
	v_exp_f32_e32 v134, v134
	v_exp_f32_e32 v135, v135
	v_cvt_pk_bf16_f32 v200, v128, v129
	v_cvt_pk_bf16_f32 v201, v130, v131
	v_cvt_pk_bf16_f32 v202, v132, v133
	v_cvt_pk_bf16_f32 v203, v134, v135
	v_add_f32_e32 v183, v128, v129
	v_add_f32_e32 v208, v130, v131
	v_add_f32_e32 v209, v132, v133
	v_add_f32_e32 v210, v134, v135
	v_add_f32_e32 v183, v183, v208
	v_add_f32_e32 v209, v209, v210
	v_add_f32_e32 v183, v183, v209
	v_add_f32_e32 v212, v212, v183
	s_waitcnt lgkmcnt(7)
	v_mfma_f32_32x32x16_bf16 v[112:127], v[216:219], v[200:203], v[112:127]
	ds_read_b128 v[216:219], v233 offset:32768
	v_exp_f32_e32 v136, v136
	s_waitcnt lgkmcnt(7)
	v_mfma_f32_32x32x16_bf16 v[96:111], v[220:223], v[200:203], v[96:111]
	ds_read_b128 v[220:223], v233 offset:36864
	v_exp_f32_e32 v137, v137
	s_nop 0
	v_cvt_pk_bf16_f32 v204, v136, v137
	v_add_f32_e32 v183, v136, v137
	s_waitcnt lgkmcnt(7)
	v_mfma_f32_32x32x16_bf16 v[80:95], v[236:239], v[200:203], v[80:95]
	ds_read_b128 v[236:239], v233 offset:40960
	v_exp_f32_e32 v138, v138
	s_waitcnt lgkmcnt(7)
	v_mfma_f32_32x32x16_bf16 v[64:79], v[240:243], v[200:203], v[64:79]
	ds_read_b128 v[240:243], v233 offset:45056
	v_exp_f32_e32 v139, v139
	s_nop 0
	v_cvt_pk_bf16_f32 v205, v138, v139
	v_add_f32_e32 v208, v138, v139
	s_waitcnt lgkmcnt(7)
	v_mfma_f32_32x32x16_bf16 v[48:63], v[184:187], v[200:203], v[48:63]
	ds_read_b128 v[184:187], v233 offset:49152
	v_exp_f32_e32 v140, v140
	s_waitcnt lgkmcnt(7)
	v_mfma_f32_32x32x16_bf16 v[32:47], v[188:191], v[200:203], v[32:47]
	ds_read_b128 v[188:191], v233 offset:53248
	v_exp_f32_e32 v141, v141
	s_nop 0
	v_cvt_pk_bf16_f32 v206, v140, v141
	v_add_f32_e32 v209, v140, v141
	s_waitcnt lgkmcnt(7)
	v_mfma_f32_32x32x16_bf16 v[16:31], v[192:195], v[200:203], v[16:31]
	ds_read_b128 v[192:195], v233 offset:57344
	v_exp_f32_e32 v142, v142
	s_waitcnt lgkmcnt(7)
	v_mfma_f32_32x32x16_bf16 v[0:15], v[196:199], v[200:203], v[0:15]
	ds_read_b128 v[196:199], v233 offset:61440
	v_exp_f32_e32 v143, v143
	s_nop 0
	v_cvt_pk_bf16_f32 v207, v142, v143
	v_add_f32_e32 v210, v142, v143
	v_add_f32_e32 v183, v183, v208
	v_add_f32_e32 v209, v209, v210
	v_add_f32_e32 v183, v183, v209
	v_add_f32_e32 v212, v212, v183
	s_waitcnt lgkmcnt(7)
; #define MFMA32(a, b, c) __builtin_amdgcn_mfma_f32_32x32x16_bf16((a), (b), (c), 0, 0, 0)
; __device__ __forceinline__ void attn_phase(LAS unsigned char* lds, const KArgs& P, int G, int c, int wv) {
;     ...
;                 for (int half = 0; half < 2; ++half) {
;     ...
;                     f32x16 s;
; #pragma unroll
;                     for (int i = 0; i < 16; ++i) s[i] = 0.f;
;                     bf16x8 fr4[2];
;                     fr4[0] = KREAD(0);
;                     __builtin_amdgcn_sched_barrier(0);
; #pragma unroll
;                     for (int ks = 0; ks < 8; ++ks) {
;                         if (ks + 1 < 8) fr4[(ks + 1) & 1] = KREAD(ks + 1);
;                         s = MFMA32(fr4[ks & 1], qf[ks], s);
;                         __builtin_amdgcn_sched_barrier(0);
;                     }
;                     bf16x8 pf0, pf1;
;                     { float pv[8];
; #pragma unroll
;                       for (int j = 0; j < 8; ++j) { const int cc = 32 * half + j;
;                           float p = __builtin_amdgcn_exp2f(s[j] + (tb + sl2 * (float)cc));
;                           if (diag && (rel0 + cc > 0)) p = 0.f;
;                           pv[j] = p; lsum += p; }
;                       u32x4 w; w.x = pk_bf16(pv[0], pv[1]); w.y = pk_bf16(pv[2], pv[3]); w.z = pk_bf16(pv[4], pv[5]); w.w = pk_bf16(pv[6], pv[7]);
;                       pf0 = __builtin_bit_cast(bf16x8, w); }
;                     __builtin_amdgcn_sched_barrier(0);
;                     u32x4 w1; float pe = 0.f;
; #pragma unroll
;                     for (int d = 0; d < 8; ++d) {
;                         O[d] = MFMA32(VREAD(2 * d), pf0, O[d]);
;                         { const int cc = 32 * half + 16 + d;
;                           float p = __builtin_amdgcn_exp2f(s[8 + d] + (tb + sl2 * (float)cc));
;                           if (diag && (rel0 + cc > 0)) p = 0.f;
;                           lsum += p;
;                           if (d & 1) w1[d >> 1] = pk_bf16(pe, p); else pe = p; }
;                         __builtin_amdgcn_sched_barrier(0);
;                     }
;                     pf1 = __builtin_bit_cast(bf16x8, w1);
; #pragma unroll
;                     for (int d = 0; d < 8; ++d) {
;                         O[d] = MFMA32(VREAD(2 * d + 1), pf1, O[d]);
;                         __builtin_amdgcn_sched_barrier(0);
;                     }
	v_mfma_f32_32x32x16_bf16 v[112:127], v[216:219], v[204:207], v[112:127]
	ds_read_b128 v[216:219], v226 offset:8192
	v_fmamk_f32 v128, v180, 0x42000000, v215
	v_fmamk_f32 v129, v180, 0x42040000, v215
	v_fmamk_f32 v130, v180, 0x42080000, v215
	v_fmamk_f32 v131, v180, 0x420c0000, v215
	v_fmamk_f32 v132, v180, 0x42100000, v215
	v_fmamk_f32 v133, v180, 0x42140000, v215
	v_fmamk_f32 v134, v180, 0x42180000, v215
	v_fmamk_f32 v135, v180, 0x421c0000, v215
	s_waitcnt lgkmcnt(7)
	v_mfma_f32_32x32x16_bf16 v[96:111], v[220:223], v[204:207], v[96:111]
	ds_read_b128 v[220:223], v227 offset:8192
	v_fmamk_f32 v136, v180, 0x42400000, v215
	v_fmamk_f32 v137, v180, 0x42440000, v215
	v_fmamk_f32 v138, v180, 0x42480000, v215
	v_fmamk_f32 v139, v180, 0x424c0000, v215
	v_fmamk_f32 v140, v180, 0x42500000, v215
	v_fmamk_f32 v141, v180, 0x42540000, v215
	v_fmamk_f32 v142, v180, 0x42580000, v215
	v_fmamk_f32 v143, v180, 0x425c0000, v215
	s_waitcnt lgkmcnt(7)
	v_mfma_f32_32x32x16_bf16 v[80:95], v[236:239], v[204:207], v[80:95]
	ds_read_b128 v[236:239], v228 offset:8192
	v_cmp_gt_i32_e32 vcc, 32, v182
	s_nop 1
	v_cndmask_b32_e32 v128, v128, v181, vcc
	v_cmp_gt_i32_e32 vcc, 33, v182
	s_nop 1
	v_cndmask_b32_e32 v129, v129, v181, vcc
	v_cmp_gt_i32_e32 vcc, 34, v182
	s_nop 1
	s_waitcnt lgkmcnt(7)
	v_mfma_f32_32x32x16_bf16 v[64:79], v[240:243], v[204:207], v[64:79]
	ds_read_b128 v[240:243], v229 offset:8192
	v_cndmask_b32_e32 v130, v130, v181, vcc
	v_cmp_gt_i32_e32 vcc, 35, v182
	s_nop 1
	v_cndmask_b32_e32 v131, v131, v181, vcc
	v_cmp_gt_i32_e32 vcc, 36, v182
	s_nop 1
	v_cndmask_b32_e32 v132, v132, v181, vcc
	v_cmp_gt_i32_e32 vcc, 37, v182
	s_waitcnt lgkmcnt(7)
	v_mfma_f32_32x32x16_bf16 v[48:63], v[184:187], v[204:207], v[48:63]
	ds_read_b128 v[184:187], v230 offset:8192
	s_nop 1
	v_cndmask_b32_e32 v133, v133, v181, vcc
	v_cmp_gt_i32_e32 vcc, 38, v182
	s_nop 1
	v_cndmask_b32_e32 v134, v134, v181, vcc
	v_cmp_gt_i32_e32 vcc, 39, v182
	s_nop 1
	v_cndmask_b32_e32 v135, v135, v181, vcc
	s_waitcnt lgkmcnt(7)
	v_mfma_f32_32x32x16_bf16 v[32:47], v[188:191], v[204:207], v[32:47]
	ds_read_b128 v[188:191], v231 offset:8192
	v_cmp_gt_i32_e32 vcc, 48, v182
	s_nop 1
	v_cndmask_b32_e32 v136, v136, v181, vcc
	v_cmp_gt_i32_e32 vcc, 49, v182
	s_nop 1
	v_cndmask_b32_e32 v137, v137, v181, vcc
	v_cmp_gt_i32_e32 vcc, 50, v182
	s_nop 1
	s_waitcnt lgkmcnt(7)
	v_mfma_f32_32x32x16_bf16 v[16:31], v[192:195], v[204:207], v[16:31]
	ds_read_b128 v[192:195], v232 offset:8192
	v_cndmask_b32_e32 v138, v138, v181, vcc
	v_cmp_gt_i32_e32 vcc, 51, v182
	s_nop 1
	v_cndmask_b32_e32 v139, v139, v181, vcc
	v_cmp_gt_i32_e32 vcc, 52, v182
	s_nop 1
	v_cndmask_b32_e32 v140, v140, v181, vcc
	v_cmp_gt_i32_e32 vcc, 53, v182
	s_waitcnt lgkmcnt(7)
	v_mfma_f32_32x32x16_bf16 v[0:15], v[196:199], v[204:207], v[0:15]
	ds_read_b128 v[196:199], v253 offset:8192
	s_nop 1
	v_cndmask_b32_e32 v141, v141, v181, vcc
	v_cmp_gt_i32_e32 vcc, 54, v182
	s_nop 1
	v_cndmask_b32_e32 v142, v142, v181, vcc
	v_cmp_gt_i32_e32 vcc, 55, v182
	s_nop 1
	v_cndmask_b32_e32 v143, v143, v181, vcc
	s_nop 1
	s_waitcnt lgkmcnt(7)
	v_mfma_f32_32x32x16_bf16 v[128:143], v[216:219], v[144:147], v[128:143]
	ds_read_b128 v[216:219], v252 offset:32768
	s_waitcnt lgkmcnt(7)
	v_mfma_f32_32x32x16_bf16 v[128:143], v[220:223], v[148:151], v[128:143]
	ds_read_b128 v[220:223], v252 offset:36864
	s_waitcnt lgkmcnt(7)
	v_mfma_f32_32x32x16_bf16 v[128:143], v[236:239], v[152:155], v[128:143]
	ds_read_b128 v[236:239], v252 offset:40960
	s_waitcnt lgkmcnt(7)
	v_mfma_f32_32x32x16_bf16 v[128:143], v[240:243], v[156:159], v[128:143]
	ds_read_b128 v[240:243], v252 offset:45056
	s_waitcnt lgkmcnt(7)
; #define MFMA32(a, b, c) __builtin_amdgcn_mfma_f32_32x32x16_bf16((a), (b), (c), 0, 0, 0)
; __device__ __forceinline__ void attn_phase(LAS unsigned char* lds, const KArgs& P, int G, int c, int wv) {
;     ...
;                 for (int half = 0; half < 2; ++half) {
;     ...
;                     f32x16 s;
; #pragma unroll
;                     for (int i = 0; i < 16; ++i) s[i] = 0.f;
;                     bf16x8 fr4[2];
;                     fr4[0] = KREAD(0);
;                     __builtin_amdgcn_sched_barrier(0);
; #pragma unroll
;                     for (int ks = 0; ks < 8; ++ks) {
;                         if (ks + 1 < 8) fr4[(ks + 1) & 1] = KREAD(ks + 1);
;                         s = MFMA32(fr4[ks & 1], qf[ks], s);
;                         __builtin_amdgcn_sched_barrier(0);
;                     }
;                     bf16x8 pf0, pf1;
;                     { float pv[8];
; #pragma unroll
;                       for (int j = 0; j < 8; ++j) { const int cc = 32 * half + j;
;                           float p = __builtin_amdgcn_exp2f(s[j] + (tb + sl2 * (float)cc));
;                           if (diag && (rel0 + cc > 0)) p = 0.f;
;                           pv[j] = p; lsum += p; }
;                       u32x4 w; w.x = pk_bf16(pv[0], pv[1]); w.y = pk_bf16(pv[2], pv[3]); w.z = pk_bf16(pv[4], pv[5]); w.w = pk_bf16(pv[6], pv[7]);
;                       pf0 = __builtin_bit_cast(bf16x8, w); }
;                     __builtin_amdgcn_sched_barrier(0);
;                     u32x4 w1; float pe = 0.f;
; #pragma unroll
;                     for (int d = 0; d < 8; ++d) {
;                         O[d] = MFMA32(VREAD(2 * d), pf0, O[d]);
;                         { const int cc = 32 * half + 16 + d;
;                           float p = __builtin_amdgcn_exp2f(s[8 + d] + (tb + sl2 * (float)cc));
;                           if (diag && (rel0 + cc > 0)) p = 0.f;
;                           lsum += p;
;                           if (d & 1) w1[d >> 1] = pk_bf16(pe, p); else pe = p; }
;                         __builtin_amdgcn_sched_barrier(0);
;                     }
;                     pf1 = __builtin_bit_cast(bf16x8, w1);
; #pragma unroll
;                     for (int d = 0; d < 8; ++d) {
;                         O[d] = MFMA32(VREAD(2 * d + 1), pf1, O[d]);
;                         __builtin_amdgcn_sched_barrier(0);
;                     }
	v_mfma_f32_32x32x16_bf16 v[128:143], v[184:187], v[160:163], v[128:143]
	ds_read_b128 v[184:187], v252 offset:49152
	s_waitcnt lgkmcnt(7)
	v_mfma_f32_32x32x16_bf16 v[128:143], v[188:191], v[164:167], v[128:143]
	ds_read_b128 v[188:191], v252 offset:53248
	s_waitcnt lgkmcnt(7)
	v_mfma_f32_32x32x16_bf16 v[128:143], v[192:195], v[168:171], v[128:143]
	ds_read_b128 v[192:195], v252 offset:57344
	s_waitcnt lgkmcnt(7)
	v_mfma_f32_32x32x16_bf16 v[128:143], v[196:199], v[172:175], v[128:143]
	ds_read_b128 v[196:199], v252 offset:61440
	s_nop 11
	v_exp_f32_e32 v128, v128
	v_exp_f32_e32 v129, v129
	v_exp_f32_e32 v130, v130
	v_exp_f32_e32 v131, v131
	v_exp_f32_e32 v132, v132
	v_exp_f32_e32 v133, v133
	v_exp_f32_e32 v134, v134
	v_exp_f32_e32 v135, v135
	v_cvt_pk_bf16_f32 v200, v128, v129
	v_cvt_pk_bf16_f32 v201, v130, v131
	v_cvt_pk_bf16_f32 v202, v132, v133
	v_cvt_pk_bf16_f32 v203, v134, v135
	v_add_f32_e32 v183, v128, v129
	v_add_f32_e32 v208, v130, v131
	v_add_f32_e32 v209, v132, v133
	v_add_f32_e32 v210, v134, v135
	v_add_f32_e32 v183, v183, v208
	v_add_f32_e32 v209, v209, v210
	v_add_f32_e32 v183, v183, v209
	v_add_f32_e32 v212, v212, v183
	s_waitcnt lgkmcnt(7)
	v_mfma_f32_32x32x16_bf16 v[112:127], v[216:219], v[200:203], v[112:127]
	ds_read_b128 v[216:219], v234 offset:32768
	v_exp_f32_e32 v136, v136
	s_waitcnt lgkmcnt(7)
	v_mfma_f32_32x32x16_bf16 v[96:111], v[220:223], v[200:203], v[96:111]
	ds_read_b128 v[220:223], v234 offset:36864
	v_exp_f32_e32 v137, v137
	s_nop 0
	v_cvt_pk_bf16_f32 v204, v136, v137
	v_add_f32_e32 v183, v136, v137
	s_waitcnt lgkmcnt(7)
	v_mfma_f32_32x32x16_bf16 v[80:95], v[236:239], v[200:203], v[80:95]
	ds_read_b128 v[236:239], v234 offset:40960
	v_exp_f32_e32 v138, v138
	s_waitcnt lgkmcnt(7)
	v_mfma_f32_32x32x16_bf16 v[64:79], v[240:243], v[200:203], v[64:79]
	ds_read_b128 v[240:243], v234 offset:45056
	v_exp_f32_e32 v139, v139
	s_nop 0
	v_cvt_pk_bf16_f32 v205, v138, v139
	v_add_f32_e32 v208, v138, v139
	s_waitcnt lgkmcnt(7)
	v_mfma_f32_32x32x16_bf16 v[48:63], v[184:187], v[200:203], v[48:63]
	ds_read_b128 v[184:187], v234 offset:49152
	v_exp_f32_e32 v140, v140
	s_waitcnt lgkmcnt(7)
	v_mfma_f32_32x32x16_bf16 v[32:47], v[188:191], v[200:203], v[32:47]
	ds_read_b128 v[188:191], v234 offset:53248
	v_exp_f32_e32 v141, v141
	s_nop 0
	v_cvt_pk_bf16_f32 v206, v140, v141
	v_add_f32_e32 v209, v140, v141
	s_waitcnt lgkmcnt(7)
	v_mfma_f32_32x32x16_bf16 v[16:31], v[192:195], v[200:203], v[16:31]
	ds_read_b128 v[192:195], v234 offset:57344
	v_exp_f32_e32 v142, v142
	s_waitcnt lgkmcnt(7)
	v_mfma_f32_32x32x16_bf16 v[0:15], v[196:199], v[200:203], v[0:15]
	ds_read_b128 v[196:199], v234 offset:61440
	v_exp_f32_e32 v143, v143
	s_nop 0
	v_cvt_pk_bf16_f32 v207, v142, v143
	v_add_f32_e32 v210, v142, v143
	v_add_f32_e32 v183, v183, v208
	v_add_f32_e32 v209, v209, v210
	v_add_f32_e32 v183, v183, v209
	v_add_f32_e32 v212, v212, v183
	s_waitcnt lgkmcnt(7)
	v_mfma_f32_32x32x16_bf16 v[112:127], v[216:219], v[204:207], v[112:127]
	s_waitcnt lgkmcnt(6)
	v_mfma_f32_32x32x16_bf16 v[96:111], v[220:223], v[204:207], v[96:111]
	s_waitcnt lgkmcnt(5)
	v_mfma_f32_32x32x16_bf16 v[80:95], v[236:239], v[204:207], v[80:95]
	s_waitcnt lgkmcnt(4)
	v_mfma_f32_32x32x16_bf16 v[64:79], v[240:243], v[204:207], v[64:79]
	s_waitcnt lgkmcnt(3)
	v_mfma_f32_32x32x16_bf16 v[48:63], v[184:187], v[204:207], v[48:63]
	s_waitcnt lgkmcnt(2)
	v_mfma_f32_32x32x16_bf16 v[32:47], v[188:191], v[204:207], v[32:47]
	s_waitcnt lgkmcnt(1)
	v_mfma_f32_32x32x16_bf16 v[16:31], v[192:195], v[204:207], v[16:31]
	s_waitcnt lgkmcnt(0)
	v_mfma_f32_32x32x16_bf16 v[0:15], v[196:199], v[204:207], v[0:15]
	s_branch .LBB0_358

; #define PG8_STAGE(bufoff, gbase, voff) do { _Pragma("unroll") for (int _i = 0; _i < 2; ++_i) \
;         __builtin_amdgcn_global_load_lds((const unsigned*)((const char*)(gbase) + (voff)[_i]), (LAS unsigned*)(lds + (bufoff) + ldsw + _i * 8192), 16, 0, 0); } while (0)
; #define PG8_LDA(dst, b, h) do { _Pragma("unroll") for (int m = 0; m < 4; ++m) _Pragma("unroll") for (int k = 0; k < 2; ++k) dst[m][k] = *(const LAS bf16x8*)(lds + PG8_SA(b, h) + aoff + m * 2048 + k * 1024); } while (0)
; #define PG8_LDB(dst, b, h) do { _Pragma("unroll") for (int n = 0; n < 2; ++n) _Pragma("unroll") for (int k = 0; k < 2; ++k) dst[n][k] = *(const LAS bf16x8*)(lds + PG8_SB(b, h) + boff + n * 2048 + k * 1024); } while (0)
; #define PG8_MMA(ai, bj, At, Bt) do { __builtin_amdgcn_s_setprio(1); _Pragma("unroll") for (int m = 0; m < 4; ++m) _Pragma("unroll") for (int n = 0; n < 2; ++n) _Pragma("unroll") for (int k = 0; k < 2; ++k) \
;         acc[ai][bj][m][n] = __builtin_amdgcn_mfma_f32_16x16x32_bf16(Bt[n][k], At[m][k], acc[ai][bj][m][n], 0, 0, 0); __builtin_amdgcn_s_setprio(0); } while (0)
; template <class Epi>
; __device__ __forceinline__ void gemm_phase(LAS unsigned char* lds, const Gemm g, const StaticOrder& S, const Epi& E, int wv) {
;     ...
;         const bool has_next = S.next(ui + 1, nxt);
;         const char* nA = has_next ? (const char*)g.A + (size_t)nxt.pm * tstepA + ((g.adiag & 1) ? (size_t)(nxt.pn >> 1) * K * 2 : 0) + kbeg : cA;
;         const char* nB = has_next ? (const char*)g.Bt + (size_t)nxt.pn * tstepB + kbeg : cB;
;         for (int t = 0; t < nt; t += 2) {
;             const bool last = (t == nt - 2);
;             const char* a1 = cA + (ptrdiff_t)(t + 1) * kstep;
;             const char* a2 = last ? nA : cA + (ptrdiff_t)(t + 2) * kstep; const char* b2 = last ? nB : cB + (ptrdiff_t)(t + 2) * kstep;
;             const char* a3 = a2 + kstep; const char* b3 = b2 + kstep;
;             PG8_LDB(B0, 0, 0); PG8_SCHED; PG8_LDA(At, 0, 0); PG8_STAGE(PG8_SA(1, 1), a1 + hstepA, voffA);
;             PG8_WAIT_L(8); PG8_BAR; PG8_WAIT_L(0); PG8_MMA(0, 0, At, B0); PG8_BAR; PG8_SCHED;
;     ...
; #pragma unroll
;         for (int a = 0; a < 2; ++a)
; #pragma unroll
;             for (int b = 0; b < 2; ++b)
; #pragma unroll
;                 for (int m = 0; m < 4; ++m)
; #pragma unroll
;                     for (int n = 0; n < 2; ++n) acc[a][b][m][n] = (f32x4){0.f, 0.f, 0.f, 0.f};
.LBB0_442:
	s_ashr_i32 s61, s60, 31
	s_lshl_b64 s[34:35], s[60:61], 20
	v_cmp_lt_i64_e32 vcc, s[62:63], v[156:157]
	s_add_u32 s62, s5, s34
	s_addc_u32 s63, s6, s35
	s_and_b64 s[34:35], vcc, exec
	s_cselect_b32 s33, s63, s71
	s_cselect_b32 s34, s62, s70
	s_ashr_i32 s59, s58, 31
	s_lshl_b64 s[38:39], s[58:59], 20
	s_add_u32 s64, s7, s38
	s_addc_u32 s65, s8, s39
	s_and_b64 s[38:39], vcc, exec
	s_cselect_b32 s35, s65, s73
	s_cselect_b32 s38, s64, s72
	s_add_u32 s39, s72, 0x100
	s_addc_u32 s40, s73, 0
	s_add_u32 s70, s70, 0x80080
	v_mov_b32_e32 v0, 0
	s_addc_u32 s71, s71, 0
	s_mov_b32 s41, -2
	s_waitcnt lgkmcnt(0)
	v_mov_b32_e32 v1, v0
	v_mov_b32_e32 v2, v0
	v_mov_b32_e32 v3, v0
	v_mov_b32_e32 v4, v0
	v_mov_b32_e32 v5, v0
	v_mov_b32_e32 v6, v0
	v_mov_b32_e32 v7, v0
	v_mov_b32_e32 v16, v0
	v_mov_b32_e32 v17, v0
	v_mov_b32_e32 v18, v0
	v_mov_b32_e32 v19, v0
	v_mov_b32_e32 v20, v0
	v_mov_b32_e32 v21, v0
	v_mov_b32_e32 v22, v0
	v_mov_b32_e32 v23, v0
	v_mov_b32_e32 v32, v0
	v_mov_b32_e32 v33, v0
	v_mov_b32_e32 v34, v0
	v_mov_b32_e32 v35, v0
	v_mov_b32_e32 v36, v0
	v_mov_b32_e32 v37, v0
	v_mov_b32_e32 v38, v0
	v_mov_b32_e32 v39, v0
	v_mov_b32_e32 v48, v0
	v_mov_b32_e32 v49, v0
	v_mov_b32_e32 v50, v0
	v_mov_b32_e32 v51, v0
	v_mov_b32_e32 v52, v0
	v_mov_b32_e32 v53, v0
	v_mov_b32_e32 v54, v0
	v_mov_b32_e32 v55, v0
	v_mov_b32_e32 v8, v0
	v_mov_b32_e32 v9, v0
	v_mov_b32_e32 v10, v0
	v_mov_b32_e32 v11, v0
	v_mov_b32_e32 v12, v0
	v_mov_b32_e32 v13, v0
	v_mov_b32_e32 v14, v0
	v_mov_b32_e32 v15, v0
	v_mov_b32_e32 v24, v0
	v_mov_b32_e32 v25, v0
	v_mov_b32_e32 v26, v0
	v_mov_b32_e32 v27, v0
	v_mov_b32_e32 v28, v0
	v_mov_b32_e32 v29, v0
	v_mov_b32_e32 v30, v0
	v_mov_b32_e32 v31, v0
	v_mov_b32_e32 v40, v0
	v_mov_b32_e32 v41, v0
	v_mov_b32_e32 v42, v0
	v_mov_b32_e32 v43, v0
	v_mov_b32_e32 v44, v0
	v_mov_b32_e32 v45, v0
	v_mov_b32_e32 v46, v0
	v_mov_b32_e32 v47, v0
	v_mov_b32_e32 v56, v0
	v_mov_b32_e32 v57, v0
	v_mov_b32_e32 v58, v0
	v_mov_b32_e32 v59, v0
	v_mov_b32_e32 v60, v0
	v_mov_b32_e32 v61, v0
	v_mov_b32_e32 v62, v0
	v_mov_b32_e32 v63, v0
	v_mov_b32_e32 v64, v0
	v_mov_b32_e32 v65, v0
	v_mov_b32_e32 v66, v0
	v_mov_b32_e32 v67, v0
	v_mov_b32_e32 v68, v0
	v_mov_b32_e32 v69, v0
	v_mov_b32_e32 v70, v0
	v_mov_b32_e32 v71, v0
	v_mov_b32_e32 v80, v0
	v_mov_b32_e32 v81, v0
	v_mov_b32_e32 v82, v0
	v_mov_b32_e32 v83, v0
	v_mov_b32_e32 v84, v0
	v_mov_b32_e32 v85, v0
	v_mov_b32_e32 v86, v0
	v_mov_b32_e32 v87, v0
	v_mov_b32_e32 v96, v0
	v_mov_b32_e32 v97, v0
	v_mov_b32_e32 v98, v0
	v_mov_b32_e32 v99, v0
	v_mov_b32_e32 v100, v0
	v_mov_b32_e32 v101, v0
	v_mov_b32_e32 v102, v0
	v_mov_b32_e32 v103, v0
	v_mov_b32_e32 v112, v0
	v_mov_b32_e32 v113, v0
	v_mov_b32_e32 v114, v0
	v_mov_b32_e32 v115, v0
	v_mov_b32_e32 v116, v0
	v_mov_b32_e32 v117, v0
	v_mov_b32_e32 v118, v0
	v_mov_b32_e32 v119, v0
	v_mov_b32_e32 v72, v0
	v_mov_b32_e32 v73, v0
	v_mov_b32_e32 v74, v0
	v_mov_b32_e32 v75, v0
	v_mov_b32_e32 v76, v0
	v_mov_b32_e32 v77, v0
	v_mov_b32_e32 v78, v0
	v_mov_b32_e32 v79, v0
	v_mov_b32_e32 v88, v0
	v_mov_b32_e32 v89, v0
	v_mov_b32_e32 v90, v0
	v_mov_b32_e32 v91, v0
	v_mov_b32_e32 v92, v0
	v_mov_b32_e32 v93, v0
	v_mov_b32_e32 v94, v0
	v_mov_b32_e32 v95, v0
	v_mov_b32_e32 v104, v0
	v_mov_b32_e32 v105, v0
	v_mov_b32_e32 v106, v0
	v_mov_b32_e32 v107, v0
	v_mov_b32_e32 v108, v0
	v_mov_b32_e32 v109, v0
	v_mov_b32_e32 v110, v0
	v_mov_b32_e32 v111, v0
	v_mov_b32_e32 v120, v0
	v_mov_b32_e32 v121, v0
	v_mov_b32_e32 v122, v0
	v_mov_b32_e32 v123, v0
	v_mov_b32_e32 v124, v0
	v_mov_b32_e32 v125, v0
	v_mov_b32_e32 v126, v0
	v_mov_b32_e32 v127, v0
	ds_read_b128 v[128:131], v179
	ds_read_b128 v[132:135], v179 offset:1024
	ds_read_b128 v[136:139], v179 offset:2048
	ds_read_b128 v[140:143], v179 offset:3072
.LBB0_443:
	s_add_u32 s42, s70, 0xfff80080
	s_addc_u32 s43, s71, -1
	s_cmp_eq_u32 s41, 28
	s_cselect_b32 s75, s33, s43
	s_cselect_b32 s74, s34, s42
	s_cselect_b32 s73, s35, s40
	s_cselect_b32 s72, s38, s39
	s_add_i32 m0, s10, 0xc000
	ds_read_b128 v[160:163], v180
	ds_read_b128 v[164:167], v180 offset:1024
	ds_read_b128 v[168:171], v180 offset:2048
	ds_read_b128 v[172:175], v180 offset:3072
	ds_read_b128 v[182:185], v180 offset:4096
	ds_read_b128 v[186:189], v180 offset:5120
	ds_read_b128 v[190:193], v180 offset:6144
	ds_read_b128 v[194:197], v180 offset:7168
	global_load_lds_dwordx4 v154, s[70:71]
	s_add_i32 m0, s10, 0xe000
	s_nop 0
	global_load_lds_dwordx4 v152, s[70:71]
	s_waitcnt lgkmcnt(8)
	s_barrier
	s_waitcnt lgkmcnt(0)
	s_setprio 1
	s_waitcnt lgkmcnt(0)
	v_mfma_f32_16x16x32_bf16 v[124:127], v[128:131], v[160:163], v[124:127]
	v_mfma_f32_16x16x32_bf16 v[120:123], v[136:139], v[160:163], v[120:123]
	v_mfma_f32_16x16x32_bf16 v[108:111], v[128:131], v[168:171], v[108:111]
	v_mfma_f32_16x16x32_bf16 v[104:107], v[136:139], v[168:171], v[104:107]
	v_mfma_f32_16x16x32_bf16 v[92:95], v[128:131], v[182:185], v[92:95]
	v_mfma_f32_16x16x32_bf16 v[88:91], v[136:139], v[182:185], v[88:91]
	v_mfma_f32_16x16x32_bf16 v[76:79], v[128:131], v[190:193], v[76:79]
	v_mfma_f32_16x16x32_bf16 v[72:75], v[136:139], v[190:193], v[72:75]
	v_mfma_f32_16x16x32_bf16 v[124:127], v[132:135], v[164:167], v[124:127]
	v_mfma_f32_16x16x32_bf16 v[120:123], v[140:143], v[164:167], v[120:123]
	v_mfma_f32_16x16x32_bf16 v[108:111], v[132:135], v[172:175], v[108:111]
	v_mfma_f32_16x16x32_bf16 v[104:107], v[140:143], v[172:175], v[104:107]
	v_mfma_f32_16x16x32_bf16 v[92:95], v[132:135], v[186:189], v[92:95]
	v_mfma_f32_16x16x32_bf16 v[88:91], v[140:143], v[186:189], v[88:91]
	v_mfma_f32_16x16x32_bf16 v[76:79], v[132:135], v[194:197], v[76:79]
	v_mfma_f32_16x16x32_bf16 v[72:75], v[140:143], v[194:197], v[72:75]
	s_setprio 0
	s_barrier
; #define PG8_STAGE(bufoff, gbase, voff) do { _Pragma("unroll") for (int _i = 0; _i < 2; ++_i) \
;         __builtin_amdgcn_global_load_lds((const unsigned*)((const char*)(gbase) + (voff)[_i]), (LAS unsigned*)(lds + (bufoff) + ldsw + _i * 8192), 16, 0, 0); } while (0)
; #define PG8_LDA(dst, b, h) do { _Pragma("unroll") for (int m = 0; m < 4; ++m) _Pragma("unroll") for (int k = 0; k < 2; ++k) dst[m][k] = *(const LAS bf16x8*)(lds + PG8_SA(b, h) + aoff + m * 2048 + k * 1024); } while (0)
; #define PG8_LDB(dst, b, h) do { _Pragma("unroll") for (int n = 0; n < 2; ++n) _Pragma("unroll") for (int k = 0; k < 2; ++k) dst[n][k] = *(const LAS bf16x8*)(lds + PG8_SB(b, h) + boff + n * 2048 + k * 1024); } while (0)
; #define PG8_MMA(ai, bj, At, Bt) do { __builtin_amdgcn_s_setprio(1); _Pragma("unroll") for (int m = 0; m < 4; ++m) _Pragma("unroll") for (int n = 0; n < 2; ++n) _Pragma("unroll") for (int k = 0; k < 2; ++k) \
;         acc[ai][bj][m][n] = __builtin_amdgcn_mfma_f32_16x16x32_bf16(Bt[n][k], At[m][k], acc[ai][bj][m][n], 0, 0, 0); __builtin_amdgcn_s_setprio(0); } while (0)
; #define PG8_WAIT_V(n) asm volatile("s_waitcnt vmcnt(" #n ")" ::: "memory")
; #define PG8_WAIT_L(n) asm volatile("s_waitcnt lgkmcnt(" #n ")" ::: "memory")
; #define PG8_BAR __builtin_amdgcn_s_barrier()
; #define PG8_SCHED __builtin_amdgcn_sched_barrier(0)
; template <class Epi>
; __device__ __forceinline__ void gemm_phase(LAS unsigned char* lds, const Gemm g, const StaticOrder& S, const Epi& E, int wv) {
;     ...
;             PG8_LDB(B1, 0, 1); PG8_STAGE(PG8_SB(0, 0), b2, voffB);
;             PG8_BAR; PG8_WAIT_L(0); PG8_MMA(0, 1, At, B1); PG8_BAR;
;             PG8_LDA(At, 0, 1); PG8_STAGE(PG8_SA(0, 0), a2, voffA);
;             PG8_BAR; PG8_WAIT_L(0); PG8_MMA(1, 0, At, B0); PG8_BAR; PG8_SCHED;
;             PG8_STAGE(PG8_SB(0, 1), b2 + hstepB, voffB);
;             PG8_WAIT_V(6); PG8_BAR; PG8_MMA(1, 1, At, B1); PG8_BAR;
;             PG8_LDB(B0, 1, 0); PG8_SCHED; PG8_LDA(At, 1, 0); PG8_STAGE(PG8_SA(0, 1), a2 + hstepA, voffA);
;             PG8_WAIT_L(8); PG8_BAR; PG8_WAIT_L(0); PG8_MMA(0, 0, At, B0); PG8_BAR; PG8_SCHED;
	s_add_i32 s42, s23, s9
	s_add_u32 s98, s72, s54
	s_addc_u32 s99, s73, s55
	s_mov_b32 m0, s42
	ds_read_b128 v[198:201], v181
	ds_read_b128 v[202:205], v181 offset:1024
	ds_read_b128 v[206:209], v181 offset:2048
	ds_read_b128 v[210:213], v181 offset:3072
	global_load_lds_dwordx4 v146, s[72:73]
	s_add_i32 m0, s42, 0x2000
	s_nop 0
	global_load_lds_dwordx4 v150, s[72:73]
	s_barrier
	s_waitcnt lgkmcnt(0)
	s_setprio 1
	s_waitcnt lgkmcnt(0)
	v_mfma_f32_16x16x32_bf16 v[116:119], v[198:201], v[160:163], v[116:119]
	v_mfma_f32_16x16x32_bf16 v[112:115], v[206:209], v[160:163], v[112:115]
	v_mfma_f32_16x16x32_bf16 v[100:103], v[198:201], v[168:171], v[100:103]
	v_mfma_f32_16x16x32_bf16 v[96:99], v[206:209], v[168:171], v[96:99]
	v_mfma_f32_16x16x32_bf16 v[84:87], v[198:201], v[182:185], v[84:87]
	v_mfma_f32_16x16x32_bf16 v[80:83], v[206:209], v[182:185], v[80:83]
	v_mfma_f32_16x16x32_bf16 v[68:71], v[198:201], v[190:193], v[68:71]
	v_mfma_f32_16x16x32_bf16 v[64:67], v[206:209], v[190:193], v[64:67]
	v_mfma_f32_16x16x32_bf16 v[116:119], v[202:205], v[164:167], v[116:119]
	v_mfma_f32_16x16x32_bf16 v[112:115], v[210:213], v[164:167], v[112:115]
	v_mfma_f32_16x16x32_bf16 v[100:103], v[202:205], v[172:175], v[100:103]
	v_mfma_f32_16x16x32_bf16 v[96:99], v[210:213], v[172:175], v[96:99]
	v_mfma_f32_16x16x32_bf16 v[84:87], v[202:205], v[186:189], v[84:87]
	v_mfma_f32_16x16x32_bf16 v[80:83], v[210:213], v[186:189], v[80:83]
	v_mfma_f32_16x16x32_bf16 v[68:71], v[202:205], v[194:197], v[68:71]
	v_mfma_f32_16x16x32_bf16 v[64:67], v[210:213], v[194:197], v[64:67]
	s_setprio 0
	s_mov_b32 m0, s10
	s_add_u32 s100, s74, s54
	s_addc_u32 s101, s75, s55
	s_barrier
	ds_read_b128 v[160:163], v180 offset:16384
	ds_read_b128 v[164:167], v180 offset:17408
	ds_read_b128 v[168:171], v180 offset:18432
	ds_read_b128 v[172:175], v180 offset:19456
	ds_read_b128 v[182:185], v180 offset:20480
	ds_read_b128 v[186:189], v180 offset:21504
	ds_read_b128 v[190:193], v180 offset:22528
	ds_read_b128 v[194:197], v180 offset:23552
	global_load_lds_dwordx4 v144, s[74:75]
	s_mov_b32 m0, s11
	s_nop 0
	global_load_lds_dwordx4 v148, s[74:75]
	s_waitcnt vmcnt(10)
	s_barrier
	s_waitcnt lgkmcnt(0)
	s_setprio 1
	s_waitcnt lgkmcnt(0)
	v_mfma_f32_16x16x32_bf16 v[60:63], v[128:131], v[160:163], v[60:63]
	v_mfma_f32_16x16x32_bf16 v[56:59], v[136:139], v[160:163], v[56:59]
	v_mfma_f32_16x16x32_bf16 v[44:47], v[128:131], v[168:171], v[44:47]
	v_mfma_f32_16x16x32_bf16 v[40:43], v[136:139], v[168:171], v[40:43]
	v_mfma_f32_16x16x32_bf16 v[28:31], v[128:131], v[182:185], v[28:31]
	v_mfma_f32_16x16x32_bf16 v[24:27], v[136:139], v[182:185], v[24:27]
	v_mfma_f32_16x16x32_bf16 v[12:15], v[128:131], v[190:193], v[12:15]
	v_mfma_f32_16x16x32_bf16 v[8:11], v[136:139], v[190:193], v[8:11]
	v_mfma_f32_16x16x32_bf16 v[60:63], v[132:135], v[164:167], v[60:63]
	v_mfma_f32_16x16x32_bf16 v[56:59], v[140:143], v[164:167], v[56:59]
	v_mfma_f32_16x16x32_bf16 v[44:47], v[132:135], v[172:175], v[44:47]
	v_mfma_f32_16x16x32_bf16 v[40:43], v[140:143], v[172:175], v[40:43]
	v_mfma_f32_16x16x32_bf16 v[28:31], v[132:135], v[186:189], v[28:31]
	v_mfma_f32_16x16x32_bf16 v[24:27], v[140:143], v[186:189], v[24:27]
	v_mfma_f32_16x16x32_bf16 v[12:15], v[132:135], v[194:197], v[12:15]
	v_mfma_f32_16x16x32_bf16 v[8:11], v[140:143], v[194:197], v[8:11]
	s_setprio 0
	s_barrier
	s_add_u32 s42, s72, 0x80000
	s_addc_u32 s43, s73, 0
	s_add_i32 s44, s24, s9
	s_mov_b32 m0, s44
	s_nop 0
	global_load_lds_dwordx4 v146, s[42:43]
	s_add_i32 m0, s44, 0x2000
	s_nop 0
	global_load_lds_dwordx4 v150, s[42:43]
	s_add_i32 s44, 0, 0x18000
	v_add_u32_e32 v140, s44, v177
	ds_read_b128 v[128:131], v140
	ds_read_b128 v[132:135], v140 offset:1024
	ds_read_b128 v[136:139], v140 offset:2048
	ds_read_b128 v[140:143], v140 offset:3072
	s_waitcnt vmcnt(6)
	s_barrier
	s_setprio 1
	v_mfma_f32_16x16x32_bf16 v[52:55], v[198:201], v[160:163], v[52:55]
	v_mfma_f32_16x16x32_bf16 v[48:51], v[206:209], v[160:163], v[48:51]
	v_mfma_f32_16x16x32_bf16 v[36:39], v[198:201], v[168:171], v[36:39]
	v_mfma_f32_16x16x32_bf16 v[32:35], v[206:209], v[168:171], v[32:35]
	v_mfma_f32_16x16x32_bf16 v[20:23], v[198:201], v[182:185], v[20:23]
	v_mfma_f32_16x16x32_bf16 v[16:19], v[206:209], v[182:185], v[16:19]
	v_mfma_f32_16x16x32_bf16 v[4:7], v[198:201], v[190:193], v[4:7]
	v_mfma_f32_16x16x32_bf16 v[0:3], v[206:209], v[190:193], v[0:3]
	v_mfma_f32_16x16x32_bf16 v[52:55], v[202:205], v[164:167], v[52:55]
	v_mfma_f32_16x16x32_bf16 v[48:51], v[210:213], v[164:167], v[48:51]
	v_mfma_f32_16x16x32_bf16 v[36:39], v[202:205], v[172:175], v[36:39]
	v_mfma_f32_16x16x32_bf16 v[32:35], v[210:213], v[172:175], v[32:35]
	v_mfma_f32_16x16x32_bf16 v[20:23], v[202:205], v[186:189], v[20:23]
	v_mfma_f32_16x16x32_bf16 v[16:19], v[210:213], v[186:189], v[16:19]
	v_mfma_f32_16x16x32_bf16 v[4:7], v[202:205], v[194:197], v[4:7]
	v_mfma_f32_16x16x32_bf16 v[0:3], v[210:213], v[194:197], v[0:3]
	s_setprio 0
	s_waitcnt lgkmcnt(0)
	s_barrier
	s_add_u32 s42, s74, 0x80000
	s_addc_u32 s43, s75, 0
	s_mov_b32 m0, s12
	ds_read_b128 v[160:163], v180 offset:32768
	ds_read_b128 v[164:167], v180 offset:33792
	ds_read_b128 v[168:171], v180 offset:34816
	ds_read_b128 v[172:175], v180 offset:35840
	ds_read_b128 v[182:185], v180 offset:36864
	ds_read_b128 v[186:189], v180 offset:37888
	ds_read_b128 v[190:193], v180 offset:38912
	ds_read_b128 v[194:197], v180 offset:39936
	global_load_lds_dwordx4 v144, s[42:43]
	s_mov_b32 m0, s13
	s_nop 0
	global_load_lds_dwordx4 v148, s[42:43]
	s_waitcnt lgkmcnt(8)
	s_barrier
; #define PG8_STAGE(bufoff, gbase, voff) do { _Pragma("unroll") for (int _i = 0; _i < 2; ++_i) \
;         __builtin_amdgcn_global_load_lds((const unsigned*)((const char*)(gbase) + (voff)[_i]), (LAS unsigned*)(lds + (bufoff) + ldsw + _i * 8192), 16, 0, 0); } while (0)
; #define PG8_LDA(dst, b, h) do { _Pragma("unroll") for (int m = 0; m < 4; ++m) _Pragma("unroll") for (int k = 0; k < 2; ++k) dst[m][k] = *(const LAS bf16x8*)(lds + PG8_SA(b, h) + aoff + m * 2048 + k * 1024); } while (0)
; #define PG8_LDB(dst, b, h) do { _Pragma("unroll") for (int n = 0; n < 2; ++n) _Pragma("unroll") for (int k = 0; k < 2; ++k) dst[n][k] = *(const LAS bf16x8*)(lds + PG8_SB(b, h) + boff + n * 2048 + k * 1024); } while (0)
; #define PG8_MMA(ai, bj, At, Bt) do { __builtin_amdgcn_s_setprio(1); _Pragma("unroll") for (int m = 0; m < 4; ++m) _Pragma("unroll") for (int n = 0; n < 2; ++n) _Pragma("unroll") for (int k = 0; k < 2; ++k) \
;         acc[ai][bj][m][n] = __builtin_amdgcn_mfma_f32_16x16x32_bf16(Bt[n][k], At[m][k], acc[ai][bj][m][n], 0, 0, 0); __builtin_amdgcn_s_setprio(0); } while (0)
; #define PG8_WAIT_L(n) asm volatile("s_waitcnt lgkmcnt(" #n ")" ::: "memory")
; #define PG8_BAR __builtin_amdgcn_s_barrier()
; #define PG8_SCHED __builtin_amdgcn_sched_barrier(0)
; template <class Epi>
; __device__ __forceinline__ void gemm_phase(LAS unsigned char* lds, const Gemm g, const StaticOrder& S, const Epi& E, int wv) {
;     ...
;             PG8_WAIT_L(8); PG8_BAR; PG8_WAIT_L(0); PG8_MMA(0, 0, At, B0); PG8_BAR; PG8_SCHED;
;             PG8_LDB(B1, 1, 1); PG8_STAGE(PG8_SB(1, 0), b3, voffB);
;             PG8_BAR; PG8_WAIT_L(0); PG8_MMA(0, 1, At, B1); PG8_BAR;
;             PG8_LDA(At, 1, 1); PG8_STAGE(PG8_SA(1, 0), a3, voffA);
;             PG8_BAR; PG8_WAIT_L(0); PG8_MMA(1, 0, At, B0); PG8_BAR; PG8_SCHED;
;             PG8_STAGE(PG8_SB(1, 1), b3 + hstepB, voffB);
	s_waitcnt lgkmcnt(0)
	s_setprio 1
	s_waitcnt lgkmcnt(0)
	v_mfma_f32_16x16x32_bf16 v[124:127], v[128:131], v[160:163], v[124:127]
	v_mfma_f32_16x16x32_bf16 v[120:123], v[136:139], v[160:163], v[120:123]
	v_mfma_f32_16x16x32_bf16 v[108:111], v[128:131], v[168:171], v[108:111]
	v_mfma_f32_16x16x32_bf16 v[104:107], v[136:139], v[168:171], v[104:107]
	v_mfma_f32_16x16x32_bf16 v[92:95], v[128:131], v[182:185], v[92:95]
	v_mfma_f32_16x16x32_bf16 v[88:91], v[136:139], v[182:185], v[88:91]
	v_mfma_f32_16x16x32_bf16 v[76:79], v[128:131], v[190:193], v[76:79]
	v_mfma_f32_16x16x32_bf16 v[72:75], v[136:139], v[190:193], v[72:75]
	v_mfma_f32_16x16x32_bf16 v[124:127], v[132:135], v[164:167], v[124:127]
	v_mfma_f32_16x16x32_bf16 v[120:123], v[140:143], v[164:167], v[120:123]
	v_mfma_f32_16x16x32_bf16 v[108:111], v[132:135], v[172:175], v[108:111]
	v_mfma_f32_16x16x32_bf16 v[104:107], v[140:143], v[172:175], v[104:107]
	v_mfma_f32_16x16x32_bf16 v[92:95], v[132:135], v[186:189], v[92:95]
	v_mfma_f32_16x16x32_bf16 v[88:91], v[140:143], v[186:189], v[88:91]
	v_mfma_f32_16x16x32_bf16 v[76:79], v[132:135], v[194:197], v[76:79]
	v_mfma_f32_16x16x32_bf16 v[72:75], v[140:143], v[194:197], v[72:75]
	s_setprio 0
	s_barrier
	s_add_i32 s45, 0, 0x1c000
	s_add_i32 s42, s44, s9
	v_add_u32_e32 v210, s45, v177
	s_mov_b32 m0, s42
	ds_read_b128 v[198:201], v210
	ds_read_b128 v[202:205], v210 offset:1024
	ds_read_b128 v[206:209], v210 offset:2048
	ds_read_b128 v[210:213], v210 offset:3072
	global_load_lds_dwordx4 v146, s[98:99]
	s_add_i32 m0, s42, 0x2000
	s_nop 0
	global_load_lds_dwordx4 v150, s[98:99]
	s_barrier
	s_waitcnt lgkmcnt(0)
	s_setprio 1
	s_waitcnt lgkmcnt(0)
	v_mfma_f32_16x16x32_bf16 v[116:119], v[198:201], v[160:163], v[116:119]
	v_mfma_f32_16x16x32_bf16 v[112:115], v[206:209], v[160:163], v[112:115]
	v_mfma_f32_16x16x32_bf16 v[100:103], v[198:201], v[168:171], v[100:103]
	v_mfma_f32_16x16x32_bf16 v[96:99], v[206:209], v[168:171], v[96:99]
	v_mfma_f32_16x16x32_bf16 v[84:87], v[198:201], v[182:185], v[84:87]
	v_mfma_f32_16x16x32_bf16 v[80:83], v[206:209], v[182:185], v[80:83]
	v_mfma_f32_16x16x32_bf16 v[68:71], v[198:201], v[190:193], v[68:71]
	v_mfma_f32_16x16x32_bf16 v[64:67], v[206:209], v[190:193], v[64:67]
	v_mfma_f32_16x16x32_bf16 v[116:119], v[202:205], v[164:167], v[116:119]
	v_mfma_f32_16x16x32_bf16 v[112:115], v[210:213], v[164:167], v[112:115]
	v_mfma_f32_16x16x32_bf16 v[100:103], v[202:205], v[172:175], v[100:103]
	v_mfma_f32_16x16x32_bf16 v[96:99], v[210:213], v[172:175], v[96:99]
	v_mfma_f32_16x16x32_bf16 v[84:87], v[202:205], v[186:189], v[84:87]
	v_mfma_f32_16x16x32_bf16 v[80:83], v[210:213], v[186:189], v[80:83]
	v_mfma_f32_16x16x32_bf16 v[68:71], v[202:205], v[194:197], v[68:71]
	v_mfma_f32_16x16x32_bf16 v[64:67], v[210:213], v[194:197], v[64:67]
	s_setprio 0
	s_mov_b32 m0, s15
	s_barrier
	ds_read_b128 v[160:163], v180 offset:49152
	ds_read_b128 v[164:167], v180 offset:50176
	ds_read_b128 v[168:171], v180 offset:51200
	ds_read_b128 v[172:175], v180 offset:52224
	ds_read_b128 v[182:185], v180 offset:53248
	ds_read_b128 v[186:189], v180 offset:54272
	ds_read_b128 v[190:193], v180 offset:55296
	ds_read_b128 v[194:197], v180 offset:56320
	global_load_lds_dwordx4 v144, s[100:101]
	s_mov_b32 m0, s22
	s_nop 0
	global_load_lds_dwordx4 v148, s[100:101]
	s_waitcnt vmcnt(10)
	s_barrier
	s_waitcnt lgkmcnt(0)
	s_setprio 1
	s_waitcnt lgkmcnt(0)
	v_mfma_f32_16x16x32_bf16 v[60:63], v[128:131], v[160:163], v[60:63]
	v_mfma_f32_16x16x32_bf16 v[56:59], v[136:139], v[160:163], v[56:59]
	v_mfma_f32_16x16x32_bf16 v[44:47], v[128:131], v[168:171], v[44:47]
	v_mfma_f32_16x16x32_bf16 v[40:43], v[136:139], v[168:171], v[40:43]
	v_mfma_f32_16x16x32_bf16 v[28:31], v[128:131], v[182:185], v[28:31]
	v_mfma_f32_16x16x32_bf16 v[24:27], v[136:139], v[182:185], v[24:27]
	v_mfma_f32_16x16x32_bf16 v[12:15], v[128:131], v[190:193], v[12:15]
	v_mfma_f32_16x16x32_bf16 v[8:11], v[136:139], v[190:193], v[8:11]
	v_mfma_f32_16x16x32_bf16 v[60:63], v[132:135], v[164:167], v[60:63]
	v_mfma_f32_16x16x32_bf16 v[56:59], v[140:143], v[164:167], v[56:59]
	v_mfma_f32_16x16x32_bf16 v[44:47], v[132:135], v[172:175], v[44:47]
	v_mfma_f32_16x16x32_bf16 v[40:43], v[140:143], v[172:175], v[40:43]
	v_mfma_f32_16x16x32_bf16 v[28:31], v[132:135], v[186:189], v[28:31]
	v_mfma_f32_16x16x32_bf16 v[24:27], v[140:143], v[186:189], v[24:27]
	v_mfma_f32_16x16x32_bf16 v[12:15], v[132:135], v[194:197], v[12:15]
	v_mfma_f32_16x16x32_bf16 v[8:11], v[140:143], v[194:197], v[8:11]
	s_setprio 0
	s_barrier
	s_add_u32 s42, s72, 0x80080
	s_addc_u32 s43, s73, 0
	s_add_i32 s44, s45, s9
	s_mov_b32 m0, s44
	s_nop 0
	global_load_lds_dwordx4 v146, s[42:43]
	s_add_i32 m0, s44, 0x2000
	s_nop 0
	global_load_lds_dwordx4 v150, s[42:43]
	ds_read_b128 v[128:131], v179
	ds_read_b128 v[132:135], v179 offset:1024
	ds_read_b128 v[136:139], v179 offset:2048
	ds_read_b128 v[140:143], v179 offset:3072
	s_waitcnt vmcnt(6)
	s_barrier
; __device__ __forceinline__ float bf_lo(unsigned w) { return __uint_as_float(w << 16); }
; #define PG8_BAR __builtin_amdgcn_s_barrier()
; template <class Epi>
; __device__ __forceinline__ void gemm_phase(LAS unsigned char* lds, const Gemm g, const StaticOrder& S, const Epi& E, int wv) {
;     ...
;             PG8_STAGE(PG8_SB(1, 1), b3 + hstepB, voffB);
;             PG8_WAIT_V(6); PG8_BAR; PG8_MMA(1, 1, At, B1); PG8_BAR;
;     __device__ __forceinline__ void operator()(const f32x4 (&acc)[2][2][4][2], const Unit& u, int wr, int wc, int fr, int fq) const {
;         const int row0 = u.pm * BM + wr * 64 + fr, col0 = u.pn * BM + wc * 32 + 8 * fq;
;         constexpr int RD = 3;
;         f32x4 hbuf[RD][4]; u32x4 hraw[RD][2]; u32x4 pbuf[RD][2]; float rsb[RD];
;     ...
;         RES_LOAD(0, 0); RES_LOAD(1, 1);
; #pragma unroll
;         for (int it = 0; it < 8; ++it) { const int ai = it >> 2, m = it & 3, sc = it % RD;
;             if (it + RD - 1 < 8) RES_LOAD((it + RD - 1) % RD, it + RD - 1);
;             asm volatile("" ::: "memory");
;             const int row = row0 + ai * HALF + m * 16; const size_t ro = (size_t)row * DM + col0;
;             float rs = 1.0f; if (MODE == 1) rs = __builtin_amdgcn_rsqf(ss_fix(rsb[sc]) * (1.0f / DM) + EPS);
;             float sq = 0.f;
; #pragma unroll
;             for (int bj = 0; bj < 2; ++bj) { const size_t off = ro + bj * HALF;
;                 f32x4 v0 = acc[ai][bj][m][0], v1 = acc[ai][bj][m][1];
;                 if (MODE == 1) { const u32x4 pw = pbuf[sc][bj];
;                     v0[0] = fast_sigmoid(rs * v0[0]) * bf_lo(pw.x); v0[1] = fast_sigmoid(rs * v0[1]) * bf_hi(pw.x); v0[2] = fast_sigmoid(rs * v0[2]) * bf_lo(pw.y); v0[3] = fast_sigmoid(rs * v0[3]) * bf_hi(pw.y);
;                     v1[0] = fast_sigmoid(rs * v1[0]) * bf_lo(pw.z); v1[1] = fast_sigmoid(rs * v1[1]) * bf_hi(pw.z); v1[2] = fast_sigmoid(rs * v1[2]) * bf_lo(pw.w); v1[3] = fast_sigmoid(rs * v1[3]) * bf_hi(pw.w); }
;                 f32x4 h0, h1;
;                 if (IN16) { const u32x4 hw = hraw[sc][bj]; h0 = (f32x4){bf_lo(hw.x), bf_hi(hw.x), bf_lo(hw.y), bf_hi(hw.y)}; h1 = (f32x4){bf_lo(hw.z), bf_hi(hw.z), bf_lo(hw.w), bf_hi(hw.w)}; }
;                 else { h0 = hbuf[sc][2 * bj]; h1 = hbuf[sc][2 * bj + 1]; }
;                 const f32x4 o0 = h0 + v0, o1 = h1 + v1;
;                 if (OUT32) { *(f32x4*)(hout + off) = o0; *(f32x4*)(hout + off + 4) = o1; }
	s_setprio 1
	v_mfma_f32_16x16x32_bf16 v[52:55], v[198:201], v[160:163], v[52:55]
	v_mfma_f32_16x16x32_bf16 v[48:51], v[206:209], v[160:163], v[48:51]
	v_mfma_f32_16x16x32_bf16 v[36:39], v[198:201], v[168:171], v[36:39]
	v_mfma_f32_16x16x32_bf16 v[32:35], v[206:209], v[168:171], v[32:35]
	v_mfma_f32_16x16x32_bf16 v[20:23], v[198:201], v[182:185], v[20:23]
	v_mfma_f32_16x16x32_bf16 v[16:19], v[206:209], v[182:185], v[16:19]
	v_mfma_f32_16x16x32_bf16 v[4:7], v[198:201], v[190:193], v[4:7]
	v_mfma_f32_16x16x32_bf16 v[0:3], v[206:209], v[190:193], v[0:3]
	v_mfma_f32_16x16x32_bf16 v[52:55], v[202:205], v[164:167], v[52:55]
	v_mfma_f32_16x16x32_bf16 v[48:51], v[210:213], v[164:167], v[48:51]
	v_mfma_f32_16x16x32_bf16 v[36:39], v[202:205], v[172:175], v[36:39]
	v_mfma_f32_16x16x32_bf16 v[32:35], v[210:213], v[172:175], v[32:35]
	v_mfma_f32_16x16x32_bf16 v[20:23], v[202:205], v[186:189], v[20:23]
	v_mfma_f32_16x16x32_bf16 v[16:19], v[210:213], v[186:189], v[16:19]
	v_mfma_f32_16x16x32_bf16 v[4:7], v[202:205], v[194:197], v[4:7]
	v_mfma_f32_16x16x32_bf16 v[0:3], v[210:213], v[194:197], v[0:3]
	s_setprio 0
	s_waitcnt lgkmcnt(0)
	s_add_i32 s41, s41, 2
	s_add_u32 s39, s39, 0x100
	s_addc_u32 s40, s40, 0
	s_add_u32 s70, s70, 0x100
	s_addc_u32 s71, s71, 0
	s_cmp_gt_u32 s41, 29
	s_barrier
	s_cbranch_scc0 .LBB0_443
	v_lshl_add_u32 v170, s66, 8, v176
	v_lshl_or_b32 v160, s68, 8, v178
	v_ashrrev_i32_e32 v171, 31, v170
	v_ashrrev_i32_e32 v161, 31, v160
	v_lshlrev_b64 v[190:191], 12, v[170:171]
	v_lshl_add_u64 v[128:129], s[30:31], 0, v[190:191]
	v_lshlrev_b64 v[162:163], 1, v[160:161]
	v_lshl_add_u64 v[164:165], v[128:129], 0, v[162:163]
	global_load_dwordx4 v[182:185], v[164:165], off
	global_load_dwordx4 v[186:189], v[164:165], off offset:256
	v_or_b32_e32 v172, 16, v170
	v_or_b32_e32 v166, 32, v170
	v_ashrrev_i32_e32 v173, 31, v172
	v_ashrrev_i32_e32 v167, 31, v166
	v_lshlrev_b64 v[174:175], 12, v[172:173]
	v_lshlrev_b64 v[168:169], 12, v[166:167]
	v_lshl_add_u64 v[128:129], s[30:31], 0, v[174:175]
	v_lshl_add_u64 v[130:131], s[30:31], 0, v[168:169]
	v_lshl_add_u64 v[128:129], v[128:129], 0, v[162:163]
	v_lshl_add_u64 v[130:131], v[130:131], 0, v[162:163]
	global_load_dwordx4 v[140:143], v[128:129], off
	global_load_dwordx4 v[136:139], v[128:129], off offset:256
	global_load_dwordx4 v[132:135], v[130:131], off
	s_nop 0
	global_load_dwordx4 v[128:131], v[130:131], off offset:256
	s_waitcnt vmcnt(0)
	v_lshlrev_b32_e32 v192, 16, v182
	v_and_b32_e32 v193, 0xffff0000, v182
	v_lshlrev_b32_e32 v182, 16, v183
	v_and_b32_e32 v183, 0xffff0000, v183
	v_lshlrev_b32_e32 v194, 16, v184
	v_and_b32_e32 v195, 0xffff0000, v184
	v_lshlrev_b32_e32 v184, 16, v185
	v_and_b32_e32 v185, 0xffff0000, v185
	v_lshlrev_b32_e32 v196, 16, v186
	v_and_b32_e32 v197, 0xffff0000, v186
	v_lshlrev_b32_e32 v186, 16, v187
	v_and_b32_e32 v187, 0xffff0000, v187
	v_lshlrev_b32_e32 v198, 16, v188
	v_and_b32_e32 v199, 0xffff0000, v188
	v_lshlrev_b32_e32 v188, 16, v189
	v_and_b32_e32 v189, 0xffff0000, v189
	v_pk_add_f32 v[126:127], v[126:127], v[182:183]
	v_pk_add_f32 v[124:125], v[124:125], v[192:193]
	v_pk_add_f32 v[122:123], v[122:123], v[184:185]
	v_pk_add_f32 v[120:121], v[120:121], v[194:195]
	v_pk_add_f32 v[118:119], v[118:119], v[186:187]
	v_pk_add_f32 v[116:117], v[116:117], v[196:197]
	v_pk_add_f32 v[182:183], v[114:115], v[188:189]
	v_pk_add_f32 v[184:185], v[112:113], v[198:199]
	v_cvt_pk_bf16_f32 v112, v124, v125
	v_cvt_pk_bf16_f32 v113, v126, v127
	v_cvt_pk_bf16_f32 v114, v120, v121
	v_cvt_pk_bf16_f32 v115, v122, v123
	v_mul_f32_e32 v125, v125, v125
	v_mul_f32_e32 v127, v127, v127
	v_mul_f32_e32 v121, v121, v121
	v_mul_f32_e32 v123, v123, v123
	v_mul_f32_e32 v186, v117, v117
	v_mul_f32_e32 v187, v119, v119
	v_mul_f32_e32 v188, v185, v185
	v_mul_f32_e32 v189, v183, v183
	v_fmac_f32_e32 v125, v124, v124
	v_fmac_f32_e32 v127, v126, v126
	v_fmac_f32_e32 v121, v120, v120
	v_fmac_f32_e32 v123, v122, v122
	v_fmac_f32_e32 v186, v116, v116
	v_fmac_f32_e32 v187, v118, v118
	v_fmac_f32_e32 v188, v184, v184
	v_fmac_f32_e32 v189, v182, v182
	v_add_f32_e32 v120, v125, v127
	v_add_f32_e32 v121, v121, v123
	v_add_f32_e32 v122, v186, v187
	v_add_f32_e32 v123, v188, v189
	v_add_f32_e32 v120, v120, v121
	v_add_f32_e32 v121, v122, v123
	v_add_f32_e32 v122, v120, v121
	ds_bpermute_b32 v123, v245, v122
	v_lshl_add_u64 v[120:121], s[50:51], 0, v[190:191]
	v_lshl_add_u64 v[120:121], v[120:121], 0, v[162:163]
	global_store_dwordx4 v[120:121], v[112:115], off
	s_waitcnt lgkmcnt(0)
	s_nop 0
	v_add_f32_e32 v112, v122, v123
	ds_bpermute_b32 v113, v244, v112
	v_cvt_pk_bf16_f32 v114, v116, v117
	v_cvt_pk_bf16_f32 v115, v118, v119
	v_cvt_pk_bf16_f32 v116, v184, v185
	v_cvt_pk_bf16_f32 v117, v182, v183
	global_store_dwordx4 v[120:121], v[114:117], off offset:256
	s_and_saveexec_b64 s[66:67], s[16:17]
	s_cbranch_execz .LBB0_446
	s_waitcnt lgkmcnt(0)
	v_add_f32_e32 v112, v112, v113
	v_fma_f32 v112, v112, s25, 0.5
	v_cvt_u32_f32_e32 v114, v112
	v_lshl_add_u64 v[112:113], v[170:171], 2, s[52:53]
	global_atomic_add v[112:113], v114, off

; #define PG8_STAGE(bufoff, gbase, voff) do { _Pragma("unroll") for (int _i = 0; _i < 2; ++_i) \
;         __builtin_amdgcn_global_load_lds((const unsigned*)((const char*)(gbase) + (voff)[_i]), (LAS unsigned*)(lds + (bufoff) + ldsw + _i * 8192), 16, 0, 0); } while (0)
; #define PG8_LDA(dst, b, h) do { _Pragma("unroll") for (int m = 0; m < 4; ++m) _Pragma("unroll") for (int k = 0; k < 2; ++k) dst[m][k] = *(const LAS bf16x8*)(lds + PG8_SA(b, h) + aoff + m * 2048 + k * 1024); } while (0)
; #define PG8_LDB(dst, b, h) do { _Pragma("unroll") for (int n = 0; n < 2; ++n) _Pragma("unroll") for (int k = 0; k < 2; ++k) dst[n][k] = *(const LAS bf16x8*)(lds + PG8_SB(b, h) + boff + n * 2048 + k * 1024); } while (0)
; #define PG8_MMA(ai, bj, At, Bt) do { __builtin_amdgcn_s_setprio(1); _Pragma("unroll") for (int m = 0; m < 4; ++m) _Pragma("unroll") for (int n = 0; n < 2; ++n) _Pragma("unroll") for (int k = 0; k < 2; ++k) \
;         acc[ai][bj][m][n] = __builtin_amdgcn_mfma_f32_16x16x32_bf16(Bt[n][k], At[m][k], acc[ai][bj][m][n], 0, 0, 0); __builtin_amdgcn_s_setprio(0); } while (0)
; template <class Epi>
; __device__ __forceinline__ void gemm_phase(LAS unsigned char* lds, const Gemm g, const StaticOrder& S, const Epi& E, int wv) {
;     ...
;         const bool has_next = S.next(ui + 1, nxt);
;         const char* nA = has_next ? (const char*)g.A + (size_t)nxt.pm * tstepA + ((g.adiag & 1) ? (size_t)(nxt.pn >> 1) * K * 2 : 0) + kbeg : cA;
;         const char* nB = has_next ? (const char*)g.Bt + (size_t)nxt.pn * tstepB + kbeg : cB;
;         for (int t = 0; t < nt; t += 2) {
;             const bool last = (t == nt - 2);
;             const char* a1 = cA + (ptrdiff_t)(t + 1) * kstep;
;             const char* a2 = last ? nA : cA + (ptrdiff_t)(t + 2) * kstep; const char* b2 = last ? nB : cB + (ptrdiff_t)(t + 2) * kstep;
;             const char* a3 = a2 + kstep; const char* b3 = b2 + kstep;
;             PG8_LDB(B0, 0, 0); PG8_SCHED; PG8_LDA(At, 0, 0); PG8_STAGE(PG8_SA(1, 1), a1 + hstepA, voffA);
;             PG8_WAIT_L(8); PG8_BAR; PG8_WAIT_L(0); PG8_MMA(0, 0, At, B0); PG8_BAR; PG8_SCHED;
;     ...
; #pragma unroll
;         for (int a = 0; a < 2; ++a)
; #pragma unroll
;             for (int b = 0; b < 2; ++b)
; #pragma unroll
;                 for (int m = 0; m < 4; ++m)
; #pragma unroll
;                     for (int n = 0; n < 2; ++n) acc[a][b][m][n] = (f32x4){0.f, 0.f, 0.f, 0.f};
.LBB0_529:
	s_ashr_i32 s59, s58, 31
	s_lshl_b64 s[38:39], s[58:59], 20
	v_cmp_lt_i64_e32 vcc, s[60:61], v[140:141]
	s_add_u32 s60, s5, s38
	s_addc_u32 s61, s6, s39
	s_and_b64 s[38:39], vcc, exec
	s_cselect_b32 s35, s61, s69
	s_cselect_b32 s38, s60, s68
	s_ashr_i32 s57, s56, 31
	s_lshl_b64 s[40:41], s[56:57], 20
	s_add_u32 s62, s7, s40
	s_addc_u32 s63, s8, s41
	s_and_b64 s[40:41], vcc, exec
	s_cselect_b32 s39, s63, s67
	s_cselect_b32 s40, s62, s66
	s_add_u32 s41, s66, 0x100
	s_addc_u32 s42, s67, 0
	s_add_u32 s66, s68, 0x80080
	v_mov_b32_e32 v0, 0
	s_addc_u32 s67, s69, 0
	s_mov_b32 s43, -2
	v_mov_b32_e32 v1, v0
	v_mov_b32_e32 v2, v0
	v_mov_b32_e32 v3, v0
	v_mov_b32_e32 v4, v0
	v_mov_b32_e32 v5, v0
	v_mov_b32_e32 v6, v0
	v_mov_b32_e32 v7, v0
	v_mov_b32_e32 v16, v0
	v_mov_b32_e32 v17, v0
	v_mov_b32_e32 v18, v0
	v_mov_b32_e32 v19, v0
	v_mov_b32_e32 v20, v0
	v_mov_b32_e32 v21, v0
	v_mov_b32_e32 v22, v0
	v_mov_b32_e32 v23, v0
	v_mov_b32_e32 v32, v0
	v_mov_b32_e32 v33, v0
	v_mov_b32_e32 v34, v0
	v_mov_b32_e32 v35, v0
	v_mov_b32_e32 v36, v0
	v_mov_b32_e32 v37, v0
	v_mov_b32_e32 v38, v0
	v_mov_b32_e32 v39, v0
	v_mov_b32_e32 v48, v0
	v_mov_b32_e32 v49, v0
	v_mov_b32_e32 v50, v0
	v_mov_b32_e32 v51, v0
	v_mov_b32_e32 v52, v0
	v_mov_b32_e32 v53, v0
	v_mov_b32_e32 v54, v0
	v_mov_b32_e32 v55, v0
	v_mov_b32_e32 v8, v0
	v_mov_b32_e32 v9, v0
	v_mov_b32_e32 v10, v0
	v_mov_b32_e32 v11, v0
	v_mov_b32_e32 v12, v0
	v_mov_b32_e32 v13, v0
	v_mov_b32_e32 v14, v0
	v_mov_b32_e32 v15, v0
	v_mov_b32_e32 v24, v0
	v_mov_b32_e32 v25, v0
	v_mov_b32_e32 v26, v0
	v_mov_b32_e32 v27, v0
	v_mov_b32_e32 v28, v0
	v_mov_b32_e32 v29, v0
	v_mov_b32_e32 v30, v0
	v_mov_b32_e32 v31, v0
	v_mov_b32_e32 v40, v0
	v_mov_b32_e32 v41, v0
	v_mov_b32_e32 v42, v0
	v_mov_b32_e32 v43, v0
	v_mov_b32_e32 v44, v0
	v_mov_b32_e32 v45, v0
	v_mov_b32_e32 v46, v0
	v_mov_b32_e32 v47, v0
	v_mov_b32_e32 v56, v0
	v_mov_b32_e32 v57, v0
	v_mov_b32_e32 v58, v0
	v_mov_b32_e32 v59, v0
	v_mov_b32_e32 v60, v0
	v_mov_b32_e32 v61, v0
	v_mov_b32_e32 v62, v0
	v_mov_b32_e32 v63, v0
	v_mov_b32_e32 v64, v0
	v_mov_b32_e32 v65, v0
	v_mov_b32_e32 v66, v0
	v_mov_b32_e32 v67, v0
	v_mov_b32_e32 v68, v0
	v_mov_b32_e32 v69, v0
	v_mov_b32_e32 v70, v0
	v_mov_b32_e32 v71, v0
	v_mov_b32_e32 v80, v0
	v_mov_b32_e32 v81, v0
	v_mov_b32_e32 v82, v0
	v_mov_b32_e32 v83, v0
	v_mov_b32_e32 v84, v0
	v_mov_b32_e32 v85, v0
	v_mov_b32_e32 v86, v0
	v_mov_b32_e32 v87, v0
	v_mov_b32_e32 v96, v0
	v_mov_b32_e32 v97, v0
	v_mov_b32_e32 v98, v0
	v_mov_b32_e32 v99, v0
	v_mov_b32_e32 v100, v0
	v_mov_b32_e32 v101, v0
	v_mov_b32_e32 v102, v0
	v_mov_b32_e32 v103, v0
	v_mov_b32_e32 v104, v0
	v_mov_b32_e32 v105, v0
	v_mov_b32_e32 v106, v0
	v_mov_b32_e32 v107, v0
	v_mov_b32_e32 v108, v0
	v_mov_b32_e32 v109, v0
	v_mov_b32_e32 v110, v0
	v_mov_b32_e32 v111, v0
	v_mov_b32_e32 v72, v0
	v_mov_b32_e32 v73, v0
	v_mov_b32_e32 v74, v0
	v_mov_b32_e32 v75, v0
	v_mov_b32_e32 v76, v0
	v_mov_b32_e32 v77, v0
	v_mov_b32_e32 v78, v0
	v_mov_b32_e32 v79, v0
	v_mov_b32_e32 v88, v0
	v_mov_b32_e32 v89, v0
	v_mov_b32_e32 v90, v0
	v_mov_b32_e32 v91, v0
	v_mov_b32_e32 v92, v0
	v_mov_b32_e32 v93, v0
	v_mov_b32_e32 v94, v0
	v_mov_b32_e32 v95, v0
	v_mov_b32_e32 v112, v0
	v_mov_b32_e32 v113, v0
	v_mov_b32_e32 v114, v0
	v_mov_b32_e32 v115, v0
	v_mov_b32_e32 v116, v0
	v_mov_b32_e32 v117, v0
	v_mov_b32_e32 v118, v0
	v_mov_b32_e32 v119, v0
	v_mov_b32_e32 v120, v0
	v_mov_b32_e32 v121, v0
	v_mov_b32_e32 v122, v0
	v_mov_b32_e32 v123, v0
	v_mov_b32_e32 v124, v0
	v_mov_b32_e32 v125, v0
	v_mov_b32_e32 v126, v0
	v_mov_b32_e32 v127, v0
	ds_read_b128 v[144:147], v153
	ds_read_b128 v[158:161], v153 offset:1024
	ds_read_b128 v[162:165], v153 offset:2048
	ds_read_b128 v[166:169], v153 offset:3072
.LBB0_530:
	s_add_u32 s44, s66, 0xfff80080
	s_addc_u32 s45, s67, -1
	s_cmp_eq_u32 s43, 28
	s_cselect_b32 s71, s35, s45
	s_cselect_b32 s70, s38, s44
	s_cselect_b32 s69, s39, s42
	s_cselect_b32 s68, s40, s41
	s_add_i32 m0, s10, 0xc000
	ds_read_b128 v[170:173], v154
	ds_read_b128 v[174:177], v154 offset:1024
	ds_read_b128 v[178:181], v154 offset:2048
	ds_read_b128 v[182:185], v154 offset:3072
	ds_read_b128 v[186:189], v154 offset:4096
	ds_read_b128 v[190:193], v154 offset:5120
	ds_read_b128 v[194:197], v154 offset:6144
	ds_read_b128 v[198:201], v154 offset:7168
	global_load_lds_dwordx4 v138, s[66:67]
	s_add_i32 m0, s10, 0xe000
	s_nop 0
	global_load_lds_dwordx4 v136, s[66:67]
	s_waitcnt lgkmcnt(8)
	s_barrier
	s_waitcnt lgkmcnt(0)
	s_setprio 1
	s_waitcnt lgkmcnt(0)
	v_mfma_f32_16x16x32_bf16 v[124:127], v[144:147], v[170:173], v[124:127]
	v_mfma_f32_16x16x32_bf16 v[120:123], v[162:165], v[170:173], v[120:123]
	v_mfma_f32_16x16x32_bf16 v[116:119], v[144:147], v[178:181], v[116:119]
	v_mfma_f32_16x16x32_bf16 v[112:115], v[162:165], v[178:181], v[112:115]
	v_mfma_f32_16x16x32_bf16 v[92:95], v[144:147], v[186:189], v[92:95]
	v_mfma_f32_16x16x32_bf16 v[88:91], v[162:165], v[186:189], v[88:91]
	v_mfma_f32_16x16x32_bf16 v[76:79], v[144:147], v[194:197], v[76:79]
	v_mfma_f32_16x16x32_bf16 v[72:75], v[162:165], v[194:197], v[72:75]
	v_mfma_f32_16x16x32_bf16 v[124:127], v[158:161], v[174:177], v[124:127]
	v_mfma_f32_16x16x32_bf16 v[120:123], v[166:169], v[174:177], v[120:123]
	v_mfma_f32_16x16x32_bf16 v[116:119], v[158:161], v[182:185], v[116:119]
	v_mfma_f32_16x16x32_bf16 v[112:115], v[166:169], v[182:185], v[112:115]
	v_mfma_f32_16x16x32_bf16 v[92:95], v[158:161], v[190:193], v[92:95]
	v_mfma_f32_16x16x32_bf16 v[88:91], v[166:169], v[190:193], v[88:91]
	v_mfma_f32_16x16x32_bf16 v[76:79], v[158:161], v[198:201], v[76:79]
	v_mfma_f32_16x16x32_bf16 v[72:75], v[166:169], v[198:201], v[72:75]
	s_setprio 0
	s_barrier
; #define PG8_STAGE(bufoff, gbase, voff) do { _Pragma("unroll") for (int _i = 0; _i < 2; ++_i) \
;         __builtin_amdgcn_global_load_lds((const unsigned*)((const char*)(gbase) + (voff)[_i]), (LAS unsigned*)(lds + (bufoff) + ldsw + _i * 8192), 16, 0, 0); } while (0)
; #define PG8_LDA(dst, b, h) do { _Pragma("unroll") for (int m = 0; m < 4; ++m) _Pragma("unroll") for (int k = 0; k < 2; ++k) dst[m][k] = *(const LAS bf16x8*)(lds + PG8_SA(b, h) + aoff + m * 2048 + k * 1024); } while (0)
; #define PG8_LDB(dst, b, h) do { _Pragma("unroll") for (int n = 0; n < 2; ++n) _Pragma("unroll") for (int k = 0; k < 2; ++k) dst[n][k] = *(const LAS bf16x8*)(lds + PG8_SB(b, h) + boff + n * 2048 + k * 1024); } while (0)
; #define PG8_MMA(ai, bj, At, Bt) do { __builtin_amdgcn_s_setprio(1); _Pragma("unroll") for (int m = 0; m < 4; ++m) _Pragma("unroll") for (int n = 0; n < 2; ++n) _Pragma("unroll") for (int k = 0; k < 2; ++k) \
;         acc[ai][bj][m][n] = __builtin_amdgcn_mfma_f32_16x16x32_bf16(Bt[n][k], At[m][k], acc[ai][bj][m][n], 0, 0, 0); __builtin_amdgcn_s_setprio(0); } while (0)
; #define PG8_WAIT_V(n) asm volatile("s_waitcnt vmcnt(" #n ")" ::: "memory")
; #define PG8_WAIT_L(n) asm volatile("s_waitcnt lgkmcnt(" #n ")" ::: "memory")
; #define PG8_BAR __builtin_amdgcn_s_barrier()
; #define PG8_SCHED __builtin_amdgcn_sched_barrier(0)
; template <class Epi>
; __device__ __forceinline__ void gemm_phase(LAS unsigned char* lds, const Gemm g, const StaticOrder& S, const Epi& E, int wv) {
;     ...
;             PG8_LDB(B1, 0, 1); PG8_STAGE(PG8_SB(0, 0), b2, voffB);
;             PG8_BAR; PG8_WAIT_L(0); PG8_MMA(0, 1, At, B1); PG8_BAR;
;             PG8_LDA(At, 0, 1); PG8_STAGE(PG8_SA(0, 0), a2, voffA);
;             PG8_BAR; PG8_WAIT_L(0); PG8_MMA(1, 0, At, B0); PG8_BAR; PG8_SCHED;
;             PG8_STAGE(PG8_SB(0, 1), b2 + hstepB, voffB);
;             PG8_WAIT_V(6); PG8_BAR; PG8_MMA(1, 1, At, B1); PG8_BAR;
;             PG8_LDB(B0, 1, 0); PG8_SCHED; PG8_LDA(At, 1, 0); PG8_STAGE(PG8_SA(0, 1), a2 + hstepA, voffA);
;             PG8_WAIT_L(8); PG8_BAR; PG8_WAIT_L(0); PG8_MMA(0, 0, At, B0); PG8_BAR; PG8_SCHED;
	s_add_i32 s44, s23, s9
	s_add_u32 s98, s68, s52
	s_addc_u32 s99, s69, s53
	s_mov_b32 m0, s44
	ds_read_b128 v[202:205], v155
	ds_read_b128 v[206:209], v155 offset:1024
	ds_read_b128 v[210:213], v155 offset:2048
	ds_read_b128 v[214:217], v155 offset:3072
	global_load_lds_dwordx4 v130, s[68:69]
	s_add_i32 m0, s44, 0x2000
	s_nop 0
	global_load_lds_dwordx4 v134, s[68:69]
	s_barrier
	s_waitcnt lgkmcnt(0)
	s_setprio 1
	s_waitcnt lgkmcnt(0)
	v_mfma_f32_16x16x32_bf16 v[108:111], v[202:205], v[170:173], v[108:111]
	v_mfma_f32_16x16x32_bf16 v[104:107], v[210:213], v[170:173], v[104:107]
	v_mfma_f32_16x16x32_bf16 v[100:103], v[202:205], v[178:181], v[100:103]
	v_mfma_f32_16x16x32_bf16 v[96:99], v[210:213], v[178:181], v[96:99]
	v_mfma_f32_16x16x32_bf16 v[84:87], v[202:205], v[186:189], v[84:87]
	v_mfma_f32_16x16x32_bf16 v[80:83], v[210:213], v[186:189], v[80:83]
	v_mfma_f32_16x16x32_bf16 v[68:71], v[202:205], v[194:197], v[68:71]
	v_mfma_f32_16x16x32_bf16 v[64:67], v[210:213], v[194:197], v[64:67]
	v_mfma_f32_16x16x32_bf16 v[108:111], v[206:209], v[174:177], v[108:111]
	v_mfma_f32_16x16x32_bf16 v[104:107], v[214:217], v[174:177], v[104:107]
	v_mfma_f32_16x16x32_bf16 v[100:103], v[206:209], v[182:185], v[100:103]
	v_mfma_f32_16x16x32_bf16 v[96:99], v[214:217], v[182:185], v[96:99]
	v_mfma_f32_16x16x32_bf16 v[84:87], v[206:209], v[190:193], v[84:87]
	v_mfma_f32_16x16x32_bf16 v[80:83], v[214:217], v[190:193], v[80:83]
	v_mfma_f32_16x16x32_bf16 v[68:71], v[206:209], v[198:201], v[68:71]
	v_mfma_f32_16x16x32_bf16 v[64:67], v[214:217], v[198:201], v[64:67]
	s_setprio 0
	s_mov_b32 m0, s10
	s_add_u32 s100, s70, s52
	s_addc_u32 s101, s71, s53
	s_barrier
	ds_read_b128 v[170:173], v154 offset:16384
	ds_read_b128 v[174:177], v154 offset:17408
	ds_read_b128 v[178:181], v154 offset:18432
	ds_read_b128 v[182:185], v154 offset:19456
	ds_read_b128 v[186:189], v154 offset:20480
	ds_read_b128 v[190:193], v154 offset:21504
	ds_read_b128 v[194:197], v154 offset:22528
	ds_read_b128 v[198:201], v154 offset:23552
	global_load_lds_dwordx4 v128, s[70:71]
	s_mov_b32 m0, s11
	s_nop 0
	global_load_lds_dwordx4 v132, s[70:71]
	s_waitcnt vmcnt(10)
	s_barrier
	s_waitcnt lgkmcnt(0)
	s_setprio 1
	s_waitcnt lgkmcnt(0)
	v_mfma_f32_16x16x32_bf16 v[60:63], v[144:147], v[170:173], v[60:63]
	v_mfma_f32_16x16x32_bf16 v[56:59], v[162:165], v[170:173], v[56:59]
	v_mfma_f32_16x16x32_bf16 v[44:47], v[144:147], v[178:181], v[44:47]
	v_mfma_f32_16x16x32_bf16 v[40:43], v[162:165], v[178:181], v[40:43]
	v_mfma_f32_16x16x32_bf16 v[28:31], v[144:147], v[186:189], v[28:31]
	v_mfma_f32_16x16x32_bf16 v[24:27], v[162:165], v[186:189], v[24:27]
	v_mfma_f32_16x16x32_bf16 v[12:15], v[144:147], v[194:197], v[12:15]
	v_mfma_f32_16x16x32_bf16 v[8:11], v[162:165], v[194:197], v[8:11]
	v_mfma_f32_16x16x32_bf16 v[60:63], v[158:161], v[174:177], v[60:63]
	v_mfma_f32_16x16x32_bf16 v[56:59], v[166:169], v[174:177], v[56:59]
	v_mfma_f32_16x16x32_bf16 v[44:47], v[158:161], v[182:185], v[44:47]
	v_mfma_f32_16x16x32_bf16 v[40:43], v[166:169], v[182:185], v[40:43]
	v_mfma_f32_16x16x32_bf16 v[28:31], v[158:161], v[190:193], v[28:31]
	v_mfma_f32_16x16x32_bf16 v[24:27], v[166:169], v[190:193], v[24:27]
	v_mfma_f32_16x16x32_bf16 v[12:15], v[158:161], v[198:201], v[12:15]
	v_mfma_f32_16x16x32_bf16 v[8:11], v[166:169], v[198:201], v[8:11]
	s_setprio 0
	s_barrier
	s_add_u32 s44, s68, 0x80000
	s_addc_u32 s45, s69, 0
	s_add_i32 s46, s24, s9
	s_mov_b32 m0, s46
	s_nop 0
	global_load_lds_dwordx4 v130, s[44:45]
	s_add_i32 m0, s46, 0x2000
	s_nop 0
	global_load_lds_dwordx4 v134, s[44:45]
	s_add_i32 s46, 0, 0x18000
	v_add_u32_e32 v157, s46, v151
	ds_read_b128 v[144:147], v157
	ds_read_b128 v[158:161], v157 offset:1024
	ds_read_b128 v[162:165], v157 offset:2048
	ds_read_b128 v[166:169], v157 offset:3072
	s_waitcnt vmcnt(6)
	s_barrier
	s_setprio 1
	v_mfma_f32_16x16x32_bf16 v[52:55], v[202:205], v[170:173], v[52:55]
	v_mfma_f32_16x16x32_bf16 v[48:51], v[210:213], v[170:173], v[48:51]
	v_mfma_f32_16x16x32_bf16 v[36:39], v[202:205], v[178:181], v[36:39]
	v_mfma_f32_16x16x32_bf16 v[32:35], v[210:213], v[178:181], v[32:35]
	v_mfma_f32_16x16x32_bf16 v[20:23], v[202:205], v[186:189], v[20:23]
	v_mfma_f32_16x16x32_bf16 v[16:19], v[210:213], v[186:189], v[16:19]
	v_mfma_f32_16x16x32_bf16 v[4:7], v[202:205], v[194:197], v[4:7]
	v_mfma_f32_16x16x32_bf16 v[0:3], v[210:213], v[194:197], v[0:3]
	v_mfma_f32_16x16x32_bf16 v[52:55], v[206:209], v[174:177], v[52:55]
	v_mfma_f32_16x16x32_bf16 v[48:51], v[214:217], v[174:177], v[48:51]
	v_mfma_f32_16x16x32_bf16 v[36:39], v[206:209], v[182:185], v[36:39]
	v_mfma_f32_16x16x32_bf16 v[32:35], v[214:217], v[182:185], v[32:35]
	v_mfma_f32_16x16x32_bf16 v[20:23], v[206:209], v[190:193], v[20:23]
	v_mfma_f32_16x16x32_bf16 v[16:19], v[214:217], v[190:193], v[16:19]
	v_mfma_f32_16x16x32_bf16 v[4:7], v[206:209], v[198:201], v[4:7]
	v_mfma_f32_16x16x32_bf16 v[0:3], v[214:217], v[198:201], v[0:3]
	s_setprio 0
	s_waitcnt lgkmcnt(0)
	s_barrier
	s_add_u32 s44, s70, 0x80000
	s_addc_u32 s45, s71, 0
	s_mov_b32 m0, s12
	ds_read_b128 v[170:173], v154 offset:32768
	ds_read_b128 v[174:177], v154 offset:33792
	ds_read_b128 v[178:181], v154 offset:34816
	ds_read_b128 v[182:185], v154 offset:35840
	ds_read_b128 v[186:189], v154 offset:36864
	ds_read_b128 v[190:193], v154 offset:37888
	ds_read_b128 v[194:197], v154 offset:38912
	ds_read_b128 v[198:201], v154 offset:39936
	global_load_lds_dwordx4 v128, s[44:45]
	s_mov_b32 m0, s13
	s_nop 0
	global_load_lds_dwordx4 v132, s[44:45]
	s_waitcnt lgkmcnt(8)
	s_barrier
; #define PG8_STAGE(bufoff, gbase, voff) do { _Pragma("unroll") for (int _i = 0; _i < 2; ++_i) \
;         __builtin_amdgcn_global_load_lds((const unsigned*)((const char*)(gbase) + (voff)[_i]), (LAS unsigned*)(lds + (bufoff) + ldsw + _i * 8192), 16, 0, 0); } while (0)
; #define PG8_LDA(dst, b, h) do { _Pragma("unroll") for (int m = 0; m < 4; ++m) _Pragma("unroll") for (int k = 0; k < 2; ++k) dst[m][k] = *(const LAS bf16x8*)(lds + PG8_SA(b, h) + aoff + m * 2048 + k * 1024); } while (0)
; #define PG8_LDB(dst, b, h) do { _Pragma("unroll") for (int n = 0; n < 2; ++n) _Pragma("unroll") for (int k = 0; k < 2; ++k) dst[n][k] = *(const LAS bf16x8*)(lds + PG8_SB(b, h) + boff + n * 2048 + k * 1024); } while (0)
; #define PG8_MMA(ai, bj, At, Bt) do { __builtin_amdgcn_s_setprio(1); _Pragma("unroll") for (int m = 0; m < 4; ++m) _Pragma("unroll") for (int n = 0; n < 2; ++n) _Pragma("unroll") for (int k = 0; k < 2; ++k) \
;         acc[ai][bj][m][n] = __builtin_amdgcn_mfma_f32_16x16x32_bf16(Bt[n][k], At[m][k], acc[ai][bj][m][n], 0, 0, 0); __builtin_amdgcn_s_setprio(0); } while (0)
; #define PG8_WAIT_V(n) asm volatile("s_waitcnt vmcnt(" #n ")" ::: "memory")
; #define PG8_WAIT_L(n) asm volatile("s_waitcnt lgkmcnt(" #n ")" ::: "memory")
; #define PG8_BAR __builtin_amdgcn_s_barrier()
; #define PG8_SCHED __builtin_amdgcn_sched_barrier(0)
; template <class Epi>
; __device__ __forceinline__ void gemm_phase(LAS unsigned char* lds, const Gemm g, const StaticOrder& S, const Epi& E, int wv) {
;     ...
;             PG8_WAIT_L(8); PG8_BAR; PG8_WAIT_L(0); PG8_MMA(0, 0, At, B0); PG8_BAR; PG8_SCHED;
;             PG8_LDB(B1, 1, 1); PG8_STAGE(PG8_SB(1, 0), b3, voffB);
;             PG8_BAR; PG8_WAIT_L(0); PG8_MMA(0, 1, At, B1); PG8_BAR;
;             PG8_LDA(At, 1, 1); PG8_STAGE(PG8_SA(1, 0), a3, voffA);
;             PG8_BAR; PG8_WAIT_L(0); PG8_MMA(1, 0, At, B0); PG8_BAR; PG8_SCHED;
;             PG8_STAGE(PG8_SB(1, 1), b3 + hstepB, voffB);
;             PG8_WAIT_V(6); PG8_BAR; PG8_MMA(1, 1, At, B1); PG8_BAR;
	s_waitcnt lgkmcnt(0)
	s_setprio 1
	s_waitcnt lgkmcnt(0)
	v_mfma_f32_16x16x32_bf16 v[124:127], v[144:147], v[170:173], v[124:127]
	v_mfma_f32_16x16x32_bf16 v[120:123], v[162:165], v[170:173], v[120:123]
	v_mfma_f32_16x16x32_bf16 v[116:119], v[144:147], v[178:181], v[116:119]
	v_mfma_f32_16x16x32_bf16 v[112:115], v[162:165], v[178:181], v[112:115]
	v_mfma_f32_16x16x32_bf16 v[92:95], v[144:147], v[186:189], v[92:95]
	v_mfma_f32_16x16x32_bf16 v[88:91], v[162:165], v[186:189], v[88:91]
	v_mfma_f32_16x16x32_bf16 v[76:79], v[144:147], v[194:197], v[76:79]
	v_mfma_f32_16x16x32_bf16 v[72:75], v[162:165], v[194:197], v[72:75]
	v_mfma_f32_16x16x32_bf16 v[124:127], v[158:161], v[174:177], v[124:127]
	v_mfma_f32_16x16x32_bf16 v[120:123], v[166:169], v[174:177], v[120:123]
	v_mfma_f32_16x16x32_bf16 v[116:119], v[158:161], v[182:185], v[116:119]
	v_mfma_f32_16x16x32_bf16 v[112:115], v[166:169], v[182:185], v[112:115]
	v_mfma_f32_16x16x32_bf16 v[92:95], v[158:161], v[190:193], v[92:95]
	v_mfma_f32_16x16x32_bf16 v[88:91], v[166:169], v[190:193], v[88:91]
	v_mfma_f32_16x16x32_bf16 v[76:79], v[158:161], v[198:201], v[76:79]
	v_mfma_f32_16x16x32_bf16 v[72:75], v[166:169], v[198:201], v[72:75]
	s_setprio 0
	s_barrier
	s_add_i32 s47, 0, 0x1c000
	s_add_i32 s44, s46, s9
	v_add_u32_e32 v157, s47, v151
	s_mov_b32 m0, s44
	ds_read_b128 v[202:205], v157
	ds_read_b128 v[206:209], v157 offset:1024
	ds_read_b128 v[210:213], v157 offset:2048
	ds_read_b128 v[214:217], v157 offset:3072
	global_load_lds_dwordx4 v130, s[98:99]
	s_add_i32 m0, s44, 0x2000
	s_nop 0
	global_load_lds_dwordx4 v134, s[98:99]
	s_barrier
	s_waitcnt lgkmcnt(0)
	s_setprio 1
	s_waitcnt lgkmcnt(0)
	v_mfma_f32_16x16x32_bf16 v[108:111], v[202:205], v[170:173], v[108:111]
	v_mfma_f32_16x16x32_bf16 v[104:107], v[210:213], v[170:173], v[104:107]
	v_mfma_f32_16x16x32_bf16 v[100:103], v[202:205], v[178:181], v[100:103]
	v_mfma_f32_16x16x32_bf16 v[96:99], v[210:213], v[178:181], v[96:99]
	v_mfma_f32_16x16x32_bf16 v[84:87], v[202:205], v[186:189], v[84:87]
	v_mfma_f32_16x16x32_bf16 v[80:83], v[210:213], v[186:189], v[80:83]
	v_mfma_f32_16x16x32_bf16 v[68:71], v[202:205], v[194:197], v[68:71]
	v_mfma_f32_16x16x32_bf16 v[64:67], v[210:213], v[194:197], v[64:67]
	v_mfma_f32_16x16x32_bf16 v[108:111], v[206:209], v[174:177], v[108:111]
	v_mfma_f32_16x16x32_bf16 v[104:107], v[214:217], v[174:177], v[104:107]
	v_mfma_f32_16x16x32_bf16 v[100:103], v[206:209], v[182:185], v[100:103]
	v_mfma_f32_16x16x32_bf16 v[96:99], v[214:217], v[182:185], v[96:99]
	v_mfma_f32_16x16x32_bf16 v[84:87], v[206:209], v[190:193], v[84:87]
	v_mfma_f32_16x16x32_bf16 v[80:83], v[214:217], v[190:193], v[80:83]
	v_mfma_f32_16x16x32_bf16 v[68:71], v[206:209], v[198:201], v[68:71]
	v_mfma_f32_16x16x32_bf16 v[64:67], v[214:217], v[198:201], v[64:67]
	s_setprio 0
	s_mov_b32 m0, s15
	s_barrier
	ds_read_b128 v[170:173], v154 offset:49152
	ds_read_b128 v[174:177], v154 offset:50176
	ds_read_b128 v[178:181], v154 offset:51200
	ds_read_b128 v[182:185], v154 offset:52224
	ds_read_b128 v[186:189], v154 offset:53248
	ds_read_b128 v[190:193], v154 offset:54272
	ds_read_b128 v[194:197], v154 offset:55296
	ds_read_b128 v[198:201], v154 offset:56320
	global_load_lds_dwordx4 v128, s[100:101]
	s_mov_b32 m0, s22
	s_nop 0
	global_load_lds_dwordx4 v132, s[100:101]
	s_waitcnt vmcnt(10)
	s_barrier
	s_waitcnt lgkmcnt(0)
	s_setprio 1
	s_waitcnt lgkmcnt(0)
	v_mfma_f32_16x16x32_bf16 v[60:63], v[144:147], v[170:173], v[60:63]
	v_mfma_f32_16x16x32_bf16 v[56:59], v[162:165], v[170:173], v[56:59]
	v_mfma_f32_16x16x32_bf16 v[44:47], v[144:147], v[178:181], v[44:47]
	v_mfma_f32_16x16x32_bf16 v[40:43], v[162:165], v[178:181], v[40:43]
	v_mfma_f32_16x16x32_bf16 v[28:31], v[144:147], v[186:189], v[28:31]
	v_mfma_f32_16x16x32_bf16 v[24:27], v[162:165], v[186:189], v[24:27]
	v_mfma_f32_16x16x32_bf16 v[12:15], v[144:147], v[194:197], v[12:15]
	v_mfma_f32_16x16x32_bf16 v[8:11], v[162:165], v[194:197], v[8:11]
	v_mfma_f32_16x16x32_bf16 v[60:63], v[158:161], v[174:177], v[60:63]
	v_mfma_f32_16x16x32_bf16 v[56:59], v[166:169], v[174:177], v[56:59]
	v_mfma_f32_16x16x32_bf16 v[44:47], v[158:161], v[182:185], v[44:47]
	v_mfma_f32_16x16x32_bf16 v[40:43], v[166:169], v[182:185], v[40:43]
	v_mfma_f32_16x16x32_bf16 v[28:31], v[158:161], v[190:193], v[28:31]
	v_mfma_f32_16x16x32_bf16 v[24:27], v[166:169], v[190:193], v[24:27]
	v_mfma_f32_16x16x32_bf16 v[12:15], v[158:161], v[198:201], v[12:15]
	v_mfma_f32_16x16x32_bf16 v[8:11], v[166:169], v[198:201], v[8:11]
	s_setprio 0
	s_barrier
	s_add_u32 s44, s68, 0x80080
	s_addc_u32 s45, s69, 0
	s_add_i32 s46, s47, s9
	s_mov_b32 m0, s46
	s_nop 0
	global_load_lds_dwordx4 v130, s[44:45]
	s_add_i32 m0, s46, 0x2000
	s_nop 0
	global_load_lds_dwordx4 v134, s[44:45]
	ds_read_b128 v[144:147], v153
	ds_read_b128 v[158:161], v153 offset:1024
	ds_read_b128 v[162:165], v153 offset:2048
	ds_read_b128 v[166:169], v153 offset:3072
	s_waitcnt vmcnt(6)
	s_barrier
	s_setprio 1
	v_mfma_f32_16x16x32_bf16 v[52:55], v[202:205], v[170:173], v[52:55]
	v_mfma_f32_16x16x32_bf16 v[48:51], v[210:213], v[170:173], v[48:51]
	v_mfma_f32_16x16x32_bf16 v[36:39], v[202:205], v[178:181], v[36:39]
	v_mfma_f32_16x16x32_bf16 v[32:35], v[210:213], v[178:181], v[32:35]
	v_mfma_f32_16x16x32_bf16 v[20:23], v[202:205], v[186:189], v[20:23]
	v_mfma_f32_16x16x32_bf16 v[16:19], v[210:213], v[186:189], v[16:19]
	v_mfma_f32_16x16x32_bf16 v[4:7], v[202:205], v[194:197], v[4:7]
	v_mfma_f32_16x16x32_bf16 v[0:3], v[210:213], v[194:197], v[0:3]
	v_mfma_f32_16x16x32_bf16 v[52:55], v[206:209], v[174:177], v[52:55]
	v_mfma_f32_16x16x32_bf16 v[48:51], v[214:217], v[174:177], v[48:51]
	v_mfma_f32_16x16x32_bf16 v[36:39], v[206:209], v[182:185], v[36:39]
	v_mfma_f32_16x16x32_bf16 v[32:35], v[214:217], v[182:185], v[32:35]
	v_mfma_f32_16x16x32_bf16 v[20:23], v[206:209], v[190:193], v[20:23]
	v_mfma_f32_16x16x32_bf16 v[16:19], v[214:217], v[190:193], v[16:19]
	v_mfma_f32_16x16x32_bf16 v[4:7], v[206:209], v[198:201], v[4:7]
	v_mfma_f32_16x16x32_bf16 v[0:3], v[214:217], v[198:201], v[0:3]
	s_setprio 0
	s_waitcnt lgkmcnt(0)
	s_add_i32 s43, s43, 2
	s_add_u32 s41, s41, 0x100
	s_addc_u32 s42, s42, 0
	s_add_u32 s66, s66, 0x100
	s_addc_u32 s67, s67, 0
	s_cmp_gt_u32 s43, 29
	s_barrier
;     __device__ __forceinline__ void operator()(const f32x4 (&acc)[2][2][4][2], const Unit& u, int wr, int wc, int fr, int fq) const {
;         const int row0 = u.pm * BM + wr * 64 + fr; int colt = u.pn * BM; bf16_t* base = O; int tsel = 0;
;         if (split_cols) { tsel = colt / split_cols; base += (size_t)tsel * split_stride; colt -= tsel * split_cols; }
;         const int col0 = colt + wc * 32 + 8 * fq;
;         f32x4 cs[2][2];
;         if (SM == 2) {
; #pragma unroll
;             for (int bj = 0; bj < 2; ++bj)
; #pragma unroll
;                 for (int n = 0; n < 2; ++n) { const f32x4 s = *(const f32x4*)(ss + u.pn * BM + wc * 32 + 8 * fq + bj * HALF + 4 * n);
; #pragma unroll
;                     for (int j = 0; j < 4; ++j) cs[bj][n][j] = __builtin_amdgcn_rsqf(ss_fix(s[j]) * (1.0f / DM) + EPS); }
;         }
;         float rsv[8];
; #pragma unroll
;         for (int it = 0; it < 8; ++it) rsv[it] = (SM == 1) ? ss[row0 + (it >> 2) * HALF + (it & 3) * 16] : 1.0f;
; #pragma unroll
;         for (int ai = 0; ai < 2; ++ai)
; #pragma unroll
;             for (int m = 0; m < 4; ++m) { const int row = row0 + ai * HALF + m * 16; float rs = 1.0f; if (SM == 1) rs = __builtin_amdgcn_rsqf(ss_fix(rsv[ai * 4 + m]) * (1.0f / DM) + EPS);
;                 bf16_t* rowp = base + (size_t)row * ldc + col0;
; #pragma unroll
;                 for (int bj = 0; bj < 2; ++bj) { f32x4 v0 = acc[ai][bj][m][0], v1 = acc[ai][bj][m][1];
;                     if (SM == 1) { v0 *= rs; v1 *= rs; }
;                     if (SM == 2) { v0 *= cs[bj][0]; v1 *= cs[bj][1]; }
;                     if (ACT == 1) {
; #pragma unroll
;                         for (int j = 0; j < 4; ++j) { const float a = fmaxf(v0[j], 0.f), b = fmaxf(v1[j], 0.f); v0[j] = a * a; v1[j] = b * b; } }
;                     if (ACT == 2) { if (tsel == 0) {
; #pragma unroll
;                         for (int j = 0; j < 4; ++j) { const float a = v0[j], b = v1[j];
;                             v0[j] = a * fast_sigmoid(1.5957691216057308f * (a + 0.044715f * a * a * a)); v1[j] = b * fast_sigmoid(1.5957691216057308f * (b + 0.044715f * b * b * b)); } } }
;                     u32x4 w; w.x = pk_bf16(v0[0], v0[1]); w.y = pk_bf16(v0[2], v0[3]); w.z = pk_bf16(v1[0], v1[1]); w.w = pk_bf16(v1[2], v1[3]);
;                     *(u32x4*)(rowp + bj * HALF) = w; } }
	s_cbranch_scc0 .LBB0_530
	v_lshl_add_u32 v146, s64, 8, v150
	v_ashrrev_i32_e32 v147, 31, v146
	v_lshl_add_u64 v[144:145], v[146:147], 2, s[50:51]
	global_load_dword v157, v[144:145], off
	global_load_dword v162, v[144:145], off offset:64
	v_lshlrev_b64 v[160:161], 14, v[146:147]
	global_load_dword v166, v[144:145], off offset:128
	global_load_dword v167, v[144:145], off offset:192
	global_load_dword v168, v[144:145], off offset:512
	global_load_dword v169, v[144:145], off offset:576
	global_load_dword v170, v[144:145], off offset:640
	global_load_dword v147, v[144:145], off offset:704
	v_lshl_or_b32 v148, s34, 8, v152
	v_ashrrev_i32_e32 v149, 31, v148
	v_lshl_add_u64 v[148:149], v[148:149], 1, s[18:19]
	v_lshl_add_u64 v[144:145], v[148:149], 0, v[160:161]
	v_or_b32_e32 v158, 16, v146
	v_ashrrev_i32_e32 v159, 31, v158
	v_lshlrev_b64 v[158:159], 14, v[158:159]
	v_lshl_add_u64 v[158:159], v[148:149], 0, v[158:159]
	s_mov_b64 s[34:35], 0x200000
	s_mov_b32 s64, s58
	s_mov_b64 s[66:67], s[62:63]
	s_mov_b64 s[68:69], s[60:61]
	s_waitcnt vmcnt(0)
	v_cvt_f32_u32_e32 v157, v157
	v_cvt_f32_u32_e32 v161, v162
	v_mul_f32_e32 v157, 0x3b800000, v157
	v_fmamk_f32 v157, v157, 0x3a000000, v156
	v_rsq_f32_e32 v160, v157
	v_mul_f32_e32 v157, 0x3b800000, v161
	v_fmamk_f32 v157, v157, 0x3a000000, v156
	v_rsq_f32_e32 v162, v157
	v_pk_mul_f32 v[126:127], v[126:127], v[160:161] op_sel_hi:[1,0]
	v_pk_mul_f32 v[124:125], v[124:125], v[160:161] op_sel_hi:[1,0]
	v_pk_mul_f32 v[122:123], v[122:123], v[160:161] op_sel_hi:[1,0]
	v_pk_mul_f32 v[120:121], v[120:121], v[160:161] op_sel_hi:[1,0]
	v_pk_mul_f32 v[110:111], v[110:111], v[160:161] op_sel_hi:[1,0]
	v_pk_mul_f32 v[108:109], v[108:109], v[160:161] op_sel_hi:[1,0]
	v_pk_mul_f32 v[106:107], v[106:107], v[160:161] op_sel_hi:[1,0]
	v_pk_mul_f32 v[104:105], v[104:105], v[160:161] op_sel_hi:[1,0]
	v_pk_mul_f32 v[118:119], v[118:119], v[162:163] op_sel_hi:[1,0]
	v_pk_mul_f32 v[116:117], v[116:117], v[162:163] op_sel_hi:[1,0]
	v_pk_mul_f32 v[114:115], v[114:115], v[162:163] op_sel_hi:[1,0]
	v_pk_mul_f32 v[112:113], v[112:113], v[162:163] op_sel_hi:[1,0]
	v_pk_mul_f32 v[160:161], v[102:103], v[162:163] op_sel_hi:[1,0]
	v_pk_mul_f32 v[100:101], v[100:101], v[162:163] op_sel_hi:[1,0]
	v_pk_mul_f32 v[164:165], v[98:99], v[162:163] op_sel_hi:[1,0]
	v_pk_mul_f32 v[162:163], v[96:97], v[162:163] op_sel_hi:[1,0]
	v_max_f32_e32 v96, 0, v124
	v_max_f32_e32 v98, 0, v120
	v_max_f32_e32 v97, 0, v125
	v_max_f32_e32 v99, 0, v121
	v_max_f32_e32 v102, 0, v126
	v_max_f32_e32 v120, 0, v122
	v_max_f32_e32 v103, 0, v127
	v_max_f32_e32 v121, 0, v123
	v_max_f32_e32 v108, 0, v108
	v_max_f32_e32 v109, 0, v109
	v_max_f32_e32 v110, 0, v110
	v_max_f32_e32 v111, 0, v111
	v_max_f32_e32 v104, 0, v104
	v_max_f32_e32 v105, 0, v105
	v_max_f32_e32 v106, 0, v106
	v_max_f32_e32 v107, 0, v107
	v_max_f32_e32 v116, 0, v116
	v_max_f32_e32 v112, 0, v112
	v_max_f32_e32 v117, 0, v117
	v_max_f32_e32 v113, 0, v113
	v_max_f32_e32 v118, 0, v118
	v_max_f32_e32 v114, 0, v114
	v_max_f32_e32 v119, 0, v119
	v_max_f32_e32 v115, 0, v115
	v_max_f32_e32 v122, 0, v100
	v_max_f32_e32 v123, 0, v101
	v_pk_mul_f32 v[96:97], v[96:97], v[96:97]
	v_pk_mul_f32 v[98:99], v[98:99], v[98:99]
	v_pk_mul_f32 v[100:101], v[102:103], v[102:103]
	v_pk_mul_f32 v[102:103], v[120:121], v[120:121]
	v_pk_mul_f32 v[108:109], v[108:109], v[108:109]
	v_pk_mul_f32 v[110:111], v[110:111], v[110:111]
	v_pk_mul_f32 v[104:105], v[104:105], v[104:105]
	v_pk_mul_f32 v[106:107], v[106:107], v[106:107]
	v_pk_mul_f32 v[116:117], v[116:117], v[116:117]
	v_pk_mul_f32 v[112:113], v[112:113], v[112:113]
	v_pk_mul_f32 v[118:119], v[118:119], v[118:119]
	v_pk_mul_f32 v[114:115], v[114:115], v[114:115]
	v_cvt_pk_bf16_f32 v96, v96, v97
	v_cvt_pk_bf16_f32 v97, v100, v101
	v_cvt_pk_bf16_f32 v98, v98, v99
	v_cvt_pk_bf16_f32 v99, v102, v103
	v_cvt_pk_bf16_f32 v100, v108, v109
	v_cvt_pk_bf16_f32 v101, v110, v111
	v_cvt_pk_bf16_f32 v102, v104, v105
	v_cvt_pk_bf16_f32 v103, v106, v107
	v_cvt_pk_bf16_f32 v104, v116, v117
	v_cvt_pk_bf16_f32 v105, v118, v119
	v_cvt_pk_bf16_f32 v106, v112, v113
	v_cvt_pk_bf16_f32 v107, v114, v115
	global_store_dwordx4 v[144:145], v[96:99], off
	global_store_dwordx4 v[144:145], v[100:103], off offset:256
	global_store_dwordx4 v[158:159], v[104:107], off
	v_pk_mul_f32 v[96:97], v[122:123], v[122:123]
	v_max_f32_e32 v100, 0, v160
	v_max_f32_e32 v101, 0, v161
	v_pk_mul_f32 v[100:101], v[100:101], v[100:101]
	v_cvt_pk_bf16_f32 v96, v96, v97
	v_cvt_pk_bf16_f32 v97, v100, v101
	v_cvt_f32_u32_e32 v100, v166
	v_max_f32_e32 v124, 0, v162
	v_max_f32_e32 v125, 0, v163
	v_max_f32_e32 v102, 0, v164
	v_max_f32_e32 v103, 0, v165
	v_pk_mul_f32 v[98:99], v[124:125], v[124:125]
	v_pk_mul_f32 v[102:103], v[102:103], v[102:103]
	v_cvt_pk_bf16_f32 v98, v98, v99
	v_cvt_pk_bf16_f32 v99, v102, v103
	global_store_dwordx4 v[158:159], v[96:99], off offset:256
	s_nop 1
	v_mul_f32_e32 v97, 0x3b800000, v100
	v_fmamk_f32 v97, v97, 0x3a000000, v156
	v_rsq_f32_e32 v98, v97
	v_or_b32_e32 v96, 32, v146
	v_ashrrev_i32_e32 v97, 31, v96
	v_lshlrev_b64 v[96:97], 14, v[96:97]
	v_pk_mul_f32 v[88:89], v[88:89], v[98:99] op_sel_hi:[1,0]
	v_pk_mul_f32 v[94:95], v[94:95], v[98:99] op_sel_hi:[1,0]
	v_pk_mul_f32 v[92:93], v[92:93], v[98:99] op_sel_hi:[1,0]
	v_pk_mul_f32 v[90:91], v[90:91], v[98:99] op_sel_hi:[1,0]
	v_max_f32_e32 v88, 0, v88
	v_max_f32_e32 v89, 0, v89
	v_max_f32_e32 v92, 0, v92
	v_max_f32_e32 v93, 0, v93
	v_pk_mul_f32 v[100:101], v[88:89], v[88:89]
	v_max_f32_e32 v88, 0, v94
	v_max_f32_e32 v90, 0, v90
	v_max_f32_e32 v89, 0, v95
	v_max_f32_e32 v91, 0, v91
	v_pk_mul_f32 v[92:93], v[92:93], v[92:93]
	v_pk_mul_f32 v[94:95], v[88:89], v[88:89]
; __device__ __forceinline__ float fast_sigmoid(float x) { return __builtin_amdgcn_rcpf(1.0f + __builtin_amdgcn_exp2f(-x * LOG2E)); }
; __device__ __forceinline__ float ss_fix(float raw) { return (float)__float_as_uint(raw) * (1.0f / 256.0f); }
;     __device__ __forceinline__ const CAS char* base() const { const CAS char* ka = (const CAS char*)__builtin_amdgcn_kernarg_segment_ptr(); asm volatile("" : "+s"(ka)); return ka; }
;     __device__ __forceinline__ void operator()(const f32x4 (&acc)[2][2][4][2], const Unit& u, int wr, int wc, int fr, int fq) const {
;     ...
;         for (int it = 0; it < 8; ++it) rsv[it] = (SM == 1) ? ss[row0 + (it >> 2) * HALF + (it & 3) * 16] : 1.0f;
; #pragma unroll
;         for (int ai = 0; ai < 2; ++ai)
; #pragma unroll
;             for (int m = 0; m < 4; ++m) { const int row = row0 + ai * HALF + m * 16; float rs = 1.0f; if (SM == 1) rs = __builtin_amdgcn_rsqf(ss_fix(rsv[ai * 4 + m]) * (1.0f / DM) + EPS);
;                 bf16_t* rowp = base + (size_t)row * ldc + col0;
; #pragma unroll
;                 for (int bj = 0; bj < 2; ++bj) { f32x4 v0 = acc[ai][bj][m][0], v1 = acc[ai][bj][m][1];
;                     if (SM == 1) { v0 *= rs; v1 *= rs; }
;                     if (SM == 2) { v0 *= cs[bj][0]; v1 *= cs[bj][1]; }
;                     if (ACT == 1) {
; #pragma unroll
;                         for (int j = 0; j < 4; ++j) { const float a = fmaxf(v0[j], 0.f), b = fmaxf(v1[j], 0.f); v0[j] = a * a; v1[j] = b * b; } }
;                     if (ACT == 2) { if (tsel == 0) {
; #pragma unroll
;                         for (int j = 0; j < 4; ++j) { const float a = v0[j], b = v1[j];
;                             v0[j] = a * fast_sigmoid(1.5957691216057308f * (a + 0.044715f * a * a * a)); v1[j] = b * fast_sigmoid(1.5957691216057308f * (b + 0.044715f * b * b * b)); } } }
;                     u32x4 w; w.x = pk_bf16(v0[0], v0[1]); w.y = pk_bf16(v0[2], v0[3]); w.z = pk_bf16(v1[0], v1[1]); w.w = pk_bf16(v1[2], v1[3]);
;                     *(u32x4*)(rowp + bj * HALF) = w; } }
	v_pk_mul_f32 v[102:103], v[90:91], v[90:91]
	v_pk_mul_f32 v[84:85], v[84:85], v[98:99] op_sel_hi:[1,0]
	v_pk_mul_f32 v[80:81], v[80:81], v[98:99] op_sel_hi:[1,0]
	v_lshl_add_u64 v[96:97], v[148:149], 0, v[96:97]
	v_cvt_pk_bf16_f32 v88, v92, v93
	v_cvt_pk_bf16_f32 v89, v94, v95
	v_cvt_pk_bf16_f32 v90, v100, v101
	v_cvt_pk_bf16_f32 v91, v102, v103
	v_pk_mul_f32 v[86:87], v[86:87], v[98:99] op_sel_hi:[1,0]
	v_max_f32_e32 v84, 0, v84
	v_max_f32_e32 v80, 0, v80
	v_max_f32_e32 v85, 0, v85
	v_max_f32_e32 v81, 0, v81
	global_store_dwordx4 v[96:97], v[88:91], off
	v_pk_mul_f32 v[84:85], v[84:85], v[84:85]
	v_pk_mul_f32 v[82:83], v[82:83], v[98:99] op_sel_hi:[1,0]
	v_pk_mul_f32 v[88:89], v[80:81], v[80:81]
	v_max_f32_e32 v80, 0, v86
	v_max_f32_e32 v81, 0, v87
	v_pk_mul_f32 v[86:87], v[80:81], v[80:81]
	v_cvt_pk_bf16_f32 v80, v84, v85
	v_cvt_f32_u32_e32 v84, v167
	v_max_f32_e32 v82, 0, v82
	v_max_f32_e32 v83, 0, v83
	v_pk_mul_f32 v[90:91], v[82:83], v[82:83]
	v_cvt_pk_bf16_f32 v81, v86, v87
	v_cvt_pk_bf16_f32 v82, v88, v89
	v_cvt_pk_bf16_f32 v83, v90, v91
	global_store_dwordx4 v[96:97], v[80:83], off offset:256
	s_nop 1
	v_mul_f32_e32 v81, 0x3b800000, v84
	v_fmamk_f32 v81, v81, 0x3a000000, v156
	v_rsq_f32_e32 v82, v81
	v_or_b32_e32 v80, 48, v146
	v_ashrrev_i32_e32 v81, 31, v80
	v_lshlrev_b64 v[80:81], 14, v[80:81]
	v_pk_mul_f32 v[72:73], v[72:73], v[82:83] op_sel_hi:[1,0]
	v_pk_mul_f32 v[78:79], v[78:79], v[82:83] op_sel_hi:[1,0]
	v_pk_mul_f32 v[76:77], v[76:77], v[82:83] op_sel_hi:[1,0]
	v_pk_mul_f32 v[74:75], v[74:75], v[82:83] op_sel_hi:[1,0]
	v_max_f32_e32 v72, 0, v72
	v_max_f32_e32 v73, 0, v73
	v_max_f32_e32 v76, 0, v76
	v_max_f32_e32 v77, 0, v77
	v_pk_mul_f32 v[84:85], v[72:73], v[72:73]
	v_max_f32_e32 v72, 0, v78
	v_max_f32_e32 v74, 0, v74
	v_max_f32_e32 v73, 0, v79
	v_max_f32_e32 v75, 0, v75
	v_pk_mul_f32 v[76:77], v[76:77], v[76:77]
	v_pk_mul_f32 v[78:79], v[72:73], v[72:73]
	v_pk_mul_f32 v[86:87], v[74:75], v[74:75]
	v_pk_mul_f32 v[66:67], v[66:67], v[82:83] op_sel_hi:[1,0]
	v_lshl_add_u64 v[80:81], v[148:149], 0, v[80:81]
	v_cvt_pk_bf16_f32 v72, v76, v77
	v_cvt_pk_bf16_f32 v73, v78, v79
	v_cvt_pk_bf16_f32 v74, v84, v85
	v_cvt_pk_bf16_f32 v75, v86, v87
	v_max_f32_e32 v66, 0, v66
	v_max_f32_e32 v67, 0, v67
	global_store_dwordx4 v[80:81], v[72:75], off
	v_pk_mul_f32 v[68:69], v[68:69], v[82:83] op_sel_hi:[1,0]
	v_pk_mul_f32 v[64:65], v[64:65], v[82:83] op_sel_hi:[1,0]
	v_pk_mul_f32 v[74:75], v[66:67], v[66:67]
	v_cvt_f32_u32_e32 v67, v168
	v_pk_mul_f32 v[70:71], v[70:71], v[82:83] op_sel_hi:[1,0]
	v_max_f32_e32 v68, 0, v68
	v_max_f32_e32 v64, 0, v64
	v_max_f32_e32 v69, 0, v69
	v_max_f32_e32 v65, 0, v65
	v_mul_f32_e32 v67, 0x3b800000, v67
	v_pk_mul_f32 v[68:69], v[68:69], v[68:69]
	v_pk_mul_f32 v[72:73], v[64:65], v[64:65]
	v_max_f32_e32 v64, 0, v70
	v_max_f32_e32 v65, 0, v71
	v_fmamk_f32 v67, v67, 0x3a000000, v156
	v_pk_mul_f32 v[70:71], v[64:65], v[64:65]
	v_cvt_pk_bf16_f32 v64, v68, v69
	v_rsq_f32_e32 v68, v67
	v_cvt_pk_bf16_f32 v65, v70, v71
	v_cvt_pk_bf16_f32 v66, v72, v73
	v_cvt_pk_bf16_f32 v67, v74, v75
	v_pk_mul_f32 v[60:61], v[60:61], v[68:69] op_sel_hi:[1,0]
	v_pk_mul_f32 v[56:57], v[56:57], v[68:69] op_sel_hi:[1,0]
	v_pk_mul_f32 v[62:63], v[62:63], v[68:69] op_sel_hi:[1,0]
	v_pk_mul_f32 v[58:59], v[58:59], v[68:69] op_sel_hi:[1,0]
	v_max_f32_e32 v60, 0, v60
	v_max_f32_e32 v56, 0, v56
	v_max_f32_e32 v61, 0, v61
	v_max_f32_e32 v57, 0, v57
	global_store_dwordx4 v[80:81], v[64:67], off offset:256
	v_pk_mul_f32 v[60:61], v[60:61], v[60:61]
	v_max_f32_e32 v58, 0, v58
	v_lshl_add_u64 v[64:65], v[144:145], 0, s[34:35]
	v_pk_mul_f32 v[66:67], v[56:57], v[56:57]
	v_max_f32_e32 v56, 0, v62
	v_max_f32_e32 v57, 0, v63
	v_max_f32_e32 v59, 0, v59
	s_mov_b32 s34, 0x200000
	v_pk_mul_f32 v[62:63], v[56:57], v[56:57]
	v_pk_mul_f32 v[70:71], v[58:59], v[58:59]
	v_cvt_pk_bf16_f32 v56, v60, v61
	v_add_co_u32_e32 v60, vcc, s34, v144
	v_pk_mul_f32 v[50:51], v[50:51], v[68:69] op_sel_hi:[1,0]
	v_cvt_pk_bf16_f32 v57, v62, v63
	v_cvt_pk_bf16_f32 v58, v66, v67
	v_cvt_pk_bf16_f32 v59, v70, v71
	v_addc_co_u32_e32 v61, vcc, 0, v145, vcc
	v_max_f32_e32 v50, 0, v50
	v_max_f32_e32 v51, 0, v51
	global_store_dwordx4 v[60:61], v[56:59], off
	v_pk_mul_f32 v[52:53], v[52:53], v[68:69] op_sel_hi:[1,0]
	v_pk_mul_f32 v[48:49], v[48:49], v[68:69] op_sel_hi:[1,0]
	v_pk_mul_f32 v[58:59], v[50:51], v[50:51]
	v_cvt_f32_u32_e32 v51, v169
	v_pk_mul_f32 v[54:55], v[54:55], v[68:69] op_sel_hi:[1,0]
	v_max_f32_e32 v52, 0, v52
	v_max_f32_e32 v48, 0, v48
	v_max_f32_e32 v53, 0, v53
	v_max_f32_e32 v49, 0, v49
	v_mul_f32_e32 v51, 0x3b800000, v51
	v_pk_mul_f32 v[52:53], v[52:53], v[52:53]
	v_pk_mul_f32 v[56:57], v[48:49], v[48:49]
	v_max_f32_e32 v48, 0, v54
	v_max_f32_e32 v49, 0, v55
	v_fmamk_f32 v51, v51, 0x3a000000, v156
	v_pk_mul_f32 v[54:55], v[48:49], v[48:49]
	v_cvt_pk_bf16_f32 v48, v52, v53
	v_rsq_f32_e32 v52, v51
	v_cvt_pk_bf16_f32 v49, v54, v55
	v_cvt_pk_bf16_f32 v50, v56, v57
	v_cvt_pk_bf16_f32 v51, v58, v59
	v_pk_mul_f32 v[44:45], v[44:45], v[52:53] op_sel_hi:[1,0]
	v_pk_mul_f32 v[40:41], v[40:41], v[52:53] op_sel_hi:[1,0]
	s_mov_b64 s[34:35], 0x240000
	v_pk_mul_f32 v[46:47], v[46:47], v[52:53] op_sel_hi:[1,0]
	v_pk_mul_f32 v[42:43], v[42:43], v[52:53] op_sel_hi:[1,0]
	v_max_f32_e32 v44, 0, v44
	v_max_f32_e32 v40, 0, v40
	v_max_f32_e32 v45, 0, v45
	v_max_f32_e32 v41, 0, v41
; __device__ __forceinline__ float fast_sigmoid(float x) { return __builtin_amdgcn_rcpf(1.0f + __builtin_amdgcn_exp2f(-x * LOG2E)); }
; __device__ __forceinline__ float ss_fix(float raw) { return (float)__float_as_uint(raw) * (1.0f / 256.0f); }
; #define PG8_WAIT_V(n) asm volatile("s_waitcnt vmcnt(" #n ")" ::: "memory")
; #define PG8_BAR __builtin_amdgcn_s_barrier()
;     __device__ __forceinline__ const CAS char* base() const { const CAS char* ka = (const CAS char*)__builtin_amdgcn_kernarg_segment_ptr(); asm volatile("" : "+s"(ka)); return ka; }
; template <class Epi>
; __device__ __forceinline__ void gemm_phase(LAS unsigned char* lds, const Gemm g, const StaticOrder& S, const Epi& E, int wv) {
;     ...
;         cur = nxt; cA = nA; cB = nB; ++ui;
;     }
;     PG8_WAIT_V(0);
;     if (wr == 0) PG8_BAR;
;     PG8_BAR;
;     __device__ __forceinline__ void operator()(const f32x4 (&acc)[2][2][4][2], const Unit& u, int wr, int wc, int fr, int fq) const {
;     ...
;             for (int m = 0; m < 4; ++m) { const int row = row0 + ai * HALF + m * 16; float rs = 1.0f; if (SM == 1) rs = __builtin_amdgcn_rsqf(ss_fix(rsv[ai * 4 + m]) * (1.0f / DM) + EPS);
;                 bf16_t* rowp = base + (size_t)row * ldc + col0;
; #pragma unroll
;                 for (int bj = 0; bj < 2; ++bj) { f32x4 v0 = acc[ai][bj][m][0], v1 = acc[ai][bj][m][1];
;                     if (SM == 1) { v0 *= rs; v1 *= rs; }
;                     if (SM == 2) { v0 *= cs[bj][0]; v1 *= cs[bj][1]; }
;                     if (ACT == 1) {
; #pragma unroll
;                         for (int j = 0; j < 4; ++j) { const float a = fmaxf(v0[j], 0.f), b = fmaxf(v1[j], 0.f); v0[j] = a * a; v1[j] = b * b; } }
;                     if (ACT == 2) { if (tsel == 0) {
; #pragma unroll
;                         for (int j = 0; j < 4; ++j) { const float a = v0[j], b = v1[j];
;                             v0[j] = a * fast_sigmoid(1.5957691216057308f * (a + 0.044715f * a * a * a)); v1[j] = b * fast_sigmoid(1.5957691216057308f * (b + 0.044715f * b * b * b)); } } }
;                     u32x4 w; w.x = pk_bf16(v0[0], v0[1]); w.y = pk_bf16(v0[2], v0[3]); w.z = pk_bf16(v1[0], v1[1]); w.w = pk_bf16(v1[2], v1[3]);
;                     *(u32x4*)(rowp + bj * HALF) = w; } }
	global_store_dwordx4 v[64:65], v[48:51], off offset:256
	v_pk_mul_f32 v[44:45], v[44:45], v[44:45]
	v_max_f32_e32 v42, 0, v42
	v_lshl_add_u64 v[48:49], v[144:145], 0, s[34:35]
	v_pk_mul_f32 v[50:51], v[40:41], v[40:41]
	v_max_f32_e32 v40, 0, v46
	v_max_f32_e32 v41, 0, v47
	v_max_f32_e32 v43, 0, v43
	s_mov_b32 s34, 0x240000
	v_pk_mul_f32 v[46:47], v[40:41], v[40:41]
	v_pk_mul_f32 v[54:55], v[42:43], v[42:43]
	v_cvt_pk_bf16_f32 v40, v44, v45
	v_add_co_u32_e32 v44, vcc, s34, v144
	v_pk_mul_f32 v[34:35], v[34:35], v[52:53] op_sel_hi:[1,0]
	v_cvt_pk_bf16_f32 v41, v46, v47
	v_cvt_pk_bf16_f32 v42, v50, v51
	v_cvt_pk_bf16_f32 v43, v54, v55
	v_addc_co_u32_e32 v45, vcc, 0, v145, vcc
	v_max_f32_e32 v34, 0, v34
	v_max_f32_e32 v35, 0, v35
	global_store_dwordx4 v[44:45], v[40:43], off
	v_pk_mul_f32 v[36:37], v[36:37], v[52:53] op_sel_hi:[1,0]
	v_pk_mul_f32 v[32:33], v[32:33], v[52:53] op_sel_hi:[1,0]
	v_pk_mul_f32 v[42:43], v[34:35], v[34:35]
	v_cvt_f32_u32_e32 v35, v170
	v_pk_mul_f32 v[38:39], v[38:39], v[52:53] op_sel_hi:[1,0]
	v_max_f32_e32 v36, 0, v36
	v_max_f32_e32 v32, 0, v32
	v_max_f32_e32 v37, 0, v37
	v_max_f32_e32 v33, 0, v33
	v_mul_f32_e32 v35, 0x3b800000, v35
	v_pk_mul_f32 v[36:37], v[36:37], v[36:37]
	v_pk_mul_f32 v[40:41], v[32:33], v[32:33]
	v_max_f32_e32 v32, 0, v38
	v_max_f32_e32 v33, 0, v39
	v_fmamk_f32 v35, v35, 0x3a000000, v156
	v_pk_mul_f32 v[38:39], v[32:33], v[32:33]
	v_cvt_pk_bf16_f32 v32, v36, v37
	v_rsq_f32_e32 v36, v35
	v_cvt_pk_bf16_f32 v33, v38, v39
	v_cvt_pk_bf16_f32 v34, v40, v41
	v_cvt_pk_bf16_f32 v35, v42, v43
	v_pk_mul_f32 v[28:29], v[28:29], v[36:37] op_sel_hi:[1,0]
	v_pk_mul_f32 v[24:25], v[24:25], v[36:37] op_sel_hi:[1,0]
	v_pk_mul_f32 v[30:31], v[30:31], v[36:37] op_sel_hi:[1,0]
	v_pk_mul_f32 v[26:27], v[26:27], v[36:37] op_sel_hi:[1,0]
	v_max_f32_e32 v28, 0, v28
	v_max_f32_e32 v24, 0, v24
	v_max_f32_e32 v29, 0, v29
	v_max_f32_e32 v25, 0, v25
	global_store_dwordx4 v[48:49], v[32:35], off offset:256
	v_pk_mul_f32 v[28:29], v[28:29], v[28:29]
	v_max_f32_e32 v26, 0, v26
	v_pk_mul_f32 v[34:35], v[24:25], v[24:25]
	v_max_f32_e32 v24, 0, v30
	v_max_f32_e32 v25, 0, v31
	v_max_f32_e32 v27, 0, v27
	v_pk_mul_f32 v[30:31], v[24:25], v[24:25]
	v_pk_mul_f32 v[38:39], v[26:27], v[26:27]
	v_cvt_pk_bf16_f32 v24, v28, v29
	v_add_co_u32_e32 v28, vcc, s25, v144
	v_pk_mul_f32 v[18:19], v[18:19], v[36:37] op_sel_hi:[1,0]
	v_cvt_pk_bf16_f32 v25, v30, v31
	v_cvt_pk_bf16_f32 v26, v34, v35
	v_cvt_pk_bf16_f32 v27, v38, v39
	v_addc_co_u32_e32 v29, vcc, 0, v145, vcc
	v_max_f32_e32 v18, 0, v18
	v_max_f32_e32 v19, 0, v19
	global_store_dwordx4 v[28:29], v[24:27], off
	v_pk_mul_f32 v[20:21], v[20:21], v[36:37] op_sel_hi:[1,0]
	v_pk_mul_f32 v[16:17], v[16:17], v[36:37] op_sel_hi:[1,0]
	v_pk_mul_f32 v[26:27], v[18:19], v[18:19]
	v_cvt_f32_u32_e32 v19, v147
	v_pk_mul_f32 v[22:23], v[22:23], v[36:37] op_sel_hi:[1,0]
	v_max_f32_e32 v20, 0, v20
	v_max_f32_e32 v16, 0, v16
	v_max_f32_e32 v21, 0, v21
	v_max_f32_e32 v17, 0, v17
	v_mul_f32_e32 v19, 0x3b800000, v19
	v_pk_mul_f32 v[20:21], v[20:21], v[20:21]
	v_pk_mul_f32 v[24:25], v[16:17], v[16:17]
	v_max_f32_e32 v16, 0, v22
	v_max_f32_e32 v17, 0, v23
	v_fmamk_f32 v19, v19, 0x3a000000, v156
	v_pk_mul_f32 v[22:23], v[16:17], v[16:17]
	v_cvt_pk_bf16_f32 v16, v20, v21
	v_rsq_f32_e32 v20, v19
	s_mov_b64 s[34:35], 0x280000
	v_lshl_add_u64 v[32:33], v[144:145], 0, s[34:35]
	v_cvt_pk_bf16_f32 v17, v22, v23
	v_pk_mul_f32 v[12:13], v[12:13], v[20:21] op_sel_hi:[1,0]
	v_pk_mul_f32 v[8:9], v[8:9], v[20:21] op_sel_hi:[1,0]
	v_cvt_pk_bf16_f32 v18, v24, v25
	v_cvt_pk_bf16_f32 v19, v26, v27
	v_pk_mul_f32 v[14:15], v[14:15], v[20:21] op_sel_hi:[1,0]
	v_pk_mul_f32 v[10:11], v[10:11], v[20:21] op_sel_hi:[1,0]
	v_max_f32_e32 v12, 0, v12
	v_max_f32_e32 v8, 0, v8
	v_max_f32_e32 v13, 0, v13
	v_max_f32_e32 v9, 0, v9
	global_store_dwordx4 v[32:33], v[16:19], off offset:256
	v_pk_mul_f32 v[12:13], v[12:13], v[12:13]
	v_max_f32_e32 v10, 0, v10
	v_pk_mul_f32 v[18:19], v[8:9], v[8:9]
	v_max_f32_e32 v8, 0, v14
	v_max_f32_e32 v9, 0, v15
	v_max_f32_e32 v11, 0, v11
	v_pk_mul_f32 v[14:15], v[8:9], v[8:9]
	v_pk_mul_f32 v[22:23], v[10:11], v[10:11]
	v_cvt_pk_bf16_f32 v8, v12, v13
	v_add_co_u32_e32 v12, vcc, s33, v144
	v_pk_mul_f32 v[0:1], v[0:1], v[20:21] op_sel_hi:[1,0]
	v_cvt_pk_bf16_f32 v9, v14, v15
	v_cvt_pk_bf16_f32 v10, v18, v19
	v_cvt_pk_bf16_f32 v11, v22, v23
	v_addc_co_u32_e32 v13, vcc, 0, v145, vcc
	v_pk_mul_f32 v[6:7], v[6:7], v[20:21] op_sel_hi:[1,0]
	v_pk_mul_f32 v[4:5], v[4:5], v[20:21] op_sel_hi:[1,0]
	v_pk_mul_f32 v[2:3], v[2:3], v[20:21] op_sel_hi:[1,0]
	v_max_f32_e32 v0, 0, v0
	v_max_f32_e32 v1, 0, v1
	global_store_dwordx4 v[12:13], v[8:11], off
	v_max_f32_e32 v4, 0, v4
	v_max_f32_e32 v5, 0, v5
	v_pk_mul_f32 v[8:9], v[0:1], v[0:1]
	v_max_f32_e32 v0, 0, v6
	v_max_f32_e32 v2, 0, v2
	v_max_f32_e32 v1, 0, v7
	v_max_f32_e32 v3, 0, v3
	v_pk_mul_f32 v[4:5], v[4:5], v[4:5]
	v_pk_mul_f32 v[6:7], v[0:1], v[0:1]
	v_pk_mul_f32 v[10:11], v[2:3], v[2:3]
	v_lshl_add_u64 v[16:17], v[144:145], 0, s[54:55]
	v_cvt_pk_bf16_f32 v0, v4, v5
	v_cvt_pk_bf16_f32 v1, v6, v7
	v_cvt_pk_bf16_f32 v2, v8, v9
	v_cvt_pk_bf16_f32 v3, v10, v11
	s_and_b64 vcc, exec, s[16:17]
	s_mov_b32 s34, s56
	global_store_dwordx4 v[16:17], v[0:3], off offset:256
	s_cbranch_vccz .LBB0_523
	s_waitcnt vmcnt(0)
	s_cmpk_gt_u32 s4, 0xff
	s_cbranch_scc1 .LBB0_534
	s_barrier

; #define PG8_STAGE(bufoff, gbase, voff) do { _Pragma("unroll") for (int _i = 0; _i < 2; ++_i) \
;         __builtin_amdgcn_global_load_lds((const unsigned*)((const char*)(gbase) + (voff)[_i]), (LAS unsigned*)(lds + (bufoff) + ldsw + _i * 8192), 16, 0, 0); } while (0)
; #define PG8_LDA(dst, b, h) do { _Pragma("unroll") for (int m = 0; m < 4; ++m) _Pragma("unroll") for (int k = 0; k < 2; ++k) dst[m][k] = *(const LAS bf16x8*)(lds + PG8_SA(b, h) + aoff + m * 2048 + k * 1024); } while (0)
; #define PG8_LDB(dst, b, h) do { _Pragma("unroll") for (int n = 0; n < 2; ++n) _Pragma("unroll") for (int k = 0; k < 2; ++k) dst[n][k] = *(const LAS bf16x8*)(lds + PG8_SB(b, h) + boff + n * 2048 + k * 1024); } while (0)
; #define PG8_MMA(ai, bj, At, Bt) do { __builtin_amdgcn_s_setprio(1); _Pragma("unroll") for (int m = 0; m < 4; ++m) _Pragma("unroll") for (int n = 0; n < 2; ++n) _Pragma("unroll") for (int k = 0; k < 2; ++k) \
;         acc[ai][bj][m][n] = __builtin_amdgcn_mfma_f32_16x16x32_bf16(Bt[n][k], At[m][k], acc[ai][bj][m][n], 0, 0, 0); __builtin_amdgcn_s_setprio(0); } while (0)
; #define PG8_WAIT_L(n) asm volatile("s_waitcnt lgkmcnt(" #n ")" ::: "memory")
; #define PG8_BAR __builtin_amdgcn_s_barrier()
; #define PG8_SCHED __builtin_amdgcn_sched_barrier(0)
; template <class Epi>
; __device__ __forceinline__ void gemm_phase(LAS unsigned char* lds, const Gemm g, const StaticOrder& S, const Epi& E, int wv) {
;     ...
;         const bool has_next = S.next(ui + 1, nxt);
;         const char* nA = has_next ? (const char*)g.A + (size_t)nxt.pm * tstepA + ((g.adiag & 1) ? (size_t)(nxt.pn >> 1) * K * 2 : 0) + kbeg : cA;
;         const char* nB = has_next ? (const char*)g.Bt + (size_t)nxt.pn * tstepB + kbeg : cB;
;         for (int t = 0; t < nt; t += 2) {
;             const bool last = (t == nt - 2);
;             const char* a1 = cA + (ptrdiff_t)(t + 1) * kstep;
;             const char* a2 = last ? nA : cA + (ptrdiff_t)(t + 2) * kstep; const char* b2 = last ? nB : cB + (ptrdiff_t)(t + 2) * kstep;
;             const char* a3 = a2 + kstep; const char* b3 = b2 + kstep;
;             PG8_LDB(B0, 0, 0); PG8_SCHED; PG8_LDA(At, 0, 0); PG8_STAGE(PG8_SA(1, 1), a1 + hstepA, voffA);
;             PG8_WAIT_L(8); PG8_BAR; PG8_WAIT_L(0); PG8_MMA(0, 0, At, B0); PG8_BAR; PG8_SCHED;
.LBB0_604:
	s_ashr_i32 s63, s62, 31
	s_lshl_b64 s[34:35], s[62:63], 22
	s_add_u32 s33, s5, s34
	s_addc_u32 s34, s6, s35
	v_cmp_lt_i64_e32 vcc, s[64:65], v[152:153]
	s_add_u32 s64, s33, 0x3f80
	s_addc_u32 s65, s34, 0
	s_and_b64 s[34:35], vcc, exec
	s_cselect_b32 s77, s65, s75
	s_cselect_b32 s76, s64, s74
	s_ashr_i32 s61, s60, 31
	s_lshl_b64 s[34:35], s[60:61], 22
	s_add_u32 s66, s14, s34
	s_addc_u32 s67, s15, s35
	s_and_b64 s[34:35], vcc, exec
	s_cselect_b32 s79, s67, s73
	s_cselect_b32 s78, s66, s72
	s_add_u32 s33, s74, 0x200000
	v_mov_b32_e32 v0, 0
	s_addc_u32 s34, s75, 0
	s_mov_b32 s35, 0
	s_waitcnt lgkmcnt(0)
	v_mov_b32_e32 v1, v0
	v_mov_b32_e32 v2, v0
	v_mov_b32_e32 v3, v0
	v_mov_b32_e32 v4, v0
	v_mov_b32_e32 v5, v0
	v_mov_b32_e32 v6, v0
	v_mov_b32_e32 v7, v0
	v_mov_b32_e32 v16, v0
	v_mov_b32_e32 v17, v0
	v_mov_b32_e32 v18, v0
	v_mov_b32_e32 v19, v0
	v_mov_b32_e32 v20, v0
	v_mov_b32_e32 v21, v0
	v_mov_b32_e32 v22, v0
	v_mov_b32_e32 v23, v0
	v_mov_b32_e32 v32, v0
	v_mov_b32_e32 v33, v0
	v_mov_b32_e32 v34, v0
	v_mov_b32_e32 v35, v0
	v_mov_b32_e32 v36, v0
	v_mov_b32_e32 v37, v0
	v_mov_b32_e32 v38, v0
	v_mov_b32_e32 v39, v0
	v_mov_b32_e32 v48, v0
	v_mov_b32_e32 v49, v0
	v_mov_b32_e32 v50, v0
	v_mov_b32_e32 v51, v0
	v_mov_b32_e32 v52, v0
	v_mov_b32_e32 v53, v0
	v_mov_b32_e32 v54, v0
	v_mov_b32_e32 v55, v0
	v_mov_b32_e32 v8, v0
	v_mov_b32_e32 v9, v0
	v_mov_b32_e32 v10, v0
	v_mov_b32_e32 v11, v0
	v_mov_b32_e32 v12, v0
	v_mov_b32_e32 v13, v0
	v_mov_b32_e32 v14, v0
	v_mov_b32_e32 v15, v0
	v_mov_b32_e32 v24, v0
	v_mov_b32_e32 v25, v0
	v_mov_b32_e32 v26, v0
	v_mov_b32_e32 v27, v0
	v_mov_b32_e32 v28, v0
	v_mov_b32_e32 v29, v0
	v_mov_b32_e32 v30, v0
	v_mov_b32_e32 v31, v0
	v_mov_b32_e32 v40, v0
	v_mov_b32_e32 v41, v0
	v_mov_b32_e32 v42, v0
	v_mov_b32_e32 v43, v0
	v_mov_b32_e32 v44, v0
	v_mov_b32_e32 v45, v0
	v_mov_b32_e32 v46, v0
	v_mov_b32_e32 v47, v0
	v_mov_b32_e32 v56, v0
	v_mov_b32_e32 v57, v0
	v_mov_b32_e32 v58, v0
	v_mov_b32_e32 v59, v0
	v_mov_b32_e32 v60, v0
	v_mov_b32_e32 v61, v0
	v_mov_b32_e32 v62, v0
	v_mov_b32_e32 v63, v0
	v_mov_b32_e32 v64, v0
	v_mov_b32_e32 v65, v0
	v_mov_b32_e32 v66, v0
	v_mov_b32_e32 v67, v0
	v_mov_b32_e32 v68, v0
	v_mov_b32_e32 v69, v0
	v_mov_b32_e32 v70, v0
	v_mov_b32_e32 v71, v0
	v_mov_b32_e32 v80, v0
	v_mov_b32_e32 v81, v0
	v_mov_b32_e32 v82, v0
	v_mov_b32_e32 v83, v0
	v_mov_b32_e32 v84, v0
	v_mov_b32_e32 v85, v0
	v_mov_b32_e32 v86, v0
	v_mov_b32_e32 v87, v0
	v_mov_b32_e32 v96, v0
	v_mov_b32_e32 v97, v0
	v_mov_b32_e32 v98, v0
	v_mov_b32_e32 v99, v0
	v_mov_b32_e32 v100, v0
	v_mov_b32_e32 v101, v0
	v_mov_b32_e32 v102, v0
	v_mov_b32_e32 v103, v0
	v_mov_b32_e32 v112, v0
	v_mov_b32_e32 v113, v0
	v_mov_b32_e32 v114, v0
	v_mov_b32_e32 v115, v0
	v_mov_b32_e32 v116, v0
	v_mov_b32_e32 v117, v0
	v_mov_b32_e32 v118, v0
	v_mov_b32_e32 v119, v0
	v_mov_b32_e32 v72, v0
	v_mov_b32_e32 v73, v0
	v_mov_b32_e32 v74, v0
	v_mov_b32_e32 v75, v0
	v_mov_b32_e32 v76, v0
	v_mov_b32_e32 v77, v0
	v_mov_b32_e32 v78, v0
	v_mov_b32_e32 v79, v0
	v_mov_b32_e32 v88, v0
	v_mov_b32_e32 v89, v0
	v_mov_b32_e32 v90, v0
	v_mov_b32_e32 v91, v0
	v_mov_b32_e32 v92, v0
	v_mov_b32_e32 v93, v0
	v_mov_b32_e32 v94, v0
	v_mov_b32_e32 v95, v0
	v_mov_b32_e32 v104, v0
	v_mov_b32_e32 v105, v0
	v_mov_b32_e32 v106, v0
	v_mov_b32_e32 v107, v0
	v_mov_b32_e32 v108, v0
	v_mov_b32_e32 v109, v0
	v_mov_b32_e32 v110, v0
	v_mov_b32_e32 v111, v0
	v_mov_b32_e32 v120, v0
	v_mov_b32_e32 v121, v0
	v_mov_b32_e32 v122, v0
	v_mov_b32_e32 v123, v0
	v_mov_b32_e32 v124, v0
	v_mov_b32_e32 v125, v0
	v_mov_b32_e32 v126, v0
	v_mov_b32_e32 v127, v0
	v_add_u32_e32 v140, s22, v173
	ds_read_b128 v[128:131], v140
	ds_read_b128 v[132:135], v140 offset:1024
	ds_read_b128 v[136:139], v140 offset:2048
	ds_read_b128 v[140:143], v140 offset:3072
	s_branch .LBB0_606
.LBB0_605:
	s_or_b32 s50, s35, 1
	s_lshl_b64 s[38:39], s[50:51], 7
	s_sub_u32 s38, 0, s38
	s_subb_u32 s39, 0, s39
	s_add_u32 s38, s33, s38
	s_addc_u32 s39, s34, s39
	s_add_i32 m0, s8, 0xc000
	ds_read_b128 v[156:159], v175
	ds_read_b128 v[160:163], v175 offset:1024
	ds_read_b128 v[164:167], v175 offset:2048
	ds_read_b128 v[168:171], v175 offset:3072
	ds_read_b128 v[176:179], v175 offset:4096
	ds_read_b128 v[180:183], v175 offset:5120
	ds_read_b128 v[184:187], v175 offset:6144
	ds_read_b128 v[188:191], v175 offset:7168
	global_load_lds_dwordx4 v144, s[38:39]
	s_add_i32 m0, s8, 0xe000
	s_nop 0
	global_load_lds_dwordx4 v148, s[38:39]
	s_waitcnt lgkmcnt(8)
	s_barrier
	s_waitcnt lgkmcnt(0)
	s_setprio 1
	s_waitcnt lgkmcnt(0)
	v_mfma_f32_16x16x32_bf16 v[124:127], v[128:131], v[156:159], v[124:127]
	v_mfma_f32_16x16x32_bf16 v[120:123], v[136:139], v[156:159], v[120:123]
	v_mfma_f32_16x16x32_bf16 v[108:111], v[128:131], v[164:167], v[108:111]
	v_mfma_f32_16x16x32_bf16 v[104:107], v[136:139], v[164:167], v[104:107]
	v_mfma_f32_16x16x32_bf16 v[92:95], v[128:131], v[176:179], v[92:95]
	v_mfma_f32_16x16x32_bf16 v[88:91], v[136:139], v[176:179], v[88:91]
	v_mfma_f32_16x16x32_bf16 v[76:79], v[128:131], v[184:187], v[76:79]
	v_mfma_f32_16x16x32_bf16 v[72:75], v[136:139], v[184:187], v[72:75]
	v_mfma_f32_16x16x32_bf16 v[124:127], v[132:135], v[160:163], v[124:127]
	v_mfma_f32_16x16x32_bf16 v[120:123], v[140:143], v[160:163], v[120:123]
	v_mfma_f32_16x16x32_bf16 v[108:111], v[132:135], v[168:171], v[108:111]
	v_mfma_f32_16x16x32_bf16 v[104:107], v[140:143], v[168:171], v[104:107]
	v_mfma_f32_16x16x32_bf16 v[92:95], v[132:135], v[180:183], v[92:95]
	v_mfma_f32_16x16x32_bf16 v[88:91], v[140:143], v[180:183], v[88:91]
	v_mfma_f32_16x16x32_bf16 v[76:79], v[132:135], v[188:191], v[76:79]
	v_mfma_f32_16x16x32_bf16 v[72:75], v[140:143], v[188:191], v[72:75]
	s_setprio 0
	s_barrier
; #define PG8_STAGE(bufoff, gbase, voff) do { _Pragma("unroll") for (int _i = 0; _i < 2; ++_i) \
;         __builtin_amdgcn_global_load_lds((const unsigned*)((const char*)(gbase) + (voff)[_i]), (LAS unsigned*)(lds + (bufoff) + ldsw + _i * 8192), 16, 0, 0); } while (0)
; #define PG8_LDA(dst, b, h) do { _Pragma("unroll") for (int m = 0; m < 4; ++m) _Pragma("unroll") for (int k = 0; k < 2; ++k) dst[m][k] = *(const LAS bf16x8*)(lds + PG8_SA(b, h) + aoff + m * 2048 + k * 1024); } while (0)
; #define PG8_LDB(dst, b, h) do { _Pragma("unroll") for (int n = 0; n < 2; ++n) _Pragma("unroll") for (int k = 0; k < 2; ++k) dst[n][k] = *(const LAS bf16x8*)(lds + PG8_SB(b, h) + boff + n * 2048 + k * 1024); } while (0)
; #define PG8_MMA(ai, bj, At, Bt) do { __builtin_amdgcn_s_setprio(1); _Pragma("unroll") for (int m = 0; m < 4; ++m) _Pragma("unroll") for (int n = 0; n < 2; ++n) _Pragma("unroll") for (int k = 0; k < 2; ++k) \
;         acc[ai][bj][m][n] = __builtin_amdgcn_mfma_f32_16x16x32_bf16(Bt[n][k], At[m][k], acc[ai][bj][m][n], 0, 0, 0); __builtin_amdgcn_s_setprio(0); } while (0)
; #define PG8_WAIT_V(n) asm volatile("s_waitcnt vmcnt(" #n ")" ::: "memory")
; #define PG8_WAIT_L(n) asm volatile("s_waitcnt lgkmcnt(" #n ")" ::: "memory")
; #define PG8_BAR __builtin_amdgcn_s_barrier()
; #define PG8_SCHED __builtin_amdgcn_sched_barrier(0)
; template <class Epi>
; __device__ __forceinline__ void gemm_phase(LAS unsigned char* lds, const Gemm g, const StaticOrder& S, const Epi& E, int wv) {
;     ...
;             PG8_LDB(B1, 0, 1); PG8_STAGE(PG8_SB(0, 0), b2, voffB);
;             PG8_BAR; PG8_WAIT_L(0); PG8_MMA(0, 1, At, B1); PG8_BAR;
;             PG8_LDA(At, 0, 1); PG8_STAGE(PG8_SA(0, 0), a2, voffA);
;             PG8_BAR; PG8_WAIT_L(0); PG8_MMA(1, 0, At, B0); PG8_BAR; PG8_SCHED;
;             PG8_STAGE(PG8_SB(0, 1), b2 + hstepB, voffB);
;             PG8_WAIT_V(6); PG8_BAR; PG8_MMA(1, 1, At, B1); PG8_BAR;
;             PG8_LDB(B0, 1, 0); PG8_SCHED; PG8_LDA(At, 1, 0); PG8_STAGE(PG8_SA(0, 1), a2 + hstepA, voffA);
;             PG8_WAIT_L(8); PG8_BAR; PG8_WAIT_L(0); PG8_MMA(0, 0, At, B0); PG8_BAR; PG8_SCHED;
	s_add_i32 s38, s22, s7
	v_add_u32_e32 v204, s23, v173
	s_add_u32 s98, s82, s58
	s_addc_u32 s99, s83, s59
	s_mov_b32 m0, s38
	ds_read_b128 v[192:195], v204
	ds_read_b128 v[196:199], v204 offset:1024
	ds_read_b128 v[200:203], v204 offset:2048
	ds_read_b128 v[204:207], v204 offset:3072
	global_load_lds_dwordx4 v146, s[82:83]
	s_add_i32 m0, s38, 0x2000
	s_nop 0
	global_load_lds_dwordx4 v150, s[82:83]
	s_barrier
	s_waitcnt lgkmcnt(0)
	s_setprio 1
	s_waitcnt lgkmcnt(0)
	v_mfma_f32_16x16x32_bf16 v[116:119], v[192:195], v[156:159], v[116:119]
	v_mfma_f32_16x16x32_bf16 v[112:115], v[200:203], v[156:159], v[112:115]
	v_mfma_f32_16x16x32_bf16 v[100:103], v[192:195], v[164:167], v[100:103]
	v_mfma_f32_16x16x32_bf16 v[96:99], v[200:203], v[164:167], v[96:99]
	v_mfma_f32_16x16x32_bf16 v[84:87], v[192:195], v[176:179], v[84:87]
	v_mfma_f32_16x16x32_bf16 v[80:83], v[200:203], v[176:179], v[80:83]
	v_mfma_f32_16x16x32_bf16 v[68:71], v[192:195], v[184:187], v[68:71]
	v_mfma_f32_16x16x32_bf16 v[64:67], v[200:203], v[184:187], v[64:67]
	v_mfma_f32_16x16x32_bf16 v[116:119], v[196:199], v[160:163], v[116:119]
	v_mfma_f32_16x16x32_bf16 v[112:115], v[204:207], v[160:163], v[112:115]
	v_mfma_f32_16x16x32_bf16 v[100:103], v[196:199], v[168:171], v[100:103]
	v_mfma_f32_16x16x32_bf16 v[96:99], v[204:207], v[168:171], v[96:99]
	v_mfma_f32_16x16x32_bf16 v[84:87], v[196:199], v[180:183], v[84:87]
	v_mfma_f32_16x16x32_bf16 v[80:83], v[204:207], v[180:183], v[80:83]
	v_mfma_f32_16x16x32_bf16 v[68:71], v[196:199], v[188:191], v[68:71]
	v_mfma_f32_16x16x32_bf16 v[64:67], v[204:207], v[188:191], v[64:67]
	s_setprio 0
	s_mov_b32 m0, s8
	s_add_u32 s100, s84, s58
	s_addc_u32 s101, s85, s59
	s_barrier
	ds_read_b128 v[156:159], v175 offset:16384
	ds_read_b128 v[160:163], v175 offset:17408
	ds_read_b128 v[164:167], v175 offset:18432
	ds_read_b128 v[168:171], v175 offset:19456
	ds_read_b128 v[176:179], v175 offset:20480
	ds_read_b128 v[180:183], v175 offset:21504
	ds_read_b128 v[184:187], v175 offset:22528
	ds_read_b128 v[188:191], v175 offset:23552
	global_load_lds_dwordx4 v144, s[84:85]
	s_mov_b32 m0, s9
	s_nop 0
	global_load_lds_dwordx4 v148, s[84:85]
	s_waitcnt vmcnt(10)
	s_barrier
	s_waitcnt lgkmcnt(0)
	s_setprio 1
	s_waitcnt lgkmcnt(0)
	v_mfma_f32_16x16x32_bf16 v[60:63], v[128:131], v[156:159], v[60:63]
	v_mfma_f32_16x16x32_bf16 v[56:59], v[136:139], v[156:159], v[56:59]
	v_mfma_f32_16x16x32_bf16 v[44:47], v[128:131], v[164:167], v[44:47]
	v_mfma_f32_16x16x32_bf16 v[40:43], v[136:139], v[164:167], v[40:43]
	v_mfma_f32_16x16x32_bf16 v[28:31], v[128:131], v[176:179], v[28:31]
	v_mfma_f32_16x16x32_bf16 v[24:27], v[136:139], v[176:179], v[24:27]
	v_mfma_f32_16x16x32_bf16 v[12:15], v[128:131], v[184:187], v[12:15]
	v_mfma_f32_16x16x32_bf16 v[8:11], v[136:139], v[184:187], v[8:11]
	v_mfma_f32_16x16x32_bf16 v[60:63], v[132:135], v[160:163], v[60:63]
	v_mfma_f32_16x16x32_bf16 v[56:59], v[140:143], v[160:163], v[56:59]
	v_mfma_f32_16x16x32_bf16 v[44:47], v[132:135], v[168:171], v[44:47]
	v_mfma_f32_16x16x32_bf16 v[40:43], v[140:143], v[168:171], v[40:43]
	v_mfma_f32_16x16x32_bf16 v[28:31], v[132:135], v[180:183], v[28:31]
	v_mfma_f32_16x16x32_bf16 v[24:27], v[140:143], v[180:183], v[24:27]
	v_mfma_f32_16x16x32_bf16 v[12:15], v[132:135], v[188:191], v[12:15]
	v_mfma_f32_16x16x32_bf16 v[8:11], v[140:143], v[188:191], v[8:11]
	s_setprio 0
	s_barrier
	s_add_u32 s38, s82, 0x200000
	s_addc_u32 s39, s83, 0
	s_add_i32 s40, s23, s7
	s_mov_b32 m0, s40
	s_nop 0
	global_load_lds_dwordx4 v146, s[38:39]
	s_add_i32 m0, s40, 0x2000
	s_nop 0
	global_load_lds_dwordx4 v150, s[38:39]
	s_add_i32 s40, 0, 0x18000
	v_add_u32_e32 v140, s40, v173
	ds_read_b128 v[128:131], v140
	ds_read_b128 v[132:135], v140 offset:1024
	ds_read_b128 v[136:139], v140 offset:2048
	ds_read_b128 v[140:143], v140 offset:3072
	s_waitcnt vmcnt(6)
	s_barrier
	s_setprio 1
	v_mfma_f32_16x16x32_bf16 v[52:55], v[192:195], v[156:159], v[52:55]
	v_mfma_f32_16x16x32_bf16 v[48:51], v[200:203], v[156:159], v[48:51]
	v_mfma_f32_16x16x32_bf16 v[36:39], v[192:195], v[164:167], v[36:39]
	v_mfma_f32_16x16x32_bf16 v[32:35], v[200:203], v[164:167], v[32:35]
	v_mfma_f32_16x16x32_bf16 v[20:23], v[192:195], v[176:179], v[20:23]
	v_mfma_f32_16x16x32_bf16 v[16:19], v[200:203], v[176:179], v[16:19]
	v_mfma_f32_16x16x32_bf16 v[4:7], v[192:195], v[184:187], v[4:7]
	v_mfma_f32_16x16x32_bf16 v[0:3], v[200:203], v[184:187], v[0:3]
	v_mfma_f32_16x16x32_bf16 v[52:55], v[196:199], v[160:163], v[52:55]
	v_mfma_f32_16x16x32_bf16 v[48:51], v[204:207], v[160:163], v[48:51]
	v_mfma_f32_16x16x32_bf16 v[36:39], v[196:199], v[168:171], v[36:39]
	v_mfma_f32_16x16x32_bf16 v[32:35], v[204:207], v[168:171], v[32:35]
	v_mfma_f32_16x16x32_bf16 v[20:23], v[196:199], v[180:183], v[20:23]
	v_mfma_f32_16x16x32_bf16 v[16:19], v[204:207], v[180:183], v[16:19]
	v_mfma_f32_16x16x32_bf16 v[4:7], v[196:199], v[188:191], v[4:7]
	v_mfma_f32_16x16x32_bf16 v[0:3], v[204:207], v[188:191], v[0:3]
	s_setprio 0
	s_waitcnt lgkmcnt(0)
	s_barrier
	s_add_u32 s38, s84, 0x200000
	s_addc_u32 s39, s85, 0
	s_mov_b32 m0, s10
	ds_read_b128 v[156:159], v175 offset:32768
	ds_read_b128 v[160:163], v175 offset:33792
	ds_read_b128 v[164:167], v175 offset:34816
	ds_read_b128 v[168:171], v175 offset:35840
	ds_read_b128 v[176:179], v175 offset:36864
	ds_read_b128 v[180:183], v175 offset:37888
	ds_read_b128 v[184:187], v175 offset:38912
	ds_read_b128 v[188:191], v175 offset:39936
	global_load_lds_dwordx4 v144, s[38:39]
	s_mov_b32 m0, s11
	s_nop 0
	global_load_lds_dwordx4 v148, s[38:39]
	s_waitcnt lgkmcnt(8)
	s_barrier
; #define PG8_STAGE(bufoff, gbase, voff) do { _Pragma("unroll") for (int _i = 0; _i < 2; ++_i) \
;         __builtin_amdgcn_global_load_lds((const unsigned*)((const char*)(gbase) + (voff)[_i]), (LAS unsigned*)(lds + (bufoff) + ldsw + _i * 8192), 16, 0, 0); } while (0)
; #define PG8_LDA(dst, b, h) do { _Pragma("unroll") for (int m = 0; m < 4; ++m) _Pragma("unroll") for (int k = 0; k < 2; ++k) dst[m][k] = *(const LAS bf16x8*)(lds + PG8_SA(b, h) + aoff + m * 2048 + k * 1024); } while (0)
; #define PG8_LDB(dst, b, h) do { _Pragma("unroll") for (int n = 0; n < 2; ++n) _Pragma("unroll") for (int k = 0; k < 2; ++k) dst[n][k] = *(const LAS bf16x8*)(lds + PG8_SB(b, h) + boff + n * 2048 + k * 1024); } while (0)
; #define PG8_MMA(ai, bj, At, Bt) do { __builtin_amdgcn_s_setprio(1); _Pragma("unroll") for (int m = 0; m < 4; ++m) _Pragma("unroll") for (int n = 0; n < 2; ++n) _Pragma("unroll") for (int k = 0; k < 2; ++k) \
;         acc[ai][bj][m][n] = __builtin_amdgcn_mfma_f32_16x16x32_bf16(Bt[n][k], At[m][k], acc[ai][bj][m][n], 0, 0, 0); __builtin_amdgcn_s_setprio(0); } while (0)
; #define PG8_WAIT_V(n) asm volatile("s_waitcnt vmcnt(" #n ")" ::: "memory")
; #define PG8_WAIT_L(n) asm volatile("s_waitcnt lgkmcnt(" #n ")" ::: "memory")
; #define PG8_BAR __builtin_amdgcn_s_barrier()
; #define PG8_SCHED __builtin_amdgcn_sched_barrier(0)
; template <class Epi>
; __device__ __forceinline__ void gemm_phase(LAS unsigned char* lds, const Gemm g, const StaticOrder& S, const Epi& E, int wv) {
;     ...
;             PG8_WAIT_L(8); PG8_BAR; PG8_WAIT_L(0); PG8_MMA(0, 0, At, B0); PG8_BAR; PG8_SCHED;
;             PG8_LDB(B1, 1, 1); PG8_STAGE(PG8_SB(1, 0), b3, voffB);
;             PG8_BAR; PG8_WAIT_L(0); PG8_MMA(0, 1, At, B1); PG8_BAR;
;             PG8_LDA(At, 1, 1); PG8_STAGE(PG8_SA(1, 0), a3, voffA);
;             PG8_BAR; PG8_WAIT_L(0); PG8_MMA(1, 0, At, B0); PG8_BAR; PG8_SCHED;
;             PG8_STAGE(PG8_SB(1, 1), b3 + hstepB, voffB);
;             PG8_WAIT_V(6); PG8_BAR; PG8_MMA(1, 1, At, B1); PG8_BAR;
	s_waitcnt lgkmcnt(0)
	s_setprio 1
	s_waitcnt lgkmcnt(0)
	v_mfma_f32_16x16x32_bf16 v[124:127], v[128:131], v[156:159], v[124:127]
	v_mfma_f32_16x16x32_bf16 v[120:123], v[136:139], v[156:159], v[120:123]
	v_mfma_f32_16x16x32_bf16 v[108:111], v[128:131], v[164:167], v[108:111]
	v_mfma_f32_16x16x32_bf16 v[104:107], v[136:139], v[164:167], v[104:107]
	v_mfma_f32_16x16x32_bf16 v[92:95], v[128:131], v[176:179], v[92:95]
	v_mfma_f32_16x16x32_bf16 v[88:91], v[136:139], v[176:179], v[88:91]
	v_mfma_f32_16x16x32_bf16 v[76:79], v[128:131], v[184:187], v[76:79]
	v_mfma_f32_16x16x32_bf16 v[72:75], v[136:139], v[184:187], v[72:75]
	v_mfma_f32_16x16x32_bf16 v[124:127], v[132:135], v[160:163], v[124:127]
	v_mfma_f32_16x16x32_bf16 v[120:123], v[140:143], v[160:163], v[120:123]
	v_mfma_f32_16x16x32_bf16 v[108:111], v[132:135], v[168:171], v[108:111]
	v_mfma_f32_16x16x32_bf16 v[104:107], v[140:143], v[168:171], v[104:107]
	v_mfma_f32_16x16x32_bf16 v[92:95], v[132:135], v[180:183], v[92:95]
	v_mfma_f32_16x16x32_bf16 v[88:91], v[140:143], v[180:183], v[88:91]
	v_mfma_f32_16x16x32_bf16 v[76:79], v[132:135], v[188:191], v[76:79]
	v_mfma_f32_16x16x32_bf16 v[72:75], v[140:143], v[188:191], v[72:75]
	s_setprio 0
	s_barrier
	s_add_i32 s41, 0, 0x1c000
	s_add_i32 s38, s40, s7
	v_add_u32_e32 v204, s41, v173
	s_mov_b32 m0, s38
	ds_read_b128 v[192:195], v204
	ds_read_b128 v[196:199], v204 offset:1024
	ds_read_b128 v[200:203], v204 offset:2048
	ds_read_b128 v[204:207], v204 offset:3072
	global_load_lds_dwordx4 v146, s[98:99]
	s_add_i32 m0, s38, 0x2000
	s_nop 0
	global_load_lds_dwordx4 v150, s[98:99]
	s_barrier
	s_waitcnt lgkmcnt(0)
	s_setprio 1
	s_waitcnt lgkmcnt(0)
	v_mfma_f32_16x16x32_bf16 v[116:119], v[192:195], v[156:159], v[116:119]
	v_mfma_f32_16x16x32_bf16 v[112:115], v[200:203], v[156:159], v[112:115]
	v_mfma_f32_16x16x32_bf16 v[100:103], v[192:195], v[164:167], v[100:103]
	v_mfma_f32_16x16x32_bf16 v[96:99], v[200:203], v[164:167], v[96:99]
	v_mfma_f32_16x16x32_bf16 v[84:87], v[192:195], v[176:179], v[84:87]
	v_mfma_f32_16x16x32_bf16 v[80:83], v[200:203], v[176:179], v[80:83]
	v_mfma_f32_16x16x32_bf16 v[68:71], v[192:195], v[184:187], v[68:71]
	v_mfma_f32_16x16x32_bf16 v[64:67], v[200:203], v[184:187], v[64:67]
	v_mfma_f32_16x16x32_bf16 v[116:119], v[196:199], v[160:163], v[116:119]
	v_mfma_f32_16x16x32_bf16 v[112:115], v[204:207], v[160:163], v[112:115]
	v_mfma_f32_16x16x32_bf16 v[100:103], v[196:199], v[168:171], v[100:103]
	v_mfma_f32_16x16x32_bf16 v[96:99], v[204:207], v[168:171], v[96:99]
	v_mfma_f32_16x16x32_bf16 v[84:87], v[196:199], v[180:183], v[84:87]
	v_mfma_f32_16x16x32_bf16 v[80:83], v[204:207], v[180:183], v[80:83]
	v_mfma_f32_16x16x32_bf16 v[68:71], v[196:199], v[188:191], v[68:71]
	v_mfma_f32_16x16x32_bf16 v[64:67], v[204:207], v[188:191], v[64:67]
	s_setprio 0
	s_mov_b32 m0, s12
	s_barrier
	ds_read_b128 v[156:159], v175 offset:49152
	ds_read_b128 v[160:163], v175 offset:50176
	ds_read_b128 v[164:167], v175 offset:51200
	ds_read_b128 v[168:171], v175 offset:52224
	ds_read_b128 v[176:179], v175 offset:53248
	ds_read_b128 v[180:183], v175 offset:54272
	ds_read_b128 v[184:187], v175 offset:55296
	ds_read_b128 v[188:191], v175 offset:56320
	global_load_lds_dwordx4 v144, s[100:101]
	s_mov_b32 m0, s13
	s_nop 0
	global_load_lds_dwordx4 v148, s[100:101]
	s_waitcnt vmcnt(10)
	s_barrier
	s_waitcnt lgkmcnt(0)
	s_setprio 1
	s_waitcnt lgkmcnt(0)
	v_mfma_f32_16x16x32_bf16 v[60:63], v[128:131], v[156:159], v[60:63]
	v_mfma_f32_16x16x32_bf16 v[56:59], v[136:139], v[156:159], v[56:59]
	v_mfma_f32_16x16x32_bf16 v[44:47], v[128:131], v[164:167], v[44:47]
	v_mfma_f32_16x16x32_bf16 v[40:43], v[136:139], v[164:167], v[40:43]
	v_mfma_f32_16x16x32_bf16 v[28:31], v[128:131], v[176:179], v[28:31]
	v_mfma_f32_16x16x32_bf16 v[24:27], v[136:139], v[176:179], v[24:27]
	v_mfma_f32_16x16x32_bf16 v[12:15], v[128:131], v[184:187], v[12:15]
	v_mfma_f32_16x16x32_bf16 v[8:11], v[136:139], v[184:187], v[8:11]
	v_mfma_f32_16x16x32_bf16 v[60:63], v[132:135], v[160:163], v[60:63]
	v_mfma_f32_16x16x32_bf16 v[56:59], v[140:143], v[160:163], v[56:59]
	v_mfma_f32_16x16x32_bf16 v[44:47], v[132:135], v[168:171], v[44:47]
	v_mfma_f32_16x16x32_bf16 v[40:43], v[140:143], v[168:171], v[40:43]
	v_mfma_f32_16x16x32_bf16 v[28:31], v[132:135], v[180:183], v[28:31]
	v_mfma_f32_16x16x32_bf16 v[24:27], v[140:143], v[180:183], v[24:27]
	v_mfma_f32_16x16x32_bf16 v[12:15], v[132:135], v[188:191], v[12:15]
	v_mfma_f32_16x16x32_bf16 v[8:11], v[140:143], v[188:191], v[8:11]
	s_setprio 0
	s_barrier
	s_add_u32 s38, s82, 0x1fff80
	s_addc_u32 s39, s83, 0
	s_add_i32 s40, s41, s7
	s_mov_b32 m0, s40
	s_nop 0
	global_load_lds_dwordx4 v146, s[38:39]
	s_add_i32 m0, s40, 0x2000
	s_nop 0
	global_load_lds_dwordx4 v150, s[38:39]
	v_add_u32_e32 v140, s22, v173
	ds_read_b128 v[128:131], v140
	ds_read_b128 v[132:135], v140 offset:1024
	ds_read_b128 v[136:139], v140 offset:2048
	ds_read_b128 v[140:143], v140 offset:3072
	s_waitcnt vmcnt(6)
	s_barrier
	s_setprio 1
	v_mfma_f32_16x16x32_bf16 v[52:55], v[192:195], v[156:159], v[52:55]
	v_mfma_f32_16x16x32_bf16 v[48:51], v[200:203], v[156:159], v[48:51]
	v_mfma_f32_16x16x32_bf16 v[36:39], v[192:195], v[164:167], v[36:39]
	v_mfma_f32_16x16x32_bf16 v[32:35], v[200:203], v[164:167], v[32:35]
	v_mfma_f32_16x16x32_bf16 v[20:23], v[192:195], v[176:179], v[20:23]
	v_mfma_f32_16x16x32_bf16 v[16:19], v[200:203], v[176:179], v[16:19]
	v_mfma_f32_16x16x32_bf16 v[4:7], v[192:195], v[184:187], v[4:7]
	v_mfma_f32_16x16x32_bf16 v[0:3], v[200:203], v[184:187], v[0:3]
	v_mfma_f32_16x16x32_bf16 v[52:55], v[196:199], v[160:163], v[52:55]
	v_mfma_f32_16x16x32_bf16 v[48:51], v[204:207], v[160:163], v[48:51]
	v_mfma_f32_16x16x32_bf16 v[36:39], v[196:199], v[168:171], v[36:39]
	v_mfma_f32_16x16x32_bf16 v[32:35], v[204:207], v[168:171], v[32:35]
	v_mfma_f32_16x16x32_bf16 v[20:23], v[196:199], v[180:183], v[20:23]
	v_mfma_f32_16x16x32_bf16 v[16:19], v[204:207], v[180:183], v[16:19]
	v_mfma_f32_16x16x32_bf16 v[4:7], v[196:199], v[188:191], v[4:7]
	v_mfma_f32_16x16x32_bf16 v[0:3], v[204:207], v[188:191], v[0:3]
	s_setprio 0
	s_waitcnt lgkmcnt(0)
	s_cmpk_gt_u32 s35, 0x7d
	s_mov_b32 s35, s80
	s_barrier
	s_cbranch_scc1 .LBB0_610

; #define PG8_STAGE(bufoff, gbase, voff) do { _Pragma("unroll") for (int _i = 0; _i < 2; ++_i) \
;         __builtin_amdgcn_global_load_lds((const unsigned*)((const char*)(gbase) + (voff)[_i]), (LAS unsigned*)(lds + (bufoff) + ldsw + _i * 8192), 16, 0, 0); } while (0)
; #define PG8_LDA(dst, b, h) do { _Pragma("unroll") for (int m = 0; m < 4; ++m) _Pragma("unroll") for (int k = 0; k < 2; ++k) dst[m][k] = *(const LAS bf16x8*)(lds + PG8_SA(b, h) + aoff + m * 2048 + k * 1024); } while (0)
; #define PG8_LDB(dst, b, h) do { _Pragma("unroll") for (int n = 0; n < 2; ++n) _Pragma("unroll") for (int k = 0; k < 2; ++k) dst[n][k] = *(const LAS bf16x8*)(lds + PG8_SB(b, h) + boff + n * 2048 + k * 1024); } while (0)
; #define PG8_MMA(ai, bj, At, Bt) do { __builtin_amdgcn_s_setprio(1); _Pragma("unroll") for (int m = 0; m < 4; ++m) _Pragma("unroll") for (int n = 0; n < 2; ++n) _Pragma("unroll") for (int k = 0; k < 2; ++k) \
;         acc[ai][bj][m][n] = __builtin_amdgcn_mfma_f32_16x16x32_bf16(Bt[n][k], At[m][k], acc[ai][bj][m][n], 0, 0, 0); __builtin_amdgcn_s_setprio(0); } while (0)
; #define PG8_WAIT_L(n) asm volatile("s_waitcnt lgkmcnt(" #n ")" ::: "memory")
; #define PG8_BAR __builtin_amdgcn_s_barrier()
; #define PG8_SCHED __builtin_amdgcn_sched_barrier(0)
; template <class Epi>
; __device__ __forceinline__ void gemm_phase(LAS unsigned char* lds, const Gemm g, const StaticOrder& S, const Epi& E, int wv) {
;     ...
;         const bool has_next = S.next(ui + 1, nxt);
;         const char* nA = has_next ? (const char*)g.A + (size_t)nxt.pm * tstepA + ((g.adiag & 1) ? (size_t)(nxt.pn >> 1) * K * 2 : 0) + kbeg : cA;
;         const char* nB = has_next ? (const char*)g.Bt + (size_t)nxt.pn * tstepB + kbeg : cB;
;         for (int t = 0; t < nt; t += 2) {
;             const bool last = (t == nt - 2);
;             const char* a1 = cA + (ptrdiff_t)(t + 1) * kstep;
;             const char* a2 = last ? nA : cA + (ptrdiff_t)(t + 2) * kstep; const char* b2 = last ? nB : cB + (ptrdiff_t)(t + 2) * kstep;
;             const char* a3 = a2 + kstep; const char* b3 = b2 + kstep;
;             PG8_LDB(B0, 0, 0); PG8_SCHED; PG8_LDA(At, 0, 0); PG8_STAGE(PG8_SA(1, 1), a1 + hstepA, voffA);
;             PG8_WAIT_L(8); PG8_BAR; PG8_WAIT_L(0); PG8_MMA(0, 0, At, B0); PG8_BAR; PG8_SCHED;
.LBB0_716:
	s_ashr_i32 s65, s64, 31
	s_lshl_b64 s[34:35], s[64:65], 20
	v_cmp_lt_i64_e32 vcc, s[66:67], v[172:173]
	s_add_u32 s66, s5, s34
	s_addc_u32 s67, s6, s35
	s_and_b64 s[34:35], vcc, exec
	s_cselect_b32 s33, s67, s77
	s_cselect_b32 s34, s66, s76
	s_ashr_i32 s63, s62, 31
	s_lshl_b64 s[38:39], s[62:63], 20
	s_add_u32 s68, s7, s38
	s_addc_u32 s69, s8, s39
	s_and_b64 s[38:39], vcc, exec
	s_cselect_b32 s35, s69, s75
	s_cselect_b32 s38, s68, s74
	s_add_u32 s39, s74, 0x100
	s_addc_u32 s40, s75, 0
	s_add_u32 s74, s76, 0x80080
	v_mov_b32_e32 v0, 0
	s_addc_u32 s75, s77, 0
	s_mov_b32 s41, -2
	s_waitcnt lgkmcnt(0)
	v_mov_b32_e32 v1, v0
	v_mov_b32_e32 v2, v0
	v_mov_b32_e32 v3, v0
	v_mov_b32_e32 v4, v0
	v_mov_b32_e32 v5, v0
	v_mov_b32_e32 v6, v0
	v_mov_b32_e32 v7, v0
	v_mov_b32_e32 v16, v0
	v_mov_b32_e32 v17, v0
	v_mov_b32_e32 v18, v0
	v_mov_b32_e32 v19, v0
	v_mov_b32_e32 v20, v0
	v_mov_b32_e32 v21, v0
	v_mov_b32_e32 v22, v0
	v_mov_b32_e32 v23, v0
	v_mov_b32_e32 v32, v0
	v_mov_b32_e32 v33, v0
	v_mov_b32_e32 v34, v0
	v_mov_b32_e32 v35, v0
	v_mov_b32_e32 v36, v0
	v_mov_b32_e32 v37, v0
	v_mov_b32_e32 v38, v0
	v_mov_b32_e32 v39, v0
	v_mov_b32_e32 v48, v0
	v_mov_b32_e32 v49, v0
	v_mov_b32_e32 v50, v0
	v_mov_b32_e32 v51, v0
	v_mov_b32_e32 v52, v0
	v_mov_b32_e32 v53, v0
	v_mov_b32_e32 v54, v0
	v_mov_b32_e32 v55, v0
	v_mov_b32_e32 v8, v0
	v_mov_b32_e32 v9, v0
	v_mov_b32_e32 v10, v0
	v_mov_b32_e32 v11, v0
	v_mov_b32_e32 v12, v0
	v_mov_b32_e32 v13, v0
	v_mov_b32_e32 v14, v0
	v_mov_b32_e32 v15, v0
	v_mov_b32_e32 v24, v0
	v_mov_b32_e32 v25, v0
	v_mov_b32_e32 v26, v0
	v_mov_b32_e32 v27, v0
	v_mov_b32_e32 v28, v0
	v_mov_b32_e32 v29, v0
	v_mov_b32_e32 v30, v0
	v_mov_b32_e32 v31, v0
	v_mov_b32_e32 v40, v0
	v_mov_b32_e32 v41, v0
	v_mov_b32_e32 v42, v0
	v_mov_b32_e32 v43, v0
	v_mov_b32_e32 v44, v0
	v_mov_b32_e32 v45, v0
	v_mov_b32_e32 v46, v0
	v_mov_b32_e32 v47, v0
	v_mov_b32_e32 v56, v0
	v_mov_b32_e32 v57, v0
	v_mov_b32_e32 v58, v0
	v_mov_b32_e32 v59, v0
	v_mov_b32_e32 v60, v0
	v_mov_b32_e32 v61, v0
	v_mov_b32_e32 v62, v0
	v_mov_b32_e32 v63, v0
	v_mov_b32_e32 v64, v0
	v_mov_b32_e32 v65, v0
	v_mov_b32_e32 v66, v0
	v_mov_b32_e32 v67, v0
	v_mov_b32_e32 v68, v0
	v_mov_b32_e32 v69, v0
	v_mov_b32_e32 v70, v0
	v_mov_b32_e32 v71, v0
	v_mov_b32_e32 v80, v0
	v_mov_b32_e32 v81, v0
	v_mov_b32_e32 v82, v0
	v_mov_b32_e32 v83, v0
	v_mov_b32_e32 v84, v0
	v_mov_b32_e32 v85, v0
	v_mov_b32_e32 v86, v0
	v_mov_b32_e32 v87, v0
	v_mov_b32_e32 v96, v0
	v_mov_b32_e32 v97, v0
	v_mov_b32_e32 v98, v0
	v_mov_b32_e32 v99, v0
	v_mov_b32_e32 v100, v0
	v_mov_b32_e32 v101, v0
	v_mov_b32_e32 v102, v0
	v_mov_b32_e32 v103, v0
	v_mov_b32_e32 v112, v0
	v_mov_b32_e32 v113, v0
	v_mov_b32_e32 v114, v0
	v_mov_b32_e32 v115, v0
	v_mov_b32_e32 v116, v0
	v_mov_b32_e32 v117, v0
	v_mov_b32_e32 v118, v0
	v_mov_b32_e32 v119, v0
	v_mov_b32_e32 v72, v0
	v_mov_b32_e32 v73, v0
	v_mov_b32_e32 v74, v0
	v_mov_b32_e32 v75, v0
	v_mov_b32_e32 v76, v0
	v_mov_b32_e32 v77, v0
	v_mov_b32_e32 v78, v0
	v_mov_b32_e32 v79, v0
	v_mov_b32_e32 v88, v0
	v_mov_b32_e32 v89, v0
	v_mov_b32_e32 v90, v0
	v_mov_b32_e32 v91, v0
	v_mov_b32_e32 v92, v0
	v_mov_b32_e32 v93, v0
	v_mov_b32_e32 v94, v0
	v_mov_b32_e32 v95, v0
	v_mov_b32_e32 v104, v0
	v_mov_b32_e32 v105, v0
	v_mov_b32_e32 v106, v0
	v_mov_b32_e32 v107, v0
	v_mov_b32_e32 v108, v0
	v_mov_b32_e32 v109, v0
	v_mov_b32_e32 v110, v0
	v_mov_b32_e32 v111, v0
	v_mov_b32_e32 v120, v0
	v_mov_b32_e32 v121, v0
	v_mov_b32_e32 v122, v0
	v_mov_b32_e32 v123, v0
	v_mov_b32_e32 v124, v0
	v_mov_b32_e32 v125, v0
	v_mov_b32_e32 v126, v0
	v_mov_b32_e32 v127, v0
	ds_read_b128 v[128:131], v193
	ds_read_b128 v[132:135], v193 offset:1024
	ds_read_b128 v[136:139], v193 offset:2048
	ds_read_b128 v[140:143], v193 offset:3072
.LBB0_717:
	s_add_u32 s42, s74, 0xfff80080
	s_addc_u32 s43, s75, -1
	s_cmp_eq_u32 s41, 28
	s_cselect_b32 s79, s33, s43
	s_cselect_b32 s78, s34, s42
	s_cselect_b32 s77, s35, s40
	s_cselect_b32 s76, s38, s39
	s_add_i32 m0, s10, 0xc000
	ds_read_b128 v[144:147], v194
	ds_read_b128 v[148:151], v194 offset:1024
	ds_read_b128 v[152:155], v194 offset:2048
	ds_read_b128 v[156:159], v194 offset:3072
	ds_read_b128 v[176:179], v194 offset:4096
	ds_read_b128 v[180:183], v194 offset:5120
	ds_read_b128 v[184:187], v194 offset:6144
	ds_read_b128 v[198:201], v194 offset:7168
	global_load_lds_dwordx4 v170, s[74:75]
	s_add_i32 m0, s10, 0xe000
	s_nop 0
	global_load_lds_dwordx4 v168, s[74:75]
	s_waitcnt lgkmcnt(8)
	s_barrier
	s_waitcnt lgkmcnt(0)
	s_setprio 1
	s_waitcnt lgkmcnt(0)
	v_mfma_f32_16x16x32_bf16 v[124:127], v[128:131], v[144:147], v[124:127]
	v_mfma_f32_16x16x32_bf16 v[120:123], v[136:139], v[144:147], v[120:123]
	v_mfma_f32_16x16x32_bf16 v[108:111], v[128:131], v[152:155], v[108:111]
	v_mfma_f32_16x16x32_bf16 v[104:107], v[136:139], v[152:155], v[104:107]
	v_mfma_f32_16x16x32_bf16 v[92:95], v[128:131], v[176:179], v[92:95]
	v_mfma_f32_16x16x32_bf16 v[88:91], v[136:139], v[176:179], v[88:91]
	v_mfma_f32_16x16x32_bf16 v[76:79], v[128:131], v[184:187], v[76:79]
	v_mfma_f32_16x16x32_bf16 v[72:75], v[136:139], v[184:187], v[72:75]
	v_mfma_f32_16x16x32_bf16 v[124:127], v[132:135], v[148:151], v[124:127]
	v_mfma_f32_16x16x32_bf16 v[120:123], v[140:143], v[148:151], v[120:123]
	v_mfma_f32_16x16x32_bf16 v[108:111], v[132:135], v[156:159], v[108:111]
	v_mfma_f32_16x16x32_bf16 v[104:107], v[140:143], v[156:159], v[104:107]
	v_mfma_f32_16x16x32_bf16 v[92:95], v[132:135], v[180:183], v[92:95]
	v_mfma_f32_16x16x32_bf16 v[88:91], v[140:143], v[180:183], v[88:91]
	v_mfma_f32_16x16x32_bf16 v[76:79], v[132:135], v[198:201], v[76:79]
	v_mfma_f32_16x16x32_bf16 v[72:75], v[140:143], v[198:201], v[72:75]
	s_setprio 0
	s_barrier
; #define PG8_STAGE(bufoff, gbase, voff) do { _Pragma("unroll") for (int _i = 0; _i < 2; ++_i) \
;         __builtin_amdgcn_global_load_lds((const unsigned*)((const char*)(gbase) + (voff)[_i]), (LAS unsigned*)(lds + (bufoff) + ldsw + _i * 8192), 16, 0, 0); } while (0)
; #define PG8_LDA(dst, b, h) do { _Pragma("unroll") for (int m = 0; m < 4; ++m) _Pragma("unroll") for (int k = 0; k < 2; ++k) dst[m][k] = *(const LAS bf16x8*)(lds + PG8_SA(b, h) + aoff + m * 2048 + k * 1024); } while (0)
; #define PG8_LDB(dst, b, h) do { _Pragma("unroll") for (int n = 0; n < 2; ++n) _Pragma("unroll") for (int k = 0; k < 2; ++k) dst[n][k] = *(const LAS bf16x8*)(lds + PG8_SB(b, h) + boff + n * 2048 + k * 1024); } while (0)
; #define PG8_MMA(ai, bj, At, Bt) do { __builtin_amdgcn_s_setprio(1); _Pragma("unroll") for (int m = 0; m < 4; ++m) _Pragma("unroll") for (int n = 0; n < 2; ++n) _Pragma("unroll") for (int k = 0; k < 2; ++k) \
;         acc[ai][bj][m][n] = __builtin_amdgcn_mfma_f32_16x16x32_bf16(Bt[n][k], At[m][k], acc[ai][bj][m][n], 0, 0, 0); __builtin_amdgcn_s_setprio(0); } while (0)
; #define PG8_WAIT_V(n) asm volatile("s_waitcnt vmcnt(" #n ")" ::: "memory")
; #define PG8_WAIT_L(n) asm volatile("s_waitcnt lgkmcnt(" #n ")" ::: "memory")
; #define PG8_BAR __builtin_amdgcn_s_barrier()
; #define PG8_SCHED __builtin_amdgcn_sched_barrier(0)
; template <class Epi>
; __device__ __forceinline__ void gemm_phase(LAS unsigned char* lds, const Gemm g, const StaticOrder& S, const Epi& E, int wv) {
;     ...
;             PG8_LDB(B1, 0, 1); PG8_STAGE(PG8_SB(0, 0), b2, voffB);
;             PG8_BAR; PG8_WAIT_L(0); PG8_MMA(0, 1, At, B1); PG8_BAR;
;             PG8_LDA(At, 0, 1); PG8_STAGE(PG8_SA(0, 0), a2, voffA);
;             PG8_BAR; PG8_WAIT_L(0); PG8_MMA(1, 0, At, B0); PG8_BAR; PG8_SCHED;
;             PG8_STAGE(PG8_SB(0, 1), b2 + hstepB, voffB);
;             PG8_WAIT_V(6); PG8_BAR; PG8_MMA(1, 1, At, B1); PG8_BAR;
;             PG8_LDB(B0, 1, 0); PG8_SCHED; PG8_LDA(At, 1, 0); PG8_STAGE(PG8_SA(0, 1), a2 + hstepA, voffA);
	s_add_i32 s42, s23, s9
	s_add_u32 s98, s76, s60
	s_addc_u32 s99, s77, s61
	s_mov_b32 m0, s42
	ds_read_b128 v[202:205], v195
	ds_read_b128 v[206:209], v195 offset:1024
	ds_read_b128 v[210:213], v195 offset:2048
	ds_read_b128 v[214:217], v195 offset:3072
	global_load_lds_dwordx4 v162, s[76:77]
	s_add_i32 m0, s42, 0x2000
	s_nop 0
	global_load_lds_dwordx4 v166, s[76:77]
	s_barrier
	s_waitcnt lgkmcnt(0)
	s_setprio 1
	s_waitcnt lgkmcnt(0)
	v_mfma_f32_16x16x32_bf16 v[116:119], v[202:205], v[144:147], v[116:119]
	v_mfma_f32_16x16x32_bf16 v[112:115], v[210:213], v[144:147], v[112:115]
	v_mfma_f32_16x16x32_bf16 v[100:103], v[202:205], v[152:155], v[100:103]
	v_mfma_f32_16x16x32_bf16 v[96:99], v[210:213], v[152:155], v[96:99]
	v_mfma_f32_16x16x32_bf16 v[84:87], v[202:205], v[176:179], v[84:87]
	v_mfma_f32_16x16x32_bf16 v[80:83], v[210:213], v[176:179], v[80:83]
	v_mfma_f32_16x16x32_bf16 v[68:71], v[202:205], v[184:187], v[68:71]
	v_mfma_f32_16x16x32_bf16 v[64:67], v[210:213], v[184:187], v[64:67]
	v_mfma_f32_16x16x32_bf16 v[116:119], v[206:209], v[148:151], v[116:119]
	v_mfma_f32_16x16x32_bf16 v[112:115], v[214:217], v[148:151], v[112:115]
	v_mfma_f32_16x16x32_bf16 v[100:103], v[206:209], v[156:159], v[100:103]
	v_mfma_f32_16x16x32_bf16 v[96:99], v[214:217], v[156:159], v[96:99]
	v_mfma_f32_16x16x32_bf16 v[84:87], v[206:209], v[180:183], v[84:87]
	v_mfma_f32_16x16x32_bf16 v[80:83], v[214:217], v[180:183], v[80:83]
	v_mfma_f32_16x16x32_bf16 v[68:71], v[206:209], v[198:201], v[68:71]
	v_mfma_f32_16x16x32_bf16 v[64:67], v[214:217], v[198:201], v[64:67]
	s_setprio 0
	s_mov_b32 m0, s10
	s_add_u32 s100, s78, s60
	s_addc_u32 s101, s79, s61
	s_barrier
	ds_read_b128 v[144:147], v194 offset:16384
	ds_read_b128 v[148:151], v194 offset:17408
	ds_read_b128 v[152:155], v194 offset:18432
	ds_read_b128 v[156:159], v194 offset:19456
	ds_read_b128 v[176:179], v194 offset:20480
	ds_read_b128 v[180:183], v194 offset:21504
	ds_read_b128 v[184:187], v194 offset:22528
	ds_read_b128 v[198:201], v194 offset:23552
	global_load_lds_dwordx4 v160, s[78:79]
	s_mov_b32 m0, s11
	s_nop 0
	global_load_lds_dwordx4 v164, s[78:79]
	s_waitcnt vmcnt(10)
	s_barrier
	s_waitcnt lgkmcnt(0)
	s_setprio 1
	s_waitcnt lgkmcnt(0)
	v_mfma_f32_16x16x32_bf16 v[60:63], v[128:131], v[144:147], v[60:63]
	v_mfma_f32_16x16x32_bf16 v[56:59], v[136:139], v[144:147], v[56:59]
	v_mfma_f32_16x16x32_bf16 v[44:47], v[128:131], v[152:155], v[44:47]
	v_mfma_f32_16x16x32_bf16 v[40:43], v[136:139], v[152:155], v[40:43]
	v_mfma_f32_16x16x32_bf16 v[28:31], v[128:131], v[176:179], v[28:31]
	v_mfma_f32_16x16x32_bf16 v[24:27], v[136:139], v[176:179], v[24:27]
	v_mfma_f32_16x16x32_bf16 v[12:15], v[128:131], v[184:187], v[12:15]
	v_mfma_f32_16x16x32_bf16 v[8:11], v[136:139], v[184:187], v[8:11]
	v_mfma_f32_16x16x32_bf16 v[60:63], v[132:135], v[148:151], v[60:63]
	v_mfma_f32_16x16x32_bf16 v[56:59], v[140:143], v[148:151], v[56:59]
	v_mfma_f32_16x16x32_bf16 v[44:47], v[132:135], v[156:159], v[44:47]
	v_mfma_f32_16x16x32_bf16 v[40:43], v[140:143], v[156:159], v[40:43]
	v_mfma_f32_16x16x32_bf16 v[28:31], v[132:135], v[180:183], v[28:31]
	v_mfma_f32_16x16x32_bf16 v[24:27], v[140:143], v[180:183], v[24:27]
	v_mfma_f32_16x16x32_bf16 v[12:15], v[132:135], v[198:201], v[12:15]
	v_mfma_f32_16x16x32_bf16 v[8:11], v[140:143], v[198:201], v[8:11]
	s_setprio 0
	s_barrier
	s_add_u32 s42, s76, 0x80000
	s_addc_u32 s43, s77, 0
	s_add_i32 s44, s24, s9
	s_mov_b32 m0, s44
	s_nop 0
	global_load_lds_dwordx4 v162, s[42:43]
	s_add_i32 m0, s44, 0x2000
	s_nop 0
	global_load_lds_dwordx4 v166, s[42:43]
	s_add_i32 s44, 0, 0x18000
	v_add_u32_e32 v140, s44, v191
	ds_read_b128 v[128:131], v140
	ds_read_b128 v[132:135], v140 offset:1024
	ds_read_b128 v[136:139], v140 offset:2048
	ds_read_b128 v[140:143], v140 offset:3072
	s_waitcnt vmcnt(6)
	s_barrier
	s_setprio 1
	v_mfma_f32_16x16x32_bf16 v[52:55], v[202:205], v[144:147], v[52:55]
	v_mfma_f32_16x16x32_bf16 v[48:51], v[210:213], v[144:147], v[48:51]
	v_mfma_f32_16x16x32_bf16 v[36:39], v[202:205], v[152:155], v[36:39]
	v_mfma_f32_16x16x32_bf16 v[32:35], v[210:213], v[152:155], v[32:35]
	v_mfma_f32_16x16x32_bf16 v[20:23], v[202:205], v[176:179], v[20:23]
	v_mfma_f32_16x16x32_bf16 v[16:19], v[210:213], v[176:179], v[16:19]
	v_mfma_f32_16x16x32_bf16 v[4:7], v[202:205], v[184:187], v[4:7]
	v_mfma_f32_16x16x32_bf16 v[0:3], v[210:213], v[184:187], v[0:3]
	v_mfma_f32_16x16x32_bf16 v[52:55], v[206:209], v[148:151], v[52:55]
	v_mfma_f32_16x16x32_bf16 v[48:51], v[214:217], v[148:151], v[48:51]
	v_mfma_f32_16x16x32_bf16 v[36:39], v[206:209], v[156:159], v[36:39]
	v_mfma_f32_16x16x32_bf16 v[32:35], v[214:217], v[156:159], v[32:35]
	v_mfma_f32_16x16x32_bf16 v[20:23], v[206:209], v[180:183], v[20:23]
	v_mfma_f32_16x16x32_bf16 v[16:19], v[214:217], v[180:183], v[16:19]
	v_mfma_f32_16x16x32_bf16 v[4:7], v[206:209], v[198:201], v[4:7]
	v_mfma_f32_16x16x32_bf16 v[0:3], v[214:217], v[198:201], v[0:3]
	s_setprio 0
	s_waitcnt lgkmcnt(0)
	s_barrier
	s_add_u32 s42, s78, 0x80000
	s_addc_u32 s43, s79, 0
	s_mov_b32 m0, s12
	ds_read_b128 v[144:147], v194 offset:32768
	ds_read_b128 v[148:151], v194 offset:33792
	ds_read_b128 v[152:155], v194 offset:34816
	ds_read_b128 v[156:159], v194 offset:35840
	ds_read_b128 v[176:179], v194 offset:36864
	ds_read_b128 v[180:183], v194 offset:37888
	ds_read_b128 v[184:187], v194 offset:38912
	ds_read_b128 v[198:201], v194 offset:39936
	global_load_lds_dwordx4 v160, s[42:43]
	s_mov_b32 m0, s13
	s_nop 0
	global_load_lds_dwordx4 v164, s[42:43]
	s_waitcnt lgkmcnt(8)
	s_barrier
; #define PG8_STAGE(bufoff, gbase, voff) do { _Pragma("unroll") for (int _i = 0; _i < 2; ++_i) \
;         __builtin_amdgcn_global_load_lds((const unsigned*)((const char*)(gbase) + (voff)[_i]), (LAS unsigned*)(lds + (bufoff) + ldsw + _i * 8192), 16, 0, 0); } while (0)
; #define PG8_LDA(dst, b, h) do { _Pragma("unroll") for (int m = 0; m < 4; ++m) _Pragma("unroll") for (int k = 0; k < 2; ++k) dst[m][k] = *(const LAS bf16x8*)(lds + PG8_SA(b, h) + aoff + m * 2048 + k * 1024); } while (0)
; #define PG8_LDB(dst, b, h) do { _Pragma("unroll") for (int n = 0; n < 2; ++n) _Pragma("unroll") for (int k = 0; k < 2; ++k) dst[n][k] = *(const LAS bf16x8*)(lds + PG8_SB(b, h) + boff + n * 2048 + k * 1024); } while (0)
; #define PG8_MMA(ai, bj, At, Bt) do { __builtin_amdgcn_s_setprio(1); _Pragma("unroll") for (int m = 0; m < 4; ++m) _Pragma("unroll") for (int n = 0; n < 2; ++n) _Pragma("unroll") for (int k = 0; k < 2; ++k) \
;         acc[ai][bj][m][n] = __builtin_amdgcn_mfma_f32_16x16x32_bf16(Bt[n][k], At[m][k], acc[ai][bj][m][n], 0, 0, 0); __builtin_amdgcn_s_setprio(0); } while (0)
; #define PG8_WAIT_V(n) asm volatile("s_waitcnt vmcnt(" #n ")" ::: "memory")
; #define PG8_WAIT_L(n) asm volatile("s_waitcnt lgkmcnt(" #n ")" ::: "memory")
; #define PG8_BAR __builtin_amdgcn_s_barrier()
; #define PG8_SCHED __builtin_amdgcn_sched_barrier(0)
; template <class Epi>
; __device__ __forceinline__ void gemm_phase(LAS unsigned char* lds, const Gemm g, const StaticOrder& S, const Epi& E, int wv) {
;     ...
;             PG8_WAIT_L(8); PG8_BAR; PG8_WAIT_L(0); PG8_MMA(0, 0, At, B0); PG8_BAR; PG8_SCHED;
;             PG8_LDB(B1, 1, 1); PG8_STAGE(PG8_SB(1, 0), b3, voffB);
;             PG8_BAR; PG8_WAIT_L(0); PG8_MMA(0, 1, At, B1); PG8_BAR;
;             PG8_LDA(At, 1, 1); PG8_STAGE(PG8_SA(1, 0), a3, voffA);
;             PG8_BAR; PG8_WAIT_L(0); PG8_MMA(1, 0, At, B0); PG8_BAR; PG8_SCHED;
;             PG8_STAGE(PG8_SB(1, 1), b3 + hstepB, voffB);
;             PG8_WAIT_V(6); PG8_BAR; PG8_MMA(1, 1, At, B1); PG8_BAR;
	s_waitcnt lgkmcnt(0)
	s_setprio 1
	s_waitcnt lgkmcnt(0)
	v_mfma_f32_16x16x32_bf16 v[124:127], v[128:131], v[144:147], v[124:127]
	v_mfma_f32_16x16x32_bf16 v[120:123], v[136:139], v[144:147], v[120:123]
	v_mfma_f32_16x16x32_bf16 v[108:111], v[128:131], v[152:155], v[108:111]
	v_mfma_f32_16x16x32_bf16 v[104:107], v[136:139], v[152:155], v[104:107]
	v_mfma_f32_16x16x32_bf16 v[92:95], v[128:131], v[176:179], v[92:95]
	v_mfma_f32_16x16x32_bf16 v[88:91], v[136:139], v[176:179], v[88:91]
	v_mfma_f32_16x16x32_bf16 v[76:79], v[128:131], v[184:187], v[76:79]
	v_mfma_f32_16x16x32_bf16 v[72:75], v[136:139], v[184:187], v[72:75]
	v_mfma_f32_16x16x32_bf16 v[124:127], v[132:135], v[148:151], v[124:127]
	v_mfma_f32_16x16x32_bf16 v[120:123], v[140:143], v[148:151], v[120:123]
	v_mfma_f32_16x16x32_bf16 v[108:111], v[132:135], v[156:159], v[108:111]
	v_mfma_f32_16x16x32_bf16 v[104:107], v[140:143], v[156:159], v[104:107]
	v_mfma_f32_16x16x32_bf16 v[92:95], v[132:135], v[180:183], v[92:95]
	v_mfma_f32_16x16x32_bf16 v[88:91], v[140:143], v[180:183], v[88:91]
	v_mfma_f32_16x16x32_bf16 v[76:79], v[132:135], v[198:201], v[76:79]
	v_mfma_f32_16x16x32_bf16 v[72:75], v[140:143], v[198:201], v[72:75]
	s_setprio 0
	s_barrier
	s_add_i32 s45, 0, 0x1c000
	s_add_i32 s42, s44, s9
	v_add_u32_e32 v197, s45, v191
	s_mov_b32 m0, s42
	ds_read_b128 v[202:205], v197
	ds_read_b128 v[206:209], v197 offset:1024
	ds_read_b128 v[210:213], v197 offset:2048
	ds_read_b128 v[214:217], v197 offset:3072
	global_load_lds_dwordx4 v162, s[98:99]
	s_add_i32 m0, s42, 0x2000
	s_nop 0
	global_load_lds_dwordx4 v166, s[98:99]
	s_barrier
	s_waitcnt lgkmcnt(0)
	s_setprio 1
	s_waitcnt lgkmcnt(0)
	v_mfma_f32_16x16x32_bf16 v[116:119], v[202:205], v[144:147], v[116:119]
	v_mfma_f32_16x16x32_bf16 v[112:115], v[210:213], v[144:147], v[112:115]
	v_mfma_f32_16x16x32_bf16 v[100:103], v[202:205], v[152:155], v[100:103]
	v_mfma_f32_16x16x32_bf16 v[96:99], v[210:213], v[152:155], v[96:99]
	v_mfma_f32_16x16x32_bf16 v[84:87], v[202:205], v[176:179], v[84:87]
	v_mfma_f32_16x16x32_bf16 v[80:83], v[210:213], v[176:179], v[80:83]
	v_mfma_f32_16x16x32_bf16 v[68:71], v[202:205], v[184:187], v[68:71]
	v_mfma_f32_16x16x32_bf16 v[64:67], v[210:213], v[184:187], v[64:67]
	v_mfma_f32_16x16x32_bf16 v[116:119], v[206:209], v[148:151], v[116:119]
	v_mfma_f32_16x16x32_bf16 v[112:115], v[214:217], v[148:151], v[112:115]
	v_mfma_f32_16x16x32_bf16 v[100:103], v[206:209], v[156:159], v[100:103]
	v_mfma_f32_16x16x32_bf16 v[96:99], v[214:217], v[156:159], v[96:99]
	v_mfma_f32_16x16x32_bf16 v[84:87], v[206:209], v[180:183], v[84:87]
	v_mfma_f32_16x16x32_bf16 v[80:83], v[214:217], v[180:183], v[80:83]
	v_mfma_f32_16x16x32_bf16 v[68:71], v[206:209], v[198:201], v[68:71]
	v_mfma_f32_16x16x32_bf16 v[64:67], v[214:217], v[198:201], v[64:67]
	s_setprio 0
	s_mov_b32 m0, s15
	s_barrier
	ds_read_b128 v[144:147], v194 offset:49152
	ds_read_b128 v[148:151], v194 offset:50176
	ds_read_b128 v[152:155], v194 offset:51200
	ds_read_b128 v[156:159], v194 offset:52224
	ds_read_b128 v[176:179], v194 offset:53248
	ds_read_b128 v[180:183], v194 offset:54272
	ds_read_b128 v[184:187], v194 offset:55296
	ds_read_b128 v[198:201], v194 offset:56320
	global_load_lds_dwordx4 v160, s[100:101]
	s_mov_b32 m0, s22
	s_nop 0
	global_load_lds_dwordx4 v164, s[100:101]
	s_waitcnt vmcnt(10)
	s_barrier
	s_waitcnt lgkmcnt(0)
	s_setprio 1
	s_waitcnt lgkmcnt(0)
	v_mfma_f32_16x16x32_bf16 v[60:63], v[128:131], v[144:147], v[60:63]
	v_mfma_f32_16x16x32_bf16 v[56:59], v[136:139], v[144:147], v[56:59]
	v_mfma_f32_16x16x32_bf16 v[44:47], v[128:131], v[152:155], v[44:47]
	v_mfma_f32_16x16x32_bf16 v[40:43], v[136:139], v[152:155], v[40:43]
	v_mfma_f32_16x16x32_bf16 v[28:31], v[128:131], v[176:179], v[28:31]
	v_mfma_f32_16x16x32_bf16 v[24:27], v[136:139], v[176:179], v[24:27]
	v_mfma_f32_16x16x32_bf16 v[12:15], v[128:131], v[184:187], v[12:15]
	v_mfma_f32_16x16x32_bf16 v[8:11], v[136:139], v[184:187], v[8:11]
	v_mfma_f32_16x16x32_bf16 v[60:63], v[132:135], v[148:151], v[60:63]
	v_mfma_f32_16x16x32_bf16 v[56:59], v[140:143], v[148:151], v[56:59]
	v_mfma_f32_16x16x32_bf16 v[44:47], v[132:135], v[156:159], v[44:47]
	v_mfma_f32_16x16x32_bf16 v[40:43], v[140:143], v[156:159], v[40:43]
	v_mfma_f32_16x16x32_bf16 v[28:31], v[132:135], v[180:183], v[28:31]
	v_mfma_f32_16x16x32_bf16 v[24:27], v[140:143], v[180:183], v[24:27]
	v_mfma_f32_16x16x32_bf16 v[12:15], v[132:135], v[198:201], v[12:15]
	v_mfma_f32_16x16x32_bf16 v[8:11], v[140:143], v[198:201], v[8:11]
	s_setprio 0
	s_barrier
	s_add_u32 s42, s76, 0x80080
	s_addc_u32 s43, s77, 0
	s_add_i32 s44, s45, s9
	s_mov_b32 m0, s44
	s_nop 0
	global_load_lds_dwordx4 v162, s[42:43]
	s_add_i32 m0, s44, 0x2000
	s_nop 0
	global_load_lds_dwordx4 v166, s[42:43]
	ds_read_b128 v[128:131], v193
	ds_read_b128 v[132:135], v193 offset:1024
	ds_read_b128 v[136:139], v193 offset:2048
	ds_read_b128 v[140:143], v193 offset:3072
	s_waitcnt vmcnt(6)
	s_barrier
	s_setprio 1
	v_mfma_f32_16x16x32_bf16 v[52:55], v[202:205], v[144:147], v[52:55]
	v_mfma_f32_16x16x32_bf16 v[48:51], v[210:213], v[144:147], v[48:51]
	v_mfma_f32_16x16x32_bf16 v[36:39], v[202:205], v[152:155], v[36:39]
	v_mfma_f32_16x16x32_bf16 v[32:35], v[210:213], v[152:155], v[32:35]
	v_mfma_f32_16x16x32_bf16 v[20:23], v[202:205], v[176:179], v[20:23]
	v_mfma_f32_16x16x32_bf16 v[16:19], v[210:213], v[176:179], v[16:19]
	v_mfma_f32_16x16x32_bf16 v[4:7], v[202:205], v[184:187], v[4:7]
	v_mfma_f32_16x16x32_bf16 v[0:3], v[210:213], v[184:187], v[0:3]
	v_mfma_f32_16x16x32_bf16 v[52:55], v[206:209], v[148:151], v[52:55]
	v_mfma_f32_16x16x32_bf16 v[48:51], v[214:217], v[148:151], v[48:51]
	v_mfma_f32_16x16x32_bf16 v[36:39], v[206:209], v[156:159], v[36:39]
	v_mfma_f32_16x16x32_bf16 v[32:35], v[214:217], v[156:159], v[32:35]
	v_mfma_f32_16x16x32_bf16 v[20:23], v[206:209], v[180:183], v[20:23]
	v_mfma_f32_16x16x32_bf16 v[16:19], v[214:217], v[180:183], v[16:19]
	v_mfma_f32_16x16x32_bf16 v[4:7], v[206:209], v[198:201], v[4:7]
	v_mfma_f32_16x16x32_bf16 v[0:3], v[214:217], v[198:201], v[0:3]
	s_setprio 0
	s_waitcnt lgkmcnt(0)
	s_add_i32 s41, s41, 2
	s_add_u32 s39, s39, 0x100
	s_addc_u32 s40, s40, 0
	s_add_u32 s74, s74, 0x100
	s_addc_u32 s75, s75, 0
	s_cmp_gt_u32 s41, 29
	s_barrier
;     __device__ __forceinline__ void operator()(const f32x4 (&acc)[2][2][4][2], const Unit& u, int wr, int wc, int fr, int fq) const {
;     ...
;         RES_LOAD(0, 0); RES_LOAD(1, 1);
	s_cbranch_scc0 .LBB0_717
	v_lshl_add_u32 v186, s70, 8, v190
	v_lshl_or_b32 v176, s72, 8, v192
	v_ashrrev_i32_e32 v187, 31, v186
	v_lshlrev_b64 v[128:129], 11, v[186:187]
	v_ashrrev_i32_e32 v177, 31, v176
	v_lshl_add_u64 v[128:129], v[128:129], 0, v[176:177]
	v_lshlrev_b64 v[178:179], 1, v[128:129]
	v_lshl_add_u64 v[180:181], v[186:187], 2, s[56:57]
	v_lshl_add_u64 v[128:129], s[58:59], 0, v[178:179]
	global_load_dword v199, v[180:181], off
	global_load_dwordx4 v[200:203], v[128:129], off
	v_or_b32_e32 v188, 16, v186
	v_or_b32_e32 v182, 32, v186
	v_ashrrev_i32_e32 v189, 31, v188
	v_ashrrev_i32_e32 v183, 31, v182
	v_lshl_add_u64 v[130:131], v[188:189], 2, s[56:57]
	v_lshlrev_b64 v[132:133], 11, v[182:183]
	v_lshl_add_u64 v[134:135], v[182:183], 2, s[56:57]
	global_load_dword v198, v[130:131], off
	global_load_dword v197, v[134:135], off
	v_lshl_add_u64 v[130:131], v[132:133], 0, v[176:177]
	v_lshl_add_u64 v[132:133], s[50:51], 0, v[178:179]
	global_load_dwordx4 v[204:207], v[132:133], off
	v_lshlrev_b64 v[128:129], 11, v[188:189]
	v_lshl_add_u64 v[128:129], v[128:129], 0, v[176:177]
	v_or_b32_e32 v132, 0x100, v178
	v_mov_b32_e32 v133, v179
	v_lshlrev_b64 v[128:129], 1, v[128:129]
	v_lshl_add_u64 v[134:135], s[50:51], 0, v[132:133]
	v_lshl_add_u64 v[132:133], s[58:59], 0, v[132:133]
	v_lshl_add_u64 v[136:137], s[50:51], 0, v[128:129]
	v_lshl_add_u64 v[138:139], s[58:59], 0, v[128:129]
	global_load_dwordx4 v[208:211], v[134:135], off
	global_load_dwordx4 v[212:215], v[132:133], off
	global_load_dwordx4 v[152:155], v[136:137], off
	global_load_dwordx4 v[156:159], v[138:139], off
	v_lshlrev_b64 v[130:131], 1, v[130:131]
	v_or_b32_e32 v128, 0x100, v128
	v_lshl_add_u64 v[140:141], s[50:51], 0, v[130:131]
	v_lshl_add_u64 v[142:143], s[58:59], 0, v[130:131]
	v_or_b32_e32 v130, 0x100, v130
	v_lshl_add_u64 v[132:133], s[50:51], 0, v[128:129]
	v_lshl_add_u64 v[128:129], s[58:59], 0, v[128:129]
	v_lshl_add_u64 v[134:135], s[50:51], 0, v[130:131]
	global_load_dwordx4 v[136:139], v[140:141], off
	s_nop 0
	global_load_dwordx4 v[140:143], v[142:143], off
	v_lshl_add_u64 v[216:217], s[58:59], 0, v[130:131]
	global_load_dwordx4 v[144:147], v[132:133], off
	global_load_dwordx4 v[148:151], v[128:129], off
	s_nop 0
	global_load_dwordx4 v[128:131], v[134:135], off
	s_nop 0
	global_load_dwordx4 v[132:135], v[216:217], off
	v_lshlrev_b64 v[184:185], 12, v[186:187]
	s_waitcnt vmcnt(0)
; __device__ __forceinline__ float bf_lo(unsigned w) { return __uint_as_float(w << 16); }
; __device__ __forceinline__ float bf_hi(unsigned w) { return __uint_as_float(w & 0xffff0000u); }
; __device__ __forceinline__ float fast_sigmoid(float x) { return __builtin_amdgcn_rcpf(1.0f + __builtin_amdgcn_exp2f(-x * LOG2E)); }
;     __device__ __forceinline__ void operator()(const f32x4 (&acc)[2][2][4][2], const Unit& u, int wr, int wc, int fr, int fq) const {
;     ...
;             const int row = row0 + ai * HALF + m * 16; const size_t ro = (size_t)row * DM + col0;
;             float rs = 1.0f; if (MODE == 1) rs = __builtin_amdgcn_rsqf(ss_fix(rsb[sc]) * (1.0f / DM) + EPS);
;             float sq = 0.f;
; #pragma unroll
;             for (int bj = 0; bj < 2; ++bj) { const size_t off = ro + bj * HALF;
;                 f32x4 v0 = acc[ai][bj][m][0], v1 = acc[ai][bj][m][1];
;                 if (MODE == 1) { const u32x4 pw = pbuf[sc][bj];
;                     v0[0] = fast_sigmoid(rs * v0[0]) * bf_lo(pw.x); v0[1] = fast_sigmoid(rs * v0[1]) * bf_hi(pw.x); v0[2] = fast_sigmoid(rs * v0[2]) * bf_lo(pw.y); v0[3] = fast_sigmoid(rs * v0[3]) * bf_hi(pw.y);
;                     v1[0] = fast_sigmoid(rs * v1[0]) * bf_lo(pw.z); v1[1] = fast_sigmoid(rs * v1[1]) * bf_hi(pw.z); v1[2] = fast_sigmoid(rs * v1[2]) * bf_lo(pw.w); v1[3] = fast_sigmoid(rs * v1[3]) * bf_hi(pw.w); }
;                 f32x4 h0, h1;
;                 if (IN16) { const u32x4 hw = hraw[sc][bj]; h0 = (f32x4){bf_lo(hw.x), bf_hi(hw.x), bf_lo(hw.y), bf_hi(hw.y)}; h1 = (f32x4){bf_lo(hw.z), bf_hi(hw.z), bf_lo(hw.w), bf_hi(hw.w)}; }
;                 else { h0 = hbuf[sc][2 * bj]; h1 = hbuf[sc][2 * bj + 1]; }
;                 const f32x4 o0 = h0 + v0, o1 = h1 + v1;
;                 if (OUT32) { *(f32x4*)(hout + off) = o0; *(f32x4*)(hout + off + 4) = o1; }
;                 if (hb) { u32x4 w; w.x = pk_bf16(o0[0], o0[1]); w.y = pk_bf16(o0[2], o0[3]); w.z = pk_bf16(o1[0], o1[1]); w.w = pk_bf16(o1[2], o1[3]); *(u32x4*)(hb + off) = w; }
;                 sq += ((o0[0] * o0[0] + o0[1] * o0[1]) + (o0[2] * o0[2] + o0[3] * o0[3])) + ((o1[0] * o1[0] + o1[1] * o1[1]) + (o1[2] * o1[2] + o1[3] * o1[3])); }
;             if (ss_out) { sq += __shfl_xor(sq, 16); sq += __shfl_xor(sq, 32); if (fq == 0) atomicAdd((unsigned*)(ss_out + row), ss_enc(sq)); }
	v_cvt_f32_u32_e32 v199, v199
	v_lshlrev_b32_e32 v218, 16, v202
	v_and_b32_e32 v219, 0xffff0000, v202
	v_lshlrev_b32_e32 v216, 16, v200
	v_mul_f32_e32 v199, 0x3b800000, v199
	v_fmamk_f32 v199, v199, 0x3a000000, v196
	v_rsq_f32_e32 v199, v199
	v_and_b32_e32 v217, 0xffff0000, v200
	v_lshlrev_b32_e32 v200, 16, v201
	v_and_b32_e32 v201, 0xffff0000, v201
	v_mul_f32_e32 v124, v124, v199
	v_mul_f32_e32 v125, v125, v199
	v_mul_f32_e32 v126, v126, v199
	v_mul_f32_e32 v127, v127, v199
	v_mul_f32_e32 v120, v120, v199
	v_mul_f32_e32 v121, v121, v199
	v_mul_f32_e32 v122, v122, v199
	v_mul_f32_e32 v123, v123, v199
	v_mul_f32_e32 v124, 0xbfb8aa3b, v124
	v_mul_f32_e32 v125, 0xbfb8aa3b, v125
	v_mul_f32_e32 v126, 0xbfb8aa3b, v126
	v_mul_f32_e32 v127, 0xbfb8aa3b, v127
	v_mul_f32_e32 v120, 0xbfb8aa3b, v120
	v_mul_f32_e32 v121, 0xbfb8aa3b, v121
	v_mul_f32_e32 v122, 0xbfb8aa3b, v122
	v_mul_f32_e32 v123, 0xbfb8aa3b, v123
	v_exp_f32_e32 v124, v124
	v_exp_f32_e32 v125, v125
	v_exp_f32_e32 v126, v126
	v_exp_f32_e32 v127, v127
	v_exp_f32_e32 v120, v120
	v_exp_f32_e32 v121, v121
	v_exp_f32_e32 v122, v122
	v_exp_f32_e32 v202, v123
	v_add_f32_e32 v123, 1.0, v124
	v_add_f32_e32 v124, 1.0, v125
	v_add_f32_e32 v125, 1.0, v126
	v_add_f32_e32 v126, 1.0, v127
	v_add_f32_e32 v127, 1.0, v120
	v_add_f32_e32 v220, 1.0, v121
	v_mul_f32_e32 v116, v116, v199
	v_mul_f32_e32 v117, v117, v199
	v_mul_f32_e32 v118, v118, v199
	v_mul_f32_e32 v119, v119, v199
	v_add_f32_e32 v221, 1.0, v122
	v_rcp_f32_e32 v121, v124
	v_rcp_f32_e32 v122, v125
	v_rcp_f32_e32 v124, v127
	v_rcp_f32_e32 v125, v220
	v_add_f32_e32 v127, 1.0, v202
	v_mul_f32_e32 v116, 0xbfb8aa3b, v116
	v_mul_f32_e32 v117, 0xbfb8aa3b, v117
	v_mul_f32_e32 v118, 0xbfb8aa3b, v118
	v_mul_f32_e32 v119, 0xbfb8aa3b, v119
	v_mul_f32_e32 v112, v112, v199
	v_mul_f32_e32 v113, v113, v199
	v_rcp_f32_e32 v120, v123
	v_rcp_f32_e32 v123, v126
	v_rcp_f32_e32 v126, v221
	v_rcp_f32_e32 v127, v127
	v_exp_f32_e32 v116, v116
	v_exp_f32_e32 v117, v117
	v_exp_f32_e32 v118, v118
	v_exp_f32_e32 v119, v119
	v_mul_f32_e32 v112, 0xbfb8aa3b, v112
	v_mul_f32_e32 v113, 0xbfb8aa3b, v113
	v_mul_f32_e32 v114, v114, v199
	v_mul_f32_e32 v115, v115, v199
	v_exp_f32_e32 v112, v112
	v_exp_f32_e32 v113, v113
	v_mul_f32_e32 v114, 0xbfb8aa3b, v114
	v_mul_f32_e32 v115, 0xbfb8aa3b, v115
	v_lshlrev_b32_e32 v222, 16, v206
	v_and_b32_e32 v223, 0xffff0000, v206
	v_exp_f32_e32 v114, v114
	v_exp_f32_e32 v115, v115
	v_lshlrev_b32_e32 v202, 16, v203
	v_and_b32_e32 v203, 0xffff0000, v203
	v_lshlrev_b32_e32 v220, 16, v204
	v_and_b32_e32 v221, 0xffff0000, v204
	v_lshlrev_b32_e32 v204, 16, v205
	v_and_b32_e32 v205, 0xffff0000, v205
	v_lshlrev_b32_e32 v206, 16, v207
	v_and_b32_e32 v207, 0xffff0000, v207
	v_pk_fma_f32 v[124:125], v[124:125], v[218:219], v[222:223]
	v_pk_fma_f32 v[200:201], v[122:123], v[200:201], v[204:205]
	v_pk_fma_f32 v[204:205], v[120:121], v[216:217], v[220:221]
	v_pk_fma_f32 v[126:127], v[126:127], v[202:203], v[206:207]
	v_cvt_pk_bf16_f32 v122, v124, v125
	v_mul_f32_e32 v125, v125, v125
	v_add_f32_e32 v116, 1.0, v116
	v_add_f32_e32 v117, 1.0, v117
	v_add_f32_e32 v118, 1.0, v118
	v_add_f32_e32 v119, 1.0, v119
	v_cvt_pk_bf16_f32 v121, v200, v201
	v_mul_f32_e32 v202, v205, v205
	v_mul_f32_e32 v201, v201, v201
	v_fmac_f32_e32 v125, v124, v124
	v_mul_f32_e32 v124, v127, v127
	v_rcp_f32_e32 v116, v116
	v_rcp_f32_e32 v117, v117
	v_rcp_f32_e32 v118, v118
	v_rcp_f32_e32 v119, v119
	v_add_f32_e32 v112, 1.0, v112
	v_add_f32_e32 v113, 1.0, v113
	v_fmac_f32_e32 v202, v204, v204
	v_fmac_f32_e32 v201, v200, v200
	v_fmac_f32_e32 v124, v126, v126
	v_rcp_f32_e32 v112, v112
	v_rcp_f32_e32 v113, v113
	v_add_f32_e32 v114, 1.0, v114
	v_add_f32_e32 v115, 1.0, v115
	v_add_f32_e32 v200, v202, v201
	v_add_f32_e32 v124, v125, v124
	v_rcp_f32_e32 v114, v114
	v_rcp_f32_e32 v115, v115
	v_cvt_pk_bf16_f32 v120, v204, v205
	v_cvt_pk_bf16_f32 v123, v126, v127
	v_add_f32_e32 v216, v200, v124
	v_lshlrev_b32_e32 v124, 16, v212
	v_and_b32_e32 v125, 0xffff0000, v212
	v_lshlrev_b32_e32 v126, 16, v213
	v_and_b32_e32 v127, 0xffff0000, v213
	v_lshlrev_b32_e32 v204, 16, v208
	v_and_b32_e32 v205, 0xffff0000, v208
	v_lshlrev_b32_e32 v206, 16, v209
	v_and_b32_e32 v207, 0xffff0000, v209
	v_lshlrev_b32_e32 v200, 16, v214
	v_and_b32_e32 v201, 0xffff0000, v214
	v_lshlrev_b32_e32 v208, 16, v210
	v_and_b32_e32 v209, 0xffff0000, v210
	v_pk_fma_f32 v[118:119], v[118:119], v[126:127], v[206:207]
	v_pk_fma_f32 v[116:117], v[116:117], v[124:125], v[204:205]
	v_lshlrev_b32_e32 v202, 16, v215
	v_and_b32_e32 v203, 0xffff0000, v215
	v_lshlrev_b32_e32 v210, 16, v211
	v_and_b32_e32 v211, 0xffff0000, v211
	v_pk_fma_f32 v[126:127], v[112:113], v[200:201], v[208:209]
	v_mul_f32_e32 v112, v117, v117
	v_mul_f32_e32 v113, v119, v119
	v_pk_fma_f32 v[124:125], v[114:115], v[202:203], v[210:211]
	v_fmac_f32_e32 v112, v116, v116
	v_fmac_f32_e32 v113, v118, v118
	v_add_f32_e32 v112, v112, v113
	v_mul_f32_e32 v113, v127, v127
	v_mul_f32_e32 v114, v125, v125
	v_fmac_f32_e32 v113, v126, v126
	v_fmac_f32_e32 v114, v124, v124
	v_add_f32_e32 v113, v113, v114
	v_add_f32_e32 v112, v112, v113
	v_add_f32_e32 v115, v216, v112
	ds_bpermute_b32 v199, v245, v115
	v_lshl_add_u64 v[112:113], s[52:53], 0, v[184:185]
	v_lshl_add_u64 v[184:185], v[176:177], 1, v[112:113]
	v_cvt_pk_bf16_f32 v114, v116, v117
	v_cvt_pk_bf16_f32 v116, v126, v127
	s_waitcnt lgkmcnt(0)
	v_add_f32_e32 v112, v115, v199
	ds_bpermute_b32 v113, v244, v112
	v_cvt_pk_bf16_f32 v115, v118, v119
	v_cvt_pk_bf16_f32 v117, v124, v125
	global_store_dwordx4 v[184:185], v[120:123], off
	global_store_dwordx4 v[184:185], v[114:117], off offset:256
	s_and_saveexec_b64 s[70:71], s[16:17]
	s_cbranch_execz .LBB0_720
	s_waitcnt lgkmcnt(0)
	v_add_f32_e32 v112, v112, v113
	v_fma_f32 v112, v112, s25, 0.5
	v_cvt_u32_f32_e32 v114, v112
	v_lshl_add_u64 v[112:113], v[186:187], 2, s[54:55]
	global_atomic_add v[112:113], v114, off

; #define PG8_STAGE(bufoff, gbase, voff) do { _Pragma("unroll") for (int _i = 0; _i < 2; ++_i) \
;         __builtin_amdgcn_global_load_lds((const unsigned*)((const char*)(gbase) + (voff)[_i]), (LAS unsigned*)(lds + (bufoff) + ldsw + _i * 8192), 16, 0, 0); } while (0)
; #define PG8_LDA(dst, b, h) do { _Pragma("unroll") for (int m = 0; m < 4; ++m) _Pragma("unroll") for (int k = 0; k < 2; ++k) dst[m][k] = *(const LAS bf16x8*)(lds + PG8_SA(b, h) + aoff + m * 2048 + k * 1024); } while (0)
; #define PG8_LDB(dst, b, h) do { _Pragma("unroll") for (int n = 0; n < 2; ++n) _Pragma("unroll") for (int k = 0; k < 2; ++k) dst[n][k] = *(const LAS bf16x8*)(lds + PG8_SB(b, h) + boff + n * 2048 + k * 1024); } while (0)
; #define PG8_MMA(ai, bj, At, Bt) do { __builtin_amdgcn_s_setprio(1); _Pragma("unroll") for (int m = 0; m < 4; ++m) _Pragma("unroll") for (int n = 0; n < 2; ++n) _Pragma("unroll") for (int k = 0; k < 2; ++k) \
;         acc[ai][bj][m][n] = __builtin_amdgcn_mfma_f32_16x16x32_bf16(Bt[n][k], At[m][k], acc[ai][bj][m][n], 0, 0, 0); __builtin_amdgcn_s_setprio(0); } while (0)
; #define PG8_WAIT_L(n) asm volatile("s_waitcnt lgkmcnt(" #n ")" ::: "memory")
; #define PG8_BAR __builtin_amdgcn_s_barrier()
; #define PG8_SCHED __builtin_amdgcn_sched_barrier(0)
; template <class Epi>
; __device__ __forceinline__ void gemm_phase(LAS unsigned char* lds, const Gemm g, const StaticOrder& S, const Epi& E, int wv) {
;     ...
;         const bool has_next = S.next(ui + 1, nxt);
;         const char* nA = has_next ? (const char*)g.A + (size_t)nxt.pm * tstepA + ((g.adiag & 1) ? (size_t)(nxt.pn >> 1) * K * 2 : 0) + kbeg : cA;
;         const char* nB = has_next ? (const char*)g.Bt + (size_t)nxt.pn * tstepB + kbeg : cB;
;         for (int t = 0; t < nt; t += 2) {
;             const bool last = (t == nt - 2);
;             const char* a1 = cA + (ptrdiff_t)(t + 1) * kstep;
;             const char* a2 = last ? nA : cA + (ptrdiff_t)(t + 2) * kstep; const char* b2 = last ? nB : cB + (ptrdiff_t)(t + 2) * kstep;
;             const char* a3 = a2 + kstep; const char* b3 = b2 + kstep;
;             PG8_LDB(B0, 0, 0); PG8_SCHED; PG8_LDA(At, 0, 0); PG8_STAGE(PG8_SA(1, 1), a1 + hstepA, voffA);
;             PG8_WAIT_L(8); PG8_BAR; PG8_WAIT_L(0); PG8_MMA(0, 0, At, B0); PG8_BAR; PG8_SCHED;
.LBB0_957:
	s_ashr_i32 s41, s40, 31
	v_cmp_lt_i64_e32 vcc, s[42:43], v[140:141]
	s_lshl_b64 s[42:43], s[40:41], 20
	s_add_u32 s42, s5, s42
	s_addc_u32 s43, s6, s43
	s_and_b64 s[44:45], vcc, exec
	s_cselect_b32 s11, s43, s51
	s_cselect_b32 s41, s42, s50
	s_ashr_i32 s39, s38, 31
	s_lshl_b64 s[44:45], s[38:39], 20
	s_add_u32 s44, s7, s44
	s_addc_u32 s45, s22, s45
	s_and_b64 s[52:53], vcc, exec
	s_cselect_b32 s39, s45, s49
	s_cselect_b32 s47, s44, s48
	s_add_u32 s68, s48, 0x100
	s_addc_u32 s69, s49, 0
	s_add_u32 s48, s50, 0x80080
	v_mov_b32_e32 v0, 0
	s_addc_u32 s49, s51, 0
	s_mov_b32 s70, -2
	v_mov_b32_e32 v1, v0
	v_mov_b32_e32 v2, v0
	v_mov_b32_e32 v3, v0
	v_mov_b32_e32 v4, v0
	v_mov_b32_e32 v5, v0
	v_mov_b32_e32 v6, v0
	v_mov_b32_e32 v7, v0
	v_mov_b32_e32 v16, v0
	v_mov_b32_e32 v17, v0
	v_mov_b32_e32 v18, v0
	v_mov_b32_e32 v19, v0
	v_mov_b32_e32 v20, v0
	v_mov_b32_e32 v21, v0
	v_mov_b32_e32 v22, v0
	v_mov_b32_e32 v23, v0
	v_mov_b32_e32 v32, v0
	v_mov_b32_e32 v33, v0
	v_mov_b32_e32 v34, v0
	v_mov_b32_e32 v35, v0
	v_mov_b32_e32 v36, v0
	v_mov_b32_e32 v37, v0
	v_mov_b32_e32 v38, v0
	v_mov_b32_e32 v39, v0
	v_mov_b32_e32 v48, v0
	v_mov_b32_e32 v49, v0
	v_mov_b32_e32 v50, v0
	v_mov_b32_e32 v51, v0
	v_mov_b32_e32 v52, v0
	v_mov_b32_e32 v53, v0
	v_mov_b32_e32 v54, v0
	v_mov_b32_e32 v55, v0
	v_mov_b32_e32 v8, v0
	v_mov_b32_e32 v9, v0
	v_mov_b32_e32 v10, v0
	v_mov_b32_e32 v11, v0
	v_mov_b32_e32 v12, v0
	v_mov_b32_e32 v13, v0
	v_mov_b32_e32 v14, v0
	v_mov_b32_e32 v15, v0
	v_mov_b32_e32 v24, v0
	v_mov_b32_e32 v25, v0
	v_mov_b32_e32 v26, v0
	v_mov_b32_e32 v27, v0
	v_mov_b32_e32 v28, v0
	v_mov_b32_e32 v29, v0
	v_mov_b32_e32 v30, v0
	v_mov_b32_e32 v31, v0
	v_mov_b32_e32 v40, v0
	v_mov_b32_e32 v41, v0
	v_mov_b32_e32 v42, v0
	v_mov_b32_e32 v43, v0
	v_mov_b32_e32 v44, v0
	v_mov_b32_e32 v45, v0
	v_mov_b32_e32 v46, v0
	v_mov_b32_e32 v47, v0
	v_mov_b32_e32 v56, v0
	v_mov_b32_e32 v57, v0
	v_mov_b32_e32 v58, v0
	v_mov_b32_e32 v59, v0
	v_mov_b32_e32 v60, v0
	v_mov_b32_e32 v61, v0
	v_mov_b32_e32 v62, v0
	v_mov_b32_e32 v63, v0
	v_mov_b32_e32 v64, v0
	v_mov_b32_e32 v65, v0
	v_mov_b32_e32 v66, v0
	v_mov_b32_e32 v67, v0
	v_mov_b32_e32 v68, v0
	v_mov_b32_e32 v69, v0
	v_mov_b32_e32 v70, v0
	v_mov_b32_e32 v71, v0
	v_mov_b32_e32 v80, v0
	v_mov_b32_e32 v81, v0
	v_mov_b32_e32 v82, v0
	v_mov_b32_e32 v83, v0
	v_mov_b32_e32 v84, v0
	v_mov_b32_e32 v85, v0
	v_mov_b32_e32 v86, v0
	v_mov_b32_e32 v87, v0
	v_mov_b32_e32 v96, v0
	v_mov_b32_e32 v97, v0
	v_mov_b32_e32 v98, v0
	v_mov_b32_e32 v99, v0
	v_mov_b32_e32 v100, v0
	v_mov_b32_e32 v101, v0
	v_mov_b32_e32 v102, v0
	v_mov_b32_e32 v103, v0
	v_mov_b32_e32 v112, v0
	v_mov_b32_e32 v113, v0
	v_mov_b32_e32 v114, v0
	v_mov_b32_e32 v115, v0
	v_mov_b32_e32 v116, v0
	v_mov_b32_e32 v117, v0
	v_mov_b32_e32 v118, v0
	v_mov_b32_e32 v119, v0
	v_mov_b32_e32 v72, v0
	v_mov_b32_e32 v73, v0
	v_mov_b32_e32 v74, v0
	v_mov_b32_e32 v75, v0
	v_mov_b32_e32 v76, v0
	v_mov_b32_e32 v77, v0
	v_mov_b32_e32 v78, v0
	v_mov_b32_e32 v79, v0
	v_mov_b32_e32 v88, v0
	v_mov_b32_e32 v89, v0
	v_mov_b32_e32 v90, v0
	v_mov_b32_e32 v91, v0
	v_mov_b32_e32 v92, v0
	v_mov_b32_e32 v93, v0
	v_mov_b32_e32 v94, v0
	v_mov_b32_e32 v95, v0
	v_mov_b32_e32 v104, v0
	v_mov_b32_e32 v105, v0
	v_mov_b32_e32 v106, v0
	v_mov_b32_e32 v107, v0
	v_mov_b32_e32 v108, v0
	v_mov_b32_e32 v109, v0
	v_mov_b32_e32 v110, v0
	v_mov_b32_e32 v111, v0
	v_mov_b32_e32 v120, v0
	v_mov_b32_e32 v121, v0
	v_mov_b32_e32 v122, v0
	v_mov_b32_e32 v123, v0
	v_mov_b32_e32 v124, v0
	v_mov_b32_e32 v125, v0
	v_mov_b32_e32 v126, v0
	v_mov_b32_e32 v127, v0
	ds_read_b128 v[144:147], v155
	ds_read_b128 v[148:151], v155 offset:1024
	ds_read_b128 v[160:163], v155 offset:2048
	ds_read_b128 v[164:167], v155 offset:3072
.LBB0_958:
	s_add_u32 s50, s48, 0xfff80080
	s_addc_u32 s51, s49, -1
	s_cmp_eq_u32 s70, 28
	s_cselect_b32 s53, s11, s51
	s_cselect_b32 s52, s41, s50
	s_cselect_b32 s51, s39, s69
	s_cselect_b32 s50, s47, s68
	s_add_i32 m0, s24, 0xc000
	ds_read_b128 v[168:171], v156
	ds_read_b128 v[172:175], v156 offset:1024
	ds_read_b128 v[176:179], v156 offset:2048
	ds_read_b128 v[180:183], v156 offset:3072
	ds_read_b128 v[184:187], v156 offset:4096
	ds_read_b128 v[188:191], v156 offset:5120
	ds_read_b128 v[192:195], v156 offset:6144
	ds_read_b128 v[196:199], v156 offset:7168
	global_load_lds_dwordx4 v138, s[48:49]
	s_add_i32 m0, s24, 0xe000
	s_nop 0
	global_load_lds_dwordx4 v136, s[48:49]
	s_waitcnt lgkmcnt(8)
	s_barrier
	s_waitcnt lgkmcnt(0)
	s_setprio 1
	s_waitcnt lgkmcnt(0)
	v_mfma_f32_16x16x32_bf16 v[124:127], v[144:147], v[168:171], v[124:127]
	v_mfma_f32_16x16x32_bf16 v[120:123], v[160:163], v[168:171], v[120:123]
	v_mfma_f32_16x16x32_bf16 v[108:111], v[144:147], v[176:179], v[108:111]
	v_mfma_f32_16x16x32_bf16 v[104:107], v[160:163], v[176:179], v[104:107]
	v_mfma_f32_16x16x32_bf16 v[92:95], v[144:147], v[184:187], v[92:95]
	v_mfma_f32_16x16x32_bf16 v[88:91], v[160:163], v[184:187], v[88:91]
	v_mfma_f32_16x16x32_bf16 v[76:79], v[144:147], v[192:195], v[76:79]
	v_mfma_f32_16x16x32_bf16 v[72:75], v[160:163], v[192:195], v[72:75]
	v_mfma_f32_16x16x32_bf16 v[124:127], v[148:151], v[172:175], v[124:127]
	v_mfma_f32_16x16x32_bf16 v[120:123], v[164:167], v[172:175], v[120:123]
	v_mfma_f32_16x16x32_bf16 v[108:111], v[148:151], v[180:183], v[108:111]
	v_mfma_f32_16x16x32_bf16 v[104:107], v[164:167], v[180:183], v[104:107]
	v_mfma_f32_16x16x32_bf16 v[92:95], v[148:151], v[188:191], v[92:95]
	v_mfma_f32_16x16x32_bf16 v[88:91], v[164:167], v[188:191], v[88:91]
	v_mfma_f32_16x16x32_bf16 v[76:79], v[148:151], v[196:199], v[76:79]
	v_mfma_f32_16x16x32_bf16 v[72:75], v[164:167], v[196:199], v[72:75]
	s_setprio 0
	s_barrier
; #define PG8_STAGE(bufoff, gbase, voff) do { _Pragma("unroll") for (int _i = 0; _i < 2; ++_i) \
;         __builtin_amdgcn_global_load_lds((const unsigned*)((const char*)(gbase) + (voff)[_i]), (LAS unsigned*)(lds + (bufoff) + ldsw + _i * 8192), 16, 0, 0); } while (0)
; #define PG8_LDA(dst, b, h) do { _Pragma("unroll") for (int m = 0; m < 4; ++m) _Pragma("unroll") for (int k = 0; k < 2; ++k) dst[m][k] = *(const LAS bf16x8*)(lds + PG8_SA(b, h) + aoff + m * 2048 + k * 1024); } while (0)
; #define PG8_LDB(dst, b, h) do { _Pragma("unroll") for (int n = 0; n < 2; ++n) _Pragma("unroll") for (int k = 0; k < 2; ++k) dst[n][k] = *(const LAS bf16x8*)(lds + PG8_SB(b, h) + boff + n * 2048 + k * 1024); } while (0)
; #define PG8_MMA(ai, bj, At, Bt) do { __builtin_amdgcn_s_setprio(1); _Pragma("unroll") for (int m = 0; m < 4; ++m) _Pragma("unroll") for (int n = 0; n < 2; ++n) _Pragma("unroll") for (int k = 0; k < 2; ++k) \
;         acc[ai][bj][m][n] = __builtin_amdgcn_mfma_f32_16x16x32_bf16(Bt[n][k], At[m][k], acc[ai][bj][m][n], 0, 0, 0); __builtin_amdgcn_s_setprio(0); } while (0)
; #define PG8_WAIT_V(n) asm volatile("s_waitcnt vmcnt(" #n ")" ::: "memory")
; #define PG8_WAIT_L(n) asm volatile("s_waitcnt lgkmcnt(" #n ")" ::: "memory")
; #define PG8_BAR __builtin_amdgcn_s_barrier()
; #define PG8_SCHED __builtin_amdgcn_sched_barrier(0)
; template <class Epi>
; __device__ __forceinline__ void gemm_phase(LAS unsigned char* lds, const Gemm g, const StaticOrder& S, const Epi& E, int wv) {
;     ...
;             PG8_LDB(B1, 0, 1); PG8_STAGE(PG8_SB(0, 0), b2, voffB);
;             PG8_BAR; PG8_WAIT_L(0); PG8_MMA(0, 1, At, B1); PG8_BAR;
;             PG8_LDA(At, 0, 1); PG8_STAGE(PG8_SA(0, 0), a2, voffA);
;             PG8_BAR; PG8_WAIT_L(0); PG8_MMA(1, 0, At, B0); PG8_BAR; PG8_SCHED;
;             PG8_STAGE(PG8_SB(0, 1), b2 + hstepB, voffB);
;             PG8_WAIT_V(6); PG8_BAR; PG8_MMA(1, 1, At, B1); PG8_BAR;
;             PG8_LDB(B0, 1, 0); PG8_SCHED; PG8_LDA(At, 1, 0); PG8_STAGE(PG8_SA(0, 1), a2 + hstepA, voffA);
	s_add_i32 s71, s60, s23
	s_add_u32 s98, s50, s16
	s_addc_u32 s99, s51, s17
	s_mov_b32 m0, s71
	ds_read_b128 v[200:203], v157
	ds_read_b128 v[204:207], v157 offset:1024
	ds_read_b128 v[208:211], v157 offset:2048
	ds_read_b128 v[212:215], v157 offset:3072
	global_load_lds_dwordx4 v130, s[50:51]
	s_add_i32 m0, s71, 0x2000
	s_nop 0
	global_load_lds_dwordx4 v134, s[50:51]
	s_barrier
	s_waitcnt lgkmcnt(0)
	s_setprio 1
	s_waitcnt lgkmcnt(0)
	v_mfma_f32_16x16x32_bf16 v[116:119], v[200:203], v[168:171], v[116:119]
	v_mfma_f32_16x16x32_bf16 v[112:115], v[208:211], v[168:171], v[112:115]
	v_mfma_f32_16x16x32_bf16 v[100:103], v[200:203], v[176:179], v[100:103]
	v_mfma_f32_16x16x32_bf16 v[96:99], v[208:211], v[176:179], v[96:99]
	v_mfma_f32_16x16x32_bf16 v[84:87], v[200:203], v[184:187], v[84:87]
	v_mfma_f32_16x16x32_bf16 v[80:83], v[208:211], v[184:187], v[80:83]
	v_mfma_f32_16x16x32_bf16 v[68:71], v[200:203], v[192:195], v[68:71]
	v_mfma_f32_16x16x32_bf16 v[64:67], v[208:211], v[192:195], v[64:67]
	v_mfma_f32_16x16x32_bf16 v[116:119], v[204:207], v[172:175], v[116:119]
	v_mfma_f32_16x16x32_bf16 v[112:115], v[212:215], v[172:175], v[112:115]
	v_mfma_f32_16x16x32_bf16 v[100:103], v[204:207], v[180:183], v[100:103]
	v_mfma_f32_16x16x32_bf16 v[96:99], v[212:215], v[180:183], v[96:99]
	v_mfma_f32_16x16x32_bf16 v[84:87], v[204:207], v[188:191], v[84:87]
	v_mfma_f32_16x16x32_bf16 v[80:83], v[212:215], v[188:191], v[80:83]
	v_mfma_f32_16x16x32_bf16 v[68:71], v[204:207], v[196:199], v[68:71]
	v_mfma_f32_16x16x32_bf16 v[64:67], v[212:215], v[196:199], v[64:67]
	s_setprio 0
	s_mov_b32 m0, s24
	s_add_u32 s100, s52, s16
	s_addc_u32 s101, s53, s17
	s_barrier
	ds_read_b128 v[168:171], v156 offset:16384
	ds_read_b128 v[172:175], v156 offset:17408
	ds_read_b128 v[176:179], v156 offset:18432
	ds_read_b128 v[180:183], v156 offset:19456
	ds_read_b128 v[184:187], v156 offset:20480
	ds_read_b128 v[188:191], v156 offset:21504
	ds_read_b128 v[192:195], v156 offset:22528
	ds_read_b128 v[196:199], v156 offset:23552
	global_load_lds_dwordx4 v128, s[52:53]
	s_mov_b32 m0, s25
	s_nop 0
	global_load_lds_dwordx4 v132, s[52:53]
	s_waitcnt vmcnt(10)
	s_barrier
	s_waitcnt lgkmcnt(0)
	s_setprio 1
	s_waitcnt lgkmcnt(0)
	v_mfma_f32_16x16x32_bf16 v[60:63], v[144:147], v[168:171], v[60:63]
	v_mfma_f32_16x16x32_bf16 v[56:59], v[160:163], v[168:171], v[56:59]
	v_mfma_f32_16x16x32_bf16 v[44:47], v[144:147], v[176:179], v[44:47]
	v_mfma_f32_16x16x32_bf16 v[40:43], v[160:163], v[176:179], v[40:43]
	v_mfma_f32_16x16x32_bf16 v[28:31], v[144:147], v[184:187], v[28:31]
	v_mfma_f32_16x16x32_bf16 v[24:27], v[160:163], v[184:187], v[24:27]
	v_mfma_f32_16x16x32_bf16 v[12:15], v[144:147], v[192:195], v[12:15]
	v_mfma_f32_16x16x32_bf16 v[8:11], v[160:163], v[192:195], v[8:11]
	v_mfma_f32_16x16x32_bf16 v[60:63], v[148:151], v[172:175], v[60:63]
	v_mfma_f32_16x16x32_bf16 v[56:59], v[164:167], v[172:175], v[56:59]
	v_mfma_f32_16x16x32_bf16 v[44:47], v[148:151], v[180:183], v[44:47]
	v_mfma_f32_16x16x32_bf16 v[40:43], v[164:167], v[180:183], v[40:43]
	v_mfma_f32_16x16x32_bf16 v[28:31], v[148:151], v[188:191], v[28:31]
	v_mfma_f32_16x16x32_bf16 v[24:27], v[164:167], v[188:191], v[24:27]
	v_mfma_f32_16x16x32_bf16 v[12:15], v[148:151], v[196:199], v[12:15]
	v_mfma_f32_16x16x32_bf16 v[8:11], v[164:167], v[196:199], v[8:11]
	s_setprio 0
	s_barrier
	s_add_u32 s72, s50, 0x80000
	s_addc_u32 s73, s51, 0
	s_add_i32 s71, s61, s23
	s_mov_b32 m0, s71
	s_nop 0
	global_load_lds_dwordx4 v130, s[72:73]
	s_add_i32 m0, s71, 0x2000
	s_nop 0
	global_load_lds_dwordx4 v134, s[72:73]
	s_add_i32 s71, 0, 0x18000
	v_add_u32_e32 v159, s71, v153
	ds_read_b128 v[144:147], v159
	ds_read_b128 v[148:151], v159 offset:1024
	ds_read_b128 v[160:163], v159 offset:2048
	ds_read_b128 v[164:167], v159 offset:3072
	s_waitcnt vmcnt(6)
	s_barrier
	s_setprio 1
	v_mfma_f32_16x16x32_bf16 v[52:55], v[200:203], v[168:171], v[52:55]
	v_mfma_f32_16x16x32_bf16 v[48:51], v[208:211], v[168:171], v[48:51]
	v_mfma_f32_16x16x32_bf16 v[36:39], v[200:203], v[176:179], v[36:39]
	v_mfma_f32_16x16x32_bf16 v[32:35], v[208:211], v[176:179], v[32:35]
	v_mfma_f32_16x16x32_bf16 v[20:23], v[200:203], v[184:187], v[20:23]
	v_mfma_f32_16x16x32_bf16 v[16:19], v[208:211], v[184:187], v[16:19]
	v_mfma_f32_16x16x32_bf16 v[4:7], v[200:203], v[192:195], v[4:7]
	v_mfma_f32_16x16x32_bf16 v[0:3], v[208:211], v[192:195], v[0:3]
	v_mfma_f32_16x16x32_bf16 v[52:55], v[204:207], v[172:175], v[52:55]
	v_mfma_f32_16x16x32_bf16 v[48:51], v[212:215], v[172:175], v[48:51]
	v_mfma_f32_16x16x32_bf16 v[36:39], v[204:207], v[180:183], v[36:39]
	v_mfma_f32_16x16x32_bf16 v[32:35], v[212:215], v[180:183], v[32:35]
	v_mfma_f32_16x16x32_bf16 v[20:23], v[204:207], v[188:191], v[20:23]
	v_mfma_f32_16x16x32_bf16 v[16:19], v[212:215], v[188:191], v[16:19]
	v_mfma_f32_16x16x32_bf16 v[4:7], v[204:207], v[196:199], v[4:7]
	v_mfma_f32_16x16x32_bf16 v[0:3], v[212:215], v[196:199], v[0:3]
	s_setprio 0
	s_waitcnt lgkmcnt(0)
	s_barrier
	s_add_u32 s52, s52, 0x80000
	s_addc_u32 s53, s53, 0
	s_mov_b32 m0, s33
	ds_read_b128 v[168:171], v156 offset:32768
	ds_read_b128 v[172:175], v156 offset:33792
	ds_read_b128 v[176:179], v156 offset:34816
	ds_read_b128 v[180:183], v156 offset:35840
	ds_read_b128 v[184:187], v156 offset:36864
	ds_read_b128 v[188:191], v156 offset:37888
	ds_read_b128 v[192:195], v156 offset:38912
	ds_read_b128 v[196:199], v156 offset:39936
	global_load_lds_dwordx4 v128, s[52:53]
	s_mov_b32 m0, s54
	s_nop 0
	global_load_lds_dwordx4 v132, s[52:53]
	s_waitcnt lgkmcnt(8)
	s_barrier
; #define PG8_STAGE(bufoff, gbase, voff) do { _Pragma("unroll") for (int _i = 0; _i < 2; ++_i) \
;         __builtin_amdgcn_global_load_lds((const unsigned*)((const char*)(gbase) + (voff)[_i]), (LAS unsigned*)(lds + (bufoff) + ldsw + _i * 8192), 16, 0, 0); } while (0)
; #define PG8_LDA(dst, b, h) do { _Pragma("unroll") for (int m = 0; m < 4; ++m) _Pragma("unroll") for (int k = 0; k < 2; ++k) dst[m][k] = *(const LAS bf16x8*)(lds + PG8_SA(b, h) + aoff + m * 2048 + k * 1024); } while (0)
; #define PG8_LDB(dst, b, h) do { _Pragma("unroll") for (int n = 0; n < 2; ++n) _Pragma("unroll") for (int k = 0; k < 2; ++k) dst[n][k] = *(const LAS bf16x8*)(lds + PG8_SB(b, h) + boff + n * 2048 + k * 1024); } while (0)
; #define PG8_MMA(ai, bj, At, Bt) do { __builtin_amdgcn_s_setprio(1); _Pragma("unroll") for (int m = 0; m < 4; ++m) _Pragma("unroll") for (int n = 0; n < 2; ++n) _Pragma("unroll") for (int k = 0; k < 2; ++k) \
;         acc[ai][bj][m][n] = __builtin_amdgcn_mfma_f32_16x16x32_bf16(Bt[n][k], At[m][k], acc[ai][bj][m][n], 0, 0, 0); __builtin_amdgcn_s_setprio(0); } while (0)
; #define PG8_WAIT_V(n) asm volatile("s_waitcnt vmcnt(" #n ")" ::: "memory")
; #define PG8_WAIT_L(n) asm volatile("s_waitcnt lgkmcnt(" #n ")" ::: "memory")
; #define PG8_BAR __builtin_amdgcn_s_barrier()
; #define PG8_SCHED __builtin_amdgcn_sched_barrier(0)
; template <class Epi>
; __device__ __forceinline__ void gemm_phase(LAS unsigned char* lds, const Gemm g, const StaticOrder& S, const Epi& E, int wv) {
;     ...
;             PG8_WAIT_L(8); PG8_BAR; PG8_WAIT_L(0); PG8_MMA(0, 0, At, B0); PG8_BAR; PG8_SCHED;
;             PG8_LDB(B1, 1, 1); PG8_STAGE(PG8_SB(1, 0), b3, voffB);
;             PG8_BAR; PG8_WAIT_L(0); PG8_MMA(0, 1, At, B1); PG8_BAR;
;             PG8_LDA(At, 1, 1); PG8_STAGE(PG8_SA(1, 0), a3, voffA);
;             PG8_BAR; PG8_WAIT_L(0); PG8_MMA(1, 0, At, B0); PG8_BAR; PG8_SCHED;
;             PG8_STAGE(PG8_SB(1, 1), b3 + hstepB, voffB);
;             PG8_WAIT_V(6); PG8_BAR; PG8_MMA(1, 1, At, B1); PG8_BAR;
	s_waitcnt lgkmcnt(0)
	s_setprio 1
	s_waitcnt lgkmcnt(0)
	v_mfma_f32_16x16x32_bf16 v[124:127], v[144:147], v[168:171], v[124:127]
	v_mfma_f32_16x16x32_bf16 v[120:123], v[160:163], v[168:171], v[120:123]
	v_mfma_f32_16x16x32_bf16 v[108:111], v[144:147], v[176:179], v[108:111]
	v_mfma_f32_16x16x32_bf16 v[104:107], v[160:163], v[176:179], v[104:107]
	v_mfma_f32_16x16x32_bf16 v[92:95], v[144:147], v[184:187], v[92:95]
	v_mfma_f32_16x16x32_bf16 v[88:91], v[160:163], v[184:187], v[88:91]
	v_mfma_f32_16x16x32_bf16 v[76:79], v[144:147], v[192:195], v[76:79]
	v_mfma_f32_16x16x32_bf16 v[72:75], v[160:163], v[192:195], v[72:75]
	v_mfma_f32_16x16x32_bf16 v[124:127], v[148:151], v[172:175], v[124:127]
	v_mfma_f32_16x16x32_bf16 v[120:123], v[164:167], v[172:175], v[120:123]
	v_mfma_f32_16x16x32_bf16 v[108:111], v[148:151], v[180:183], v[108:111]
	v_mfma_f32_16x16x32_bf16 v[104:107], v[164:167], v[180:183], v[104:107]
	v_mfma_f32_16x16x32_bf16 v[92:95], v[148:151], v[188:191], v[92:95]
	v_mfma_f32_16x16x32_bf16 v[88:91], v[164:167], v[188:191], v[88:91]
	v_mfma_f32_16x16x32_bf16 v[76:79], v[148:151], v[196:199], v[76:79]
	v_mfma_f32_16x16x32_bf16 v[72:75], v[164:167], v[196:199], v[72:75]
	s_setprio 0
	s_barrier
	s_add_i32 s52, 0, 0x1c000
	s_add_i32 s53, s71, s23
	v_add_u32_e32 v159, s52, v153
	s_mov_b32 m0, s53
	ds_read_b128 v[200:203], v159
	ds_read_b128 v[204:207], v159 offset:1024
	ds_read_b128 v[208:211], v159 offset:2048
	ds_read_b128 v[212:215], v159 offset:3072
	global_load_lds_dwordx4 v130, s[98:99]
	s_add_i32 m0, s53, 0x2000
	s_nop 0
	global_load_lds_dwordx4 v134, s[98:99]
	s_barrier
	s_waitcnt lgkmcnt(0)
	s_setprio 1
	s_waitcnt lgkmcnt(0)
	v_mfma_f32_16x16x32_bf16 v[116:119], v[200:203], v[168:171], v[116:119]
	v_mfma_f32_16x16x32_bf16 v[112:115], v[208:211], v[168:171], v[112:115]
	v_mfma_f32_16x16x32_bf16 v[100:103], v[200:203], v[176:179], v[100:103]
	v_mfma_f32_16x16x32_bf16 v[96:99], v[208:211], v[176:179], v[96:99]
	v_mfma_f32_16x16x32_bf16 v[84:87], v[200:203], v[184:187], v[84:87]
	v_mfma_f32_16x16x32_bf16 v[80:83], v[208:211], v[184:187], v[80:83]
	v_mfma_f32_16x16x32_bf16 v[68:71], v[200:203], v[192:195], v[68:71]
	v_mfma_f32_16x16x32_bf16 v[64:67], v[208:211], v[192:195], v[64:67]
	v_mfma_f32_16x16x32_bf16 v[116:119], v[204:207], v[172:175], v[116:119]
	v_mfma_f32_16x16x32_bf16 v[112:115], v[212:215], v[172:175], v[112:115]
	v_mfma_f32_16x16x32_bf16 v[100:103], v[204:207], v[180:183], v[100:103]
	v_mfma_f32_16x16x32_bf16 v[96:99], v[212:215], v[180:183], v[96:99]
	v_mfma_f32_16x16x32_bf16 v[84:87], v[204:207], v[188:191], v[84:87]
	v_mfma_f32_16x16x32_bf16 v[80:83], v[212:215], v[188:191], v[80:83]
	v_mfma_f32_16x16x32_bf16 v[68:71], v[204:207], v[196:199], v[68:71]
	v_mfma_f32_16x16x32_bf16 v[64:67], v[212:215], v[196:199], v[64:67]
	s_setprio 0
	s_mov_b32 m0, s58
	s_barrier
	ds_read_b128 v[168:171], v156 offset:49152
	ds_read_b128 v[172:175], v156 offset:50176
	ds_read_b128 v[176:179], v156 offset:51200
	ds_read_b128 v[180:183], v156 offset:52224
	ds_read_b128 v[184:187], v156 offset:53248
	ds_read_b128 v[188:191], v156 offset:54272
	ds_read_b128 v[192:195], v156 offset:55296
	ds_read_b128 v[196:199], v156 offset:56320
	global_load_lds_dwordx4 v128, s[100:101]
	s_mov_b32 m0, s59
	s_nop 0
	global_load_lds_dwordx4 v132, s[100:101]
	s_waitcnt vmcnt(10)
	s_barrier
	s_waitcnt lgkmcnt(0)
	s_setprio 1
	s_waitcnt lgkmcnt(0)
	v_mfma_f32_16x16x32_bf16 v[60:63], v[144:147], v[168:171], v[60:63]
	v_mfma_f32_16x16x32_bf16 v[56:59], v[160:163], v[168:171], v[56:59]
	v_mfma_f32_16x16x32_bf16 v[44:47], v[144:147], v[176:179], v[44:47]
	v_mfma_f32_16x16x32_bf16 v[40:43], v[160:163], v[176:179], v[40:43]
	v_mfma_f32_16x16x32_bf16 v[28:31], v[144:147], v[184:187], v[28:31]
	v_mfma_f32_16x16x32_bf16 v[24:27], v[160:163], v[184:187], v[24:27]
	v_mfma_f32_16x16x32_bf16 v[12:15], v[144:147], v[192:195], v[12:15]
	v_mfma_f32_16x16x32_bf16 v[8:11], v[160:163], v[192:195], v[8:11]
	v_mfma_f32_16x16x32_bf16 v[60:63], v[148:151], v[172:175], v[60:63]
	v_mfma_f32_16x16x32_bf16 v[56:59], v[164:167], v[172:175], v[56:59]
	v_mfma_f32_16x16x32_bf16 v[44:47], v[148:151], v[180:183], v[44:47]
	v_mfma_f32_16x16x32_bf16 v[40:43], v[164:167], v[180:183], v[40:43]
	v_mfma_f32_16x16x32_bf16 v[28:31], v[148:151], v[188:191], v[28:31]
	v_mfma_f32_16x16x32_bf16 v[24:27], v[164:167], v[188:191], v[24:27]
	v_mfma_f32_16x16x32_bf16 v[12:15], v[148:151], v[196:199], v[12:15]
	v_mfma_f32_16x16x32_bf16 v[8:11], v[164:167], v[196:199], v[8:11]
	s_setprio 0
	s_barrier
	s_add_u32 s50, s50, 0x80080
	s_addc_u32 s51, s51, 0
	s_add_i32 s52, s52, s23
	s_mov_b32 m0, s52
	s_nop 0
	global_load_lds_dwordx4 v130, s[50:51]
	s_add_i32 m0, s52, 0x2000
	s_nop 0
	global_load_lds_dwordx4 v134, s[50:51]
	ds_read_b128 v[144:147], v155
	ds_read_b128 v[148:151], v155 offset:1024
	ds_read_b128 v[160:163], v155 offset:2048
	ds_read_b128 v[164:167], v155 offset:3072
	s_waitcnt vmcnt(6)
	s_barrier
; __device__ __forceinline__ float fast_sigmoid(float x) { return __builtin_amdgcn_rcpf(1.0f + __builtin_amdgcn_exp2f(-x * LOG2E)); }
; __device__ __forceinline__ float ss_fix(float raw) { return (float)__float_as_uint(raw) * (1.0f / 256.0f); }
; #define PG8_MMA(ai, bj, At, Bt) do { __builtin_amdgcn_s_setprio(1); _Pragma("unroll") for (int m = 0; m < 4; ++m) _Pragma("unroll") for (int n = 0; n < 2; ++n) _Pragma("unroll") for (int k = 0; k < 2; ++k) \
;         acc[ai][bj][m][n] = __builtin_amdgcn_mfma_f32_16x16x32_bf16(Bt[n][k], At[m][k], acc[ai][bj][m][n], 0, 0, 0); __builtin_amdgcn_s_setprio(0); } while (0)
; #define PG8_WAIT_V(n) asm volatile("s_waitcnt vmcnt(" #n ")" ::: "memory")
; template <class Epi>
; __device__ __forceinline__ void gemm_phase(LAS unsigned char* lds, const Gemm g, const StaticOrder& S, const Epi& E, int wv) {
;     ...
;             PG8_WAIT_V(6); PG8_BAR; PG8_MMA(1, 1, At, B1); PG8_BAR;
;         }
;     __device__ __forceinline__ void operator()(const f32x4 (&acc)[2][2][4][2], const Unit& u, int wr, int wc, int fr, int fq) const {
;     ...
;         float rsv[8];
; #pragma unroll
;         for (int it = 0; it < 8; ++it) rsv[it] = (SM == 1) ? ss[row0 + (it >> 2) * HALF + (it & 3) * 16] : 1.0f;
; #pragma unroll
;         for (int ai = 0; ai < 2; ++ai)
; #pragma unroll
;             for (int m = 0; m < 4; ++m) { const int row = row0 + ai * HALF + m * 16; float rs = 1.0f; if (SM == 1) rs = __builtin_amdgcn_rsqf(ss_fix(rsv[ai * 4 + m]) * (1.0f / DM) + EPS);
;                 bf16_t* rowp = base + (size_t)row * ldc + col0;
; #pragma unroll
;                 for (int bj = 0; bj < 2; ++bj) { f32x4 v0 = acc[ai][bj][m][0], v1 = acc[ai][bj][m][1];
;                     if (SM == 1) { v0 *= rs; v1 *= rs; }
;                     if (SM == 2) { v0 *= cs[bj][0]; v1 *= cs[bj][1]; }
;                     if (ACT == 1) {
; #pragma unroll
;                         for (int j = 0; j < 4; ++j) { const float a = fmaxf(v0[j], 0.f), b = fmaxf(v1[j], 0.f); v0[j] = a * a; v1[j] = b * b; } }
;                     if (ACT == 2) { if (tsel == 0) {
; #pragma unroll
;                         for (int j = 0; j < 4; ++j) { const float a = v0[j], b = v1[j];
;                             v0[j] = a * fast_sigmoid(1.5957691216057308f * (a + 0.044715f * a * a * a)); v1[j] = b * fast_sigmoid(1.5957691216057308f * (b + 0.044715f * b * b * b)); } } }
	s_setprio 1
	v_mfma_f32_16x16x32_bf16 v[52:55], v[200:203], v[168:171], v[52:55]
	v_mfma_f32_16x16x32_bf16 v[48:51], v[208:211], v[168:171], v[48:51]
	v_mfma_f32_16x16x32_bf16 v[36:39], v[200:203], v[176:179], v[36:39]
	v_mfma_f32_16x16x32_bf16 v[32:35], v[208:211], v[176:179], v[32:35]
	v_mfma_f32_16x16x32_bf16 v[20:23], v[200:203], v[184:187], v[20:23]
	v_mfma_f32_16x16x32_bf16 v[16:19], v[208:211], v[184:187], v[16:19]
	v_mfma_f32_16x16x32_bf16 v[4:7], v[200:203], v[192:195], v[4:7]
	v_mfma_f32_16x16x32_bf16 v[0:3], v[208:211], v[192:195], v[0:3]
	v_mfma_f32_16x16x32_bf16 v[52:55], v[204:207], v[172:175], v[52:55]
	v_mfma_f32_16x16x32_bf16 v[48:51], v[212:215], v[172:175], v[48:51]
	v_mfma_f32_16x16x32_bf16 v[36:39], v[204:207], v[180:183], v[36:39]
	v_mfma_f32_16x16x32_bf16 v[32:35], v[212:215], v[180:183], v[32:35]
	v_mfma_f32_16x16x32_bf16 v[20:23], v[204:207], v[188:191], v[20:23]
	v_mfma_f32_16x16x32_bf16 v[16:19], v[212:215], v[188:191], v[16:19]
	v_mfma_f32_16x16x32_bf16 v[4:7], v[204:207], v[196:199], v[4:7]
	v_mfma_f32_16x16x32_bf16 v[0:3], v[212:215], v[196:199], v[0:3]
	s_setprio 0
	s_waitcnt lgkmcnt(0)
	s_add_i32 s70, s70, 2
	s_add_u32 s68, s68, 0x100
	s_addc_u32 s69, s69, 0
	s_add_u32 s48, s48, 0x100
	s_addc_u32 s49, s49, 0
	s_cmp_gt_u32 s70, 29
	s_barrier
	s_cbranch_scc0 .LBB0_958
	v_lshl_add_u32 v144, s46, 8, v152
	v_ashrrev_i32_e32 v145, 31, v144
	v_lshl_add_u64 v[146:147], v[144:145], 2, s[14:15]
	global_load_dword v148, v[146:147], off
	global_load_dword v165, v[146:147], off offset:64
	global_load_dword v164, v[146:147], off offset:128
	global_load_dword v163, v[146:147], off offset:192
	global_load_dword v162, v[146:147], off offset:512
	global_load_dword v161, v[146:147], off offset:576
	global_load_dword v160, v[146:147], off offset:640
	global_load_dword v159, v[146:147], off offset:704
	s_add_i32 s11, s10, 7
	s_cmp_lt_u32 s11, 15
	s_cselect_b64 s[46:47], -1, 0
	s_cmp_gt_u32 s11, 14
	s_waitcnt vmcnt(0)
	v_cvt_f32_u32_e32 v146, v148
	v_mul_f32_e32 v146, 0x3b800000, v146
	v_fmamk_f32 v146, v146, 0x3a000000, v158
	v_rsq_f32_e32 v146, v146
	s_nop 0
	v_pk_mul_f32 v[126:127], v[126:127], v[146:147] op_sel_hi:[1,0]
	v_pk_mul_f32 v[124:125], v[124:125], v[146:147] op_sel_hi:[1,0]
	v_pk_mul_f32 v[148:149], v[122:123], v[146:147] op_sel_hi:[1,0]
	v_pk_mul_f32 v[150:151], v[120:121], v[146:147] op_sel_hi:[1,0]
	s_cbranch_scc1 .LBB0_961
	v_mul_f32_e32 v121, 0x3d372713, v150
	v_mul_f32_e32 v121, v150, v121
	v_mul_f32_e32 v122, 0x3d372713, v125
	v_fma_f32 v121, v150, v121, v150
	v_mul_f32_e32 v122, v125, v122
	v_mov_b32_e32 v123, v125
	v_mul_f32_e32 v121, 0x3fcc422a, v121
	v_fmac_f32_e32 v123, v123, v122
	v_mul_f32_e32 v121, 0xbfb8aa3b, v121
	v_mul_f32_e32 v122, 0x3fcc422a, v123
	v_exp_f32_e32 v121, v121
	v_mul_f32_e32 v122, 0xbfb8aa3b, v122
	v_exp_f32_e32 v123, v122
	v_mov_b32_e32 v147, v151
	v_add_f32_e32 v121, 1.0, v121
	v_rcp_f32_e32 v122, v121
	v_add_f32_e32 v121, 1.0, v123
	v_mul_f32_e32 v123, 0x3d372713, v151
	v_mul_f32_e32 v123, v151, v123
	v_fmac_f32_e32 v147, v147, v123
	v_mul_f32_e32 v123, 0x3fcc422a, v147
	v_mul_f32_e32 v147, 0x3d372713, v126
	v_mul_f32_e32 v147, v126, v147
	v_mul_f32_e32 v166, 0x3d372713, v148
	v_fma_f32 v147, v126, v147, v126
	v_mul_f32_e32 v166, v148, v166
	v_mul_f32_e32 v147, 0x3fcc422a, v147
	v_fma_f32 v166, v148, v166, v148
	v_mul_f32_e32 v147, 0xbfb8aa3b, v147
	v_mul_f32_e32 v166, 0x3fcc422a, v166
	v_exp_f32_e32 v147, v147
	v_mul_f32_e32 v166, 0xbfb8aa3b, v166
	v_exp_f32_e32 v167, v166
	v_mul_f32_e32 v120, 0x3d372713, v124
	v_add_f32_e32 v147, 1.0, v147
	v_rcp_f32_e32 v166, v147
	v_add_f32_e32 v147, 1.0, v167
	v_mul_f32_e32 v167, 0x3d372713, v127
	v_mul_f32_e32 v167, v127, v167
	v_mul_f32_e32 v168, 0x3d372713, v149
	v_mul_f32_e32 v120, v124, v120
	v_fma_f32 v167, v127, v167, v127
	v_mul_f32_e32 v168, v149, v168
	v_fma_f32 v120, v124, v120, v124
	v_mul_f32_e32 v167, 0x3fcc422a, v167
	v_fma_f32 v168, v149, v168, v149
	v_mul_f32_e32 v120, 0x3fcc422a, v120
	v_mul_f32_e32 v167, 0xbfb8aa3b, v167
	v_mul_f32_e32 v168, 0x3fcc422a, v168
	v_mul_f32_e32 v120, 0xbfb8aa3b, v120
	v_mul_f32_e32 v123, 0xbfb8aa3b, v123
	v_exp_f32_e32 v167, v167
	v_mul_f32_e32 v168, 0xbfb8aa3b, v168
	v_exp_f32_e32 v120, v120
	v_exp_f32_e32 v123, v123
	v_exp_f32_e32 v169, v168
	v_rcp_f32_e32 v168, v147
	v_add_f32_e32 v147, 1.0, v167
	v_add_f32_e32 v120, 1.0, v120
	v_add_f32_e32 v123, 1.0, v123
	v_rcp_f32_e32 v167, v147
	v_add_f32_e32 v147, 1.0, v169
	v_rcp_f32_e32 v120, v120
	v_rcp_f32_e32 v121, v121
	v_rcp_f32_e32 v169, v147
	v_rcp_f32_e32 v123, v123
	v_pk_mul_f32 v[126:127], v[126:127], v[166:167]
	v_pk_mul_f32 v[124:125], v[124:125], v[120:121]
	v_pk_mul_f32 v[148:149], v[148:149], v[168:169]
	v_pk_mul_f32 v[150:151], v[150:151], v[122:123]

; #define PG8_STAGE(bufoff, gbase, voff) do { _Pragma("unroll") for (int _i = 0; _i < 2; ++_i) \
;         __builtin_amdgcn_global_load_lds((const unsigned*)((const char*)(gbase) + (voff)[_i]), (LAS unsigned*)(lds + (bufoff) + ldsw + _i * 8192), 16, 0, 0); } while (0)
; #define PG8_LDA(dst, b, h) do { _Pragma("unroll") for (int m = 0; m < 4; ++m) _Pragma("unroll") for (int k = 0; k < 2; ++k) dst[m][k] = *(const LAS bf16x8*)(lds + PG8_SA(b, h) + aoff + m * 2048 + k * 1024); } while (0)
; #define PG8_LDB(dst, b, h) do { _Pragma("unroll") for (int n = 0; n < 2; ++n) _Pragma("unroll") for (int k = 0; k < 2; ++k) dst[n][k] = *(const LAS bf16x8*)(lds + PG8_SB(b, h) + boff + n * 2048 + k * 1024); } while (0)
; #define PG8_MMA(ai, bj, At, Bt) do { __builtin_amdgcn_s_setprio(1); _Pragma("unroll") for (int m = 0; m < 4; ++m) _Pragma("unroll") for (int n = 0; n < 2; ++n) _Pragma("unroll") for (int k = 0; k < 2; ++k) \
;         acc[ai][bj][m][n] = __builtin_amdgcn_mfma_f32_16x16x32_bf16(Bt[n][k], At[m][k], acc[ai][bj][m][n], 0, 0, 0); __builtin_amdgcn_s_setprio(0); } while (0)
; #define PG8_WAIT_L(n) asm volatile("s_waitcnt lgkmcnt(" #n ")" ::: "memory")
; #define PG8_BAR __builtin_amdgcn_s_barrier()
; #define PG8_SCHED __builtin_amdgcn_sched_barrier(0)
; template <class Epi>
; __device__ __forceinline__ void gemm_phase(LAS unsigned char* lds, const Gemm g, const StaticOrder& S, const Epi& E, int wv) {
;     ...
;         const bool has_next = S.next(ui + 1, nxt);
;         const char* nA = has_next ? (const char*)g.A + (size_t)nxt.pm * tstepA + ((g.adiag & 1) ? (size_t)(nxt.pn >> 1) * K * 2 : 0) + kbeg : cA;
;         const char* nB = has_next ? (const char*)g.Bt + (size_t)nxt.pn * tstepB + kbeg : cB;
;         for (int t = 0; t < nt; t += 2) {
;             const bool last = (t == nt - 2);
;             const char* a1 = cA + (ptrdiff_t)(t + 1) * kstep;
;             const char* a2 = last ? nA : cA + (ptrdiff_t)(t + 2) * kstep; const char* b2 = last ? nB : cB + (ptrdiff_t)(t + 2) * kstep;
;             const char* a3 = a2 + kstep; const char* b3 = b2 + kstep;
;             PG8_LDB(B0, 0, 0); PG8_SCHED; PG8_LDA(At, 0, 0); PG8_STAGE(PG8_SA(1, 1), a1 + hstepA, voffA);
;             PG8_WAIT_L(8); PG8_BAR; PG8_WAIT_L(0); PG8_MMA(0, 0, At, B0); PG8_BAR; PG8_SCHED;
.LBB0_1580:
	s_ashr_i32 s37, s36, 31
	v_cmp_lt_i64_e32 vcc, s[38:39], v[156:157]
	s_lshl_b64 s[38:39], s[36:37], 20
	s_add_u32 s38, s5, s38
	s_addc_u32 s39, s22, s39
	s_and_b64 s[40:41], vcc, exec
	s_cselect_b32 s37, s39, s47
	s_cselect_b32 s43, s38, s46
	s_ashr_i32 s35, s34, 31
	s_lshl_b64 s[40:41], s[34:35], 20
	s_add_u32 s40, s23, s40
	s_addc_u32 s41, s24, s41
	s_and_b64 s[50:51], vcc, exec
	s_cselect_b32 s35, s41, s49
	s_cselect_b32 s60, s40, s48
	s_add_u32 s61, s48, 0x100
	s_addc_u32 s62, s49, 0
	s_add_u32 s46, s46, 0x80080
	v_mov_b32_e32 v0, 0
	s_addc_u32 s47, s47, 0
	s_mov_b32 s63, -2
	s_waitcnt lgkmcnt(0)
	v_mov_b32_e32 v1, v0
	v_mov_b32_e32 v2, v0
	v_mov_b32_e32 v3, v0
	v_mov_b32_e32 v4, v0
	v_mov_b32_e32 v5, v0
	v_mov_b32_e32 v6, v0
	v_mov_b32_e32 v7, v0
	v_mov_b32_e32 v16, v0
	v_mov_b32_e32 v17, v0
	v_mov_b32_e32 v18, v0
	v_mov_b32_e32 v19, v0
	v_mov_b32_e32 v20, v0
	v_mov_b32_e32 v21, v0
	v_mov_b32_e32 v22, v0
	v_mov_b32_e32 v23, v0
	v_mov_b32_e32 v32, v0
	v_mov_b32_e32 v33, v0
	v_mov_b32_e32 v34, v0
	v_mov_b32_e32 v35, v0
	v_mov_b32_e32 v36, v0
	v_mov_b32_e32 v37, v0
	v_mov_b32_e32 v38, v0
	v_mov_b32_e32 v39, v0
	v_mov_b32_e32 v48, v0
	v_mov_b32_e32 v49, v0
	v_mov_b32_e32 v50, v0
	v_mov_b32_e32 v51, v0
	v_mov_b32_e32 v52, v0
	v_mov_b32_e32 v53, v0
	v_mov_b32_e32 v54, v0
	v_mov_b32_e32 v55, v0
	v_mov_b32_e32 v8, v0
	v_mov_b32_e32 v9, v0
	v_mov_b32_e32 v10, v0
	v_mov_b32_e32 v11, v0
	v_mov_b32_e32 v12, v0
	v_mov_b32_e32 v13, v0
	v_mov_b32_e32 v14, v0
	v_mov_b32_e32 v15, v0
	v_mov_b32_e32 v24, v0
	v_mov_b32_e32 v25, v0
	v_mov_b32_e32 v26, v0
	v_mov_b32_e32 v27, v0
	v_mov_b32_e32 v28, v0
	v_mov_b32_e32 v29, v0
	v_mov_b32_e32 v30, v0
	v_mov_b32_e32 v31, v0
	v_mov_b32_e32 v40, v0
	v_mov_b32_e32 v41, v0
	v_mov_b32_e32 v42, v0
	v_mov_b32_e32 v43, v0
	v_mov_b32_e32 v44, v0
	v_mov_b32_e32 v45, v0
	v_mov_b32_e32 v46, v0
	v_mov_b32_e32 v47, v0
	v_mov_b32_e32 v56, v0
	v_mov_b32_e32 v57, v0
	v_mov_b32_e32 v58, v0
	v_mov_b32_e32 v59, v0
	v_mov_b32_e32 v60, v0
	v_mov_b32_e32 v61, v0
	v_mov_b32_e32 v62, v0
	v_mov_b32_e32 v63, v0
	v_mov_b32_e32 v64, v0
	v_mov_b32_e32 v65, v0
	v_mov_b32_e32 v66, v0
	v_mov_b32_e32 v67, v0
	v_mov_b32_e32 v68, v0
	v_mov_b32_e32 v69, v0
	v_mov_b32_e32 v70, v0
	v_mov_b32_e32 v71, v0
	v_mov_b32_e32 v80, v0
	v_mov_b32_e32 v81, v0
	v_mov_b32_e32 v82, v0
	v_mov_b32_e32 v83, v0
	v_mov_b32_e32 v84, v0
	v_mov_b32_e32 v85, v0
	v_mov_b32_e32 v86, v0
	v_mov_b32_e32 v87, v0
	v_mov_b32_e32 v96, v0
	v_mov_b32_e32 v97, v0
	v_mov_b32_e32 v98, v0
	v_mov_b32_e32 v99, v0
	v_mov_b32_e32 v100, v0
	v_mov_b32_e32 v101, v0
	v_mov_b32_e32 v102, v0
	v_mov_b32_e32 v103, v0
	v_mov_b32_e32 v112, v0
	v_mov_b32_e32 v113, v0
	v_mov_b32_e32 v114, v0
	v_mov_b32_e32 v115, v0
	v_mov_b32_e32 v116, v0
	v_mov_b32_e32 v117, v0
	v_mov_b32_e32 v118, v0
	v_mov_b32_e32 v119, v0
	v_mov_b32_e32 v72, v0
	v_mov_b32_e32 v73, v0
	v_mov_b32_e32 v74, v0
	v_mov_b32_e32 v75, v0
	v_mov_b32_e32 v76, v0
	v_mov_b32_e32 v77, v0
	v_mov_b32_e32 v78, v0
	v_mov_b32_e32 v79, v0
	v_mov_b32_e32 v88, v0
	v_mov_b32_e32 v89, v0
	v_mov_b32_e32 v90, v0
	v_mov_b32_e32 v91, v0
	v_mov_b32_e32 v92, v0
	v_mov_b32_e32 v93, v0
	v_mov_b32_e32 v94, v0
	v_mov_b32_e32 v95, v0
	v_mov_b32_e32 v104, v0
	v_mov_b32_e32 v105, v0
	v_mov_b32_e32 v106, v0
	v_mov_b32_e32 v107, v0
	v_mov_b32_e32 v108, v0
	v_mov_b32_e32 v109, v0
	v_mov_b32_e32 v110, v0
	v_mov_b32_e32 v111, v0
	v_mov_b32_e32 v120, v0
	v_mov_b32_e32 v121, v0
	v_mov_b32_e32 v122, v0
	v_mov_b32_e32 v123, v0
	v_mov_b32_e32 v124, v0
	v_mov_b32_e32 v125, v0
	v_mov_b32_e32 v126, v0
	v_mov_b32_e32 v127, v0
	ds_read_b128 v[128:131], v179
	ds_read_b128 v[132:135], v179 offset:1024
	ds_read_b128 v[136:139], v179 offset:2048
	ds_read_b128 v[140:143], v179 offset:3072
.LBB0_1581:
	s_add_u32 s48, s46, 0xfff80080
	s_addc_u32 s49, s47, -1
	s_cmp_eq_u32 s63, 28
	s_cselect_b32 s51, s37, s49
	s_cselect_b32 s50, s43, s48
	s_cselect_b32 s49, s35, s62
	s_cselect_b32 s48, s60, s61
	s_add_i32 m0, s33, 0xc000
	ds_read_b128 v[160:163], v180
	ds_read_b128 v[164:167], v180 offset:1024
	ds_read_b128 v[168:171], v180 offset:2048
	ds_read_b128 v[172:175], v180 offset:3072
	ds_read_b128 v[182:185], v180 offset:4096
	ds_read_b128 v[186:189], v180 offset:5120
	ds_read_b128 v[190:193], v180 offset:6144
	ds_read_b128 v[194:197], v180 offset:7168
	global_load_lds_dwordx4 v154, s[46:47]
	s_add_i32 m0, s33, 0xe000
	s_nop 0
	global_load_lds_dwordx4 v152, s[46:47]
	s_waitcnt lgkmcnt(8)
	s_barrier
	s_waitcnt lgkmcnt(0)
	s_setprio 1
	s_waitcnt lgkmcnt(0)
	v_mfma_f32_16x16x32_bf16 v[124:127], v[128:131], v[160:163], v[124:127]
	v_mfma_f32_16x16x32_bf16 v[120:123], v[136:139], v[160:163], v[120:123]
	v_mfma_f32_16x16x32_bf16 v[108:111], v[128:131], v[168:171], v[108:111]
	v_mfma_f32_16x16x32_bf16 v[104:107], v[136:139], v[168:171], v[104:107]
	v_mfma_f32_16x16x32_bf16 v[92:95], v[128:131], v[182:185], v[92:95]
	v_mfma_f32_16x16x32_bf16 v[88:91], v[136:139], v[182:185], v[88:91]
	v_mfma_f32_16x16x32_bf16 v[76:79], v[128:131], v[190:193], v[76:79]
	v_mfma_f32_16x16x32_bf16 v[72:75], v[136:139], v[190:193], v[72:75]
	v_mfma_f32_16x16x32_bf16 v[124:127], v[132:135], v[164:167], v[124:127]
	v_mfma_f32_16x16x32_bf16 v[120:123], v[140:143], v[164:167], v[120:123]
	v_mfma_f32_16x16x32_bf16 v[108:111], v[132:135], v[172:175], v[108:111]
	v_mfma_f32_16x16x32_bf16 v[104:107], v[140:143], v[172:175], v[104:107]
	v_mfma_f32_16x16x32_bf16 v[92:95], v[132:135], v[186:189], v[92:95]
	v_mfma_f32_16x16x32_bf16 v[88:91], v[140:143], v[186:189], v[88:91]
	v_mfma_f32_16x16x32_bf16 v[76:79], v[132:135], v[194:197], v[76:79]
	v_mfma_f32_16x16x32_bf16 v[72:75], v[140:143], v[194:197], v[72:75]
	s_setprio 0
	s_barrier
; #define PG8_STAGE(bufoff, gbase, voff) do { _Pragma("unroll") for (int _i = 0; _i < 2; ++_i) \
;         __builtin_amdgcn_global_load_lds((const unsigned*)((const char*)(gbase) + (voff)[_i]), (LAS unsigned*)(lds + (bufoff) + ldsw + _i * 8192), 16, 0, 0); } while (0)
; #define PG8_LDA(dst, b, h) do { _Pragma("unroll") for (int m = 0; m < 4; ++m) _Pragma("unroll") for (int k = 0; k < 2; ++k) dst[m][k] = *(const LAS bf16x8*)(lds + PG8_SA(b, h) + aoff + m * 2048 + k * 1024); } while (0)
; #define PG8_LDB(dst, b, h) do { _Pragma("unroll") for (int n = 0; n < 2; ++n) _Pragma("unroll") for (int k = 0; k < 2; ++k) dst[n][k] = *(const LAS bf16x8*)(lds + PG8_SB(b, h) + boff + n * 2048 + k * 1024); } while (0)
; #define PG8_MMA(ai, bj, At, Bt) do { __builtin_amdgcn_s_setprio(1); _Pragma("unroll") for (int m = 0; m < 4; ++m) _Pragma("unroll") for (int n = 0; n < 2; ++n) _Pragma("unroll") for (int k = 0; k < 2; ++k) \
;         acc[ai][bj][m][n] = __builtin_amdgcn_mfma_f32_16x16x32_bf16(Bt[n][k], At[m][k], acc[ai][bj][m][n], 0, 0, 0); __builtin_amdgcn_s_setprio(0); } while (0)
; #define PG8_WAIT_V(n) asm volatile("s_waitcnt vmcnt(" #n ")" ::: "memory")
; #define PG8_WAIT_L(n) asm volatile("s_waitcnt lgkmcnt(" #n ")" ::: "memory")
; #define PG8_BAR __builtin_amdgcn_s_barrier()
; #define PG8_SCHED __builtin_amdgcn_sched_barrier(0)
; template <class Epi>
; __device__ __forceinline__ void gemm_phase(LAS unsigned char* lds, const Gemm g, const StaticOrder& S, const Epi& E, int wv) {
;     ...
;             PG8_LDB(B1, 0, 1); PG8_STAGE(PG8_SB(0, 0), b2, voffB);
;             PG8_BAR; PG8_WAIT_L(0); PG8_MMA(0, 1, At, B1); PG8_BAR;
;             PG8_LDA(At, 0, 1); PG8_STAGE(PG8_SA(0, 0), a2, voffA);
;             PG8_BAR; PG8_WAIT_L(0); PG8_MMA(1, 0, At, B0); PG8_BAR; PG8_SCHED;
;             PG8_STAGE(PG8_SB(0, 1), b2 + hstepB, voffB);
;             PG8_WAIT_V(6); PG8_BAR; PG8_MMA(1, 1, At, B1); PG8_BAR;
;             PG8_LDB(B0, 1, 0); PG8_SCHED; PG8_LDA(At, 1, 0); PG8_STAGE(PG8_SA(0, 1), a2 + hstepA, voffA);
	s_add_i32 s64, s57, s25
	s_add_u32 s98, s48, s16
	s_addc_u32 s99, s49, s17
	s_mov_b32 m0, s64
	ds_read_b128 v[198:201], v181
	ds_read_b128 v[202:205], v181 offset:1024
	ds_read_b128 v[206:209], v181 offset:2048
	ds_read_b128 v[210:213], v181 offset:3072
	global_load_lds_dwordx4 v146, s[48:49]
	s_add_i32 m0, s64, 0x2000
	s_nop 0
	global_load_lds_dwordx4 v150, s[48:49]
	s_barrier
	s_waitcnt lgkmcnt(0)
	s_setprio 1
	s_waitcnt lgkmcnt(0)
	v_mfma_f32_16x16x32_bf16 v[116:119], v[198:201], v[160:163], v[116:119]
	v_mfma_f32_16x16x32_bf16 v[112:115], v[206:209], v[160:163], v[112:115]
	v_mfma_f32_16x16x32_bf16 v[100:103], v[198:201], v[168:171], v[100:103]
	v_mfma_f32_16x16x32_bf16 v[96:99], v[206:209], v[168:171], v[96:99]
	v_mfma_f32_16x16x32_bf16 v[84:87], v[198:201], v[182:185], v[84:87]
	v_mfma_f32_16x16x32_bf16 v[80:83], v[206:209], v[182:185], v[80:83]
	v_mfma_f32_16x16x32_bf16 v[68:71], v[198:201], v[190:193], v[68:71]
	v_mfma_f32_16x16x32_bf16 v[64:67], v[206:209], v[190:193], v[64:67]
	v_mfma_f32_16x16x32_bf16 v[116:119], v[202:205], v[164:167], v[116:119]
	v_mfma_f32_16x16x32_bf16 v[112:115], v[210:213], v[164:167], v[112:115]
	v_mfma_f32_16x16x32_bf16 v[100:103], v[202:205], v[172:175], v[100:103]
	v_mfma_f32_16x16x32_bf16 v[96:99], v[210:213], v[172:175], v[96:99]
	v_mfma_f32_16x16x32_bf16 v[84:87], v[202:205], v[186:189], v[84:87]
	v_mfma_f32_16x16x32_bf16 v[80:83], v[210:213], v[186:189], v[80:83]
	v_mfma_f32_16x16x32_bf16 v[68:71], v[202:205], v[194:197], v[68:71]
	v_mfma_f32_16x16x32_bf16 v[64:67], v[210:213], v[194:197], v[64:67]
	s_setprio 0
	s_mov_b32 m0, s33
	s_add_u32 s100, s50, s16
	s_addc_u32 s101, s51, s17
	s_barrier
	ds_read_b128 v[160:163], v180 offset:16384
	ds_read_b128 v[164:167], v180 offset:17408
	ds_read_b128 v[168:171], v180 offset:18432
	ds_read_b128 v[172:175], v180 offset:19456
	ds_read_b128 v[182:185], v180 offset:20480
	ds_read_b128 v[186:189], v180 offset:21504
	ds_read_b128 v[190:193], v180 offset:22528
	ds_read_b128 v[194:197], v180 offset:23552
	global_load_lds_dwordx4 v144, s[50:51]
	s_mov_b32 m0, s45
	s_nop 0
	global_load_lds_dwordx4 v148, s[50:51]
	s_waitcnt vmcnt(10)
	s_barrier
	s_waitcnt lgkmcnt(0)
	s_setprio 1
	s_waitcnt lgkmcnt(0)
	v_mfma_f32_16x16x32_bf16 v[60:63], v[128:131], v[160:163], v[60:63]
	v_mfma_f32_16x16x32_bf16 v[56:59], v[136:139], v[160:163], v[56:59]
	v_mfma_f32_16x16x32_bf16 v[44:47], v[128:131], v[168:171], v[44:47]
	v_mfma_f32_16x16x32_bf16 v[40:43], v[136:139], v[168:171], v[40:43]
	v_mfma_f32_16x16x32_bf16 v[28:31], v[128:131], v[182:185], v[28:31]
	v_mfma_f32_16x16x32_bf16 v[24:27], v[136:139], v[182:185], v[24:27]
	v_mfma_f32_16x16x32_bf16 v[12:15], v[128:131], v[190:193], v[12:15]
	v_mfma_f32_16x16x32_bf16 v[8:11], v[136:139], v[190:193], v[8:11]
	v_mfma_f32_16x16x32_bf16 v[60:63], v[132:135], v[164:167], v[60:63]
	v_mfma_f32_16x16x32_bf16 v[56:59], v[140:143], v[164:167], v[56:59]
	v_mfma_f32_16x16x32_bf16 v[44:47], v[132:135], v[172:175], v[44:47]
	v_mfma_f32_16x16x32_bf16 v[40:43], v[140:143], v[172:175], v[40:43]
	v_mfma_f32_16x16x32_bf16 v[28:31], v[132:135], v[186:189], v[28:31]
	v_mfma_f32_16x16x32_bf16 v[24:27], v[140:143], v[186:189], v[24:27]
	v_mfma_f32_16x16x32_bf16 v[12:15], v[132:135], v[194:197], v[12:15]
	v_mfma_f32_16x16x32_bf16 v[8:11], v[140:143], v[194:197], v[8:11]
	s_setprio 0
	s_barrier
	s_add_u32 s64, s48, 0x80000
	s_addc_u32 s65, s49, 0
	s_add_i32 s66, s58, s25
	s_mov_b32 m0, s66
	s_nop 0
	global_load_lds_dwordx4 v146, s[64:65]
	s_add_i32 m0, s66, 0x2000
	s_nop 0
	global_load_lds_dwordx4 v150, s[64:65]
	s_add_i32 s64, 0, 0x18000
	v_add_u32_e32 v140, s64, v177
	ds_read_b128 v[128:131], v140
	ds_read_b128 v[132:135], v140 offset:1024
	ds_read_b128 v[136:139], v140 offset:2048
	ds_read_b128 v[140:143], v140 offset:3072
	s_waitcnt vmcnt(6)
	s_barrier
	s_setprio 1
	v_mfma_f32_16x16x32_bf16 v[52:55], v[198:201], v[160:163], v[52:55]
	v_mfma_f32_16x16x32_bf16 v[48:51], v[206:209], v[160:163], v[48:51]
	v_mfma_f32_16x16x32_bf16 v[36:39], v[198:201], v[168:171], v[36:39]
	v_mfma_f32_16x16x32_bf16 v[32:35], v[206:209], v[168:171], v[32:35]
	v_mfma_f32_16x16x32_bf16 v[20:23], v[198:201], v[182:185], v[20:23]
	v_mfma_f32_16x16x32_bf16 v[16:19], v[206:209], v[182:185], v[16:19]
	v_mfma_f32_16x16x32_bf16 v[4:7], v[198:201], v[190:193], v[4:7]
	v_mfma_f32_16x16x32_bf16 v[0:3], v[206:209], v[190:193], v[0:3]
	v_mfma_f32_16x16x32_bf16 v[52:55], v[202:205], v[164:167], v[52:55]
	v_mfma_f32_16x16x32_bf16 v[48:51], v[210:213], v[164:167], v[48:51]
	v_mfma_f32_16x16x32_bf16 v[36:39], v[202:205], v[172:175], v[36:39]
	v_mfma_f32_16x16x32_bf16 v[32:35], v[210:213], v[172:175], v[32:35]
	v_mfma_f32_16x16x32_bf16 v[20:23], v[202:205], v[186:189], v[20:23]
	v_mfma_f32_16x16x32_bf16 v[16:19], v[210:213], v[186:189], v[16:19]
	v_mfma_f32_16x16x32_bf16 v[4:7], v[202:205], v[194:197], v[4:7]
	v_mfma_f32_16x16x32_bf16 v[0:3], v[210:213], v[194:197], v[0:3]
	s_setprio 0
	s_waitcnt lgkmcnt(0)
	s_barrier
	s_add_u32 s50, s50, 0x80000
	s_addc_u32 s51, s51, 0
	s_mov_b32 m0, s52
	ds_read_b128 v[160:163], v180 offset:32768
	ds_read_b128 v[164:167], v180 offset:33792
	ds_read_b128 v[168:171], v180 offset:34816
	ds_read_b128 v[172:175], v180 offset:35840
	ds_read_b128 v[182:185], v180 offset:36864
	ds_read_b128 v[186:189], v180 offset:37888
	ds_read_b128 v[190:193], v180 offset:38912
	ds_read_b128 v[194:197], v180 offset:39936
	global_load_lds_dwordx4 v144, s[50:51]
	s_mov_b32 m0, s53
	s_nop 0
	global_load_lds_dwordx4 v148, s[50:51]
	s_waitcnt lgkmcnt(8)
	s_barrier
; #define PG8_STAGE(bufoff, gbase, voff) do { _Pragma("unroll") for (int _i = 0; _i < 2; ++_i) \
;         __builtin_amdgcn_global_load_lds((const unsigned*)((const char*)(gbase) + (voff)[_i]), (LAS unsigned*)(lds + (bufoff) + ldsw + _i * 8192), 16, 0, 0); } while (0)
; #define PG8_LDA(dst, b, h) do { _Pragma("unroll") for (int m = 0; m < 4; ++m) _Pragma("unroll") for (int k = 0; k < 2; ++k) dst[m][k] = *(const LAS bf16x8*)(lds + PG8_SA(b, h) + aoff + m * 2048 + k * 1024); } while (0)
; #define PG8_LDB(dst, b, h) do { _Pragma("unroll") for (int n = 0; n < 2; ++n) _Pragma("unroll") for (int k = 0; k < 2; ++k) dst[n][k] = *(const LAS bf16x8*)(lds + PG8_SB(b, h) + boff + n * 2048 + k * 1024); } while (0)
; #define PG8_MMA(ai, bj, At, Bt) do { __builtin_amdgcn_s_setprio(1); _Pragma("unroll") for (int m = 0; m < 4; ++m) _Pragma("unroll") for (int n = 0; n < 2; ++n) _Pragma("unroll") for (int k = 0; k < 2; ++k) \
;         acc[ai][bj][m][n] = __builtin_amdgcn_mfma_f32_16x16x32_bf16(Bt[n][k], At[m][k], acc[ai][bj][m][n], 0, 0, 0); __builtin_amdgcn_s_setprio(0); } while (0)
; #define PG8_WAIT_V(n) asm volatile("s_waitcnt vmcnt(" #n ")" ::: "memory")
; #define PG8_WAIT_L(n) asm volatile("s_waitcnt lgkmcnt(" #n ")" ::: "memory")
; #define PG8_BAR __builtin_amdgcn_s_barrier()
; #define PG8_SCHED __builtin_amdgcn_sched_barrier(0)
; template <class Epi>
; __device__ __forceinline__ void gemm_phase(LAS unsigned char* lds, const Gemm g, const StaticOrder& S, const Epi& E, int wv) {
;     ...
;             PG8_WAIT_L(8); PG8_BAR; PG8_WAIT_L(0); PG8_MMA(0, 0, At, B0); PG8_BAR; PG8_SCHED;
;             PG8_LDB(B1, 1, 1); PG8_STAGE(PG8_SB(1, 0), b3, voffB);
;             PG8_BAR; PG8_WAIT_L(0); PG8_MMA(0, 1, At, B1); PG8_BAR;
;             PG8_LDA(At, 1, 1); PG8_STAGE(PG8_SA(1, 0), a3, voffA);
;             PG8_BAR; PG8_WAIT_L(0); PG8_MMA(1, 0, At, B0); PG8_BAR; PG8_SCHED;
;             PG8_STAGE(PG8_SB(1, 1), b3 + hstepB, voffB);
;             PG8_WAIT_V(6); PG8_BAR; PG8_MMA(1, 1, At, B1); PG8_BAR;
	s_waitcnt lgkmcnt(0)
	s_setprio 1
	s_waitcnt lgkmcnt(0)
	v_mfma_f32_16x16x32_bf16 v[124:127], v[128:131], v[160:163], v[124:127]
	v_mfma_f32_16x16x32_bf16 v[120:123], v[136:139], v[160:163], v[120:123]
	v_mfma_f32_16x16x32_bf16 v[108:111], v[128:131], v[168:171], v[108:111]
	v_mfma_f32_16x16x32_bf16 v[104:107], v[136:139], v[168:171], v[104:107]
	v_mfma_f32_16x16x32_bf16 v[92:95], v[128:131], v[182:185], v[92:95]
	v_mfma_f32_16x16x32_bf16 v[88:91], v[136:139], v[182:185], v[88:91]
	v_mfma_f32_16x16x32_bf16 v[76:79], v[128:131], v[190:193], v[76:79]
	v_mfma_f32_16x16x32_bf16 v[72:75], v[136:139], v[190:193], v[72:75]
	v_mfma_f32_16x16x32_bf16 v[124:127], v[132:135], v[164:167], v[124:127]
	v_mfma_f32_16x16x32_bf16 v[120:123], v[140:143], v[164:167], v[120:123]
	v_mfma_f32_16x16x32_bf16 v[108:111], v[132:135], v[172:175], v[108:111]
	v_mfma_f32_16x16x32_bf16 v[104:107], v[140:143], v[172:175], v[104:107]
	v_mfma_f32_16x16x32_bf16 v[92:95], v[132:135], v[186:189], v[92:95]
	v_mfma_f32_16x16x32_bf16 v[88:91], v[140:143], v[186:189], v[88:91]
	v_mfma_f32_16x16x32_bf16 v[76:79], v[132:135], v[194:197], v[76:79]
	v_mfma_f32_16x16x32_bf16 v[72:75], v[140:143], v[194:197], v[72:75]
	s_setprio 0
	s_barrier
	s_add_i32 s50, 0, 0x1c000
	s_add_i32 s51, s64, s25
	v_add_u32_e32 v210, s50, v177
	s_mov_b32 m0, s51
	ds_read_b128 v[198:201], v210
	ds_read_b128 v[202:205], v210 offset:1024
	ds_read_b128 v[206:209], v210 offset:2048
	ds_read_b128 v[210:213], v210 offset:3072
	global_load_lds_dwordx4 v146, s[98:99]
	s_add_i32 m0, s51, 0x2000
	s_nop 0
	global_load_lds_dwordx4 v150, s[98:99]
	s_barrier
	s_waitcnt lgkmcnt(0)
	s_setprio 1
	s_waitcnt lgkmcnt(0)
	v_mfma_f32_16x16x32_bf16 v[116:119], v[198:201], v[160:163], v[116:119]
	v_mfma_f32_16x16x32_bf16 v[112:115], v[206:209], v[160:163], v[112:115]
	v_mfma_f32_16x16x32_bf16 v[100:103], v[198:201], v[168:171], v[100:103]
	v_mfma_f32_16x16x32_bf16 v[96:99], v[206:209], v[168:171], v[96:99]
	v_mfma_f32_16x16x32_bf16 v[84:87], v[198:201], v[182:185], v[84:87]
	v_mfma_f32_16x16x32_bf16 v[80:83], v[206:209], v[182:185], v[80:83]
	v_mfma_f32_16x16x32_bf16 v[68:71], v[198:201], v[190:193], v[68:71]
	v_mfma_f32_16x16x32_bf16 v[64:67], v[206:209], v[190:193], v[64:67]
	v_mfma_f32_16x16x32_bf16 v[116:119], v[202:205], v[164:167], v[116:119]
	v_mfma_f32_16x16x32_bf16 v[112:115], v[210:213], v[164:167], v[112:115]
	v_mfma_f32_16x16x32_bf16 v[100:103], v[202:205], v[172:175], v[100:103]
	v_mfma_f32_16x16x32_bf16 v[96:99], v[210:213], v[172:175], v[96:99]
	v_mfma_f32_16x16x32_bf16 v[84:87], v[202:205], v[186:189], v[84:87]
	v_mfma_f32_16x16x32_bf16 v[80:83], v[210:213], v[186:189], v[80:83]
	v_mfma_f32_16x16x32_bf16 v[68:71], v[202:205], v[194:197], v[68:71]
	v_mfma_f32_16x16x32_bf16 v[64:67], v[210:213], v[194:197], v[64:67]
	s_setprio 0
	s_mov_b32 m0, s55
	s_barrier
	ds_read_b128 v[160:163], v180 offset:49152
	ds_read_b128 v[164:167], v180 offset:50176
	ds_read_b128 v[168:171], v180 offset:51200
	ds_read_b128 v[172:175], v180 offset:52224
	ds_read_b128 v[182:185], v180 offset:53248
	ds_read_b128 v[186:189], v180 offset:54272
	ds_read_b128 v[190:193], v180 offset:55296
	ds_read_b128 v[194:197], v180 offset:56320
	global_load_lds_dwordx4 v144, s[100:101]
	s_mov_b32 m0, s56
	s_nop 0
	global_load_lds_dwordx4 v148, s[100:101]
	s_waitcnt vmcnt(10)
	s_barrier
	s_waitcnt lgkmcnt(0)
	s_setprio 1
	s_waitcnt lgkmcnt(0)
	v_mfma_f32_16x16x32_bf16 v[60:63], v[128:131], v[160:163], v[60:63]
	v_mfma_f32_16x16x32_bf16 v[56:59], v[136:139], v[160:163], v[56:59]
	v_mfma_f32_16x16x32_bf16 v[44:47], v[128:131], v[168:171], v[44:47]
	v_mfma_f32_16x16x32_bf16 v[40:43], v[136:139], v[168:171], v[40:43]
	v_mfma_f32_16x16x32_bf16 v[28:31], v[128:131], v[182:185], v[28:31]
	v_mfma_f32_16x16x32_bf16 v[24:27], v[136:139], v[182:185], v[24:27]
	v_mfma_f32_16x16x32_bf16 v[12:15], v[128:131], v[190:193], v[12:15]
	v_mfma_f32_16x16x32_bf16 v[8:11], v[136:139], v[190:193], v[8:11]
	v_mfma_f32_16x16x32_bf16 v[60:63], v[132:135], v[164:167], v[60:63]
	v_mfma_f32_16x16x32_bf16 v[56:59], v[140:143], v[164:167], v[56:59]
	v_mfma_f32_16x16x32_bf16 v[44:47], v[132:135], v[172:175], v[44:47]
	v_mfma_f32_16x16x32_bf16 v[40:43], v[140:143], v[172:175], v[40:43]
	v_mfma_f32_16x16x32_bf16 v[28:31], v[132:135], v[186:189], v[28:31]
	v_mfma_f32_16x16x32_bf16 v[24:27], v[140:143], v[186:189], v[24:27]
	v_mfma_f32_16x16x32_bf16 v[12:15], v[132:135], v[194:197], v[12:15]
	v_mfma_f32_16x16x32_bf16 v[8:11], v[140:143], v[194:197], v[8:11]
	s_setprio 0
	s_barrier
	s_add_u32 s48, s48, 0x80080
	s_addc_u32 s49, s49, 0
	s_add_i32 s50, s50, s25
	s_mov_b32 m0, s50
	s_nop 0
	global_load_lds_dwordx4 v146, s[48:49]
	s_add_i32 m0, s50, 0x2000
	s_nop 0
	global_load_lds_dwordx4 v150, s[48:49]
	ds_read_b128 v[128:131], v179
	ds_read_b128 v[132:135], v179 offset:1024
	ds_read_b128 v[136:139], v179 offset:2048
	ds_read_b128 v[140:143], v179 offset:3072
	s_waitcnt vmcnt(6)
	s_barrier
; #define PG8_BAR __builtin_amdgcn_s_barrier()
; template <class Epi>
; __device__ __forceinline__ void gemm_phase(LAS unsigned char* lds, const Gemm g, const StaticOrder& S, const Epi& E, int wv) {
;     ...
;             PG8_WAIT_V(6); PG8_BAR; PG8_MMA(1, 1, At, B1); PG8_BAR;
;         }
;     __device__ __forceinline__ void operator()(const f32x4 (&acc)[2][2][4][2], const Unit& u, int wr, int wc, int fr, int fq) const {
;     ...
;         RES_LOAD(0, 0); RES_LOAD(1, 1);
; #pragma unroll
;         for (int it = 0; it < 8; ++it) { const int ai = it >> 2, m = it & 3, sc = it % RD;
;             if (it + RD - 1 < 8) RES_LOAD((it + RD - 1) % RD, it + RD - 1);
;             asm volatile("" ::: "memory");
;             const int row = row0 + ai * HALF + m * 16; const size_t ro = (size_t)row * DM + col0;
;             float rs = 1.0f; if (MODE == 1) rs = __builtin_amdgcn_rsqf(ss_fix(rsb[sc]) * (1.0f / DM) + EPS);
;             float sq = 0.f;
; #pragma unroll
;             for (int bj = 0; bj < 2; ++bj) { const size_t off = ro + bj * HALF;
;                 f32x4 v0 = acc[ai][bj][m][0], v1 = acc[ai][bj][m][1];
;                 if (MODE == 1) { const u32x4 pw = pbuf[sc][bj];
;                     v0[0] = fast_sigmoid(rs * v0[0]) * bf_lo(pw.x); v0[1] = fast_sigmoid(rs * v0[1]) * bf_hi(pw.x); v0[2] = fast_sigmoid(rs * v0[2]) * bf_lo(pw.y); v0[3] = fast_sigmoid(rs * v0[3]) * bf_hi(pw.y);
;                     v1[0] = fast_sigmoid(rs * v1[0]) * bf_lo(pw.z); v1[1] = fast_sigmoid(rs * v1[1]) * bf_hi(pw.z); v1[2] = fast_sigmoid(rs * v1[2]) * bf_lo(pw.w); v1[3] = fast_sigmoid(rs * v1[3]) * bf_hi(pw.w); }
;                 f32x4 h0, h1;
;                 if (IN16) { const u32x4 hw = hraw[sc][bj]; h0 = (f32x4){bf_lo(hw.x), bf_hi(hw.x), bf_lo(hw.y), bf_hi(hw.y)}; h1 = (f32x4){bf_lo(hw.z), bf_hi(hw.z), bf_lo(hw.w), bf_hi(hw.w)}; }
;                 else { h0 = hbuf[sc][2 * bj]; h1 = hbuf[sc][2 * bj + 1]; }
;                 const f32x4 o0 = h0 + v0, o1 = h1 + v1;
;                 if (OUT32) { *(f32x4*)(hout + off) = o0; *(f32x4*)(hout + off + 4) = o1; }
;                 if (hb) { u32x4 w; w.x = pk_bf16(o0[0], o0[1]); w.y = pk_bf16(o0[2], o0[3]); w.z = pk_bf16(o1[0], o1[1]); w.w = pk_bf16(o1[2], o1[3]); *(u32x4*)(hb + off) = w; }
;                 sq += ((o0[0] * o0[0] + o0[1] * o0[1]) + (o0[2] * o0[2] + o0[3] * o0[3])) + ((o1[0] * o1[0] + o1[1] * o1[1]) + (o1[2] * o1[2] + o1[3] * o1[3])); }
	s_setprio 1
	v_mfma_f32_16x16x32_bf16 v[52:55], v[198:201], v[160:163], v[52:55]
	v_mfma_f32_16x16x32_bf16 v[48:51], v[206:209], v[160:163], v[48:51]
	v_mfma_f32_16x16x32_bf16 v[36:39], v[198:201], v[168:171], v[36:39]
	v_mfma_f32_16x16x32_bf16 v[32:35], v[206:209], v[168:171], v[32:35]
	v_mfma_f32_16x16x32_bf16 v[20:23], v[198:201], v[182:185], v[20:23]
	v_mfma_f32_16x16x32_bf16 v[16:19], v[206:209], v[182:185], v[16:19]
	v_mfma_f32_16x16x32_bf16 v[4:7], v[198:201], v[190:193], v[4:7]
	v_mfma_f32_16x16x32_bf16 v[0:3], v[206:209], v[190:193], v[0:3]
	v_mfma_f32_16x16x32_bf16 v[52:55], v[202:205], v[164:167], v[52:55]
	v_mfma_f32_16x16x32_bf16 v[48:51], v[210:213], v[164:167], v[48:51]
	v_mfma_f32_16x16x32_bf16 v[36:39], v[202:205], v[172:175], v[36:39]
	v_mfma_f32_16x16x32_bf16 v[32:35], v[210:213], v[172:175], v[32:35]
	v_mfma_f32_16x16x32_bf16 v[20:23], v[202:205], v[186:189], v[20:23]
	v_mfma_f32_16x16x32_bf16 v[16:19], v[210:213], v[186:189], v[16:19]
	v_mfma_f32_16x16x32_bf16 v[4:7], v[202:205], v[194:197], v[4:7]
	v_mfma_f32_16x16x32_bf16 v[0:3], v[210:213], v[194:197], v[0:3]
	s_setprio 0
	s_waitcnt lgkmcnt(0)
	s_add_i32 s63, s63, 2
	s_add_u32 s61, s61, 0x100
	s_addc_u32 s62, s62, 0
	s_add_u32 s46, s46, 0x100
	s_addc_u32 s47, s47, 0
	s_cmp_gt_u32 s63, 29
	s_barrier
	s_cbranch_scc0 .LBB0_1581
	v_lshl_add_u32 v170, s42, 8, v176
	v_lshl_or_b32 v160, s44, 8, v178
	v_ashrrev_i32_e32 v171, 31, v170
	v_ashrrev_i32_e32 v161, 31, v160
	v_lshlrev_b64 v[190:191], 12, v[170:171]
	v_lshl_add_u64 v[128:129], s[10:11], 0, v[190:191]
	v_lshlrev_b64 v[162:163], 1, v[160:161]
	v_lshl_add_u64 v[164:165], v[128:129], 0, v[162:163]
	global_load_dwordx4 v[182:185], v[164:165], off
	global_load_dwordx4 v[186:189], v[164:165], off offset:256
	v_or_b32_e32 v172, 16, v170
	v_or_b32_e32 v166, 32, v170
	v_ashrrev_i32_e32 v173, 31, v172
	v_ashrrev_i32_e32 v167, 31, v166
	v_lshlrev_b64 v[174:175], 12, v[172:173]
	v_lshlrev_b64 v[168:169], 12, v[166:167]
	v_lshl_add_u64 v[128:129], s[10:11], 0, v[174:175]
	v_lshl_add_u64 v[130:131], s[10:11], 0, v[168:169]
	v_lshl_add_u64 v[128:129], v[128:129], 0, v[162:163]
	v_lshl_add_u64 v[130:131], v[130:131], 0, v[162:163]
	global_load_dwordx4 v[140:143], v[128:129], off
	global_load_dwordx4 v[136:139], v[128:129], off offset:256
	global_load_dwordx4 v[132:135], v[130:131], off
	s_nop 0
	global_load_dwordx4 v[128:131], v[130:131], off offset:256
	s_waitcnt vmcnt(0)
	v_lshlrev_b32_e32 v192, 16, v182
	v_and_b32_e32 v193, 0xffff0000, v182
	v_lshlrev_b32_e32 v182, 16, v183
	v_and_b32_e32 v183, 0xffff0000, v183
	v_lshlrev_b32_e32 v194, 16, v184
	v_and_b32_e32 v195, 0xffff0000, v184
	v_lshlrev_b32_e32 v184, 16, v185
	v_and_b32_e32 v185, 0xffff0000, v185
	v_lshlrev_b32_e32 v196, 16, v186
	v_and_b32_e32 v197, 0xffff0000, v186
	v_lshlrev_b32_e32 v186, 16, v187
	v_and_b32_e32 v187, 0xffff0000, v187
	v_lshlrev_b32_e32 v198, 16, v188
	v_and_b32_e32 v199, 0xffff0000, v188
	v_lshlrev_b32_e32 v188, 16, v189
	v_and_b32_e32 v189, 0xffff0000, v189
	v_pk_add_f32 v[126:127], v[126:127], v[182:183]
	v_pk_add_f32 v[124:125], v[124:125], v[192:193]
	v_pk_add_f32 v[122:123], v[122:123], v[184:185]
	v_pk_add_f32 v[120:121], v[120:121], v[194:195]
	v_pk_add_f32 v[118:119], v[118:119], v[186:187]
	v_pk_add_f32 v[116:117], v[116:117], v[196:197]
	v_pk_add_f32 v[182:183], v[114:115], v[188:189]
	v_pk_add_f32 v[184:185], v[112:113], v[198:199]
	v_cvt_pk_bf16_f32 v112, v124, v125
	v_cvt_pk_bf16_f32 v113, v126, v127
	v_cvt_pk_bf16_f32 v114, v120, v121
	v_cvt_pk_bf16_f32 v115, v122, v123
	v_mul_f32_e32 v125, v125, v125
	v_mul_f32_e32 v127, v127, v127
	v_mul_f32_e32 v121, v121, v121
	v_mul_f32_e32 v123, v123, v123
	v_mul_f32_e32 v186, v117, v117
	v_mul_f32_e32 v187, v119, v119
	v_mul_f32_e32 v188, v185, v185
	v_mul_f32_e32 v189, v183, v183
	v_fmac_f32_e32 v125, v124, v124
	v_fmac_f32_e32 v127, v126, v126
	v_fmac_f32_e32 v121, v120, v120
	v_fmac_f32_e32 v123, v122, v122
	v_fmac_f32_e32 v186, v116, v116
	v_fmac_f32_e32 v187, v118, v118
	v_fmac_f32_e32 v188, v184, v184
	v_fmac_f32_e32 v189, v182, v182
	v_add_f32_e32 v120, v125, v127
	v_add_f32_e32 v121, v121, v123
	v_add_f32_e32 v122, v186, v187
	v_add_f32_e32 v123, v188, v189
	v_add_f32_e32 v120, v120, v121
	v_add_f32_e32 v121, v122, v123
	v_add_f32_e32 v122, v120, v121
	ds_bpermute_b32 v123, v245, v122
	v_lshl_add_u64 v[120:121], s[12:13], 0, v[190:191]
	v_lshl_add_u64 v[120:121], v[120:121], 0, v[162:163]
	global_store_dwordx4 v[120:121], v[112:115], off
	s_waitcnt lgkmcnt(0)
	s_nop 0
	v_add_f32_e32 v112, v122, v123
	ds_bpermute_b32 v113, v244, v112
	v_cvt_pk_bf16_f32 v114, v116, v117
	v_cvt_pk_bf16_f32 v115, v118, v119
	v_cvt_pk_bf16_f32 v116, v184, v185
	v_cvt_pk_bf16_f32 v117, v182, v183
	global_store_dwordx4 v[120:121], v[114:117], off offset:256
	s_and_saveexec_b64 s[42:43], s[6:7]
	s_cbranch_execz .LBB0_1584
	s_waitcnt lgkmcnt(0)
	v_add_f32_e32 v112, v112, v113
	v_fma_f32 v112, v112, s59, 0.5
	v_cvt_u32_f32_e32 v114, v112
	v_lshl_add_u64 v[112:113], v[170:171], 2, s[14:15]
	global_atomic_add v[112:113], v114, off

; #define PG8_STAGE(bufoff, gbase, voff) do { _Pragma("unroll") for (int _i = 0; _i < 2; ++_i) \
;         __builtin_amdgcn_global_load_lds((const unsigned*)((const char*)(gbase) + (voff)[_i]), (LAS unsigned*)(lds + (bufoff) + ldsw + _i * 8192), 16, 0, 0); } while (0)
; #define PG8_LDA(dst, b, h) do { _Pragma("unroll") for (int m = 0; m < 4; ++m) _Pragma("unroll") for (int k = 0; k < 2; ++k) dst[m][k] = *(const LAS bf16x8*)(lds + PG8_SA(b, h) + aoff + m * 2048 + k * 1024); } while (0)
; #define PG8_LDB(dst, b, h) do { _Pragma("unroll") for (int n = 0; n < 2; ++n) _Pragma("unroll") for (int k = 0; k < 2; ++k) dst[n][k] = *(const LAS bf16x8*)(lds + PG8_SB(b, h) + boff + n * 2048 + k * 1024); } while (0)
; #define PG8_MMA(ai, bj, At, Bt) do { __builtin_amdgcn_s_setprio(1); _Pragma("unroll") for (int m = 0; m < 4; ++m) _Pragma("unroll") for (int n = 0; n < 2; ++n) _Pragma("unroll") for (int k = 0; k < 2; ++k) \
;         acc[ai][bj][m][n] = __builtin_amdgcn_mfma_f32_16x16x32_bf16(Bt[n][k], At[m][k], acc[ai][bj][m][n], 0, 0, 0); __builtin_amdgcn_s_setprio(0); } while (0)
; #define PG8_WAIT_L(n) asm volatile("s_waitcnt lgkmcnt(" #n ")" ::: "memory")
; #define PG8_BAR __builtin_amdgcn_s_barrier()
; #define PG8_SCHED __builtin_amdgcn_sched_barrier(0)
; template <class Epi>
; __device__ __forceinline__ void gemm_phase(LAS unsigned char* lds, const Gemm g, const StaticOrder& S, const Epi& E, int wv) {
;     ...
;         const bool has_next = S.next(ui + 1, nxt);
;         const char* nA = has_next ? (const char*)g.A + (size_t)nxt.pm * tstepA + ((g.adiag & 1) ? (size_t)(nxt.pn >> 1) * K * 2 : 0) + kbeg : cA;
;         const char* nB = has_next ? (const char*)g.Bt + (size_t)nxt.pn * tstepB + kbeg : cB;
;         for (int t = 0; t < nt; t += 2) {
;             const bool last = (t == nt - 2);
;             const char* a1 = cA + (ptrdiff_t)(t + 1) * kstep;
;             const char* a2 = last ? nA : cA + (ptrdiff_t)(t + 2) * kstep; const char* b2 = last ? nB : cB + (ptrdiff_t)(t + 2) * kstep;
;             const char* a3 = a2 + kstep; const char* b3 = b2 + kstep;
;             PG8_LDB(B0, 0, 0); PG8_SCHED; PG8_LDA(At, 0, 0); PG8_STAGE(PG8_SA(1, 1), a1 + hstepA, voffA);
;             PG8_WAIT_L(8); PG8_BAR; PG8_WAIT_L(0); PG8_MMA(0, 0, At, B0); PG8_BAR; PG8_SCHED;
.LBB0_1667:
	s_ashr_i32 s37, s36, 31
	v_cmp_lt_i64_e32 vcc, s[38:39], v[140:141]
	s_lshl_b64 s[38:39], s[36:37], 20
	s_add_u32 s38, s5, s38
	s_addc_u32 s39, s22, s39
	s_and_b64 s[40:41], vcc, exec
	s_cselect_b32 s37, s39, s47
	s_cselect_b32 s62, s38, s46
	s_ashr_i32 s35, s34, 31
	s_lshl_b64 s[40:41], s[34:35], 20
	s_add_u32 s40, s23, s40
	s_addc_u32 s41, s24, s41
	s_and_b64 s[48:49], vcc, exec
	s_cselect_b32 s35, s41, s45
	s_cselect_b32 s63, s40, s44
	s_add_u32 s64, s44, 0x100
	s_addc_u32 s65, s45, 0
	s_add_u32 s44, s46, 0x80080
	v_mov_b32_e32 v0, 0
	s_addc_u32 s45, s47, 0
	s_mov_b32 s66, -2
	v_mov_b32_e32 v1, v0
	v_mov_b32_e32 v2, v0
	v_mov_b32_e32 v3, v0
	v_mov_b32_e32 v4, v0
	v_mov_b32_e32 v5, v0
	v_mov_b32_e32 v6, v0
	v_mov_b32_e32 v7, v0
	v_mov_b32_e32 v16, v0
	v_mov_b32_e32 v17, v0
	v_mov_b32_e32 v18, v0
	v_mov_b32_e32 v19, v0
	v_mov_b32_e32 v20, v0
	v_mov_b32_e32 v21, v0
	v_mov_b32_e32 v22, v0
	v_mov_b32_e32 v23, v0
	v_mov_b32_e32 v32, v0
	v_mov_b32_e32 v33, v0
	v_mov_b32_e32 v34, v0
	v_mov_b32_e32 v35, v0
	v_mov_b32_e32 v36, v0
	v_mov_b32_e32 v37, v0
	v_mov_b32_e32 v38, v0
	v_mov_b32_e32 v39, v0
	v_mov_b32_e32 v48, v0
	v_mov_b32_e32 v49, v0
	v_mov_b32_e32 v50, v0
	v_mov_b32_e32 v51, v0
	v_mov_b32_e32 v52, v0
	v_mov_b32_e32 v53, v0
	v_mov_b32_e32 v54, v0
	v_mov_b32_e32 v55, v0
	v_mov_b32_e32 v8, v0
	v_mov_b32_e32 v9, v0
	v_mov_b32_e32 v10, v0
	v_mov_b32_e32 v11, v0
	v_mov_b32_e32 v12, v0
	v_mov_b32_e32 v13, v0
	v_mov_b32_e32 v14, v0
	v_mov_b32_e32 v15, v0
	v_mov_b32_e32 v24, v0
	v_mov_b32_e32 v25, v0
	v_mov_b32_e32 v26, v0
	v_mov_b32_e32 v27, v0
	v_mov_b32_e32 v28, v0
	v_mov_b32_e32 v29, v0
	v_mov_b32_e32 v30, v0
	v_mov_b32_e32 v31, v0
	v_mov_b32_e32 v40, v0
	v_mov_b32_e32 v41, v0
	v_mov_b32_e32 v42, v0
	v_mov_b32_e32 v43, v0
	v_mov_b32_e32 v44, v0
	v_mov_b32_e32 v45, v0
	v_mov_b32_e32 v46, v0
	v_mov_b32_e32 v47, v0
	v_mov_b32_e32 v56, v0
	v_mov_b32_e32 v57, v0
	v_mov_b32_e32 v58, v0
	v_mov_b32_e32 v59, v0
	v_mov_b32_e32 v60, v0
	v_mov_b32_e32 v61, v0
	v_mov_b32_e32 v62, v0
	v_mov_b32_e32 v63, v0
	v_mov_b32_e32 v64, v0
	v_mov_b32_e32 v65, v0
	v_mov_b32_e32 v66, v0
	v_mov_b32_e32 v67, v0
	v_mov_b32_e32 v68, v0
	v_mov_b32_e32 v69, v0
	v_mov_b32_e32 v70, v0
	v_mov_b32_e32 v71, v0
	v_mov_b32_e32 v80, v0
	v_mov_b32_e32 v81, v0
	v_mov_b32_e32 v82, v0
	v_mov_b32_e32 v83, v0
	v_mov_b32_e32 v84, v0
	v_mov_b32_e32 v85, v0
	v_mov_b32_e32 v86, v0
	v_mov_b32_e32 v87, v0
	v_mov_b32_e32 v96, v0
	v_mov_b32_e32 v97, v0
	v_mov_b32_e32 v98, v0
	v_mov_b32_e32 v99, v0
	v_mov_b32_e32 v100, v0
	v_mov_b32_e32 v101, v0
	v_mov_b32_e32 v102, v0
	v_mov_b32_e32 v103, v0
	v_mov_b32_e32 v104, v0
	v_mov_b32_e32 v105, v0
	v_mov_b32_e32 v106, v0
	v_mov_b32_e32 v107, v0
	v_mov_b32_e32 v108, v0
	v_mov_b32_e32 v109, v0
	v_mov_b32_e32 v110, v0
	v_mov_b32_e32 v111, v0
	v_mov_b32_e32 v72, v0
	v_mov_b32_e32 v73, v0
	v_mov_b32_e32 v74, v0
	v_mov_b32_e32 v75, v0
	v_mov_b32_e32 v76, v0
	v_mov_b32_e32 v77, v0
	v_mov_b32_e32 v78, v0
	v_mov_b32_e32 v79, v0
	v_mov_b32_e32 v88, v0
	v_mov_b32_e32 v89, v0
	v_mov_b32_e32 v90, v0
	v_mov_b32_e32 v91, v0
	v_mov_b32_e32 v92, v0
	v_mov_b32_e32 v93, v0
	v_mov_b32_e32 v94, v0
	v_mov_b32_e32 v95, v0
	v_mov_b32_e32 v112, v0
	v_mov_b32_e32 v113, v0
	v_mov_b32_e32 v114, v0
	v_mov_b32_e32 v115, v0
	v_mov_b32_e32 v116, v0
	v_mov_b32_e32 v117, v0
	v_mov_b32_e32 v118, v0
	v_mov_b32_e32 v119, v0
	v_mov_b32_e32 v120, v0
	v_mov_b32_e32 v121, v0
	v_mov_b32_e32 v122, v0
	v_mov_b32_e32 v123, v0
	v_mov_b32_e32 v124, v0
	v_mov_b32_e32 v125, v0
	v_mov_b32_e32 v126, v0
	v_mov_b32_e32 v127, v0
	ds_read_b128 v[144:147], v153
	ds_read_b128 v[158:161], v153 offset:1024
	ds_read_b128 v[162:165], v153 offset:2048
	ds_read_b128 v[166:169], v153 offset:3072
.LBB0_1668:
	s_add_u32 s46, s44, 0xfff80080
	s_addc_u32 s47, s45, -1
	s_cmp_eq_u32 s66, 28
	s_cselect_b32 s49, s37, s47
	s_cselect_b32 s48, s62, s46
	s_cselect_b32 s47, s35, s65
	s_cselect_b32 s46, s63, s64
	s_add_i32 m0, s33, 0xc000
	ds_read_b128 v[170:173], v154
	ds_read_b128 v[174:177], v154 offset:1024
	ds_read_b128 v[178:181], v154 offset:2048
	ds_read_b128 v[182:185], v154 offset:3072
	ds_read_b128 v[186:189], v154 offset:4096
	ds_read_b128 v[190:193], v154 offset:5120
	ds_read_b128 v[194:197], v154 offset:6144
	ds_read_b128 v[198:201], v154 offset:7168
	global_load_lds_dwordx4 v138, s[44:45]
	s_add_i32 m0, s33, 0xe000
	s_nop 0
	global_load_lds_dwordx4 v136, s[44:45]
	s_waitcnt lgkmcnt(8)
	s_barrier
	s_waitcnt lgkmcnt(0)
	s_setprio 1
	s_waitcnt lgkmcnt(0)
	v_mfma_f32_16x16x32_bf16 v[124:127], v[144:147], v[170:173], v[124:127]
	v_mfma_f32_16x16x32_bf16 v[120:123], v[162:165], v[170:173], v[120:123]
	v_mfma_f32_16x16x32_bf16 v[116:119], v[144:147], v[178:181], v[116:119]
	v_mfma_f32_16x16x32_bf16 v[112:115], v[162:165], v[178:181], v[112:115]
	v_mfma_f32_16x16x32_bf16 v[92:95], v[144:147], v[186:189], v[92:95]
	v_mfma_f32_16x16x32_bf16 v[88:91], v[162:165], v[186:189], v[88:91]
	v_mfma_f32_16x16x32_bf16 v[76:79], v[144:147], v[194:197], v[76:79]
	v_mfma_f32_16x16x32_bf16 v[72:75], v[162:165], v[194:197], v[72:75]
	v_mfma_f32_16x16x32_bf16 v[124:127], v[158:161], v[174:177], v[124:127]
	v_mfma_f32_16x16x32_bf16 v[120:123], v[166:169], v[174:177], v[120:123]
	v_mfma_f32_16x16x32_bf16 v[116:119], v[158:161], v[182:185], v[116:119]
	v_mfma_f32_16x16x32_bf16 v[112:115], v[166:169], v[182:185], v[112:115]
	v_mfma_f32_16x16x32_bf16 v[92:95], v[158:161], v[190:193], v[92:95]
	v_mfma_f32_16x16x32_bf16 v[88:91], v[166:169], v[190:193], v[88:91]
	v_mfma_f32_16x16x32_bf16 v[76:79], v[158:161], v[198:201], v[76:79]
	v_mfma_f32_16x16x32_bf16 v[72:75], v[166:169], v[198:201], v[72:75]
	s_setprio 0
	s_barrier
; #define PG8_STAGE(bufoff, gbase, voff) do { _Pragma("unroll") for (int _i = 0; _i < 2; ++_i) \
;         __builtin_amdgcn_global_load_lds((const unsigned*)((const char*)(gbase) + (voff)[_i]), (LAS unsigned*)(lds + (bufoff) + ldsw + _i * 8192), 16, 0, 0); } while (0)
; #define PG8_LDA(dst, b, h) do { _Pragma("unroll") for (int m = 0; m < 4; ++m) _Pragma("unroll") for (int k = 0; k < 2; ++k) dst[m][k] = *(const LAS bf16x8*)(lds + PG8_SA(b, h) + aoff + m * 2048 + k * 1024); } while (0)
; #define PG8_LDB(dst, b, h) do { _Pragma("unroll") for (int n = 0; n < 2; ++n) _Pragma("unroll") for (int k = 0; k < 2; ++k) dst[n][k] = *(const LAS bf16x8*)(lds + PG8_SB(b, h) + boff + n * 2048 + k * 1024); } while (0)
; #define PG8_MMA(ai, bj, At, Bt) do { __builtin_amdgcn_s_setprio(1); _Pragma("unroll") for (int m = 0; m < 4; ++m) _Pragma("unroll") for (int n = 0; n < 2; ++n) _Pragma("unroll") for (int k = 0; k < 2; ++k) \
;         acc[ai][bj][m][n] = __builtin_amdgcn_mfma_f32_16x16x32_bf16(Bt[n][k], At[m][k], acc[ai][bj][m][n], 0, 0, 0); __builtin_amdgcn_s_setprio(0); } while (0)
; #define PG8_WAIT_V(n) asm volatile("s_waitcnt vmcnt(" #n ")" ::: "memory")
; #define PG8_WAIT_L(n) asm volatile("s_waitcnt lgkmcnt(" #n ")" ::: "memory")
; #define PG8_BAR __builtin_amdgcn_s_barrier()
; #define PG8_SCHED __builtin_amdgcn_sched_barrier(0)
; template <class Epi>
; __device__ __forceinline__ void gemm_phase(LAS unsigned char* lds, const Gemm g, const StaticOrder& S, const Epi& E, int wv) {
;     ...
;             PG8_LDB(B1, 0, 1); PG8_STAGE(PG8_SB(0, 0), b2, voffB);
;             PG8_BAR; PG8_WAIT_L(0); PG8_MMA(0, 1, At, B1); PG8_BAR;
;             PG8_LDA(At, 0, 1); PG8_STAGE(PG8_SA(0, 0), a2, voffA);
;             PG8_BAR; PG8_WAIT_L(0); PG8_MMA(1, 0, At, B0); PG8_BAR; PG8_SCHED;
;             PG8_STAGE(PG8_SB(0, 1), b2 + hstepB, voffB);
;             PG8_WAIT_V(6); PG8_BAR; PG8_MMA(1, 1, At, B1); PG8_BAR;
;             PG8_LDB(B0, 1, 0); PG8_SCHED; PG8_LDA(At, 1, 0); PG8_STAGE(PG8_SA(0, 1), a2 + hstepA, voffA);
	s_add_i32 s67, s55, s25
	s_add_u32 s98, s46, s12
	s_addc_u32 s99, s47, s13
	s_mov_b32 m0, s67
	ds_read_b128 v[202:205], v155
	ds_read_b128 v[206:209], v155 offset:1024
	ds_read_b128 v[210:213], v155 offset:2048
	ds_read_b128 v[214:217], v155 offset:3072
	global_load_lds_dwordx4 v130, s[46:47]
	s_add_i32 m0, s67, 0x2000
	s_nop 0
	global_load_lds_dwordx4 v134, s[46:47]
	s_barrier
	s_waitcnt lgkmcnt(0)
	s_setprio 1
	s_waitcnt lgkmcnt(0)
	v_mfma_f32_16x16x32_bf16 v[108:111], v[202:205], v[170:173], v[108:111]
	v_mfma_f32_16x16x32_bf16 v[104:107], v[210:213], v[170:173], v[104:107]
	v_mfma_f32_16x16x32_bf16 v[100:103], v[202:205], v[178:181], v[100:103]
	v_mfma_f32_16x16x32_bf16 v[96:99], v[210:213], v[178:181], v[96:99]
	v_mfma_f32_16x16x32_bf16 v[84:87], v[202:205], v[186:189], v[84:87]
	v_mfma_f32_16x16x32_bf16 v[80:83], v[210:213], v[186:189], v[80:83]
	v_mfma_f32_16x16x32_bf16 v[68:71], v[202:205], v[194:197], v[68:71]
	v_mfma_f32_16x16x32_bf16 v[64:67], v[210:213], v[194:197], v[64:67]
	v_mfma_f32_16x16x32_bf16 v[108:111], v[206:209], v[174:177], v[108:111]
	v_mfma_f32_16x16x32_bf16 v[104:107], v[214:217], v[174:177], v[104:107]
	v_mfma_f32_16x16x32_bf16 v[100:103], v[206:209], v[182:185], v[100:103]
	v_mfma_f32_16x16x32_bf16 v[96:99], v[214:217], v[182:185], v[96:99]
	v_mfma_f32_16x16x32_bf16 v[84:87], v[206:209], v[190:193], v[84:87]
	v_mfma_f32_16x16x32_bf16 v[80:83], v[214:217], v[190:193], v[80:83]
	v_mfma_f32_16x16x32_bf16 v[68:71], v[206:209], v[198:201], v[68:71]
	v_mfma_f32_16x16x32_bf16 v[64:67], v[214:217], v[198:201], v[64:67]
	s_setprio 0
	s_mov_b32 m0, s33
	s_add_u32 s100, s48, s12
	s_addc_u32 s101, s49, s13
	s_barrier
	ds_read_b128 v[170:173], v154 offset:16384
	ds_read_b128 v[174:177], v154 offset:17408
	ds_read_b128 v[178:181], v154 offset:18432
	ds_read_b128 v[182:185], v154 offset:19456
	ds_read_b128 v[186:189], v154 offset:20480
	ds_read_b128 v[190:193], v154 offset:21504
	ds_read_b128 v[194:197], v154 offset:22528
	ds_read_b128 v[198:201], v154 offset:23552
	global_load_lds_dwordx4 v128, s[48:49]
	s_mov_b32 m0, s43
	s_nop 0
	global_load_lds_dwordx4 v132, s[48:49]
	s_waitcnt vmcnt(10)
	s_barrier
	s_waitcnt lgkmcnt(0)
	s_setprio 1
	s_waitcnt lgkmcnt(0)
	v_mfma_f32_16x16x32_bf16 v[60:63], v[144:147], v[170:173], v[60:63]
	v_mfma_f32_16x16x32_bf16 v[56:59], v[162:165], v[170:173], v[56:59]
	v_mfma_f32_16x16x32_bf16 v[44:47], v[144:147], v[178:181], v[44:47]
	v_mfma_f32_16x16x32_bf16 v[40:43], v[162:165], v[178:181], v[40:43]
	v_mfma_f32_16x16x32_bf16 v[28:31], v[144:147], v[186:189], v[28:31]
	v_mfma_f32_16x16x32_bf16 v[24:27], v[162:165], v[186:189], v[24:27]
	v_mfma_f32_16x16x32_bf16 v[12:15], v[144:147], v[194:197], v[12:15]
	v_mfma_f32_16x16x32_bf16 v[8:11], v[162:165], v[194:197], v[8:11]
	v_mfma_f32_16x16x32_bf16 v[60:63], v[158:161], v[174:177], v[60:63]
	v_mfma_f32_16x16x32_bf16 v[56:59], v[166:169], v[174:177], v[56:59]
	v_mfma_f32_16x16x32_bf16 v[44:47], v[158:161], v[182:185], v[44:47]
	v_mfma_f32_16x16x32_bf16 v[40:43], v[166:169], v[182:185], v[40:43]
	v_mfma_f32_16x16x32_bf16 v[28:31], v[158:161], v[190:193], v[28:31]
	v_mfma_f32_16x16x32_bf16 v[24:27], v[166:169], v[190:193], v[24:27]
	v_mfma_f32_16x16x32_bf16 v[12:15], v[158:161], v[198:201], v[12:15]
	v_mfma_f32_16x16x32_bf16 v[8:11], v[166:169], v[198:201], v[8:11]
	s_setprio 0
	s_barrier
	s_add_u32 s68, s46, 0x80000
	s_addc_u32 s69, s47, 0
	s_add_i32 s67, s56, s25
	s_mov_b32 m0, s67
	s_nop 0
	global_load_lds_dwordx4 v130, s[68:69]
	s_add_i32 m0, s67, 0x2000
	s_nop 0
	global_load_lds_dwordx4 v134, s[68:69]
	s_add_i32 s67, 0, 0x18000
	v_add_u32_e32 v157, s67, v151
	ds_read_b128 v[144:147], v157
	ds_read_b128 v[158:161], v157 offset:1024
	ds_read_b128 v[162:165], v157 offset:2048
	ds_read_b128 v[166:169], v157 offset:3072
	s_waitcnt vmcnt(6)
	s_barrier
	s_setprio 1
	v_mfma_f32_16x16x32_bf16 v[52:55], v[202:205], v[170:173], v[52:55]
	v_mfma_f32_16x16x32_bf16 v[48:51], v[210:213], v[170:173], v[48:51]
	v_mfma_f32_16x16x32_bf16 v[36:39], v[202:205], v[178:181], v[36:39]
	v_mfma_f32_16x16x32_bf16 v[32:35], v[210:213], v[178:181], v[32:35]
	v_mfma_f32_16x16x32_bf16 v[20:23], v[202:205], v[186:189], v[20:23]
	v_mfma_f32_16x16x32_bf16 v[16:19], v[210:213], v[186:189], v[16:19]
	v_mfma_f32_16x16x32_bf16 v[4:7], v[202:205], v[194:197], v[4:7]
	v_mfma_f32_16x16x32_bf16 v[0:3], v[210:213], v[194:197], v[0:3]
	v_mfma_f32_16x16x32_bf16 v[52:55], v[206:209], v[174:177], v[52:55]
	v_mfma_f32_16x16x32_bf16 v[48:51], v[214:217], v[174:177], v[48:51]
	v_mfma_f32_16x16x32_bf16 v[36:39], v[206:209], v[182:185], v[36:39]
	v_mfma_f32_16x16x32_bf16 v[32:35], v[214:217], v[182:185], v[32:35]
	v_mfma_f32_16x16x32_bf16 v[20:23], v[206:209], v[190:193], v[20:23]
	v_mfma_f32_16x16x32_bf16 v[16:19], v[214:217], v[190:193], v[16:19]
	v_mfma_f32_16x16x32_bf16 v[4:7], v[206:209], v[198:201], v[4:7]
	v_mfma_f32_16x16x32_bf16 v[0:3], v[214:217], v[198:201], v[0:3]
	s_setprio 0
	s_waitcnt lgkmcnt(0)
	s_barrier
	s_add_u32 s48, s48, 0x80000
	s_addc_u32 s49, s49, 0
	s_mov_b32 m0, s50
	ds_read_b128 v[170:173], v154 offset:32768
	ds_read_b128 v[174:177], v154 offset:33792
	ds_read_b128 v[178:181], v154 offset:34816
	ds_read_b128 v[182:185], v154 offset:35840
	ds_read_b128 v[186:189], v154 offset:36864
	ds_read_b128 v[190:193], v154 offset:37888
	ds_read_b128 v[194:197], v154 offset:38912
	ds_read_b128 v[198:201], v154 offset:39936
	global_load_lds_dwordx4 v128, s[48:49]
	s_mov_b32 m0, s51
	s_nop 0
	global_load_lds_dwordx4 v132, s[48:49]
	s_waitcnt lgkmcnt(8)
	s_barrier
; #define PG8_STAGE(bufoff, gbase, voff) do { _Pragma("unroll") for (int _i = 0; _i < 2; ++_i) \
;         __builtin_amdgcn_global_load_lds((const unsigned*)((const char*)(gbase) + (voff)[_i]), (LAS unsigned*)(lds + (bufoff) + ldsw + _i * 8192), 16, 0, 0); } while (0)
; #define PG8_LDA(dst, b, h) do { _Pragma("unroll") for (int m = 0; m < 4; ++m) _Pragma("unroll") for (int k = 0; k < 2; ++k) dst[m][k] = *(const LAS bf16x8*)(lds + PG8_SA(b, h) + aoff + m * 2048 + k * 1024); } while (0)
; #define PG8_LDB(dst, b, h) do { _Pragma("unroll") for (int n = 0; n < 2; ++n) _Pragma("unroll") for (int k = 0; k < 2; ++k) dst[n][k] = *(const LAS bf16x8*)(lds + PG8_SB(b, h) + boff + n * 2048 + k * 1024); } while (0)
; #define PG8_MMA(ai, bj, At, Bt) do { __builtin_amdgcn_s_setprio(1); _Pragma("unroll") for (int m = 0; m < 4; ++m) _Pragma("unroll") for (int n = 0; n < 2; ++n) _Pragma("unroll") for (int k = 0; k < 2; ++k) \
;         acc[ai][bj][m][n] = __builtin_amdgcn_mfma_f32_16x16x32_bf16(Bt[n][k], At[m][k], acc[ai][bj][m][n], 0, 0, 0); __builtin_amdgcn_s_setprio(0); } while (0)
; #define PG8_WAIT_V(n) asm volatile("s_waitcnt vmcnt(" #n ")" ::: "memory")
; #define PG8_WAIT_L(n) asm volatile("s_waitcnt lgkmcnt(" #n ")" ::: "memory")
; #define PG8_BAR __builtin_amdgcn_s_barrier()
; #define PG8_SCHED __builtin_amdgcn_sched_barrier(0)
; template <class Epi>
; __device__ __forceinline__ void gemm_phase(LAS unsigned char* lds, const Gemm g, const StaticOrder& S, const Epi& E, int wv) {
;     ...
;             PG8_WAIT_L(8); PG8_BAR; PG8_WAIT_L(0); PG8_MMA(0, 0, At, B0); PG8_BAR; PG8_SCHED;
;             PG8_LDB(B1, 1, 1); PG8_STAGE(PG8_SB(1, 0), b3, voffB);
;             PG8_BAR; PG8_WAIT_L(0); PG8_MMA(0, 1, At, B1); PG8_BAR;
;             PG8_LDA(At, 1, 1); PG8_STAGE(PG8_SA(1, 0), a3, voffA);
;             PG8_BAR; PG8_WAIT_L(0); PG8_MMA(1, 0, At, B0); PG8_BAR; PG8_SCHED;
;             PG8_STAGE(PG8_SB(1, 1), b3 + hstepB, voffB);
;             PG8_WAIT_V(6); PG8_BAR; PG8_MMA(1, 1, At, B1); PG8_BAR;
	s_waitcnt lgkmcnt(0)
	s_setprio 1
	s_waitcnt lgkmcnt(0)
	v_mfma_f32_16x16x32_bf16 v[124:127], v[144:147], v[170:173], v[124:127]
	v_mfma_f32_16x16x32_bf16 v[120:123], v[162:165], v[170:173], v[120:123]
	v_mfma_f32_16x16x32_bf16 v[116:119], v[144:147], v[178:181], v[116:119]
	v_mfma_f32_16x16x32_bf16 v[112:115], v[162:165], v[178:181], v[112:115]
	v_mfma_f32_16x16x32_bf16 v[92:95], v[144:147], v[186:189], v[92:95]
	v_mfma_f32_16x16x32_bf16 v[88:91], v[162:165], v[186:189], v[88:91]
	v_mfma_f32_16x16x32_bf16 v[76:79], v[144:147], v[194:197], v[76:79]
	v_mfma_f32_16x16x32_bf16 v[72:75], v[162:165], v[194:197], v[72:75]
	v_mfma_f32_16x16x32_bf16 v[124:127], v[158:161], v[174:177], v[124:127]
	v_mfma_f32_16x16x32_bf16 v[120:123], v[166:169], v[174:177], v[120:123]
	v_mfma_f32_16x16x32_bf16 v[116:119], v[158:161], v[182:185], v[116:119]
	v_mfma_f32_16x16x32_bf16 v[112:115], v[166:169], v[182:185], v[112:115]
	v_mfma_f32_16x16x32_bf16 v[92:95], v[158:161], v[190:193], v[92:95]
	v_mfma_f32_16x16x32_bf16 v[88:91], v[166:169], v[190:193], v[88:91]
	v_mfma_f32_16x16x32_bf16 v[76:79], v[158:161], v[198:201], v[76:79]
	v_mfma_f32_16x16x32_bf16 v[72:75], v[166:169], v[198:201], v[72:75]
	s_setprio 0
	s_barrier
	s_add_i32 s48, 0, 0x1c000
	s_add_i32 s49, s67, s25
	v_add_u32_e32 v157, s48, v151
	s_mov_b32 m0, s49
	ds_read_b128 v[202:205], v157
	ds_read_b128 v[206:209], v157 offset:1024
	ds_read_b128 v[210:213], v157 offset:2048
	ds_read_b128 v[214:217], v157 offset:3072
	global_load_lds_dwordx4 v130, s[98:99]
	s_add_i32 m0, s49, 0x2000
	s_nop 0
	global_load_lds_dwordx4 v134, s[98:99]
	s_barrier
	s_waitcnt lgkmcnt(0)
	s_setprio 1
	s_waitcnt lgkmcnt(0)
	v_mfma_f32_16x16x32_bf16 v[108:111], v[202:205], v[170:173], v[108:111]
	v_mfma_f32_16x16x32_bf16 v[104:107], v[210:213], v[170:173], v[104:107]
	v_mfma_f32_16x16x32_bf16 v[100:103], v[202:205], v[178:181], v[100:103]
	v_mfma_f32_16x16x32_bf16 v[96:99], v[210:213], v[178:181], v[96:99]
	v_mfma_f32_16x16x32_bf16 v[84:87], v[202:205], v[186:189], v[84:87]
	v_mfma_f32_16x16x32_bf16 v[80:83], v[210:213], v[186:189], v[80:83]
	v_mfma_f32_16x16x32_bf16 v[68:71], v[202:205], v[194:197], v[68:71]
	v_mfma_f32_16x16x32_bf16 v[64:67], v[210:213], v[194:197], v[64:67]
	v_mfma_f32_16x16x32_bf16 v[108:111], v[206:209], v[174:177], v[108:111]
	v_mfma_f32_16x16x32_bf16 v[104:107], v[214:217], v[174:177], v[104:107]
	v_mfma_f32_16x16x32_bf16 v[100:103], v[206:209], v[182:185], v[100:103]
	v_mfma_f32_16x16x32_bf16 v[96:99], v[214:217], v[182:185], v[96:99]
	v_mfma_f32_16x16x32_bf16 v[84:87], v[206:209], v[190:193], v[84:87]
	v_mfma_f32_16x16x32_bf16 v[80:83], v[214:217], v[190:193], v[80:83]
	v_mfma_f32_16x16x32_bf16 v[68:71], v[206:209], v[198:201], v[68:71]
	v_mfma_f32_16x16x32_bf16 v[64:67], v[214:217], v[198:201], v[64:67]
	s_setprio 0
	s_mov_b32 m0, s53
	s_barrier
	ds_read_b128 v[170:173], v154 offset:49152
	ds_read_b128 v[174:177], v154 offset:50176
	ds_read_b128 v[178:181], v154 offset:51200
	ds_read_b128 v[182:185], v154 offset:52224
	ds_read_b128 v[186:189], v154 offset:53248
	ds_read_b128 v[190:193], v154 offset:54272
	ds_read_b128 v[194:197], v154 offset:55296
	ds_read_b128 v[198:201], v154 offset:56320
	global_load_lds_dwordx4 v128, s[100:101]
	s_mov_b32 m0, s54
	s_nop 0
	global_load_lds_dwordx4 v132, s[100:101]
	s_waitcnt vmcnt(10)
	s_barrier
	s_waitcnt lgkmcnt(0)
	s_setprio 1
	s_waitcnt lgkmcnt(0)
	v_mfma_f32_16x16x32_bf16 v[60:63], v[144:147], v[170:173], v[60:63]
	v_mfma_f32_16x16x32_bf16 v[56:59], v[162:165], v[170:173], v[56:59]
	v_mfma_f32_16x16x32_bf16 v[44:47], v[144:147], v[178:181], v[44:47]
	v_mfma_f32_16x16x32_bf16 v[40:43], v[162:165], v[178:181], v[40:43]
	v_mfma_f32_16x16x32_bf16 v[28:31], v[144:147], v[186:189], v[28:31]
	v_mfma_f32_16x16x32_bf16 v[24:27], v[162:165], v[186:189], v[24:27]
	v_mfma_f32_16x16x32_bf16 v[12:15], v[144:147], v[194:197], v[12:15]
	v_mfma_f32_16x16x32_bf16 v[8:11], v[162:165], v[194:197], v[8:11]
	v_mfma_f32_16x16x32_bf16 v[60:63], v[158:161], v[174:177], v[60:63]
	v_mfma_f32_16x16x32_bf16 v[56:59], v[166:169], v[174:177], v[56:59]
	v_mfma_f32_16x16x32_bf16 v[44:47], v[158:161], v[182:185], v[44:47]
	v_mfma_f32_16x16x32_bf16 v[40:43], v[166:169], v[182:185], v[40:43]
	v_mfma_f32_16x16x32_bf16 v[28:31], v[158:161], v[190:193], v[28:31]
	v_mfma_f32_16x16x32_bf16 v[24:27], v[166:169], v[190:193], v[24:27]
	v_mfma_f32_16x16x32_bf16 v[12:15], v[158:161], v[198:201], v[12:15]
	v_mfma_f32_16x16x32_bf16 v[8:11], v[166:169], v[198:201], v[8:11]
	s_setprio 0
	s_barrier
	s_add_u32 s46, s46, 0x80080
	s_addc_u32 s47, s47, 0
	s_add_i32 s48, s48, s25
	s_mov_b32 m0, s48
	s_nop 0
	global_load_lds_dwordx4 v130, s[46:47]
	s_add_i32 m0, s48, 0x2000
	s_nop 0
	global_load_lds_dwordx4 v134, s[46:47]
	ds_read_b128 v[144:147], v153
	ds_read_b128 v[158:161], v153 offset:1024
	ds_read_b128 v[162:165], v153 offset:2048
	ds_read_b128 v[166:169], v153 offset:3072
	s_waitcnt vmcnt(6)
	s_barrier
	s_setprio 1
	v_mfma_f32_16x16x32_bf16 v[52:55], v[202:205], v[170:173], v[52:55]
	v_mfma_f32_16x16x32_bf16 v[48:51], v[210:213], v[170:173], v[48:51]
	v_mfma_f32_16x16x32_bf16 v[36:39], v[202:205], v[178:181], v[36:39]
	v_mfma_f32_16x16x32_bf16 v[32:35], v[210:213], v[178:181], v[32:35]
	v_mfma_f32_16x16x32_bf16 v[20:23], v[202:205], v[186:189], v[20:23]
	v_mfma_f32_16x16x32_bf16 v[16:19], v[210:213], v[186:189], v[16:19]
	v_mfma_f32_16x16x32_bf16 v[4:7], v[202:205], v[194:197], v[4:7]
	v_mfma_f32_16x16x32_bf16 v[0:3], v[210:213], v[194:197], v[0:3]
	v_mfma_f32_16x16x32_bf16 v[52:55], v[206:209], v[174:177], v[52:55]
	v_mfma_f32_16x16x32_bf16 v[48:51], v[214:217], v[174:177], v[48:51]
	v_mfma_f32_16x16x32_bf16 v[36:39], v[206:209], v[182:185], v[36:39]
	v_mfma_f32_16x16x32_bf16 v[32:35], v[214:217], v[182:185], v[32:35]
	v_mfma_f32_16x16x32_bf16 v[20:23], v[206:209], v[190:193], v[20:23]
	v_mfma_f32_16x16x32_bf16 v[16:19], v[214:217], v[190:193], v[16:19]
	v_mfma_f32_16x16x32_bf16 v[4:7], v[206:209], v[198:201], v[4:7]
	v_mfma_f32_16x16x32_bf16 v[0:3], v[214:217], v[198:201], v[0:3]
	s_setprio 0
	s_waitcnt lgkmcnt(0)
	s_add_i32 s66, s66, 2
	s_add_u32 s64, s64, 0x100
	s_addc_u32 s65, s65, 0
	s_add_u32 s44, s44, 0x100
	s_addc_u32 s45, s45, 0
	s_cmp_gt_u32 s66, 29
	s_barrier
; __device__ __forceinline__ float fast_sigmoid(float x) { return __builtin_amdgcn_rcpf(1.0f + __builtin_amdgcn_exp2f(-x * LOG2E)); }
; __device__ __forceinline__ float ss_fix(float raw) { return (float)__float_as_uint(raw) * (1.0f / 256.0f); }
; #define PG8_WAIT_V(n) asm volatile("s_waitcnt vmcnt(" #n ")" ::: "memory")
; #define PG8_BAR __builtin_amdgcn_s_barrier()
; template <class Epi>
; __device__ __forceinline__ void gemm_phase(LAS unsigned char* lds, const Gemm g, const StaticOrder& S, const Epi& E, int wv) {
;     ...
;             PG8_WAIT_V(6); PG8_BAR; PG8_MMA(1, 1, At, B1); PG8_BAR;
;         }
;     __device__ __forceinline__ void operator()(const f32x4 (&acc)[2][2][4][2], const Unit& u, int wr, int wc, int fr, int fq) const {
;     ...
;         float rsv[8];
; #pragma unroll
;         for (int it = 0; it < 8; ++it) rsv[it] = (SM == 1) ? ss[row0 + (it >> 2) * HALF + (it & 3) * 16] : 1.0f;
; #pragma unroll
;         for (int ai = 0; ai < 2; ++ai)
; #pragma unroll
;             for (int m = 0; m < 4; ++m) { const int row = row0 + ai * HALF + m * 16; float rs = 1.0f; if (SM == 1) rs = __builtin_amdgcn_rsqf(ss_fix(rsv[ai * 4 + m]) * (1.0f / DM) + EPS);
;                 bf16_t* rowp = base + (size_t)row * ldc + col0;
; #pragma unroll
;                 for (int bj = 0; bj < 2; ++bj) { f32x4 v0 = acc[ai][bj][m][0], v1 = acc[ai][bj][m][1];
;                     if (SM == 1) { v0 *= rs; v1 *= rs; }
;                     if (SM == 2) { v0 *= cs[bj][0]; v1 *= cs[bj][1]; }
;                     if (ACT == 1) {
; #pragma unroll
;                         for (int j = 0; j < 4; ++j) { const float a = fmaxf(v0[j], 0.f), b = fmaxf(v1[j], 0.f); v0[j] = a * a; v1[j] = b * b; } }
;                     if (ACT == 2) { if (tsel == 0) {
; #pragma unroll
;                         for (int j = 0; j < 4; ++j) { const float a = v0[j], b = v1[j];
;                             v0[j] = a * fast_sigmoid(1.5957691216057308f * (a + 0.044715f * a * a * a)); v1[j] = b * fast_sigmoid(1.5957691216057308f * (b + 0.044715f * b * b * b)); } } }
;                     u32x4 w; w.x = pk_bf16(v0[0], v0[1]); w.y = pk_bf16(v0[2], v0[3]); w.z = pk_bf16(v1[0], v1[1]); w.w = pk_bf16(v1[2], v1[3]);
;                     *(u32x4*)(rowp + bj * HALF) = w; } }
	s_cbranch_scc0 .LBB0_1668
	v_lshl_add_u32 v146, s42, 8, v150
	v_ashrrev_i32_e32 v147, 31, v146
	v_lshl_add_u64 v[144:145], v[146:147], 2, s[10:11]
	global_load_dword v157, v[144:145], off
	global_load_dword v162, v[144:145], off offset:64
	v_lshlrev_b64 v[160:161], 14, v[146:147]
	global_load_dword v166, v[144:145], off offset:128
	global_load_dword v167, v[144:145], off offset:192
	global_load_dword v168, v[144:145], off offset:512
	global_load_dword v169, v[144:145], off offset:576
	global_load_dword v170, v[144:145], off offset:640
	global_load_dword v147, v[144:145], off offset:704
	v_lshl_or_b32 v148, s61, 8, v152
	v_ashrrev_i32_e32 v149, 31, v148
	v_lshl_add_u64 v[148:149], v[148:149], 1, s[8:9]
	v_lshl_add_u64 v[144:145], v[148:149], 0, v[160:161]
	v_or_b32_e32 v158, 16, v146
	v_ashrrev_i32_e32 v159, 31, v158
	v_lshlrev_b64 v[158:159], 14, v[158:159]
	v_lshl_add_u64 v[158:159], v[148:149], 0, v[158:159]
	s_mov_b32 s61, s34
	s_mov_b32 s42, s36
	s_mov_b64 s[44:45], s[40:41]
	s_mov_b64 s[46:47], s[38:39]
	s_waitcnt vmcnt(0)
	v_cvt_f32_u32_e32 v157, v157
	v_cvt_f32_u32_e32 v161, v162
	v_mul_f32_e32 v157, 0x3b800000, v157
	v_fmamk_f32 v157, v157, 0x3a000000, v156
	v_rsq_f32_e32 v160, v157
	v_mul_f32_e32 v157, 0x3b800000, v161
	v_fmamk_f32 v157, v157, 0x3a000000, v156
	v_rsq_f32_e32 v162, v157
	v_pk_mul_f32 v[126:127], v[126:127], v[160:161] op_sel_hi:[1,0]
	v_pk_mul_f32 v[124:125], v[124:125], v[160:161] op_sel_hi:[1,0]
	v_pk_mul_f32 v[122:123], v[122:123], v[160:161] op_sel_hi:[1,0]
	v_pk_mul_f32 v[120:121], v[120:121], v[160:161] op_sel_hi:[1,0]
	v_pk_mul_f32 v[110:111], v[110:111], v[160:161] op_sel_hi:[1,0]
	v_pk_mul_f32 v[108:109], v[108:109], v[160:161] op_sel_hi:[1,0]
	v_pk_mul_f32 v[106:107], v[106:107], v[160:161] op_sel_hi:[1,0]
	v_pk_mul_f32 v[104:105], v[104:105], v[160:161] op_sel_hi:[1,0]
	v_pk_mul_f32 v[118:119], v[118:119], v[162:163] op_sel_hi:[1,0]
	v_pk_mul_f32 v[116:117], v[116:117], v[162:163] op_sel_hi:[1,0]
	v_pk_mul_f32 v[114:115], v[114:115], v[162:163] op_sel_hi:[1,0]
	v_pk_mul_f32 v[112:113], v[112:113], v[162:163] op_sel_hi:[1,0]
	v_pk_mul_f32 v[160:161], v[102:103], v[162:163] op_sel_hi:[1,0]
	v_pk_mul_f32 v[100:101], v[100:101], v[162:163] op_sel_hi:[1,0]
	v_pk_mul_f32 v[164:165], v[98:99], v[162:163] op_sel_hi:[1,0]
	v_pk_mul_f32 v[162:163], v[96:97], v[162:163] op_sel_hi:[1,0]
	v_max_f32_e32 v96, 0, v124
	v_max_f32_e32 v98, 0, v120
	v_max_f32_e32 v97, 0, v125
	v_max_f32_e32 v99, 0, v121
	v_max_f32_e32 v102, 0, v126
	v_max_f32_e32 v120, 0, v122
	v_max_f32_e32 v103, 0, v127
	v_max_f32_e32 v121, 0, v123
	v_max_f32_e32 v108, 0, v108
	v_max_f32_e32 v109, 0, v109
	v_max_f32_e32 v110, 0, v110
	v_max_f32_e32 v111, 0, v111
	v_max_f32_e32 v104, 0, v104
	v_max_f32_e32 v105, 0, v105
	v_max_f32_e32 v106, 0, v106
	v_max_f32_e32 v107, 0, v107
	v_max_f32_e32 v116, 0, v116
	v_max_f32_e32 v112, 0, v112
	v_max_f32_e32 v117, 0, v117
	v_max_f32_e32 v113, 0, v113
	v_max_f32_e32 v118, 0, v118
	v_max_f32_e32 v114, 0, v114
	v_max_f32_e32 v119, 0, v119
	v_max_f32_e32 v115, 0, v115
	v_max_f32_e32 v122, 0, v100
	v_max_f32_e32 v123, 0, v101
	v_pk_mul_f32 v[96:97], v[96:97], v[96:97]
	v_pk_mul_f32 v[98:99], v[98:99], v[98:99]
	v_pk_mul_f32 v[100:101], v[102:103], v[102:103]
	v_pk_mul_f32 v[102:103], v[120:121], v[120:121]
	v_pk_mul_f32 v[108:109], v[108:109], v[108:109]
	v_pk_mul_f32 v[110:111], v[110:111], v[110:111]
	v_pk_mul_f32 v[104:105], v[104:105], v[104:105]
	v_pk_mul_f32 v[106:107], v[106:107], v[106:107]
	v_pk_mul_f32 v[116:117], v[116:117], v[116:117]
	v_pk_mul_f32 v[112:113], v[112:113], v[112:113]
	v_pk_mul_f32 v[118:119], v[118:119], v[118:119]
	v_pk_mul_f32 v[114:115], v[114:115], v[114:115]
	v_cvt_pk_bf16_f32 v96, v96, v97
	v_cvt_pk_bf16_f32 v97, v100, v101
	v_cvt_pk_bf16_f32 v98, v98, v99
	v_cvt_pk_bf16_f32 v99, v102, v103
	v_cvt_pk_bf16_f32 v100, v108, v109
	v_cvt_pk_bf16_f32 v101, v110, v111
	v_cvt_pk_bf16_f32 v102, v104, v105
	v_cvt_pk_bf16_f32 v103, v106, v107
	v_cvt_pk_bf16_f32 v104, v116, v117
	v_cvt_pk_bf16_f32 v105, v118, v119
	v_cvt_pk_bf16_f32 v106, v112, v113
	v_cvt_pk_bf16_f32 v107, v114, v115
	global_store_dwordx4 v[144:145], v[96:99], off
	global_store_dwordx4 v[144:145], v[100:103], off offset:256
	global_store_dwordx4 v[158:159], v[104:107], off
	v_pk_mul_f32 v[96:97], v[122:123], v[122:123]
	v_max_f32_e32 v100, 0, v160
	v_max_f32_e32 v101, 0, v161
	v_pk_mul_f32 v[100:101], v[100:101], v[100:101]
	v_cvt_pk_bf16_f32 v96, v96, v97
	v_cvt_pk_bf16_f32 v97, v100, v101
	v_cvt_f32_u32_e32 v100, v166
	v_max_f32_e32 v124, 0, v162
	v_max_f32_e32 v125, 0, v163
	v_max_f32_e32 v102, 0, v164
	v_max_f32_e32 v103, 0, v165
	v_pk_mul_f32 v[98:99], v[124:125], v[124:125]
	v_pk_mul_f32 v[102:103], v[102:103], v[102:103]
	v_cvt_pk_bf16_f32 v98, v98, v99
	v_cvt_pk_bf16_f32 v99, v102, v103
	global_store_dwordx4 v[158:159], v[96:99], off offset:256
	s_nop 1
	v_mul_f32_e32 v97, 0x3b800000, v100
	v_fmamk_f32 v97, v97, 0x3a000000, v156
	v_rsq_f32_e32 v98, v97
	v_or_b32_e32 v96, 32, v146
	v_ashrrev_i32_e32 v97, 31, v96
	v_lshlrev_b64 v[96:97], 14, v[96:97]
	v_pk_mul_f32 v[88:89], v[88:89], v[98:99] op_sel_hi:[1,0]
	v_pk_mul_f32 v[94:95], v[94:95], v[98:99] op_sel_hi:[1,0]
	v_pk_mul_f32 v[92:93], v[92:93], v[98:99] op_sel_hi:[1,0]
	v_pk_mul_f32 v[90:91], v[90:91], v[98:99] op_sel_hi:[1,0]
	v_max_f32_e32 v88, 0, v88
	v_max_f32_e32 v89, 0, v89
	v_max_f32_e32 v92, 0, v92
	v_max_f32_e32 v93, 0, v93
	v_pk_mul_f32 v[100:101], v[88:89], v[88:89]
	v_max_f32_e32 v88, 0, v94
	v_max_f32_e32 v90, 0, v90
	v_max_f32_e32 v89, 0, v95
	v_max_f32_e32 v91, 0, v91
	v_pk_mul_f32 v[92:93], v[92:93], v[92:93]
	v_pk_mul_f32 v[94:95], v[88:89], v[88:89]
; __device__ __forceinline__ float fast_sigmoid(float x) { return __builtin_amdgcn_rcpf(1.0f + __builtin_amdgcn_exp2f(-x * LOG2E)); }
; __device__ __forceinline__ float ss_fix(float raw) { return (float)__float_as_uint(raw) * (1.0f / 256.0f); }
;     __device__ __forceinline__ const CAS char* base() const { const CAS char* ka = (const CAS char*)__builtin_amdgcn_kernarg_segment_ptr(); asm volatile("" : "+s"(ka)); return ka; }
;     __device__ __forceinline__ void operator()(const f32x4 (&acc)[2][2][4][2], const Unit& u, int wr, int wc, int fr, int fq) const {
;     ...
;             for (int m = 0; m < 4; ++m) { const int row = row0 + ai * HALF + m * 16; float rs = 1.0f; if (SM == 1) rs = __builtin_amdgcn_rsqf(ss_fix(rsv[ai * 4 + m]) * (1.0f / DM) + EPS);
;                 bf16_t* rowp = base + (size_t)row * ldc + col0;
; #pragma unroll
;                 for (int bj = 0; bj < 2; ++bj) { f32x4 v0 = acc[ai][bj][m][0], v1 = acc[ai][bj][m][1];
;                     if (SM == 1) { v0 *= rs; v1 *= rs; }
;                     if (SM == 2) { v0 *= cs[bj][0]; v1 *= cs[bj][1]; }
;                     if (ACT == 1) {
; #pragma unroll
;                         for (int j = 0; j < 4; ++j) { const float a = fmaxf(v0[j], 0.f), b = fmaxf(v1[j], 0.f); v0[j] = a * a; v1[j] = b * b; } }
;                     if (ACT == 2) { if (tsel == 0) {
; #pragma unroll
;                         for (int j = 0; j < 4; ++j) { const float a = v0[j], b = v1[j];
;                             v0[j] = a * fast_sigmoid(1.5957691216057308f * (a + 0.044715f * a * a * a)); v1[j] = b * fast_sigmoid(1.5957691216057308f * (b + 0.044715f * b * b * b)); } } }
;                     u32x4 w; w.x = pk_bf16(v0[0], v0[1]); w.y = pk_bf16(v0[2], v0[3]); w.z = pk_bf16(v1[0], v1[1]); w.w = pk_bf16(v1[2], v1[3]);
;                     *(u32x4*)(rowp + bj * HALF) = w; } }
	v_pk_mul_f32 v[102:103], v[90:91], v[90:91]
	v_pk_mul_f32 v[84:85], v[84:85], v[98:99] op_sel_hi:[1,0]
	v_pk_mul_f32 v[80:81], v[80:81], v[98:99] op_sel_hi:[1,0]
	v_lshl_add_u64 v[96:97], v[148:149], 0, v[96:97]
	v_cvt_pk_bf16_f32 v88, v92, v93
	v_cvt_pk_bf16_f32 v89, v94, v95
	v_cvt_pk_bf16_f32 v90, v100, v101
	v_cvt_pk_bf16_f32 v91, v102, v103
	v_pk_mul_f32 v[86:87], v[86:87], v[98:99] op_sel_hi:[1,0]
	v_max_f32_e32 v84, 0, v84
	v_max_f32_e32 v80, 0, v80
	v_max_f32_e32 v85, 0, v85
	v_max_f32_e32 v81, 0, v81
	global_store_dwordx4 v[96:97], v[88:91], off
	v_pk_mul_f32 v[84:85], v[84:85], v[84:85]
	v_pk_mul_f32 v[82:83], v[82:83], v[98:99] op_sel_hi:[1,0]
	v_pk_mul_f32 v[88:89], v[80:81], v[80:81]
	v_max_f32_e32 v80, 0, v86
	v_max_f32_e32 v81, 0, v87
	v_pk_mul_f32 v[86:87], v[80:81], v[80:81]
	v_cvt_pk_bf16_f32 v80, v84, v85
	v_cvt_f32_u32_e32 v84, v167
	v_max_f32_e32 v82, 0, v82
	v_max_f32_e32 v83, 0, v83
	v_pk_mul_f32 v[90:91], v[82:83], v[82:83]
	v_cvt_pk_bf16_f32 v81, v86, v87
	v_cvt_pk_bf16_f32 v82, v88, v89
	v_cvt_pk_bf16_f32 v83, v90, v91
	global_store_dwordx4 v[96:97], v[80:83], off offset:256
	s_nop 1
	v_mul_f32_e32 v81, 0x3b800000, v84
	v_fmamk_f32 v81, v81, 0x3a000000, v156
	v_rsq_f32_e32 v82, v81
	v_or_b32_e32 v80, 48, v146
	v_ashrrev_i32_e32 v81, 31, v80
	v_lshlrev_b64 v[80:81], 14, v[80:81]
	v_pk_mul_f32 v[72:73], v[72:73], v[82:83] op_sel_hi:[1,0]
	v_pk_mul_f32 v[78:79], v[78:79], v[82:83] op_sel_hi:[1,0]
	v_pk_mul_f32 v[76:77], v[76:77], v[82:83] op_sel_hi:[1,0]
	v_pk_mul_f32 v[74:75], v[74:75], v[82:83] op_sel_hi:[1,0]
	v_max_f32_e32 v72, 0, v72
	v_max_f32_e32 v73, 0, v73
	v_max_f32_e32 v76, 0, v76
	v_max_f32_e32 v77, 0, v77
	v_pk_mul_f32 v[84:85], v[72:73], v[72:73]
	v_max_f32_e32 v72, 0, v78
	v_max_f32_e32 v74, 0, v74
	v_max_f32_e32 v73, 0, v79
	v_max_f32_e32 v75, 0, v75
	v_pk_mul_f32 v[76:77], v[76:77], v[76:77]
	v_pk_mul_f32 v[78:79], v[72:73], v[72:73]
	v_pk_mul_f32 v[86:87], v[74:75], v[74:75]
	v_pk_mul_f32 v[66:67], v[66:67], v[82:83] op_sel_hi:[1,0]
	v_lshl_add_u64 v[80:81], v[148:149], 0, v[80:81]
	v_cvt_pk_bf16_f32 v72, v76, v77
	v_cvt_pk_bf16_f32 v73, v78, v79
	v_cvt_pk_bf16_f32 v74, v84, v85
	v_cvt_pk_bf16_f32 v75, v86, v87
	v_max_f32_e32 v66, 0, v66
	v_max_f32_e32 v67, 0, v67
	global_store_dwordx4 v[80:81], v[72:75], off
	v_pk_mul_f32 v[68:69], v[68:69], v[82:83] op_sel_hi:[1,0]
	v_pk_mul_f32 v[64:65], v[64:65], v[82:83] op_sel_hi:[1,0]
	v_pk_mul_f32 v[74:75], v[66:67], v[66:67]
	v_cvt_f32_u32_e32 v67, v168
	v_pk_mul_f32 v[70:71], v[70:71], v[82:83] op_sel_hi:[1,0]
	v_max_f32_e32 v68, 0, v68
	v_max_f32_e32 v64, 0, v64
	v_max_f32_e32 v69, 0, v69
	v_max_f32_e32 v65, 0, v65
	v_mul_f32_e32 v67, 0x3b800000, v67
	v_pk_mul_f32 v[68:69], v[68:69], v[68:69]
	v_pk_mul_f32 v[72:73], v[64:65], v[64:65]
	v_max_f32_e32 v64, 0, v70
	v_max_f32_e32 v65, 0, v71
	v_fmamk_f32 v67, v67, 0x3a000000, v156
	v_pk_mul_f32 v[70:71], v[64:65], v[64:65]
	v_cvt_pk_bf16_f32 v64, v68, v69
	v_rsq_f32_e32 v68, v67
	v_cvt_pk_bf16_f32 v65, v70, v71
	v_cvt_pk_bf16_f32 v66, v72, v73
	v_cvt_pk_bf16_f32 v67, v74, v75
	v_pk_mul_f32 v[60:61], v[60:61], v[68:69] op_sel_hi:[1,0]
	v_pk_mul_f32 v[56:57], v[56:57], v[68:69] op_sel_hi:[1,0]
	v_pk_mul_f32 v[62:63], v[62:63], v[68:69] op_sel_hi:[1,0]
	v_pk_mul_f32 v[58:59], v[58:59], v[68:69] op_sel_hi:[1,0]
	v_max_f32_e32 v60, 0, v60
	v_max_f32_e32 v56, 0, v56
	v_max_f32_e32 v61, 0, v61
	v_max_f32_e32 v57, 0, v57
	global_store_dwordx4 v[80:81], v[64:67], off offset:256
	v_pk_mul_f32 v[60:61], v[60:61], v[60:61]
	v_max_f32_e32 v58, 0, v58
	v_pk_mul_f32 v[66:67], v[56:57], v[56:57]
	v_max_f32_e32 v56, 0, v62
	v_max_f32_e32 v57, 0, v63
	v_max_f32_e32 v59, 0, v59
	v_pk_mul_f32 v[62:63], v[56:57], v[56:57]
	v_pk_mul_f32 v[70:71], v[58:59], v[58:59]
	v_cvt_pk_bf16_f32 v56, v60, v61
	v_add_co_u32_e32 v60, vcc, s57, v144
	v_pk_mul_f32 v[50:51], v[50:51], v[68:69] op_sel_hi:[1,0]
	v_cvt_pk_bf16_f32 v57, v62, v63
	v_cvt_pk_bf16_f32 v58, v66, v67
	v_cvt_pk_bf16_f32 v59, v70, v71
	v_addc_co_u32_e32 v61, vcc, 0, v145, vcc
	v_max_f32_e32 v50, 0, v50
	v_max_f32_e32 v51, 0, v51
	global_store_dwordx4 v[60:61], v[56:59], off
	v_pk_mul_f32 v[52:53], v[52:53], v[68:69] op_sel_hi:[1,0]
	v_pk_mul_f32 v[48:49], v[48:49], v[68:69] op_sel_hi:[1,0]
	v_pk_mul_f32 v[58:59], v[50:51], v[50:51]
	v_cvt_f32_u32_e32 v51, v169
	v_pk_mul_f32 v[54:55], v[54:55], v[68:69] op_sel_hi:[1,0]
	v_max_f32_e32 v52, 0, v52
	v_max_f32_e32 v48, 0, v48
	v_max_f32_e32 v53, 0, v53
	v_max_f32_e32 v49, 0, v49
	v_mul_f32_e32 v51, 0x3b800000, v51
	v_pk_mul_f32 v[52:53], v[52:53], v[52:53]
	v_pk_mul_f32 v[56:57], v[48:49], v[48:49]
	v_max_f32_e32 v48, 0, v54
	v_max_f32_e32 v49, 0, v55
	v_fmamk_f32 v51, v51, 0x3a000000, v156
	v_pk_mul_f32 v[54:55], v[48:49], v[48:49]
	v_cvt_pk_bf16_f32 v48, v52, v53
	v_rsq_f32_e32 v52, v51
	v_lshl_add_u64 v[64:65], v[144:145], 0, s[14:15]
	v_cvt_pk_bf16_f32 v49, v54, v55
	v_cvt_pk_bf16_f32 v50, v56, v57
	v_pk_mul_f32 v[44:45], v[44:45], v[52:53] op_sel_hi:[1,0]
	v_pk_mul_f32 v[40:41], v[40:41], v[52:53] op_sel_hi:[1,0]
	v_cvt_pk_bf16_f32 v51, v58, v59
	v_pk_mul_f32 v[46:47], v[46:47], v[52:53] op_sel_hi:[1,0]
	v_pk_mul_f32 v[42:43], v[42:43], v[52:53] op_sel_hi:[1,0]
	v_max_f32_e32 v44, 0, v44
	v_max_f32_e32 v40, 0, v40
	v_max_f32_e32 v45, 0, v45
	v_max_f32_e32 v41, 0, v41
; __device__ __forceinline__ float fast_sigmoid(float x) { return __builtin_amdgcn_rcpf(1.0f + __builtin_amdgcn_exp2f(-x * LOG2E)); }
; __device__ __forceinline__ float ss_fix(float raw) { return (float)__float_as_uint(raw) * (1.0f / 256.0f); }
; #define PG8_WAIT_V(n) asm volatile("s_waitcnt vmcnt(" #n ")" ::: "memory")
; #define PG8_BAR __builtin_amdgcn_s_barrier()
;     __device__ __forceinline__ const CAS char* base() const { const CAS char* ka = (const CAS char*)__builtin_amdgcn_kernarg_segment_ptr(); asm volatile("" : "+s"(ka)); return ka; }
; template <class Epi>
; __device__ __forceinline__ void gemm_phase(LAS unsigned char* lds, const Gemm g, const StaticOrder& S, const Epi& E, int wv) {
;     ...
;     PG8_WAIT_V(0);
;     if (wr == 0) PG8_BAR;
;     PG8_BAR;
;     __device__ __forceinline__ void operator()(const f32x4 (&acc)[2][2][4][2], const Unit& u, int wr, int wc, int fr, int fq) const {
;     ...
;             for (int m = 0; m < 4; ++m) { const int row = row0 + ai * HALF + m * 16; float rs = 1.0f; if (SM == 1) rs = __builtin_amdgcn_rsqf(ss_fix(rsv[ai * 4 + m]) * (1.0f / DM) + EPS);
;                 bf16_t* rowp = base + (size_t)row * ldc + col0;
; #pragma unroll
;                 for (int bj = 0; bj < 2; ++bj) { f32x4 v0 = acc[ai][bj][m][0], v1 = acc[ai][bj][m][1];
;                     if (SM == 1) { v0 *= rs; v1 *= rs; }
;                     if (SM == 2) { v0 *= cs[bj][0]; v1 *= cs[bj][1]; }
;                     if (ACT == 1) {
; #pragma unroll
;                         for (int j = 0; j < 4; ++j) { const float a = fmaxf(v0[j], 0.f), b = fmaxf(v1[j], 0.f); v0[j] = a * a; v1[j] = b * b; } }
;                     if (ACT == 2) { if (tsel == 0) {
; #pragma unroll
;                         for (int j = 0; j < 4; ++j) { const float a = v0[j], b = v1[j];
;                             v0[j] = a * fast_sigmoid(1.5957691216057308f * (a + 0.044715f * a * a * a)); v1[j] = b * fast_sigmoid(1.5957691216057308f * (b + 0.044715f * b * b * b)); } } }
;                     u32x4 w; w.x = pk_bf16(v0[0], v0[1]); w.y = pk_bf16(v0[2], v0[3]); w.z = pk_bf16(v1[0], v1[1]); w.w = pk_bf16(v1[2], v1[3]);
;                     *(u32x4*)(rowp + bj * HALF) = w; } }
	global_store_dwordx4 v[64:65], v[48:51], off offset:256
	v_pk_mul_f32 v[44:45], v[44:45], v[44:45]
	v_max_f32_e32 v42, 0, v42
	v_pk_mul_f32 v[50:51], v[40:41], v[40:41]
	v_max_f32_e32 v40, 0, v46
	v_max_f32_e32 v41, 0, v47
	v_max_f32_e32 v43, 0, v43
	v_pk_mul_f32 v[46:47], v[40:41], v[40:41]
	v_pk_mul_f32 v[54:55], v[42:43], v[42:43]
	v_cvt_pk_bf16_f32 v40, v44, v45
	v_add_co_u32_e32 v44, vcc, s58, v144
	v_pk_mul_f32 v[34:35], v[34:35], v[52:53] op_sel_hi:[1,0]
	v_cvt_pk_bf16_f32 v41, v46, v47
	v_cvt_pk_bf16_f32 v42, v50, v51
	v_cvt_pk_bf16_f32 v43, v54, v55
	v_addc_co_u32_e32 v45, vcc, 0, v145, vcc
	v_max_f32_e32 v34, 0, v34
	v_max_f32_e32 v35, 0, v35
	global_store_dwordx4 v[44:45], v[40:43], off
	v_pk_mul_f32 v[36:37], v[36:37], v[52:53] op_sel_hi:[1,0]
	v_pk_mul_f32 v[32:33], v[32:33], v[52:53] op_sel_hi:[1,0]
	v_pk_mul_f32 v[42:43], v[34:35], v[34:35]
	v_cvt_f32_u32_e32 v35, v170
	v_pk_mul_f32 v[38:39], v[38:39], v[52:53] op_sel_hi:[1,0]
	v_max_f32_e32 v36, 0, v36
	v_max_f32_e32 v32, 0, v32
	v_max_f32_e32 v37, 0, v37
	v_max_f32_e32 v33, 0, v33
	v_mul_f32_e32 v35, 0x3b800000, v35
	v_pk_mul_f32 v[36:37], v[36:37], v[36:37]
	v_pk_mul_f32 v[40:41], v[32:33], v[32:33]
	v_max_f32_e32 v32, 0, v38
	v_max_f32_e32 v33, 0, v39
	v_fmamk_f32 v35, v35, 0x3a000000, v156
	v_pk_mul_f32 v[38:39], v[32:33], v[32:33]
	v_cvt_pk_bf16_f32 v32, v36, v37
	v_rsq_f32_e32 v36, v35
	v_lshl_add_u64 v[48:49], v[144:145], 0, s[16:17]
	v_cvt_pk_bf16_f32 v33, v38, v39
	v_cvt_pk_bf16_f32 v34, v40, v41
	v_pk_mul_f32 v[28:29], v[28:29], v[36:37] op_sel_hi:[1,0]
	v_pk_mul_f32 v[24:25], v[24:25], v[36:37] op_sel_hi:[1,0]
	v_cvt_pk_bf16_f32 v35, v42, v43
	v_pk_mul_f32 v[30:31], v[30:31], v[36:37] op_sel_hi:[1,0]
	v_pk_mul_f32 v[26:27], v[26:27], v[36:37] op_sel_hi:[1,0]
	v_max_f32_e32 v28, 0, v28
	v_max_f32_e32 v24, 0, v24
	v_max_f32_e32 v29, 0, v29
	v_max_f32_e32 v25, 0, v25
	global_store_dwordx4 v[48:49], v[32:35], off offset:256
	v_pk_mul_f32 v[28:29], v[28:29], v[28:29]
	v_max_f32_e32 v26, 0, v26
	v_pk_mul_f32 v[34:35], v[24:25], v[24:25]
	v_max_f32_e32 v24, 0, v30
	v_max_f32_e32 v25, 0, v31
	v_max_f32_e32 v27, 0, v27
	v_pk_mul_f32 v[30:31], v[24:25], v[24:25]
	v_pk_mul_f32 v[38:39], v[26:27], v[26:27]
	v_cvt_pk_bf16_f32 v24, v28, v29
	v_add_co_u32_e32 v28, vcc, s59, v144
	v_pk_mul_f32 v[18:19], v[18:19], v[36:37] op_sel_hi:[1,0]
	v_cvt_pk_bf16_f32 v25, v30, v31
	v_cvt_pk_bf16_f32 v26, v34, v35
	v_cvt_pk_bf16_f32 v27, v38, v39
	v_addc_co_u32_e32 v29, vcc, 0, v145, vcc
	v_max_f32_e32 v18, 0, v18
	v_max_f32_e32 v19, 0, v19
	global_store_dwordx4 v[28:29], v[24:27], off
	v_pk_mul_f32 v[20:21], v[20:21], v[36:37] op_sel_hi:[1,0]
	v_pk_mul_f32 v[16:17], v[16:17], v[36:37] op_sel_hi:[1,0]
	v_pk_mul_f32 v[26:27], v[18:19], v[18:19]
	v_cvt_f32_u32_e32 v19, v147
	v_pk_mul_f32 v[22:23], v[22:23], v[36:37] op_sel_hi:[1,0]
	v_max_f32_e32 v20, 0, v20
	v_max_f32_e32 v16, 0, v16
	v_max_f32_e32 v21, 0, v21
	v_max_f32_e32 v17, 0, v17
	v_mul_f32_e32 v19, 0x3b800000, v19
	v_pk_mul_f32 v[20:21], v[20:21], v[20:21]
	v_pk_mul_f32 v[24:25], v[16:17], v[16:17]
	v_max_f32_e32 v16, 0, v22
	v_max_f32_e32 v17, 0, v23
	v_fmamk_f32 v19, v19, 0x3a000000, v156
	v_pk_mul_f32 v[22:23], v[16:17], v[16:17]
	v_cvt_pk_bf16_f32 v16, v20, v21
	v_rsq_f32_e32 v20, v19
	v_lshl_add_u64 v[32:33], v[144:145], 0, s[18:19]
	v_cvt_pk_bf16_f32 v17, v22, v23
	v_cvt_pk_bf16_f32 v18, v24, v25
	v_pk_mul_f32 v[12:13], v[12:13], v[20:21] op_sel_hi:[1,0]
	v_pk_mul_f32 v[8:9], v[8:9], v[20:21] op_sel_hi:[1,0]
	v_cvt_pk_bf16_f32 v19, v26, v27
	v_pk_mul_f32 v[14:15], v[14:15], v[20:21] op_sel_hi:[1,0]
	v_pk_mul_f32 v[10:11], v[10:11], v[20:21] op_sel_hi:[1,0]
	v_max_f32_e32 v12, 0, v12
	v_max_f32_e32 v8, 0, v8
	v_max_f32_e32 v13, 0, v13
	v_max_f32_e32 v9, 0, v9
	global_store_dwordx4 v[32:33], v[16:19], off offset:256
	v_pk_mul_f32 v[12:13], v[12:13], v[12:13]
	v_max_f32_e32 v10, 0, v10
	v_pk_mul_f32 v[18:19], v[8:9], v[8:9]
	v_max_f32_e32 v8, 0, v14
	v_max_f32_e32 v9, 0, v15
	v_max_f32_e32 v11, 0, v11
	v_pk_mul_f32 v[14:15], v[8:9], v[8:9]
	v_pk_mul_f32 v[22:23], v[10:11], v[10:11]
	v_cvt_pk_bf16_f32 v8, v12, v13
	v_add_co_u32_e32 v12, vcc, s60, v144
	v_pk_mul_f32 v[0:1], v[0:1], v[20:21] op_sel_hi:[1,0]
	v_cvt_pk_bf16_f32 v9, v14, v15
	v_cvt_pk_bf16_f32 v10, v18, v19
	v_cvt_pk_bf16_f32 v11, v22, v23
	v_addc_co_u32_e32 v13, vcc, 0, v145, vcc
	v_pk_mul_f32 v[6:7], v[6:7], v[20:21] op_sel_hi:[1,0]
	v_pk_mul_f32 v[4:5], v[4:5], v[20:21] op_sel_hi:[1,0]
	v_pk_mul_f32 v[2:3], v[2:3], v[20:21] op_sel_hi:[1,0]
	v_max_f32_e32 v0, 0, v0
	v_max_f32_e32 v1, 0, v1
	global_store_dwordx4 v[12:13], v[8:11], off
	v_max_f32_e32 v4, 0, v4
	v_max_f32_e32 v5, 0, v5
	v_pk_mul_f32 v[8:9], v[0:1], v[0:1]
	v_max_f32_e32 v0, 0, v6
	v_max_f32_e32 v2, 0, v2
	v_max_f32_e32 v1, 0, v7
	v_max_f32_e32 v3, 0, v3
	v_pk_mul_f32 v[4:5], v[4:5], v[4:5]
	v_pk_mul_f32 v[6:7], v[0:1], v[0:1]
	v_pk_mul_f32 v[10:11], v[2:3], v[2:3]
	v_lshl_add_u64 v[16:17], v[144:145], 0, s[30:31]
	v_cvt_pk_bf16_f32 v0, v4, v5
	v_cvt_pk_bf16_f32 v1, v6, v7
	v_cvt_pk_bf16_f32 v2, v8, v9
	v_cvt_pk_bf16_f32 v3, v10, v11
	s_and_b64 vcc, exec, s[6:7]
	global_store_dwordx4 v[16:17], v[0:3], off offset:256
	s_cbranch_vccz .LBB0_1661
	s_waitcnt vmcnt(0)
	s_cmpk_gt_u32 s4, 0xff
	s_cbranch_scc1 .LBB0_1672
	s_barrier

; #define PG8_BAR __builtin_amdgcn_s_barrier()
; template <class Epi>
; __device__ __forceinline__ void gemm_phase(LAS unsigned char* lds, const Gemm g, const StaticOrder& S, const Epi& E, int wv) {
;     ...
;         const bool has_next = S.next(ui + 1, nxt);
;         const char* nA = has_next ? (const char*)g.A + (size_t)nxt.pm * tstepA + ((g.adiag & 1) ? (size_t)(nxt.pn >> 1) * K * 2 : 0) + kbeg : cA;
;         const char* nB = has_next ? (const char*)g.Bt + (size_t)nxt.pn * tstepB + kbeg : cB;
;         for (int t = 0; t < nt; t += 2) {
;             const bool last = (t == nt - 2);
;             const char* a1 = cA + (ptrdiff_t)(t + 1) * kstep;
;             const char* a2 = last ? nA : cA + (ptrdiff_t)(t + 2) * kstep; const char* b2 = last ? nB : cB + (ptrdiff_t)(t + 2) * kstep;
;             const char* a3 = a2 + kstep; const char* b3 = b2 + kstep;
;             PG8_LDB(B0, 0, 0); PG8_SCHED; PG8_LDA(At, 0, 0); PG8_STAGE(PG8_SA(1, 1), a1 + hstepA, voffA);
;             PG8_WAIT_L(8); PG8_BAR; PG8_WAIT_L(0); PG8_MMA(0, 0, At, B0); PG8_BAR; PG8_SCHED;
;             PG8_LDB(B1, 0, 1); PG8_STAGE(PG8_SB(0, 0), b2, voffB);
;             PG8_BAR; PG8_WAIT_L(0); PG8_MMA(0, 1, At, B1); PG8_BAR;
;             PG8_LDA(At, 0, 1); PG8_STAGE(PG8_SA(0, 0), a2, voffA);
;             PG8_BAR; PG8_WAIT_L(0); PG8_MMA(1, 0, At, B0); PG8_BAR; PG8_SCHED;
;             PG8_STAGE(PG8_SB(0, 1), b2 + hstepB, voffB);
;             PG8_WAIT_V(6); PG8_BAR; PG8_MMA(1, 1, At, B1); PG8_BAR;
;             PG8_LDB(B0, 1, 0); PG8_SCHED; PG8_LDA(At, 1, 0); PG8_STAGE(PG8_SA(0, 1), a2 + hstepA, voffA);
;             PG8_WAIT_L(8); PG8_BAR; PG8_WAIT_L(0); PG8_MMA(0, 0, At, B0); PG8_BAR; PG8_SCHED;
;             PG8_LDB(B1, 1, 1); PG8_STAGE(PG8_SB(1, 0), b3, voffB);
;             PG8_BAR; PG8_WAIT_L(0); PG8_MMA(0, 1, At, B1); PG8_BAR;
;             PG8_LDA(At, 1, 1); PG8_STAGE(PG8_SA(1, 0), a3, voffA);
;             PG8_BAR; PG8_WAIT_L(0); PG8_MMA(1, 0, At, B0); PG8_BAR; PG8_SCHED;
;             PG8_STAGE(PG8_SB(1, 1), b3 + hstepB, voffB);
;             PG8_WAIT_V(6); PG8_BAR; PG8_MMA(1, 1, At, B1); PG8_BAR;
;         }
;         E(acc, cur, wr, wc, fr, fq);
;         if (!has_next) break;
; #pragma unroll
;         for (int a = 0; a < 2; ++a)
; #pragma unroll
;             for (int b = 0; b < 2; ++b)
; #pragma unroll
;                 for (int m = 0; m < 4; ++m)
; #pragma unroll
.LBB0_1742:
	s_ashr_i32 s37, s36, 31
	v_cmp_lt_i64_e32 vcc, s[38:39], v[152:153]
	s_lshl_b64 s[38:39], s[36:37], 22
	s_add_u32 s10, s5, s38
	s_addc_u32 s35, s22, s39
	s_add_u32 s38, s10, 0x3f80
	s_addc_u32 s39, s35, 0
	s_and_b64 s[40:41], vcc, exec
	s_cselect_b32 s51, s39, s49
	s_cselect_b32 s50, s38, s48
	s_ashr_i32 s35, s34, 31
	s_lshl_b64 s[40:41], s[34:35], 22
	s_add_u32 s40, s62, s40
	s_addc_u32 s41, s63, s41
	s_and_b64 s[52:53], vcc, exec
	s_cselect_b32 s53, s41, s47
	s_cselect_b32 s52, s40, s46
	s_add_u32 s35, s48, 0x200000
	v_mov_b32_e32 v0, 0
	s_addc_u32 s37, s49, 0
	s_mov_b32 s43, 0
	s_waitcnt lgkmcnt(0)
	v_mov_b32_e32 v1, v0
	v_mov_b32_e32 v2, v0
	v_mov_b32_e32 v3, v0
	v_mov_b32_e32 v4, v0
	v_mov_b32_e32 v5, v0
	v_mov_b32_e32 v6, v0
	v_mov_b32_e32 v7, v0
	v_mov_b32_e32 v16, v0
	v_mov_b32_e32 v17, v0
	v_mov_b32_e32 v18, v0
	v_mov_b32_e32 v19, v0
	v_mov_b32_e32 v20, v0
	v_mov_b32_e32 v21, v0
	v_mov_b32_e32 v22, v0
	v_mov_b32_e32 v23, v0
	v_mov_b32_e32 v32, v0
	v_mov_b32_e32 v33, v0
	v_mov_b32_e32 v34, v0
	v_mov_b32_e32 v35, v0
	v_mov_b32_e32 v36, v0
	v_mov_b32_e32 v37, v0
	v_mov_b32_e32 v38, v0
	v_mov_b32_e32 v39, v0
	v_mov_b32_e32 v48, v0
	v_mov_b32_e32 v49, v0
	v_mov_b32_e32 v50, v0
	v_mov_b32_e32 v51, v0
	v_mov_b32_e32 v52, v0
	v_mov_b32_e32 v53, v0
	v_mov_b32_e32 v54, v0
	v_mov_b32_e32 v55, v0
	v_mov_b32_e32 v8, v0
	v_mov_b32_e32 v9, v0
	v_mov_b32_e32 v10, v0
	v_mov_b32_e32 v11, v0
	v_mov_b32_e32 v12, v0
	v_mov_b32_e32 v13, v0
	v_mov_b32_e32 v14, v0
	v_mov_b32_e32 v15, v0
	v_mov_b32_e32 v24, v0
	v_mov_b32_e32 v25, v0
	v_mov_b32_e32 v26, v0
	v_mov_b32_e32 v27, v0
	v_mov_b32_e32 v28, v0
	v_mov_b32_e32 v29, v0
	v_mov_b32_e32 v30, v0
	v_mov_b32_e32 v31, v0
	v_mov_b32_e32 v40, v0
	v_mov_b32_e32 v41, v0
	v_mov_b32_e32 v42, v0
	v_mov_b32_e32 v43, v0
	v_mov_b32_e32 v44, v0
	v_mov_b32_e32 v45, v0
	v_mov_b32_e32 v46, v0
	v_mov_b32_e32 v47, v0
	v_mov_b32_e32 v56, v0
	v_mov_b32_e32 v57, v0
	v_mov_b32_e32 v58, v0
	v_mov_b32_e32 v59, v0
	v_mov_b32_e32 v60, v0
	v_mov_b32_e32 v61, v0
	v_mov_b32_e32 v62, v0
	v_mov_b32_e32 v63, v0
	v_mov_b32_e32 v64, v0
	v_mov_b32_e32 v65, v0
	v_mov_b32_e32 v66, v0
	v_mov_b32_e32 v67, v0
	v_mov_b32_e32 v68, v0
	v_mov_b32_e32 v69, v0
	v_mov_b32_e32 v70, v0
	v_mov_b32_e32 v71, v0
	v_mov_b32_e32 v80, v0
	v_mov_b32_e32 v81, v0
	v_mov_b32_e32 v82, v0
	v_mov_b32_e32 v83, v0
	v_mov_b32_e32 v84, v0
	v_mov_b32_e32 v85, v0
	v_mov_b32_e32 v86, v0
	v_mov_b32_e32 v87, v0
	v_mov_b32_e32 v96, v0
	v_mov_b32_e32 v97, v0
	v_mov_b32_e32 v98, v0
	v_mov_b32_e32 v99, v0
	v_mov_b32_e32 v100, v0
	v_mov_b32_e32 v101, v0
	v_mov_b32_e32 v102, v0
	v_mov_b32_e32 v103, v0
	v_mov_b32_e32 v112, v0
	v_mov_b32_e32 v113, v0
	v_mov_b32_e32 v114, v0
	v_mov_b32_e32 v115, v0
	v_mov_b32_e32 v116, v0
	v_mov_b32_e32 v117, v0
	v_mov_b32_e32 v118, v0
	v_mov_b32_e32 v119, v0
	v_mov_b32_e32 v72, v0
	v_mov_b32_e32 v73, v0
	v_mov_b32_e32 v74, v0
	v_mov_b32_e32 v75, v0
	v_mov_b32_e32 v76, v0
	v_mov_b32_e32 v77, v0
	v_mov_b32_e32 v78, v0
	v_mov_b32_e32 v79, v0
	v_mov_b32_e32 v88, v0
	v_mov_b32_e32 v89, v0
	v_mov_b32_e32 v90, v0
	v_mov_b32_e32 v91, v0
	v_mov_b32_e32 v92, v0
	v_mov_b32_e32 v93, v0
	v_mov_b32_e32 v94, v0
	v_mov_b32_e32 v95, v0
	v_mov_b32_e32 v104, v0
	v_mov_b32_e32 v105, v0
	v_mov_b32_e32 v106, v0
	v_mov_b32_e32 v107, v0
	v_mov_b32_e32 v108, v0
	v_mov_b32_e32 v109, v0
	v_mov_b32_e32 v110, v0
	v_mov_b32_e32 v111, v0
	v_mov_b32_e32 v120, v0
	v_mov_b32_e32 v121, v0
	v_mov_b32_e32 v122, v0
	v_mov_b32_e32 v123, v0
	v_mov_b32_e32 v124, v0
	v_mov_b32_e32 v125, v0
	v_mov_b32_e32 v126, v0
	v_mov_b32_e32 v127, v0
	v_add_u32_e32 v140, s64, v173
	ds_read_b128 v[128:131], v140
	ds_read_b128 v[132:135], v140 offset:1024
	ds_read_b128 v[136:139], v140 offset:2048
	ds_read_b128 v[140:143], v140 offset:3072
	s_branch .LBB0_1744
.LBB0_1743:
	s_or_b32 s10, s43, 1
	s_lshl_b64 s[68:69], s[10:11], 7
	s_sub_u32 s10, 0, s68
	s_subb_u32 s55, 0, s69
	s_add_u32 s68, s35, s10
	s_addc_u32 s69, s37, s55
	s_add_i32 m0, s24, 0xc000
	ds_read_b128 v[156:159], v175
	ds_read_b128 v[160:163], v175 offset:1024
	ds_read_b128 v[164:167], v175 offset:2048
	ds_read_b128 v[168:171], v175 offset:3072
	ds_read_b128 v[176:179], v175 offset:4096
	ds_read_b128 v[180:183], v175 offset:5120
	ds_read_b128 v[184:187], v175 offset:6144
	ds_read_b128 v[188:191], v175 offset:7168
	global_load_lds_dwordx4 v144, s[68:69]
	s_add_i32 m0, s24, 0xe000
	s_nop 0
	global_load_lds_dwordx4 v148, s[68:69]
	s_waitcnt lgkmcnt(8)
	s_barrier
	s_waitcnt lgkmcnt(0)
	s_setprio 1
	s_waitcnt lgkmcnt(0)
	v_mfma_f32_16x16x32_bf16 v[124:127], v[128:131], v[156:159], v[124:127]
	v_mfma_f32_16x16x32_bf16 v[120:123], v[136:139], v[156:159], v[120:123]
	v_mfma_f32_16x16x32_bf16 v[108:111], v[128:131], v[164:167], v[108:111]
	v_mfma_f32_16x16x32_bf16 v[104:107], v[136:139], v[164:167], v[104:107]
	v_mfma_f32_16x16x32_bf16 v[92:95], v[128:131], v[176:179], v[92:95]
	v_mfma_f32_16x16x32_bf16 v[88:91], v[136:139], v[176:179], v[88:91]
	v_mfma_f32_16x16x32_bf16 v[76:79], v[128:131], v[184:187], v[76:79]
	v_mfma_f32_16x16x32_bf16 v[72:75], v[136:139], v[184:187], v[72:75]
	v_mfma_f32_16x16x32_bf16 v[124:127], v[132:135], v[160:163], v[124:127]
	v_mfma_f32_16x16x32_bf16 v[120:123], v[140:143], v[160:163], v[120:123]
	v_mfma_f32_16x16x32_bf16 v[108:111], v[132:135], v[168:171], v[108:111]
	v_mfma_f32_16x16x32_bf16 v[104:107], v[140:143], v[168:171], v[104:107]
	v_mfma_f32_16x16x32_bf16 v[92:95], v[132:135], v[180:183], v[92:95]
	v_mfma_f32_16x16x32_bf16 v[88:91], v[140:143], v[180:183], v[88:91]
	v_mfma_f32_16x16x32_bf16 v[76:79], v[132:135], v[188:191], v[76:79]
	v_mfma_f32_16x16x32_bf16 v[72:75], v[140:143], v[188:191], v[72:75]
	s_setprio 0
	s_barrier
; #define PG8_STAGE(bufoff, gbase, voff) do { _Pragma("unroll") for (int _i = 0; _i < 2; ++_i) \
;         __builtin_amdgcn_global_load_lds((const unsigned*)((const char*)(gbase) + (voff)[_i]), (LAS unsigned*)(lds + (bufoff) + ldsw + _i * 8192), 16, 0, 0); } while (0)
; #define PG8_LDA(dst, b, h) do { _Pragma("unroll") for (int m = 0; m < 4; ++m) _Pragma("unroll") for (int k = 0; k < 2; ++k) dst[m][k] = *(const LAS bf16x8*)(lds + PG8_SA(b, h) + aoff + m * 2048 + k * 1024); } while (0)
; #define PG8_LDB(dst, b, h) do { _Pragma("unroll") for (int n = 0; n < 2; ++n) _Pragma("unroll") for (int k = 0; k < 2; ++k) dst[n][k] = *(const LAS bf16x8*)(lds + PG8_SB(b, h) + boff + n * 2048 + k * 1024); } while (0)
; #define PG8_MMA(ai, bj, At, Bt) do { __builtin_amdgcn_s_setprio(1); _Pragma("unroll") for (int m = 0; m < 4; ++m) _Pragma("unroll") for (int n = 0; n < 2; ++n) _Pragma("unroll") for (int k = 0; k < 2; ++k) \
;         acc[ai][bj][m][n] = __builtin_amdgcn_mfma_f32_16x16x32_bf16(Bt[n][k], At[m][k], acc[ai][bj][m][n], 0, 0, 0); __builtin_amdgcn_s_setprio(0); } while (0)
; #define PG8_WAIT_V(n) asm volatile("s_waitcnt vmcnt(" #n ")" ::: "memory")
; #define PG8_WAIT_L(n) asm volatile("s_waitcnt lgkmcnt(" #n ")" ::: "memory")
; #define PG8_BAR __builtin_amdgcn_s_barrier()
; #define PG8_SCHED __builtin_amdgcn_sched_barrier(0)
; template <class Epi>
; __device__ __forceinline__ void gemm_phase(LAS unsigned char* lds, const Gemm g, const StaticOrder& S, const Epi& E, int wv) {
;     ...
;             PG8_LDB(B1, 0, 1); PG8_STAGE(PG8_SB(0, 0), b2, voffB);
;             PG8_BAR; PG8_WAIT_L(0); PG8_MMA(0, 1, At, B1); PG8_BAR;
;             PG8_LDA(At, 0, 1); PG8_STAGE(PG8_SA(0, 0), a2, voffA);
;             PG8_BAR; PG8_WAIT_L(0); PG8_MMA(1, 0, At, B0); PG8_BAR; PG8_SCHED;
;             PG8_STAGE(PG8_SB(0, 1), b2 + hstepB, voffB);
;             PG8_WAIT_V(6); PG8_BAR; PG8_MMA(1, 1, At, B1); PG8_BAR;
;             PG8_LDB(B0, 1, 0); PG8_SCHED; PG8_LDA(At, 1, 0); PG8_STAGE(PG8_SA(0, 1), a2 + hstepA, voffA);
;             PG8_WAIT_L(8); PG8_BAR; PG8_WAIT_L(0); PG8_MMA(0, 0, At, B0); PG8_BAR; PG8_SCHED;
	s_add_i32 s10, s64, s23
	v_add_u32_e32 v204, s65, v173
	s_add_u32 s98, s56, s18
	s_addc_u32 s99, s57, s19
	s_mov_b32 m0, s10
	ds_read_b128 v[192:195], v204
	ds_read_b128 v[196:199], v204 offset:1024
	ds_read_b128 v[200:203], v204 offset:2048
	ds_read_b128 v[204:207], v204 offset:3072
	global_load_lds_dwordx4 v146, s[56:57]
	s_add_i32 m0, s10, 0x2000
	s_nop 0
	global_load_lds_dwordx4 v150, s[56:57]
	s_barrier
	s_waitcnt lgkmcnt(0)
	s_setprio 1
	s_waitcnt lgkmcnt(0)
	v_mfma_f32_16x16x32_bf16 v[116:119], v[192:195], v[156:159], v[116:119]
	v_mfma_f32_16x16x32_bf16 v[112:115], v[200:203], v[156:159], v[112:115]
	v_mfma_f32_16x16x32_bf16 v[100:103], v[192:195], v[164:167], v[100:103]
	v_mfma_f32_16x16x32_bf16 v[96:99], v[200:203], v[164:167], v[96:99]
	v_mfma_f32_16x16x32_bf16 v[84:87], v[192:195], v[176:179], v[84:87]
	v_mfma_f32_16x16x32_bf16 v[80:83], v[200:203], v[176:179], v[80:83]
	v_mfma_f32_16x16x32_bf16 v[68:71], v[192:195], v[184:187], v[68:71]
	v_mfma_f32_16x16x32_bf16 v[64:67], v[200:203], v[184:187], v[64:67]
	v_mfma_f32_16x16x32_bf16 v[116:119], v[196:199], v[160:163], v[116:119]
	v_mfma_f32_16x16x32_bf16 v[112:115], v[204:207], v[160:163], v[112:115]
	v_mfma_f32_16x16x32_bf16 v[100:103], v[196:199], v[168:171], v[100:103]
	v_mfma_f32_16x16x32_bf16 v[96:99], v[204:207], v[168:171], v[96:99]
	v_mfma_f32_16x16x32_bf16 v[84:87], v[196:199], v[180:183], v[84:87]
	v_mfma_f32_16x16x32_bf16 v[80:83], v[204:207], v[180:183], v[80:83]
	v_mfma_f32_16x16x32_bf16 v[68:71], v[196:199], v[188:191], v[68:71]
	v_mfma_f32_16x16x32_bf16 v[64:67], v[204:207], v[188:191], v[64:67]
	s_setprio 0
	s_mov_b32 m0, s24
	s_add_u32 s100, s58, s18
	s_addc_u32 s101, s59, s19
	s_barrier
	ds_read_b128 v[156:159], v175 offset:16384
	ds_read_b128 v[160:163], v175 offset:17408
	ds_read_b128 v[164:167], v175 offset:18432
	ds_read_b128 v[168:171], v175 offset:19456
	ds_read_b128 v[176:179], v175 offset:20480
	ds_read_b128 v[180:183], v175 offset:21504
	ds_read_b128 v[184:187], v175 offset:22528
	ds_read_b128 v[188:191], v175 offset:23552
	global_load_lds_dwordx4 v144, s[58:59]
	s_mov_b32 m0, s25
	s_nop 0
	global_load_lds_dwordx4 v148, s[58:59]
	s_waitcnt vmcnt(10)
	s_barrier
	s_waitcnt lgkmcnt(0)
	s_setprio 1
	s_waitcnt lgkmcnt(0)
	v_mfma_f32_16x16x32_bf16 v[60:63], v[128:131], v[156:159], v[60:63]
	v_mfma_f32_16x16x32_bf16 v[56:59], v[136:139], v[156:159], v[56:59]
	v_mfma_f32_16x16x32_bf16 v[44:47], v[128:131], v[164:167], v[44:47]
	v_mfma_f32_16x16x32_bf16 v[40:43], v[136:139], v[164:167], v[40:43]
	v_mfma_f32_16x16x32_bf16 v[28:31], v[128:131], v[176:179], v[28:31]
	v_mfma_f32_16x16x32_bf16 v[24:27], v[136:139], v[176:179], v[24:27]
	v_mfma_f32_16x16x32_bf16 v[12:15], v[128:131], v[184:187], v[12:15]
	v_mfma_f32_16x16x32_bf16 v[8:11], v[136:139], v[184:187], v[8:11]
	v_mfma_f32_16x16x32_bf16 v[60:63], v[132:135], v[160:163], v[60:63]
	v_mfma_f32_16x16x32_bf16 v[56:59], v[140:143], v[160:163], v[56:59]
	v_mfma_f32_16x16x32_bf16 v[44:47], v[132:135], v[168:171], v[44:47]
	v_mfma_f32_16x16x32_bf16 v[40:43], v[140:143], v[168:171], v[40:43]
	v_mfma_f32_16x16x32_bf16 v[28:31], v[132:135], v[180:183], v[28:31]
	v_mfma_f32_16x16x32_bf16 v[24:27], v[140:143], v[180:183], v[24:27]
	v_mfma_f32_16x16x32_bf16 v[12:15], v[132:135], v[188:191], v[12:15]
	v_mfma_f32_16x16x32_bf16 v[8:11], v[140:143], v[188:191], v[8:11]
	s_setprio 0
	s_barrier
	s_add_u32 s68, s56, 0x200000
	s_addc_u32 s69, s57, 0
	s_add_i32 s10, s65, s23
	s_mov_b32 m0, s10
	s_nop 0
	global_load_lds_dwordx4 v146, s[68:69]
	s_add_i32 m0, s10, 0x2000
	s_nop 0
	global_load_lds_dwordx4 v150, s[68:69]
	s_add_i32 s10, 0, 0x18000
	v_add_u32_e32 v140, s10, v173
	ds_read_b128 v[128:131], v140
	ds_read_b128 v[132:135], v140 offset:1024
	ds_read_b128 v[136:139], v140 offset:2048
	ds_read_b128 v[140:143], v140 offset:3072
	s_waitcnt vmcnt(6)
	s_barrier
	s_setprio 1
	v_mfma_f32_16x16x32_bf16 v[52:55], v[192:195], v[156:159], v[52:55]
	v_mfma_f32_16x16x32_bf16 v[48:51], v[200:203], v[156:159], v[48:51]
	v_mfma_f32_16x16x32_bf16 v[36:39], v[192:195], v[164:167], v[36:39]
	v_mfma_f32_16x16x32_bf16 v[32:35], v[200:203], v[164:167], v[32:35]
	v_mfma_f32_16x16x32_bf16 v[20:23], v[192:195], v[176:179], v[20:23]
	v_mfma_f32_16x16x32_bf16 v[16:19], v[200:203], v[176:179], v[16:19]
	v_mfma_f32_16x16x32_bf16 v[4:7], v[192:195], v[184:187], v[4:7]
	v_mfma_f32_16x16x32_bf16 v[0:3], v[200:203], v[184:187], v[0:3]
	v_mfma_f32_16x16x32_bf16 v[52:55], v[196:199], v[160:163], v[52:55]
	v_mfma_f32_16x16x32_bf16 v[48:51], v[204:207], v[160:163], v[48:51]
	v_mfma_f32_16x16x32_bf16 v[36:39], v[196:199], v[168:171], v[36:39]
	v_mfma_f32_16x16x32_bf16 v[32:35], v[204:207], v[168:171], v[32:35]
	v_mfma_f32_16x16x32_bf16 v[20:23], v[196:199], v[180:183], v[20:23]
	v_mfma_f32_16x16x32_bf16 v[16:19], v[204:207], v[180:183], v[16:19]
	v_mfma_f32_16x16x32_bf16 v[4:7], v[196:199], v[188:191], v[4:7]
	v_mfma_f32_16x16x32_bf16 v[0:3], v[204:207], v[188:191], v[0:3]
	s_setprio 0
	s_waitcnt lgkmcnt(0)
	s_barrier
	s_add_u32 s58, s58, 0x200000
	s_addc_u32 s59, s59, 0
	s_mov_b32 m0, s33
	ds_read_b128 v[156:159], v175 offset:32768
	ds_read_b128 v[160:163], v175 offset:33792
	ds_read_b128 v[164:167], v175 offset:34816
	ds_read_b128 v[168:171], v175 offset:35840
	ds_read_b128 v[176:179], v175 offset:36864
	ds_read_b128 v[180:183], v175 offset:37888
	ds_read_b128 v[184:187], v175 offset:38912
	ds_read_b128 v[188:191], v175 offset:39936
	global_load_lds_dwordx4 v144, s[58:59]
	s_mov_b32 m0, s45
	s_nop 0
	global_load_lds_dwordx4 v148, s[58:59]
	s_waitcnt lgkmcnt(8)
	s_barrier
; #define PG8_STAGE(bufoff, gbase, voff) do { _Pragma("unroll") for (int _i = 0; _i < 2; ++_i) \
;         __builtin_amdgcn_global_load_lds((const unsigned*)((const char*)(gbase) + (voff)[_i]), (LAS unsigned*)(lds + (bufoff) + ldsw + _i * 8192), 16, 0, 0); } while (0)
; #define PG8_LDA(dst, b, h) do { _Pragma("unroll") for (int m = 0; m < 4; ++m) _Pragma("unroll") for (int k = 0; k < 2; ++k) dst[m][k] = *(const LAS bf16x8*)(lds + PG8_SA(b, h) + aoff + m * 2048 + k * 1024); } while (0)
; #define PG8_LDB(dst, b, h) do { _Pragma("unroll") for (int n = 0; n < 2; ++n) _Pragma("unroll") for (int k = 0; k < 2; ++k) dst[n][k] = *(const LAS bf16x8*)(lds + PG8_SB(b, h) + boff + n * 2048 + k * 1024); } while (0)
; #define PG8_MMA(ai, bj, At, Bt) do { __builtin_amdgcn_s_setprio(1); _Pragma("unroll") for (int m = 0; m < 4; ++m) _Pragma("unroll") for (int n = 0; n < 2; ++n) _Pragma("unroll") for (int k = 0; k < 2; ++k) \
;         acc[ai][bj][m][n] = __builtin_amdgcn_mfma_f32_16x16x32_bf16(Bt[n][k], At[m][k], acc[ai][bj][m][n], 0, 0, 0); __builtin_amdgcn_s_setprio(0); } while (0)
; #define PG8_WAIT_V(n) asm volatile("s_waitcnt vmcnt(" #n ")" ::: "memory")
; #define PG8_WAIT_L(n) asm volatile("s_waitcnt lgkmcnt(" #n ")" ::: "memory")
; #define PG8_BAR __builtin_amdgcn_s_barrier()
; #define PG8_SCHED __builtin_amdgcn_sched_barrier(0)
; template <class Epi>
; __device__ __forceinline__ void gemm_phase(LAS unsigned char* lds, const Gemm g, const StaticOrder& S, const Epi& E, int wv) {
;     ...
;             PG8_WAIT_L(8); PG8_BAR; PG8_WAIT_L(0); PG8_MMA(0, 0, At, B0); PG8_BAR; PG8_SCHED;
;             PG8_LDB(B1, 1, 1); PG8_STAGE(PG8_SB(1, 0), b3, voffB);
;             PG8_BAR; PG8_WAIT_L(0); PG8_MMA(0, 1, At, B1); PG8_BAR;
;             PG8_LDA(At, 1, 1); PG8_STAGE(PG8_SA(1, 0), a3, voffA);
;             PG8_BAR; PG8_WAIT_L(0); PG8_MMA(1, 0, At, B0); PG8_BAR; PG8_SCHED;
;             PG8_STAGE(PG8_SB(1, 1), b3 + hstepB, voffB);
;             PG8_WAIT_V(6); PG8_BAR; PG8_MMA(1, 1, At, B1); PG8_BAR;
	s_waitcnt lgkmcnt(0)
	s_setprio 1
	s_waitcnt lgkmcnt(0)
	v_mfma_f32_16x16x32_bf16 v[124:127], v[128:131], v[156:159], v[124:127]
	v_mfma_f32_16x16x32_bf16 v[120:123], v[136:139], v[156:159], v[120:123]
	v_mfma_f32_16x16x32_bf16 v[108:111], v[128:131], v[164:167], v[108:111]
	v_mfma_f32_16x16x32_bf16 v[104:107], v[136:139], v[164:167], v[104:107]
	v_mfma_f32_16x16x32_bf16 v[92:95], v[128:131], v[176:179], v[92:95]
	v_mfma_f32_16x16x32_bf16 v[88:91], v[136:139], v[176:179], v[88:91]
	v_mfma_f32_16x16x32_bf16 v[76:79], v[128:131], v[184:187], v[76:79]
	v_mfma_f32_16x16x32_bf16 v[72:75], v[136:139], v[184:187], v[72:75]
	v_mfma_f32_16x16x32_bf16 v[124:127], v[132:135], v[160:163], v[124:127]
	v_mfma_f32_16x16x32_bf16 v[120:123], v[140:143], v[160:163], v[120:123]
	v_mfma_f32_16x16x32_bf16 v[108:111], v[132:135], v[168:171], v[108:111]
	v_mfma_f32_16x16x32_bf16 v[104:107], v[140:143], v[168:171], v[104:107]
	v_mfma_f32_16x16x32_bf16 v[92:95], v[132:135], v[180:183], v[92:95]
	v_mfma_f32_16x16x32_bf16 v[88:91], v[140:143], v[180:183], v[88:91]
	v_mfma_f32_16x16x32_bf16 v[76:79], v[132:135], v[188:191], v[76:79]
	v_mfma_f32_16x16x32_bf16 v[72:75], v[140:143], v[188:191], v[72:75]
	s_setprio 0
	s_barrier
	s_add_i32 s55, 0, 0x1c000
	s_add_i32 s10, s10, s23
	v_add_u32_e32 v204, s55, v173
	s_mov_b32 m0, s10
	ds_read_b128 v[192:195], v204
	ds_read_b128 v[196:199], v204 offset:1024
	ds_read_b128 v[200:203], v204 offset:2048
	ds_read_b128 v[204:207], v204 offset:3072
	global_load_lds_dwordx4 v146, s[98:99]
	s_add_i32 m0, s10, 0x2000
	s_nop 0
	global_load_lds_dwordx4 v150, s[98:99]
	s_barrier
	s_waitcnt lgkmcnt(0)
	s_setprio 1
	s_waitcnt lgkmcnt(0)
	v_mfma_f32_16x16x32_bf16 v[116:119], v[192:195], v[156:159], v[116:119]
	v_mfma_f32_16x16x32_bf16 v[112:115], v[200:203], v[156:159], v[112:115]
	v_mfma_f32_16x16x32_bf16 v[100:103], v[192:195], v[164:167], v[100:103]
	v_mfma_f32_16x16x32_bf16 v[96:99], v[200:203], v[164:167], v[96:99]
	v_mfma_f32_16x16x32_bf16 v[84:87], v[192:195], v[176:179], v[84:87]
	v_mfma_f32_16x16x32_bf16 v[80:83], v[200:203], v[176:179], v[80:83]
	v_mfma_f32_16x16x32_bf16 v[68:71], v[192:195], v[184:187], v[68:71]
	v_mfma_f32_16x16x32_bf16 v[64:67], v[200:203], v[184:187], v[64:67]
	v_mfma_f32_16x16x32_bf16 v[116:119], v[196:199], v[160:163], v[116:119]
	v_mfma_f32_16x16x32_bf16 v[112:115], v[204:207], v[160:163], v[112:115]
	v_mfma_f32_16x16x32_bf16 v[100:103], v[196:199], v[168:171], v[100:103]
	v_mfma_f32_16x16x32_bf16 v[96:99], v[204:207], v[168:171], v[96:99]
	v_mfma_f32_16x16x32_bf16 v[84:87], v[196:199], v[180:183], v[84:87]
	v_mfma_f32_16x16x32_bf16 v[80:83], v[204:207], v[180:183], v[80:83]
	v_mfma_f32_16x16x32_bf16 v[68:71], v[196:199], v[188:191], v[68:71]
	v_mfma_f32_16x16x32_bf16 v[64:67], v[204:207], v[188:191], v[64:67]
	s_setprio 0
	s_mov_b32 m0, s60
	s_barrier
	ds_read_b128 v[156:159], v175 offset:49152
	ds_read_b128 v[160:163], v175 offset:50176
	ds_read_b128 v[164:167], v175 offset:51200
	ds_read_b128 v[168:171], v175 offset:52224
	ds_read_b128 v[176:179], v175 offset:53248
	ds_read_b128 v[180:183], v175 offset:54272
	ds_read_b128 v[184:187], v175 offset:55296
	ds_read_b128 v[188:191], v175 offset:56320
	global_load_lds_dwordx4 v144, s[100:101]
	s_mov_b32 m0, s61
	s_nop 0
	global_load_lds_dwordx4 v148, s[100:101]
	s_waitcnt vmcnt(10)
	s_barrier
	s_waitcnt lgkmcnt(0)
	s_setprio 1
	s_waitcnt lgkmcnt(0)
	v_mfma_f32_16x16x32_bf16 v[60:63], v[128:131], v[156:159], v[60:63]
	v_mfma_f32_16x16x32_bf16 v[56:59], v[136:139], v[156:159], v[56:59]
	v_mfma_f32_16x16x32_bf16 v[44:47], v[128:131], v[164:167], v[44:47]
	v_mfma_f32_16x16x32_bf16 v[40:43], v[136:139], v[164:167], v[40:43]
	v_mfma_f32_16x16x32_bf16 v[28:31], v[128:131], v[176:179], v[28:31]
	v_mfma_f32_16x16x32_bf16 v[24:27], v[136:139], v[176:179], v[24:27]
	v_mfma_f32_16x16x32_bf16 v[12:15], v[128:131], v[184:187], v[12:15]
	v_mfma_f32_16x16x32_bf16 v[8:11], v[136:139], v[184:187], v[8:11]
	v_mfma_f32_16x16x32_bf16 v[60:63], v[132:135], v[160:163], v[60:63]
	v_mfma_f32_16x16x32_bf16 v[56:59], v[140:143], v[160:163], v[56:59]
	v_mfma_f32_16x16x32_bf16 v[44:47], v[132:135], v[168:171], v[44:47]
	v_mfma_f32_16x16x32_bf16 v[40:43], v[140:143], v[168:171], v[40:43]
	v_mfma_f32_16x16x32_bf16 v[28:31], v[132:135], v[180:183], v[28:31]
	v_mfma_f32_16x16x32_bf16 v[24:27], v[140:143], v[180:183], v[24:27]
	v_mfma_f32_16x16x32_bf16 v[12:15], v[132:135], v[188:191], v[12:15]
	v_mfma_f32_16x16x32_bf16 v[8:11], v[140:143], v[188:191], v[8:11]
	s_setprio 0
	s_barrier
	s_add_u32 s56, s56, 0x1fff80
	s_addc_u32 s57, s57, 0
	s_add_i32 s10, s55, s23
	s_mov_b32 m0, s10
	s_nop 0
	global_load_lds_dwordx4 v146, s[56:57]
	s_add_i32 m0, s10, 0x2000
	s_nop 0
	global_load_lds_dwordx4 v150, s[56:57]
	v_add_u32_e32 v140, s64, v173
	ds_read_b128 v[128:131], v140
	ds_read_b128 v[132:135], v140 offset:1024
	ds_read_b128 v[136:139], v140 offset:2048
	ds_read_b128 v[140:143], v140 offset:3072
	s_waitcnt vmcnt(6)
	s_barrier
	s_setprio 1
	v_mfma_f32_16x16x32_bf16 v[52:55], v[192:195], v[156:159], v[52:55]
	v_mfma_f32_16x16x32_bf16 v[48:51], v[200:203], v[156:159], v[48:51]
	v_mfma_f32_16x16x32_bf16 v[36:39], v[192:195], v[164:167], v[36:39]
	v_mfma_f32_16x16x32_bf16 v[32:35], v[200:203], v[164:167], v[32:35]
	v_mfma_f32_16x16x32_bf16 v[20:23], v[192:195], v[176:179], v[20:23]
	v_mfma_f32_16x16x32_bf16 v[16:19], v[200:203], v[176:179], v[16:19]
	v_mfma_f32_16x16x32_bf16 v[4:7], v[192:195], v[184:187], v[4:7]
	v_mfma_f32_16x16x32_bf16 v[0:3], v[200:203], v[184:187], v[0:3]
	v_mfma_f32_16x16x32_bf16 v[52:55], v[196:199], v[160:163], v[52:55]
	v_mfma_f32_16x16x32_bf16 v[48:51], v[204:207], v[160:163], v[48:51]
	v_mfma_f32_16x16x32_bf16 v[36:39], v[196:199], v[168:171], v[36:39]
	v_mfma_f32_16x16x32_bf16 v[32:35], v[204:207], v[168:171], v[32:35]
	v_mfma_f32_16x16x32_bf16 v[20:23], v[196:199], v[180:183], v[20:23]
	v_mfma_f32_16x16x32_bf16 v[16:19], v[204:207], v[180:183], v[16:19]
	v_mfma_f32_16x16x32_bf16 v[4:7], v[196:199], v[188:191], v[4:7]
	v_mfma_f32_16x16x32_bf16 v[0:3], v[204:207], v[188:191], v[0:3]
	s_setprio 0
	s_waitcnt lgkmcnt(0)
	s_cmpk_gt_u32 s43, 0x7d
	s_mov_b32 s43, s54
	s_barrier
	s_cbranch_scc1 .LBB0_1748

; #define PG8_BAR __builtin_amdgcn_s_barrier()
; template <class Epi>
; __device__ __forceinline__ void gemm_phase(LAS unsigned char* lds, const Gemm g, const StaticOrder& S, const Epi& E, int wv) {
;     ...
;         const bool has_next = S.next(ui + 1, nxt);
;         const char* nA = has_next ? (const char*)g.A + (size_t)nxt.pm * tstepA + ((g.adiag & 1) ? (size_t)(nxt.pn >> 1) * K * 2 : 0) + kbeg : cA;
;         const char* nB = has_next ? (const char*)g.Bt + (size_t)nxt.pn * tstepB + kbeg : cB;
;         for (int t = 0; t < nt; t += 2) {
;             const bool last = (t == nt - 2);
;             const char* a1 = cA + (ptrdiff_t)(t + 1) * kstep;
;             const char* a2 = last ? nA : cA + (ptrdiff_t)(t + 2) * kstep; const char* b2 = last ? nB : cB + (ptrdiff_t)(t + 2) * kstep;
;             const char* a3 = a2 + kstep; const char* b3 = b2 + kstep;
;             PG8_LDB(B0, 0, 0); PG8_SCHED; PG8_LDA(At, 0, 0); PG8_STAGE(PG8_SA(1, 1), a1 + hstepA, voffA);
;             PG8_WAIT_L(8); PG8_BAR; PG8_WAIT_L(0); PG8_MMA(0, 0, At, B0); PG8_BAR; PG8_SCHED;
;             PG8_LDB(B1, 0, 1); PG8_STAGE(PG8_SB(0, 0), b2, voffB);
;             PG8_BAR; PG8_WAIT_L(0); PG8_MMA(0, 1, At, B1); PG8_BAR;
;             PG8_LDA(At, 0, 1); PG8_STAGE(PG8_SA(0, 0), a2, voffA);
;             PG8_BAR; PG8_WAIT_L(0); PG8_MMA(1, 0, At, B0); PG8_BAR; PG8_SCHED;
;             PG8_STAGE(PG8_SB(0, 1), b2 + hstepB, voffB);
;             PG8_WAIT_V(6); PG8_BAR; PG8_MMA(1, 1, At, B1); PG8_BAR;
;             PG8_LDB(B0, 1, 0); PG8_SCHED; PG8_LDA(At, 1, 0); PG8_STAGE(PG8_SA(0, 1), a2 + hstepA, voffA);
;             PG8_WAIT_L(8); PG8_BAR; PG8_WAIT_L(0); PG8_MMA(0, 0, At, B0); PG8_BAR; PG8_SCHED;
;             PG8_LDB(B1, 1, 1); PG8_STAGE(PG8_SB(1, 0), b3, voffB);
;             PG8_BAR; PG8_WAIT_L(0); PG8_MMA(0, 1, At, B1); PG8_BAR;
;             PG8_LDA(At, 1, 1); PG8_STAGE(PG8_SA(1, 0), a3, voffA);
;             PG8_BAR; PG8_WAIT_L(0); PG8_MMA(1, 0, At, B0); PG8_BAR; PG8_SCHED;
;             PG8_STAGE(PG8_SB(1, 1), b3 + hstepB, voffB);
;             PG8_WAIT_V(6); PG8_BAR; PG8_MMA(1, 1, At, B1); PG8_BAR;
;         }
;         E(acc, cur, wr, wc, fr, fq);
;         if (!has_next) break;
; #pragma unroll
;         for (int a = 0; a < 2; ++a)
; #pragma unroll
;             for (int b = 0; b < 2; ++b)
; #pragma unroll
;                 for (int m = 0; m < 4; ++m)
; #pragma unroll
.LBB0_1852:
	s_ashr_i32 s19, s18, 31
	v_cmp_lt_i64_e32 vcc, s[20:21], v[172:173]
	s_lshl_b64 s[20:21], s[18:19], 20
	s_add_u32 s20, s36, s20
	s_addc_u32 s21, s37, s21
	s_and_b64 s[22:23], vcc, exec
	s_cselect_b32 s19, s21, s31
	s_cselect_b32 s50, s20, s30
	s_ashr_i32 s17, s16, 31
	s_lshl_b64 s[22:23], s[16:17], 20
	s_add_u32 s22, s38, s22
	s_addc_u32 s23, s39, s23
	s_and_b64 s[34:35], vcc, exec
	s_cselect_b32 s17, s23, s29
	s_cselect_b32 s51, s22, s28
	s_add_u32 s52, s28, 0x100
	s_addc_u32 s53, s29, 0
	s_add_u32 s28, s30, 0x80080
	v_mov_b32_e32 v0, 0
	s_addc_u32 s29, s31, 0
	s_mov_b32 s54, -2
	v_mov_b32_e32 v1, v0
	v_mov_b32_e32 v2, v0
	v_mov_b32_e32 v3, v0
	v_mov_b32_e32 v4, v0
	v_mov_b32_e32 v5, v0
	v_mov_b32_e32 v6, v0
	v_mov_b32_e32 v7, v0
	v_mov_b32_e32 v16, v0
	v_mov_b32_e32 v17, v0
	v_mov_b32_e32 v18, v0
	v_mov_b32_e32 v19, v0
	v_mov_b32_e32 v20, v0
	v_mov_b32_e32 v21, v0
	v_mov_b32_e32 v22, v0
	v_mov_b32_e32 v23, v0
	v_mov_b32_e32 v32, v0
	v_mov_b32_e32 v33, v0
	v_mov_b32_e32 v34, v0
	v_mov_b32_e32 v35, v0
	v_mov_b32_e32 v36, v0
	v_mov_b32_e32 v37, v0
	v_mov_b32_e32 v38, v0
	v_mov_b32_e32 v39, v0
	v_mov_b32_e32 v48, v0
	v_mov_b32_e32 v49, v0
	v_mov_b32_e32 v50, v0
	v_mov_b32_e32 v51, v0
	v_mov_b32_e32 v52, v0
	v_mov_b32_e32 v53, v0
	v_mov_b32_e32 v54, v0
	v_mov_b32_e32 v55, v0
	v_mov_b32_e32 v8, v0
	v_mov_b32_e32 v9, v0
	v_mov_b32_e32 v10, v0
	v_mov_b32_e32 v11, v0
	v_mov_b32_e32 v12, v0
	v_mov_b32_e32 v13, v0
	v_mov_b32_e32 v14, v0
	v_mov_b32_e32 v15, v0
	v_mov_b32_e32 v24, v0
	v_mov_b32_e32 v25, v0
	v_mov_b32_e32 v26, v0
	v_mov_b32_e32 v27, v0
	v_mov_b32_e32 v28, v0
	v_mov_b32_e32 v29, v0
	v_mov_b32_e32 v30, v0
	v_mov_b32_e32 v31, v0
	v_mov_b32_e32 v40, v0
	v_mov_b32_e32 v41, v0
	v_mov_b32_e32 v42, v0
	v_mov_b32_e32 v43, v0
	v_mov_b32_e32 v44, v0
	v_mov_b32_e32 v45, v0
	v_mov_b32_e32 v46, v0
	v_mov_b32_e32 v47, v0
	v_mov_b32_e32 v56, v0
	v_mov_b32_e32 v57, v0
	v_mov_b32_e32 v58, v0
	v_mov_b32_e32 v59, v0
	v_mov_b32_e32 v60, v0
	v_mov_b32_e32 v61, v0
	v_mov_b32_e32 v62, v0
	v_mov_b32_e32 v63, v0
	v_mov_b32_e32 v64, v0
	v_mov_b32_e32 v65, v0
	v_mov_b32_e32 v66, v0
	v_mov_b32_e32 v67, v0
	v_mov_b32_e32 v68, v0
	v_mov_b32_e32 v69, v0
	v_mov_b32_e32 v70, v0
	v_mov_b32_e32 v71, v0
	v_mov_b32_e32 v80, v0
	v_mov_b32_e32 v81, v0
	v_mov_b32_e32 v82, v0
	v_mov_b32_e32 v83, v0
	v_mov_b32_e32 v84, v0
	v_mov_b32_e32 v85, v0
	v_mov_b32_e32 v86, v0
	v_mov_b32_e32 v87, v0
	v_mov_b32_e32 v96, v0
	v_mov_b32_e32 v97, v0
	v_mov_b32_e32 v98, v0
	v_mov_b32_e32 v99, v0
	v_mov_b32_e32 v100, v0
	v_mov_b32_e32 v101, v0
	v_mov_b32_e32 v102, v0
	v_mov_b32_e32 v103, v0
	v_mov_b32_e32 v112, v0
	v_mov_b32_e32 v113, v0
	v_mov_b32_e32 v114, v0
	v_mov_b32_e32 v115, v0
	v_mov_b32_e32 v116, v0
	v_mov_b32_e32 v117, v0
	v_mov_b32_e32 v118, v0
	v_mov_b32_e32 v119, v0
	v_mov_b32_e32 v72, v0
	v_mov_b32_e32 v73, v0
	v_mov_b32_e32 v74, v0
	v_mov_b32_e32 v75, v0
	v_mov_b32_e32 v76, v0
	v_mov_b32_e32 v77, v0
	v_mov_b32_e32 v78, v0
	v_mov_b32_e32 v79, v0
	v_mov_b32_e32 v88, v0
	v_mov_b32_e32 v89, v0
	v_mov_b32_e32 v90, v0
	v_mov_b32_e32 v91, v0
	v_mov_b32_e32 v92, v0
	v_mov_b32_e32 v93, v0
	v_mov_b32_e32 v94, v0
	v_mov_b32_e32 v95, v0
	v_mov_b32_e32 v104, v0
	v_mov_b32_e32 v105, v0
	v_mov_b32_e32 v106, v0
	v_mov_b32_e32 v107, v0
	v_mov_b32_e32 v108, v0
	v_mov_b32_e32 v109, v0
	v_mov_b32_e32 v110, v0
	v_mov_b32_e32 v111, v0
	v_mov_b32_e32 v120, v0
	v_mov_b32_e32 v121, v0
	v_mov_b32_e32 v122, v0
	v_mov_b32_e32 v123, v0
	v_mov_b32_e32 v124, v0
	v_mov_b32_e32 v125, v0
	v_mov_b32_e32 v126, v0
	v_mov_b32_e32 v127, v0
	ds_read_b128 v[128:131], v193
	ds_read_b128 v[132:135], v193 offset:1024
	ds_read_b128 v[136:139], v193 offset:2048
	ds_read_b128 v[140:143], v193 offset:3072
.LBB0_1853:
	s_add_u32 s30, s28, 0xfff80080
	s_addc_u32 s31, s29, -1
	s_cmp_eq_u32 s54, 28
	s_cselect_b32 s35, s19, s31
	s_cselect_b32 s34, s50, s30
	s_cselect_b32 s31, s17, s53
	s_cselect_b32 s30, s51, s52
	s_add_i32 m0, s25, 0xc000
	ds_read_b128 v[144:147], v194
	ds_read_b128 v[148:151], v194 offset:1024
	ds_read_b128 v[152:155], v194 offset:2048
	ds_read_b128 v[156:159], v194 offset:3072
	ds_read_b128 v[176:179], v194 offset:4096
	ds_read_b128 v[180:183], v194 offset:5120
	ds_read_b128 v[184:187], v194 offset:6144
	ds_read_b128 v[198:201], v194 offset:7168
	global_load_lds_dwordx4 v170, s[28:29]
	s_add_i32 m0, s25, 0xe000
	s_nop 0
	global_load_lds_dwordx4 v168, s[28:29]
	s_waitcnt lgkmcnt(8)
	s_barrier
	s_waitcnt lgkmcnt(0)
	s_setprio 1
	s_waitcnt lgkmcnt(0)
	v_mfma_f32_16x16x32_bf16 v[124:127], v[128:131], v[144:147], v[124:127]
	v_mfma_f32_16x16x32_bf16 v[120:123], v[136:139], v[144:147], v[120:123]
	v_mfma_f32_16x16x32_bf16 v[108:111], v[128:131], v[152:155], v[108:111]
	v_mfma_f32_16x16x32_bf16 v[104:107], v[136:139], v[152:155], v[104:107]
	v_mfma_f32_16x16x32_bf16 v[92:95], v[128:131], v[176:179], v[92:95]
	v_mfma_f32_16x16x32_bf16 v[88:91], v[136:139], v[176:179], v[88:91]
	v_mfma_f32_16x16x32_bf16 v[76:79], v[128:131], v[184:187], v[76:79]
	v_mfma_f32_16x16x32_bf16 v[72:75], v[136:139], v[184:187], v[72:75]
	v_mfma_f32_16x16x32_bf16 v[124:127], v[132:135], v[148:151], v[124:127]
	v_mfma_f32_16x16x32_bf16 v[120:123], v[140:143], v[148:151], v[120:123]
	v_mfma_f32_16x16x32_bf16 v[108:111], v[132:135], v[156:159], v[108:111]
	v_mfma_f32_16x16x32_bf16 v[104:107], v[140:143], v[156:159], v[104:107]
	v_mfma_f32_16x16x32_bf16 v[92:95], v[132:135], v[180:183], v[92:95]
	v_mfma_f32_16x16x32_bf16 v[88:91], v[140:143], v[180:183], v[88:91]
	v_mfma_f32_16x16x32_bf16 v[76:79], v[132:135], v[198:201], v[76:79]
	v_mfma_f32_16x16x32_bf16 v[72:75], v[140:143], v[198:201], v[72:75]
	s_setprio 0
	s_barrier
; #define PG8_STAGE(bufoff, gbase, voff) do { _Pragma("unroll") for (int _i = 0; _i < 2; ++_i) \
;         __builtin_amdgcn_global_load_lds((const unsigned*)((const char*)(gbase) + (voff)[_i]), (LAS unsigned*)(lds + (bufoff) + ldsw + _i * 8192), 16, 0, 0); } while (0)
; #define PG8_LDA(dst, b, h) do { _Pragma("unroll") for (int m = 0; m < 4; ++m) _Pragma("unroll") for (int k = 0; k < 2; ++k) dst[m][k] = *(const LAS bf16x8*)(lds + PG8_SA(b, h) + aoff + m * 2048 + k * 1024); } while (0)
; #define PG8_LDB(dst, b, h) do { _Pragma("unroll") for (int n = 0; n < 2; ++n) _Pragma("unroll") for (int k = 0; k < 2; ++k) dst[n][k] = *(const LAS bf16x8*)(lds + PG8_SB(b, h) + boff + n * 2048 + k * 1024); } while (0)
; #define PG8_MMA(ai, bj, At, Bt) do { __builtin_amdgcn_s_setprio(1); _Pragma("unroll") for (int m = 0; m < 4; ++m) _Pragma("unroll") for (int n = 0; n < 2; ++n) _Pragma("unroll") for (int k = 0; k < 2; ++k) \
;         acc[ai][bj][m][n] = __builtin_amdgcn_mfma_f32_16x16x32_bf16(Bt[n][k], At[m][k], acc[ai][bj][m][n], 0, 0, 0); __builtin_amdgcn_s_setprio(0); } while (0)
; #define PG8_WAIT_V(n) asm volatile("s_waitcnt vmcnt(" #n ")" ::: "memory")
; #define PG8_WAIT_L(n) asm volatile("s_waitcnt lgkmcnt(" #n ")" ::: "memory")
; #define PG8_BAR __builtin_amdgcn_s_barrier()
; #define PG8_SCHED __builtin_amdgcn_sched_barrier(0)
; template <class Epi>
; __device__ __forceinline__ void gemm_phase(LAS unsigned char* lds, const Gemm g, const StaticOrder& S, const Epi& E, int wv) {
;     ...
;             PG8_LDB(B1, 0, 1); PG8_STAGE(PG8_SB(0, 0), b2, voffB);
;             PG8_BAR; PG8_WAIT_L(0); PG8_MMA(0, 1, At, B1); PG8_BAR;
;             PG8_LDA(At, 0, 1); PG8_STAGE(PG8_SA(0, 0), a2, voffA);
;             PG8_BAR; PG8_WAIT_L(0); PG8_MMA(1, 0, At, B0); PG8_BAR; PG8_SCHED;
;             PG8_STAGE(PG8_SB(0, 1), b2 + hstepB, voffB);
;             PG8_WAIT_V(6); PG8_BAR; PG8_MMA(1, 1, At, B1); PG8_BAR;
;             PG8_LDB(B0, 1, 0); PG8_SCHED; PG8_LDA(At, 1, 0); PG8_STAGE(PG8_SA(0, 1), a2 + hstepA, voffA);
;             PG8_WAIT_L(8); PG8_BAR; PG8_WAIT_L(0); PG8_MMA(0, 0, At, B0); PG8_BAR; PG8_SCHED;
	s_add_i32 s55, s47, s40
	s_add_u32 s98, s30, s12
	s_addc_u32 s99, s31, s13
	s_mov_b32 m0, s55
	ds_read_b128 v[202:205], v195
	ds_read_b128 v[206:209], v195 offset:1024
	ds_read_b128 v[210:213], v195 offset:2048
	ds_read_b128 v[214:217], v195 offset:3072
	global_load_lds_dwordx4 v162, s[30:31]
	s_add_i32 m0, s55, 0x2000
	s_nop 0
	global_load_lds_dwordx4 v166, s[30:31]
	s_barrier
	s_waitcnt lgkmcnt(0)
	s_setprio 1
	s_waitcnt lgkmcnt(0)
	v_mfma_f32_16x16x32_bf16 v[116:119], v[202:205], v[144:147], v[116:119]
	v_mfma_f32_16x16x32_bf16 v[112:115], v[210:213], v[144:147], v[112:115]
	v_mfma_f32_16x16x32_bf16 v[100:103], v[202:205], v[152:155], v[100:103]
	v_mfma_f32_16x16x32_bf16 v[96:99], v[210:213], v[152:155], v[96:99]
	v_mfma_f32_16x16x32_bf16 v[84:87], v[202:205], v[176:179], v[84:87]
	v_mfma_f32_16x16x32_bf16 v[80:83], v[210:213], v[176:179], v[80:83]
	v_mfma_f32_16x16x32_bf16 v[68:71], v[202:205], v[184:187], v[68:71]
	v_mfma_f32_16x16x32_bf16 v[64:67], v[210:213], v[184:187], v[64:67]
	v_mfma_f32_16x16x32_bf16 v[116:119], v[206:209], v[148:151], v[116:119]
	v_mfma_f32_16x16x32_bf16 v[112:115], v[214:217], v[148:151], v[112:115]
	v_mfma_f32_16x16x32_bf16 v[100:103], v[206:209], v[156:159], v[100:103]
	v_mfma_f32_16x16x32_bf16 v[96:99], v[214:217], v[156:159], v[96:99]
	v_mfma_f32_16x16x32_bf16 v[84:87], v[206:209], v[180:183], v[84:87]
	v_mfma_f32_16x16x32_bf16 v[80:83], v[214:217], v[180:183], v[80:83]
	v_mfma_f32_16x16x32_bf16 v[68:71], v[206:209], v[198:201], v[68:71]
	v_mfma_f32_16x16x32_bf16 v[64:67], v[214:217], v[198:201], v[64:67]
	s_setprio 0
	s_mov_b32 m0, s25
	s_add_u32 s100, s34, s12
	s_addc_u32 s101, s35, s13
	s_barrier
	ds_read_b128 v[144:147], v194 offset:16384
	ds_read_b128 v[148:151], v194 offset:17408
	ds_read_b128 v[152:155], v194 offset:18432
	ds_read_b128 v[156:159], v194 offset:19456
	ds_read_b128 v[176:179], v194 offset:20480
	ds_read_b128 v[180:183], v194 offset:21504
	ds_read_b128 v[184:187], v194 offset:22528
	ds_read_b128 v[198:201], v194 offset:23552
	global_load_lds_dwordx4 v160, s[34:35]
	s_mov_b32 m0, s41
	s_nop 0
	global_load_lds_dwordx4 v164, s[34:35]
	s_waitcnt vmcnt(10)
	s_barrier
	s_waitcnt lgkmcnt(0)
	s_setprio 1
	s_waitcnt lgkmcnt(0)
	v_mfma_f32_16x16x32_bf16 v[60:63], v[128:131], v[144:147], v[60:63]
	v_mfma_f32_16x16x32_bf16 v[56:59], v[136:139], v[144:147], v[56:59]
	v_mfma_f32_16x16x32_bf16 v[44:47], v[128:131], v[152:155], v[44:47]
	v_mfma_f32_16x16x32_bf16 v[40:43], v[136:139], v[152:155], v[40:43]
	v_mfma_f32_16x16x32_bf16 v[28:31], v[128:131], v[176:179], v[28:31]
	v_mfma_f32_16x16x32_bf16 v[24:27], v[136:139], v[176:179], v[24:27]
	v_mfma_f32_16x16x32_bf16 v[12:15], v[128:131], v[184:187], v[12:15]
	v_mfma_f32_16x16x32_bf16 v[8:11], v[136:139], v[184:187], v[8:11]
	v_mfma_f32_16x16x32_bf16 v[60:63], v[132:135], v[148:151], v[60:63]
	v_mfma_f32_16x16x32_bf16 v[56:59], v[140:143], v[148:151], v[56:59]
	v_mfma_f32_16x16x32_bf16 v[44:47], v[132:135], v[156:159], v[44:47]
	v_mfma_f32_16x16x32_bf16 v[40:43], v[140:143], v[156:159], v[40:43]
	v_mfma_f32_16x16x32_bf16 v[28:31], v[132:135], v[180:183], v[28:31]
	v_mfma_f32_16x16x32_bf16 v[24:27], v[140:143], v[180:183], v[24:27]
	v_mfma_f32_16x16x32_bf16 v[12:15], v[132:135], v[198:201], v[12:15]
	v_mfma_f32_16x16x32_bf16 v[8:11], v[140:143], v[198:201], v[8:11]
	s_setprio 0
	s_barrier
	s_add_u32 s56, s30, 0x80000
	s_addc_u32 s57, s31, 0
	s_add_i32 s55, s48, s40
	s_mov_b32 m0, s55
	s_nop 0
	global_load_lds_dwordx4 v162, s[56:57]
	s_add_i32 m0, s55, 0x2000
	s_nop 0
	global_load_lds_dwordx4 v166, s[56:57]
	s_add_i32 s55, 0, 0x18000
	v_add_u32_e32 v140, s55, v191
	ds_read_b128 v[128:131], v140
	ds_read_b128 v[132:135], v140 offset:1024
	ds_read_b128 v[136:139], v140 offset:2048
	ds_read_b128 v[140:143], v140 offset:3072
	s_waitcnt vmcnt(6)
	s_barrier
	s_setprio 1
	v_mfma_f32_16x16x32_bf16 v[52:55], v[202:205], v[144:147], v[52:55]
	v_mfma_f32_16x16x32_bf16 v[48:51], v[210:213], v[144:147], v[48:51]
	v_mfma_f32_16x16x32_bf16 v[36:39], v[202:205], v[152:155], v[36:39]
	v_mfma_f32_16x16x32_bf16 v[32:35], v[210:213], v[152:155], v[32:35]
	v_mfma_f32_16x16x32_bf16 v[20:23], v[202:205], v[176:179], v[20:23]
	v_mfma_f32_16x16x32_bf16 v[16:19], v[210:213], v[176:179], v[16:19]
	v_mfma_f32_16x16x32_bf16 v[4:7], v[202:205], v[184:187], v[4:7]
	v_mfma_f32_16x16x32_bf16 v[0:3], v[210:213], v[184:187], v[0:3]
	v_mfma_f32_16x16x32_bf16 v[52:55], v[206:209], v[148:151], v[52:55]
	v_mfma_f32_16x16x32_bf16 v[48:51], v[214:217], v[148:151], v[48:51]
	v_mfma_f32_16x16x32_bf16 v[36:39], v[206:209], v[156:159], v[36:39]
	v_mfma_f32_16x16x32_bf16 v[32:35], v[214:217], v[156:159], v[32:35]
	v_mfma_f32_16x16x32_bf16 v[20:23], v[206:209], v[180:183], v[20:23]
	v_mfma_f32_16x16x32_bf16 v[16:19], v[214:217], v[180:183], v[16:19]
	v_mfma_f32_16x16x32_bf16 v[4:7], v[206:209], v[198:201], v[4:7]
	v_mfma_f32_16x16x32_bf16 v[0:3], v[214:217], v[198:201], v[0:3]
	s_setprio 0
	s_waitcnt lgkmcnt(0)
	s_barrier
	s_add_u32 s34, s34, 0x80000
	s_addc_u32 s35, s35, 0
	s_mov_b32 m0, s42
	ds_read_b128 v[144:147], v194 offset:32768
	ds_read_b128 v[148:151], v194 offset:33792
	ds_read_b128 v[152:155], v194 offset:34816
	ds_read_b128 v[156:159], v194 offset:35840
	ds_read_b128 v[176:179], v194 offset:36864
	ds_read_b128 v[180:183], v194 offset:37888
	ds_read_b128 v[184:187], v194 offset:38912
	ds_read_b128 v[198:201], v194 offset:39936
	global_load_lds_dwordx4 v160, s[34:35]
	s_mov_b32 m0, s43
	s_nop 0
	global_load_lds_dwordx4 v164, s[34:35]
	s_waitcnt lgkmcnt(8)
	s_barrier
; #define PG8_STAGE(bufoff, gbase, voff) do { _Pragma("unroll") for (int _i = 0; _i < 2; ++_i) \
;         __builtin_amdgcn_global_load_lds((const unsigned*)((const char*)(gbase) + (voff)[_i]), (LAS unsigned*)(lds + (bufoff) + ldsw + _i * 8192), 16, 0, 0); } while (0)
; #define PG8_LDA(dst, b, h) do { _Pragma("unroll") for (int m = 0; m < 4; ++m) _Pragma("unroll") for (int k = 0; k < 2; ++k) dst[m][k] = *(const LAS bf16x8*)(lds + PG8_SA(b, h) + aoff + m * 2048 + k * 1024); } while (0)
; #define PG8_LDB(dst, b, h) do { _Pragma("unroll") for (int n = 0; n < 2; ++n) _Pragma("unroll") for (int k = 0; k < 2; ++k) dst[n][k] = *(const LAS bf16x8*)(lds + PG8_SB(b, h) + boff + n * 2048 + k * 1024); } while (0)
; #define PG8_MMA(ai, bj, At, Bt) do { __builtin_amdgcn_s_setprio(1); _Pragma("unroll") for (int m = 0; m < 4; ++m) _Pragma("unroll") for (int n = 0; n < 2; ++n) _Pragma("unroll") for (int k = 0; k < 2; ++k) \
;         acc[ai][bj][m][n] = __builtin_amdgcn_mfma_f32_16x16x32_bf16(Bt[n][k], At[m][k], acc[ai][bj][m][n], 0, 0, 0); __builtin_amdgcn_s_setprio(0); } while (0)
; #define PG8_WAIT_V(n) asm volatile("s_waitcnt vmcnt(" #n ")" ::: "memory")
; #define PG8_WAIT_L(n) asm volatile("s_waitcnt lgkmcnt(" #n ")" ::: "memory")
; #define PG8_BAR __builtin_amdgcn_s_barrier()
; #define PG8_SCHED __builtin_amdgcn_sched_barrier(0)
; template <class Epi>
; __device__ __forceinline__ void gemm_phase(LAS unsigned char* lds, const Gemm g, const StaticOrder& S, const Epi& E, int wv) {
;     ...
;             PG8_WAIT_L(8); PG8_BAR; PG8_WAIT_L(0); PG8_MMA(0, 0, At, B0); PG8_BAR; PG8_SCHED;
;             PG8_LDB(B1, 1, 1); PG8_STAGE(PG8_SB(1, 0), b3, voffB);
;             PG8_BAR; PG8_WAIT_L(0); PG8_MMA(0, 1, At, B1); PG8_BAR;
;             PG8_LDA(At, 1, 1); PG8_STAGE(PG8_SA(1, 0), a3, voffA);
;             PG8_BAR; PG8_WAIT_L(0); PG8_MMA(1, 0, At, B0); PG8_BAR; PG8_SCHED;
;             PG8_STAGE(PG8_SB(1, 1), b3 + hstepB, voffB);
;             PG8_WAIT_V(6); PG8_BAR; PG8_MMA(1, 1, At, B1); PG8_BAR;
;         }
	s_waitcnt lgkmcnt(0)
	s_setprio 1
	s_waitcnt lgkmcnt(0)
	v_mfma_f32_16x16x32_bf16 v[124:127], v[128:131], v[144:147], v[124:127]
	v_mfma_f32_16x16x32_bf16 v[120:123], v[136:139], v[144:147], v[120:123]
	v_mfma_f32_16x16x32_bf16 v[108:111], v[128:131], v[152:155], v[108:111]
	v_mfma_f32_16x16x32_bf16 v[104:107], v[136:139], v[152:155], v[104:107]
	v_mfma_f32_16x16x32_bf16 v[92:95], v[128:131], v[176:179], v[92:95]
	v_mfma_f32_16x16x32_bf16 v[88:91], v[136:139], v[176:179], v[88:91]
	v_mfma_f32_16x16x32_bf16 v[76:79], v[128:131], v[184:187], v[76:79]
	v_mfma_f32_16x16x32_bf16 v[72:75], v[136:139], v[184:187], v[72:75]
	v_mfma_f32_16x16x32_bf16 v[124:127], v[132:135], v[148:151], v[124:127]
	v_mfma_f32_16x16x32_bf16 v[120:123], v[140:143], v[148:151], v[120:123]
	v_mfma_f32_16x16x32_bf16 v[108:111], v[132:135], v[156:159], v[108:111]
	v_mfma_f32_16x16x32_bf16 v[104:107], v[140:143], v[156:159], v[104:107]
	v_mfma_f32_16x16x32_bf16 v[92:95], v[132:135], v[180:183], v[92:95]
	v_mfma_f32_16x16x32_bf16 v[88:91], v[140:143], v[180:183], v[88:91]
	v_mfma_f32_16x16x32_bf16 v[76:79], v[132:135], v[198:201], v[76:79]
	v_mfma_f32_16x16x32_bf16 v[72:75], v[140:143], v[198:201], v[72:75]
	s_setprio 0
	s_barrier
	s_add_i32 s34, 0, 0x1c000
	s_add_i32 s35, s55, s40
	v_add_u32_e32 v197, s34, v191
	s_mov_b32 m0, s35
	ds_read_b128 v[202:205], v197
	ds_read_b128 v[206:209], v197 offset:1024
	ds_read_b128 v[210:213], v197 offset:2048
	ds_read_b128 v[214:217], v197 offset:3072
	global_load_lds_dwordx4 v162, s[98:99]
	s_add_i32 m0, s35, 0x2000
	s_nop 0
	global_load_lds_dwordx4 v166, s[98:99]
	s_barrier
	s_waitcnt lgkmcnt(0)
	s_setprio 1
	s_waitcnt lgkmcnt(0)
	v_mfma_f32_16x16x32_bf16 v[116:119], v[202:205], v[144:147], v[116:119]
	v_mfma_f32_16x16x32_bf16 v[112:115], v[210:213], v[144:147], v[112:115]
	v_mfma_f32_16x16x32_bf16 v[100:103], v[202:205], v[152:155], v[100:103]
	v_mfma_f32_16x16x32_bf16 v[96:99], v[210:213], v[152:155], v[96:99]
	v_mfma_f32_16x16x32_bf16 v[84:87], v[202:205], v[176:179], v[84:87]
	v_mfma_f32_16x16x32_bf16 v[80:83], v[210:213], v[176:179], v[80:83]
	v_mfma_f32_16x16x32_bf16 v[68:71], v[202:205], v[184:187], v[68:71]
	v_mfma_f32_16x16x32_bf16 v[64:67], v[210:213], v[184:187], v[64:67]
	v_mfma_f32_16x16x32_bf16 v[116:119], v[206:209], v[148:151], v[116:119]
	v_mfma_f32_16x16x32_bf16 v[112:115], v[214:217], v[148:151], v[112:115]
	v_mfma_f32_16x16x32_bf16 v[100:103], v[206:209], v[156:159], v[100:103]
	v_mfma_f32_16x16x32_bf16 v[96:99], v[214:217], v[156:159], v[96:99]
	v_mfma_f32_16x16x32_bf16 v[84:87], v[206:209], v[180:183], v[84:87]
	v_mfma_f32_16x16x32_bf16 v[80:83], v[214:217], v[180:183], v[80:83]
	v_mfma_f32_16x16x32_bf16 v[68:71], v[206:209], v[198:201], v[68:71]
	v_mfma_f32_16x16x32_bf16 v[64:67], v[214:217], v[198:201], v[64:67]
	s_setprio 0
	s_mov_b32 m0, s45
	s_barrier
	ds_read_b128 v[144:147], v194 offset:49152
	ds_read_b128 v[148:151], v194 offset:50176
	ds_read_b128 v[152:155], v194 offset:51200
	ds_read_b128 v[156:159], v194 offset:52224
	ds_read_b128 v[176:179], v194 offset:53248
	ds_read_b128 v[180:183], v194 offset:54272
	ds_read_b128 v[184:187], v194 offset:55296
	ds_read_b128 v[198:201], v194 offset:56320
	global_load_lds_dwordx4 v160, s[100:101]
	s_mov_b32 m0, s46
	s_nop 0
	global_load_lds_dwordx4 v164, s[100:101]
	s_waitcnt vmcnt(10)
	s_barrier
	s_waitcnt lgkmcnt(0)
	s_setprio 1
	s_waitcnt lgkmcnt(0)
	v_mfma_f32_16x16x32_bf16 v[60:63], v[128:131], v[144:147], v[60:63]
	v_mfma_f32_16x16x32_bf16 v[56:59], v[136:139], v[144:147], v[56:59]
	v_mfma_f32_16x16x32_bf16 v[44:47], v[128:131], v[152:155], v[44:47]
	v_mfma_f32_16x16x32_bf16 v[40:43], v[136:139], v[152:155], v[40:43]
	v_mfma_f32_16x16x32_bf16 v[28:31], v[128:131], v[176:179], v[28:31]
	v_mfma_f32_16x16x32_bf16 v[24:27], v[136:139], v[176:179], v[24:27]
	v_mfma_f32_16x16x32_bf16 v[12:15], v[128:131], v[184:187], v[12:15]
	v_mfma_f32_16x16x32_bf16 v[8:11], v[136:139], v[184:187], v[8:11]
	v_mfma_f32_16x16x32_bf16 v[60:63], v[132:135], v[148:151], v[60:63]
	v_mfma_f32_16x16x32_bf16 v[56:59], v[140:143], v[148:151], v[56:59]
	v_mfma_f32_16x16x32_bf16 v[44:47], v[132:135], v[156:159], v[44:47]
	v_mfma_f32_16x16x32_bf16 v[40:43], v[140:143], v[156:159], v[40:43]
	v_mfma_f32_16x16x32_bf16 v[28:31], v[132:135], v[180:183], v[28:31]
	v_mfma_f32_16x16x32_bf16 v[24:27], v[140:143], v[180:183], v[24:27]
	v_mfma_f32_16x16x32_bf16 v[12:15], v[132:135], v[198:201], v[12:15]
	v_mfma_f32_16x16x32_bf16 v[8:11], v[140:143], v[198:201], v[8:11]
	s_setprio 0
	s_barrier
	s_add_u32 s30, s30, 0x80080
	s_addc_u32 s31, s31, 0
	s_add_i32 s34, s34, s40
	s_mov_b32 m0, s34
	s_nop 0
	global_load_lds_dwordx4 v162, s[30:31]
	s_add_i32 m0, s34, 0x2000
	s_nop 0
	global_load_lds_dwordx4 v166, s[30:31]
	ds_read_b128 v[128:131], v193
	ds_read_b128 v[132:135], v193 offset:1024
	ds_read_b128 v[136:139], v193 offset:2048
	ds_read_b128 v[140:143], v193 offset:3072
	s_waitcnt vmcnt(6)
	s_barrier
	s_setprio 1
	v_mfma_f32_16x16x32_bf16 v[52:55], v[202:205], v[144:147], v[52:55]
	v_mfma_f32_16x16x32_bf16 v[48:51], v[210:213], v[144:147], v[48:51]
	v_mfma_f32_16x16x32_bf16 v[36:39], v[202:205], v[152:155], v[36:39]
	v_mfma_f32_16x16x32_bf16 v[32:35], v[210:213], v[152:155], v[32:35]
	v_mfma_f32_16x16x32_bf16 v[20:23], v[202:205], v[176:179], v[20:23]
	v_mfma_f32_16x16x32_bf16 v[16:19], v[210:213], v[176:179], v[16:19]
	v_mfma_f32_16x16x32_bf16 v[4:7], v[202:205], v[184:187], v[4:7]
	v_mfma_f32_16x16x32_bf16 v[0:3], v[210:213], v[184:187], v[0:3]
	v_mfma_f32_16x16x32_bf16 v[52:55], v[206:209], v[148:151], v[52:55]
	v_mfma_f32_16x16x32_bf16 v[48:51], v[214:217], v[148:151], v[48:51]
	v_mfma_f32_16x16x32_bf16 v[36:39], v[206:209], v[156:159], v[36:39]
	v_mfma_f32_16x16x32_bf16 v[32:35], v[214:217], v[156:159], v[32:35]
	v_mfma_f32_16x16x32_bf16 v[20:23], v[206:209], v[180:183], v[20:23]
	v_mfma_f32_16x16x32_bf16 v[16:19], v[214:217], v[180:183], v[16:19]
	v_mfma_f32_16x16x32_bf16 v[4:7], v[206:209], v[198:201], v[4:7]
	v_mfma_f32_16x16x32_bf16 v[0:3], v[214:217], v[198:201], v[0:3]
	s_setprio 0
	s_waitcnt lgkmcnt(0)
	s_add_i32 s54, s54, 2
	s_add_u32 s52, s52, 0x100
	s_addc_u32 s53, s53, 0
	s_add_u32 s28, s28, 0x100
	s_addc_u32 s29, s29, 0
	s_cmp_gt_u32 s54, 29
	s_barrier
; __device__ __forceinline__ float bf_lo(unsigned w) { return __uint_as_float(w << 16); }
; __device__ __forceinline__ float bf_hi(unsigned w) { return __uint_as_float(w & 0xffff0000u); }
; __device__ __forceinline__ float fast_sigmoid(float x) { return __builtin_amdgcn_rcpf(1.0f + __builtin_amdgcn_exp2f(-x * LOG2E)); }
; __device__ __forceinline__ float ss_fix(float raw) { return (float)__float_as_uint(raw) * (1.0f / 256.0f); }
;     __device__ __forceinline__ void operator()(const f32x4 (&acc)[2][2][4][2], const Unit& u, int wr, int wc, int fr, int fq) const {
;     ...
;         RES_LOAD(0, 0); RES_LOAD(1, 1);
; #pragma unroll
;         for (int it = 0; it < 8; ++it) { const int ai = it >> 2, m = it & 3, sc = it % RD;
;             if (it + RD - 1 < 8) RES_LOAD((it + RD - 1) % RD, it + RD - 1);
;             asm volatile("" ::: "memory");
;             const int row = row0 + ai * HALF + m * 16; const size_t ro = (size_t)row * DM + col0;
;             float rs = 1.0f; if (MODE == 1) rs = __builtin_amdgcn_rsqf(ss_fix(rsb[sc]) * (1.0f / DM) + EPS);
;             float sq = 0.f;
; #pragma unroll
;             for (int bj = 0; bj < 2; ++bj) { const size_t off = ro + bj * HALF;
;                 f32x4 v0 = acc[ai][bj][m][0], v1 = acc[ai][bj][m][1];
;                 if (MODE == 1) { const u32x4 pw = pbuf[sc][bj];
;                     v0[0] = fast_sigmoid(rs * v0[0]) * bf_lo(pw.x); v0[1] = fast_sigmoid(rs * v0[1]) * bf_hi(pw.x); v0[2] = fast_sigmoid(rs * v0[2]) * bf_lo(pw.y); v0[3] = fast_sigmoid(rs * v0[3]) * bf_hi(pw.y);
;                     v1[0] = fast_sigmoid(rs * v1[0]) * bf_lo(pw.z); v1[1] = fast_sigmoid(rs * v1[1]) * bf_hi(pw.z); v1[2] = fast_sigmoid(rs * v1[2]) * bf_lo(pw.w); v1[3] = fast_sigmoid(rs * v1[3]) * bf_hi(pw.w); }
;                 f32x4 h0, h1;
;                 if (IN16) { const u32x4 hw = hraw[sc][bj]; h0 = (f32x4){bf_lo(hw.x), bf_hi(hw.x), bf_lo(hw.y), bf_hi(hw.y)}; h1 = (f32x4){bf_lo(hw.z), bf_hi(hw.z), bf_lo(hw.w), bf_hi(hw.w)}; }
	s_cbranch_scc0 .LBB0_1853
	v_lshl_add_u32 v178, s24, 8, v190
	v_lshl_or_b32 v176, s49, 8, v192
	v_ashrrev_i32_e32 v179, 31, v178
	v_lshlrev_b64 v[128:129], 11, v[178:179]
	v_ashrrev_i32_e32 v177, 31, v176
	v_lshl_add_u64 v[186:187], v[128:129], 0, v[176:177]
	v_lshlrev_b64 v[128:129], 1, v[186:187]
	v_lshl_add_u64 v[180:181], v[178:179], 2, s[8:9]
	v_lshl_add_u64 v[130:131], s[10:11], 0, v[128:129]
	global_load_dword v184, v[180:181], off
	global_load_dwordx4 v[198:201], v[130:131], off
	v_or_b32_e32 v130, 32, v178
	v_ashrrev_i32_e32 v131, 31, v130
	v_lshl_add_u64 v[132:133], v[130:131], 2, s[8:9]
	global_load_dword v179, v[132:133], off
	v_or_b32_e32 v132, 16, v178
	v_ashrrev_i32_e32 v133, 31, v132
	v_lshlrev_b64 v[134:135], 11, v[132:133]
	v_lshl_add_u64 v[132:133], v[132:133], 2, s[8:9]
	global_load_dword v197, v[132:133], off
	v_lshl_add_u64 v[132:133], s[6:7], 0, v[128:129]
	global_load_dwordx4 v[202:205], v[132:133], off
	v_lshlrev_b64 v[130:131], 11, v[130:131]
	v_lshl_add_u64 v[188:189], v[134:135], 0, v[176:177]
	v_or_b32_e32 v128, 0x100, v128
	v_lshl_add_u64 v[182:183], v[130:131], 0, v[176:177]
	v_lshlrev_b64 v[130:131], 1, v[188:189]
	v_lshl_add_u64 v[134:135], s[6:7], 0, v[128:129]
	v_lshl_add_u64 v[128:129], s[10:11], 0, v[128:129]
	v_lshl_add_u64 v[136:137], s[6:7], 0, v[130:131]
	v_lshl_add_u64 v[138:139], s[10:11], 0, v[130:131]
	global_load_dwordx4 v[206:209], v[134:135], off
	global_load_dwordx4 v[210:213], v[128:129], off
	global_load_dwordx4 v[152:155], v[136:137], off
	global_load_dwordx4 v[156:159], v[138:139], off
	v_lshlrev_b64 v[132:133], 1, v[182:183]
	v_or_b32_e32 v130, 0x100, v130
	v_lshl_add_u64 v[140:141], s[6:7], 0, v[132:133]
	v_lshl_add_u64 v[142:143], s[10:11], 0, v[132:133]
	v_or_b32_e32 v132, 0x100, v132
	v_lshl_add_u64 v[128:129], s[6:7], 0, v[130:131]
	v_lshl_add_u64 v[130:131], s[10:11], 0, v[130:131]
	v_lshl_add_u64 v[134:135], s[6:7], 0, v[132:133]
	v_lshl_add_u64 v[132:133], s[10:11], 0, v[132:133]
	global_load_dwordx4 v[136:139], v[140:141], off
	s_nop 0
	global_load_dwordx4 v[140:143], v[142:143], off
	s_nop 0
	global_load_dwordx4 v[144:147], v[128:129], off
	global_load_dwordx4 v[148:151], v[130:131], off
	s_nop 0
	global_load_dwordx4 v[128:131], v[134:135], off
	s_nop 0
	global_load_dwordx4 v[132:135], v[132:133], off
	s_and_b64 vcc, exec, s[0:1]
	s_mov_b32 s49, s16
	s_mov_b32 s24, s18
	s_mov_b64 s[28:29], s[22:23]
	s_mov_b64 s[30:31], s[20:21]
	s_waitcnt vmcnt(0)
	v_cvt_f32_u32_e32 v214, v184
	v_lshlrev_b32_e32 v184, 16, v198
	v_and_b32_e32 v185, 0xffff0000, v198
	v_and_b32_e32 v215, 0xffff0000, v200
	v_mul_f32_e32 v214, 0x3b800000, v214
	v_fmamk_f32 v214, v214, 0x3a000000, v196
	v_rsq_f32_e32 v220, v214
	v_lshlrev_b32_e32 v214, 16, v200
	v_lshlrev_b32_e32 v200, 16, v201
	v_and_b32_e32 v201, 0xffff0000, v201
	v_mul_f32_e32 v124, v124, v220
	v_mul_f32_e32 v125, v125, v220
	v_mul_f32_e32 v126, v126, v220
	v_mul_f32_e32 v127, v127, v220
	v_mul_f32_e32 v120, v120, v220
	v_mul_f32_e32 v121, v121, v220
	v_mul_f32_e32 v122, v122, v220
	v_mul_f32_e32 v123, v123, v220
	v_mul_f32_e32 v124, 0xbfb8aa3b, v124
	v_mul_f32_e32 v125, 0xbfb8aa3b, v125
	v_mul_f32_e32 v126, 0xbfb8aa3b, v126
	v_mul_f32_e32 v127, 0xbfb8aa3b, v127
	v_mul_f32_e32 v120, 0xbfb8aa3b, v120
	v_mul_f32_e32 v121, 0xbfb8aa3b, v121
	v_mul_f32_e32 v122, 0xbfb8aa3b, v122
	v_mul_f32_e32 v123, 0xbfb8aa3b, v123
	v_exp_f32_e32 v124, v124
	v_exp_f32_e32 v125, v125
	v_exp_f32_e32 v126, v126
	v_exp_f32_e32 v127, v127
	v_exp_f32_e32 v120, v120
	v_exp_f32_e32 v121, v121
	v_exp_f32_e32 v122, v122
	v_exp_f32_e32 v123, v123
	v_mul_f32_e32 v112, v112, v220
	v_add_f32_e32 v124, 1.0, v124
	v_add_f32_e32 v125, 1.0, v125
	v_add_f32_e32 v126, 1.0, v126
	v_add_f32_e32 v127, 1.0, v127
	v_add_f32_e32 v216, 1.0, v120
	v_add_f32_e32 v217, 1.0, v121
	v_add_f32_e32 v218, 1.0, v122
	v_add_f32_e32 v219, 1.0, v123
	v_mul_f32_e32 v112, 0xbfb8aa3b, v112
	v_mul_f32_e32 v113, v113, v220
	v_rcp_f32_e32 v120, v124
	v_rcp_f32_e32 v121, v125
	v_rcp_f32_e32 v122, v126
	v_rcp_f32_e32 v123, v127
	v_rcp_f32_e32 v124, v216
	v_rcp_f32_e32 v125, v217
	v_rcp_f32_e32 v126, v218
	v_rcp_f32_e32 v127, v219
	v_exp_f32_e32 v112, v112
	v_mul_f32_e32 v113, 0xbfb8aa3b, v113
	v_exp_f32_e32 v113, v113
	v_lshlrev_b32_e32 v216, 16, v202
	v_and_b32_e32 v217, 0xffff0000, v202
	v_lshlrev_b32_e32 v218, 16, v204
	v_and_b32_e32 v219, 0xffff0000, v204
	v_lshlrev_b32_e32 v204, 16, v205
	v_and_b32_e32 v205, 0xffff0000, v205
	v_pk_fma_f32 v[120:121], v[120:121], v[184:185], v[216:217]
	v_pk_fma_f32 v[126:127], v[126:127], v[200:201], v[204:205]
	v_pk_fma_f32 v[124:125], v[124:125], v[214:215], v[218:219]
	v_lshl_add_u64 v[184:185], v[186:187], 2, s[4:5]
	v_add_f32_e32 v112, 1.0, v112
	global_store_dwordx4 v[184:185], v[124:127], off offset:16
	v_mul_f32_e32 v116, v116, v220
	v_mul_f32_e32 v117, v117, v220
	v_rcp_f32_e32 v124, v112
	v_add_f32_e32 v112, 1.0, v113
	v_rcp_f32_e32 v125, v112
	v_mul_f32_e32 v112, v114, v220
	v_mul_f32_e32 v118, v118, v220
	v_mul_f32_e32 v119, v119, v220
	v_mul_f32_e32 v112, 0xbfb8aa3b, v112
	v_mul_f32_e32 v113, v115, v220
	v_mul_f32_e32 v116, 0xbfb8aa3b, v116
	v_mul_f32_e32 v117, 0xbfb8aa3b, v117
	v_mul_f32_e32 v118, 0xbfb8aa3b, v118
	v_mul_f32_e32 v119, 0xbfb8aa3b, v119
	v_exp_f32_e32 v112, v112
	v_mul_f32_e32 v113, 0xbfb8aa3b, v113
	v_exp_f32_e32 v116, v116
	v_exp_f32_e32 v117, v117
	v_exp_f32_e32 v118, v118
	v_exp_f32_e32 v119, v119
	v_exp_f32_e32 v113, v113
	v_lshlrev_b32_e32 v198, 16, v199
	v_and_b32_e32 v199, 0xffff0000, v199
	v_lshlrev_b32_e32 v202, 16, v203
	v_and_b32_e32 v203, 0xffff0000, v203
	v_add_f32_e32 v112, 1.0, v112
	v_pk_fma_f32 v[122:123], v[122:123], v[198:199], v[202:203]
; __device__ __forceinline__ float bf_lo(unsigned w) { return __uint_as_float(w << 16); }
; __device__ __forceinline__ float bf_hi(unsigned w) { return __uint_as_float(w & 0xffff0000u); }
; __device__ __forceinline__ float fast_sigmoid(float x) { return __builtin_amdgcn_rcpf(1.0f + __builtin_amdgcn_exp2f(-x * LOG2E)); }
;     __device__ __forceinline__ void operator()(const f32x4 (&acc)[2][2][4][2], const Unit& u, int wr, int wc, int fr, int fq) const {
;     ...
;         for (int it = 0; it < 8; ++it) { const int ai = it >> 2, m = it & 3, sc = it % RD;
;             if (it + RD - 1 < 8) RES_LOAD((it + RD - 1) % RD, it + RD - 1);
;             asm volatile("" ::: "memory");
;             const int row = row0 + ai * HALF + m * 16; const size_t ro = (size_t)row * DM + col0;
;             float rs = 1.0f; if (MODE == 1) rs = __builtin_amdgcn_rsqf(ss_fix(rsb[sc]) * (1.0f / DM) + EPS);
;             float sq = 0.f;
; #pragma unroll
;             for (int bj = 0; bj < 2; ++bj) { const size_t off = ro + bj * HALF;
;                 f32x4 v0 = acc[ai][bj][m][0], v1 = acc[ai][bj][m][1];
;                 if (MODE == 1) { const u32x4 pw = pbuf[sc][bj];
;                     v0[0] = fast_sigmoid(rs * v0[0]) * bf_lo(pw.x); v0[1] = fast_sigmoid(rs * v0[1]) * bf_hi(pw.x); v0[2] = fast_sigmoid(rs * v0[2]) * bf_lo(pw.y); v0[3] = fast_sigmoid(rs * v0[3]) * bf_hi(pw.y);
;                     v1[0] = fast_sigmoid(rs * v1[0]) * bf_lo(pw.z); v1[1] = fast_sigmoid(rs * v1[1]) * bf_hi(pw.z); v1[2] = fast_sigmoid(rs * v1[2]) * bf_lo(pw.w); v1[3] = fast_sigmoid(rs * v1[3]) * bf_hi(pw.w); }
;                 f32x4 h0, h1;
;                 if (IN16) { const u32x4 hw = hraw[sc][bj]; h0 = (f32x4){bf_lo(hw.x), bf_hi(hw.x), bf_lo(hw.y), bf_hi(hw.y)}; h1 = (f32x4){bf_lo(hw.z), bf_hi(hw.z), bf_lo(hw.w), bf_hi(hw.w)}; }
;                 else { h0 = hbuf[sc][2 * bj]; h1 = hbuf[sc][2 * bj + 1]; }
;                 const f32x4 o0 = h0 + v0, o1 = h1 + v1;
;                 if (OUT32) { *(f32x4*)(hout + off) = o0; *(f32x4*)(hout + off + 4) = o1; }
;                 if (hb) { u32x4 w; w.x = pk_bf16(o0[0], o0[1]); w.y = pk_bf16(o0[2], o0[3]); w.z = pk_bf16(o1[0], o1[1]); w.w = pk_bf16(o1[2], o1[3]); *(u32x4*)(hb + off) = w; }
;                 sq += ((o0[0] * o0[0] + o0[1] * o0[1]) + (o0[2] * o0[2] + o0[3] * o0[3])) + ((o1[0] * o1[0] + o1[1] * o1[1]) + (o1[2] * o1[2] + o1[3] * o1[3])); }
	v_add_f32_e32 v116, 1.0, v116
	v_add_f32_e32 v117, 1.0, v117
	v_add_f32_e32 v118, 1.0, v118
	v_add_f32_e32 v119, 1.0, v119
	v_rcp_f32_e32 v198, v112
	v_add_f32_e32 v112, 1.0, v113
	v_rcp_f32_e32 v116, v116
	v_rcp_f32_e32 v117, v117
	v_rcp_f32_e32 v118, v118
	v_rcp_f32_e32 v119, v119
	v_rcp_f32_e32 v199, v112
	global_store_dwordx4 v[184:185], v[120:123], off
	v_lshlrev_b32_e32 v200, 16, v213
	v_and_b32_e32 v201, 0xffff0000, v213
	v_lshlrev_b32_e32 v120, 16, v210
	v_and_b32_e32 v121, 0xffff0000, v210
	v_lshlrev_b32_e32 v122, 16, v211
	v_and_b32_e32 v123, 0xffff0000, v211
	v_lshlrev_b32_e32 v112, 16, v206
	v_and_b32_e32 v113, 0xffff0000, v206
	v_lshlrev_b32_e32 v114, 16, v207
	v_and_b32_e32 v115, 0xffff0000, v207
	v_lshlrev_b32_e32 v204, 16, v209
	v_and_b32_e32 v205, 0xffff0000, v209
	v_lshlrev_b32_e32 v126, 16, v212
	v_and_b32_e32 v127, 0xffff0000, v212
	v_lshlrev_b32_e32 v202, 16, v208
	v_and_b32_e32 v203, 0xffff0000, v208
	v_pk_fma_f32 v[114:115], v[118:119], v[122:123], v[114:115]
	v_pk_fma_f32 v[112:113], v[116:117], v[120:121], v[112:113]
	v_pk_fma_f32 v[118:119], v[198:199], v[200:201], v[204:205]
	v_pk_fma_f32 v[116:117], v[124:125], v[126:127], v[202:203]
	global_store_dwordx4 v[184:185], v[112:115], off offset:512
	global_store_dwordx4 v[184:185], v[116:119], off offset:528
	v_or_b32_e32 v198, 48, v178
	v_ashrrev_i32_e32 v199, 31, v198
	v_cvt_f32_u32_e32 v118, v197
	v_lshlrev_b64 v[112:113], 11, v[198:199]
	v_lshl_add_u64 v[198:199], v[198:199], 2, s[8:9]
	v_mul_f32_e32 v118, 0x3b800000, v118
	v_fmamk_f32 v118, v118, 0x3a000000, v196
	v_rsq_f32_e32 v197, v118
	global_load_dword v206, v[198:199], off
	v_lshl_add_u64 v[184:185], v[112:113], 0, v[176:177]
	v_lshlrev_b64 v[116:117], 1, v[184:185]
	v_mul_f32_e32 v104, v104, v197
	v_mul_f32_e32 v104, 0xbfb8aa3b, v104
	v_mul_f32_e32 v105, v105, v197
	v_exp_f32_e32 v104, v104
	v_mul_f32_e32 v105, 0xbfb8aa3b, v105
	v_exp_f32_e32 v105, v105
	v_mul_f32_e32 v108, v108, v197
	v_add_f32_e32 v104, 1.0, v104
	v_rcp_f32_e32 v200, v104
	v_add_f32_e32 v104, 1.0, v105
	v_rcp_f32_e32 v201, v104
	v_mul_f32_e32 v104, v106, v197
	v_mul_f32_e32 v109, v109, v197
	v_mul_f32_e32 v110, v110, v197
	v_mul_f32_e32 v111, v111, v197
	v_mul_f32_e32 v104, 0xbfb8aa3b, v104
	v_mul_f32_e32 v105, v107, v197
	v_mul_f32_e32 v108, 0xbfb8aa3b, v108
	v_mul_f32_e32 v109, 0xbfb8aa3b, v109
	v_mul_f32_e32 v110, 0xbfb8aa3b, v110
	v_mul_f32_e32 v111, 0xbfb8aa3b, v111
	v_exp_f32_e32 v104, v104
	v_mul_f32_e32 v105, 0xbfb8aa3b, v105
	v_exp_f32_e32 v108, v108
	v_exp_f32_e32 v109, v109
	v_exp_f32_e32 v110, v110
	v_exp_f32_e32 v111, v111
	v_exp_f32_e32 v105, v105
	v_add_f32_e32 v104, 1.0, v104
	v_mul_f32_e32 v96, v96, v197
	v_add_f32_e32 v108, 1.0, v108
	v_add_f32_e32 v109, 1.0, v109
	v_add_f32_e32 v110, 1.0, v110
	v_add_f32_e32 v111, 1.0, v111
	v_rcp_f32_e32 v204, v104
	v_add_f32_e32 v104, 1.0, v105
	v_mul_f32_e32 v96, 0xbfb8aa3b, v96
	v_mul_f32_e32 v97, v97, v197
	v_rcp_f32_e32 v108, v108
	v_rcp_f32_e32 v109, v109
	v_rcp_f32_e32 v110, v110
	v_rcp_f32_e32 v111, v111
	v_rcp_f32_e32 v205, v104
	v_exp_f32_e32 v96, v96
	v_mul_f32_e32 v97, 0xbfb8aa3b, v97
	v_exp_f32_e32 v97, v97
	v_lshl_add_u64 v[112:113], s[6:7], 0, v[116:117]
	global_load_dwordx4 v[120:123], v[112:113], off
	v_lshl_add_u64 v[112:113], s[10:11], 0, v[116:117]
	v_or_b32_e32 v116, 0x100, v116
	v_lshlrev_b32_e32 v198, 16, v156
	v_and_b32_e32 v199, 0xffff0000, v156
	v_lshlrev_b32_e32 v156, 16, v157
	v_and_b32_e32 v157, 0xffff0000, v157
	v_lshlrev_b32_e32 v202, 16, v158
	v_and_b32_e32 v203, 0xffff0000, v158
	v_lshlrev_b32_e32 v158, 16, v159
	v_and_b32_e32 v159, 0xffff0000, v159
	v_lshlrev_b32_e32 v104, 16, v152
	v_and_b32_e32 v105, 0xffff0000, v152
	v_lshlrev_b32_e32 v106, 16, v153
	v_and_b32_e32 v107, 0xffff0000, v153
	v_lshlrev_b32_e32 v152, 16, v154
	v_and_b32_e32 v153, 0xffff0000, v154
	v_lshlrev_b32_e32 v154, 16, v155
	v_and_b32_e32 v155, 0xffff0000, v155
	global_load_dwordx4 v[124:127], v[112:113], off
	v_lshl_add_u64 v[112:113], s[6:7], 0, v[116:117]
	v_lshl_add_u64 v[116:117], s[10:11], 0, v[116:117]
	v_pk_fma_f32 v[106:107], v[110:111], v[156:157], v[106:107]
	v_pk_fma_f32 v[104:105], v[108:109], v[198:199], v[104:105]
	v_pk_fma_f32 v[110:111], v[204:205], v[158:159], v[154:155]
	v_pk_fma_f32 v[108:109], v[200:201], v[202:203], v[152:153]
	v_lshl_add_u64 v[152:153], v[188:189], 2, s[4:5]
	v_add_f32_e32 v96, 1.0, v96
	global_load_dwordx4 v[112:115], v[112:113], off
	v_mul_f32_e32 v100, v100, v197
	global_load_dwordx4 v[116:119], v[116:117], off
	global_store_dwordx4 v[152:153], v[108:111], off offset:16
	v_mul_f32_e32 v101, v101, v197
	v_mul_f32_e32 v102, v102, v197
	v_rcp_f32_e32 v108, v96
	v_add_f32_e32 v96, 1.0, v97
	v_rcp_f32_e32 v109, v96
	v_mul_f32_e32 v96, v98, v197
	v_mul_f32_e32 v103, v103, v197
	v_mul_f32_e32 v96, 0xbfb8aa3b, v96
	v_mul_f32_e32 v97, v99, v197
	v_mul_f32_e32 v100, 0xbfb8aa3b, v100
	v_mul_f32_e32 v101, 0xbfb8aa3b, v101
	v_mul_f32_e32 v102, 0xbfb8aa3b, v102
	v_mul_f32_e32 v103, 0xbfb8aa3b, v103
	v_exp_f32_e32 v96, v96
	v_mul_f32_e32 v97, 0xbfb8aa3b, v97
	v_exp_f32_e32 v100, v100
	v_exp_f32_e32 v101, v101
	v_exp_f32_e32 v102, v102
	v_exp_f32_e32 v103, v103
	v_exp_f32_e32 v97, v97
	v_add_f32_e32 v96, 1.0, v96
	global_store_dwordx4 v[152:153], v[104:107], off
	v_add_f32_e32 v100, 1.0, v100
	v_add_f32_e32 v101, 1.0, v101
	v_lshlrev_b32_e32 v104, 16, v148
	v_and_b32_e32 v105, 0xffff0000, v148
	v_add_f32_e32 v102, 1.0, v102
	v_add_f32_e32 v103, 1.0, v103
	v_rcp_f32_e32 v148, v96
	v_add_f32_e32 v96, 1.0, v97
	v_rcp_f32_e32 v100, v100
	v_rcp_f32_e32 v101, v101
	v_rcp_f32_e32 v102, v102
	v_rcp_f32_e32 v103, v103
	v_lshlrev_b32_e32 v106, 16, v149
; __device__ __forceinline__ float bf_lo(unsigned w) { return __uint_as_float(w << 16); }
; __device__ __forceinline__ float bf_hi(unsigned w) { return __uint_as_float(w & 0xffff0000u); }
; __device__ __forceinline__ float fast_sigmoid(float x) { return __builtin_amdgcn_rcpf(1.0f + __builtin_amdgcn_exp2f(-x * LOG2E)); }
;     __device__ __forceinline__ void operator()(const f32x4 (&acc)[2][2][4][2], const Unit& u, int wr, int wc, int fr, int fq) const {
;     ...
;         for (int it = 0; it < 8; ++it) { const int ai = it >> 2, m = it & 3, sc = it % RD;
;             if (it + RD - 1 < 8) RES_LOAD((it + RD - 1) % RD, it + RD - 1);
;             asm volatile("" ::: "memory");
;             const int row = row0 + ai * HALF + m * 16; const size_t ro = (size_t)row * DM + col0;
;             float rs = 1.0f; if (MODE == 1) rs = __builtin_amdgcn_rsqf(ss_fix(rsb[sc]) * (1.0f / DM) + EPS);
;             float sq = 0.f;
; #pragma unroll
;             for (int bj = 0; bj < 2; ++bj) { const size_t off = ro + bj * HALF;
;                 f32x4 v0 = acc[ai][bj][m][0], v1 = acc[ai][bj][m][1];
;                 if (MODE == 1) { const u32x4 pw = pbuf[sc][bj];
;                     v0[0] = fast_sigmoid(rs * v0[0]) * bf_lo(pw.x); v0[1] = fast_sigmoid(rs * v0[1]) * bf_hi(pw.x); v0[2] = fast_sigmoid(rs * v0[2]) * bf_lo(pw.y); v0[3] = fast_sigmoid(rs * v0[3]) * bf_hi(pw.y);
;                     v1[0] = fast_sigmoid(rs * v1[0]) * bf_lo(pw.z); v1[1] = fast_sigmoid(rs * v1[1]) * bf_hi(pw.z); v1[2] = fast_sigmoid(rs * v1[2]) * bf_lo(pw.w); v1[3] = fast_sigmoid(rs * v1[3]) * bf_hi(pw.w); }
;                 f32x4 h0, h1;
;                 if (IN16) { const u32x4 hw = hraw[sc][bj]; h0 = (f32x4){bf_lo(hw.x), bf_hi(hw.x), bf_lo(hw.y), bf_hi(hw.y)}; h1 = (f32x4){bf_lo(hw.z), bf_hi(hw.z), bf_lo(hw.w), bf_hi(hw.w)}; }
;                 else { h0 = hbuf[sc][2 * bj]; h1 = hbuf[sc][2 * bj + 1]; }
;                 const f32x4 o0 = h0 + v0, o1 = h1 + v1;
;                 if (OUT32) { *(f32x4*)(hout + off) = o0; *(f32x4*)(hout + off + 4) = o1; }
;                 if (hb) { u32x4 w; w.x = pk_bf16(o0[0], o0[1]); w.y = pk_bf16(o0[2], o0[3]); w.z = pk_bf16(o1[0], o1[1]); w.w = pk_bf16(o1[2], o1[3]); *(u32x4*)(hb + off) = w; }
;                 sq += ((o0[0] * o0[0] + o0[1] * o0[1]) + (o0[2] * o0[2] + o0[3] * o0[3])) + ((o1[0] * o1[0] + o1[1] * o1[1]) + (o1[2] * o1[2] + o1[3] * o1[3])); }
	v_and_b32_e32 v107, 0xffff0000, v149
	v_rcp_f32_e32 v149, v96
	v_lshlrev_b32_e32 v110, 16, v150
	v_and_b32_e32 v111, 0xffff0000, v150
	v_lshlrev_b32_e32 v150, 16, v151
	v_and_b32_e32 v151, 0xffff0000, v151
	v_lshlrev_b32_e32 v96, 16, v144
	v_and_b32_e32 v97, 0xffff0000, v144
	v_lshlrev_b32_e32 v98, 16, v145
	v_and_b32_e32 v99, 0xffff0000, v145
	v_lshlrev_b32_e32 v144, 16, v146
	v_and_b32_e32 v145, 0xffff0000, v146
	v_lshlrev_b32_e32 v146, 16, v147
	v_and_b32_e32 v147, 0xffff0000, v147
	v_pk_fma_f32 v[98:99], v[102:103], v[106:107], v[98:99]
	v_pk_fma_f32 v[96:97], v[100:101], v[104:105], v[96:97]
	v_pk_fma_f32 v[102:103], v[148:149], v[150:151], v[146:147]
	v_pk_fma_f32 v[100:101], v[108:109], v[110:111], v[144:145]
	global_store_dwordx4 v[152:153], v[96:99], off offset:512
	global_store_dwordx4 v[152:153], v[100:103], off offset:528
	v_lshl_add_u64 v[144:145], v[186:187], 0, s[14:15]
	v_lshlrev_b32_e32 v146, 16, v140
	v_cvt_f32_u32_e32 v102, v179
	v_lshlrev_b64 v[100:101], 1, v[144:145]
	v_lshl_add_u64 v[96:97], s[6:7], 0, v[100:101]
	global_load_dwordx4 v[104:107], v[96:97], off
	v_mul_f32_e32 v102, 0x3b800000, v102
	v_fmamk_f32 v102, v102, 0x3a000000, v196
	v_rsq_f32_e32 v154, v102
	v_lshl_add_u64 v[96:97], s[10:11], 0, v[100:101]
	v_or_b32_e32 v100, 0x100, v100
	global_load_dwordx4 v[108:111], v[96:97], off
	v_lshl_add_u64 v[96:97], s[6:7], 0, v[100:101]
	v_lshl_add_u64 v[100:101], s[10:11], 0, v[100:101]
	global_load_dwordx4 v[96:99], v[96:97], off
	s_nop 0
	global_load_dwordx4 v[100:103], v[100:101], off
	s_nop 0
	global_load_dword v155, v[180:181], off offset:512
	v_mul_f32_e32 v88, v88, v154
	v_mul_f32_e32 v88, 0xbfb8aa3b, v88
	v_mul_f32_e32 v89, v89, v154
	v_exp_f32_e32 v88, v88
	v_mul_f32_e32 v89, 0xbfb8aa3b, v89
	v_exp_f32_e32 v89, v89
	v_mul_f32_e32 v92, v92, v154
	v_add_f32_e32 v88, 1.0, v88
	v_rcp_f32_e32 v148, v88
	v_add_f32_e32 v88, 1.0, v89
	v_rcp_f32_e32 v149, v88
	v_mul_f32_e32 v88, v90, v154
	v_mul_f32_e32 v93, v93, v154
	v_mul_f32_e32 v94, v94, v154
	v_mul_f32_e32 v95, v95, v154
	v_mul_f32_e32 v88, 0xbfb8aa3b, v88
	v_mul_f32_e32 v89, v91, v154
	v_mul_f32_e32 v92, 0xbfb8aa3b, v92
	v_mul_f32_e32 v93, 0xbfb8aa3b, v93
	v_mul_f32_e32 v94, 0xbfb8aa3b, v94
	v_mul_f32_e32 v95, 0xbfb8aa3b, v95
	v_exp_f32_e32 v88, v88
	v_mul_f32_e32 v89, 0xbfb8aa3b, v89
	v_exp_f32_e32 v92, v92
	v_exp_f32_e32 v93, v93
	v_exp_f32_e32 v94, v94
	v_exp_f32_e32 v95, v95
	v_exp_f32_e32 v89, v89
	v_add_f32_e32 v88, 1.0, v88
	v_mul_f32_e32 v80, v80, v154
	v_add_f32_e32 v92, 1.0, v92
	v_add_f32_e32 v93, 1.0, v93
	v_add_f32_e32 v94, 1.0, v94
	v_add_f32_e32 v95, 1.0, v95
	v_rcp_f32_e32 v152, v88
	v_add_f32_e32 v88, 1.0, v89
	v_mul_f32_e32 v80, 0xbfb8aa3b, v80
	v_mul_f32_e32 v81, v81, v154
	v_rcp_f32_e32 v92, v92
	v_rcp_f32_e32 v93, v93
	v_rcp_f32_e32 v94, v94
	v_rcp_f32_e32 v95, v95
	v_rcp_f32_e32 v153, v88
	v_exp_f32_e32 v80, v80
	v_mul_f32_e32 v81, 0xbfb8aa3b, v81
	v_exp_f32_e32 v81, v81
	v_and_b32_e32 v147, 0xffff0000, v140
	v_lshlrev_b32_e32 v140, 16, v141
	v_and_b32_e32 v141, 0xffff0000, v141
	v_lshlrev_b32_e32 v150, 16, v142
	v_and_b32_e32 v151, 0xffff0000, v142
	v_lshlrev_b32_e32 v142, 16, v143
	v_and_b32_e32 v143, 0xffff0000, v143
	v_lshlrev_b32_e32 v88, 16, v136
	v_and_b32_e32 v89, 0xffff0000, v136
	v_lshlrev_b32_e32 v90, 16, v137
	v_and_b32_e32 v91, 0xffff0000, v137
	v_lshlrev_b32_e32 v136, 16, v138
	v_and_b32_e32 v137, 0xffff0000, v138
	v_lshlrev_b32_e32 v138, 16, v139
	v_and_b32_e32 v139, 0xffff0000, v139
	v_pk_fma_f32 v[90:91], v[94:95], v[140:141], v[90:91]
	v_pk_fma_f32 v[88:89], v[92:93], v[146:147], v[88:89]
	v_pk_fma_f32 v[94:95], v[152:153], v[142:143], v[138:139]
	v_pk_fma_f32 v[92:93], v[148:149], v[150:151], v[136:137]
	v_lshl_add_u64 v[136:137], v[182:183], 2, s[4:5]
	v_add_f32_e32 v80, 1.0, v80
	global_store_dwordx4 v[136:137], v[92:95], off offset:16
	v_mul_f32_e32 v84, v84, v154
	v_mul_f32_e32 v85, v85, v154
	v_rcp_f32_e32 v92, v80
	v_add_f32_e32 v80, 1.0, v81
	v_rcp_f32_e32 v93, v80
	v_mul_f32_e32 v80, v82, v154
	v_mul_f32_e32 v86, v86, v154
	v_mul_f32_e32 v87, v87, v154
	v_mul_f32_e32 v80, 0xbfb8aa3b, v80
	v_mul_f32_e32 v81, v83, v154
	v_mul_f32_e32 v84, 0xbfb8aa3b, v84
	v_mul_f32_e32 v85, 0xbfb8aa3b, v85
	v_mul_f32_e32 v86, 0xbfb8aa3b, v86
	v_mul_f32_e32 v87, 0xbfb8aa3b, v87
	v_exp_f32_e32 v80, v80
	v_mul_f32_e32 v81, 0xbfb8aa3b, v81
	v_exp_f32_e32 v84, v84
	v_exp_f32_e32 v85, v85
	v_exp_f32_e32 v86, v86
	v_exp_f32_e32 v87, v87
	v_exp_f32_e32 v81, v81
	v_add_f32_e32 v80, 1.0, v80
	global_store_dwordx4 v[136:137], v[88:91], off
	v_add_f32_e32 v84, 1.0, v84
	v_add_f32_e32 v85, 1.0, v85
	v_lshlrev_b32_e32 v88, 16, v132
	v_and_b32_e32 v89, 0xffff0000, v132
	v_add_f32_e32 v86, 1.0, v86
	v_add_f32_e32 v87, 1.0, v87
	v_rcp_f32_e32 v132, v80
	v_add_f32_e32 v80, 1.0, v81
	v_rcp_f32_e32 v84, v84
	v_rcp_f32_e32 v85, v85
	v_rcp_f32_e32 v86, v86
	v_rcp_f32_e32 v87, v87
	v_lshlrev_b32_e32 v90, 16, v133
	v_and_b32_e32 v91, 0xffff0000, v133
	v_rcp_f32_e32 v133, v80
	v_lshlrev_b32_e32 v94, 16, v134
	v_and_b32_e32 v95, 0xffff0000, v134
	v_lshlrev_b32_e32 v134, 16, v135
	v_and_b32_e32 v135, 0xffff0000, v135
	v_lshlrev_b32_e32 v80, 16, v128
	v_and_b32_e32 v81, 0xffff0000, v128
	v_lshlrev_b32_e32 v82, 16, v129
	v_and_b32_e32 v83, 0xffff0000, v129
	v_lshlrev_b32_e32 v128, 16, v130
	v_and_b32_e32 v129, 0xffff0000, v130
	v_lshlrev_b32_e32 v130, 16, v131
	v_and_b32_e32 v131, 0xffff0000, v131
	v_pk_fma_f32 v[82:83], v[86:87], v[90:91], v[82:83]
	v_pk_fma_f32 v[80:81], v[84:85], v[88:89], v[80:81]
	v_pk_fma_f32 v[86:87], v[132:133], v[134:135], v[130:131]
	v_pk_fma_f32 v[84:85], v[92:93], v[94:95], v[128:129]
	global_store_dwordx4 v[136:137], v[80:83], off offset:512
	global_store_dwordx4 v[136:137], v[84:87], off offset:528
	v_add_u32_e32 v128, 0x90, v178
	v_ashrrev_i32_e32 v129, 31, v128
	s_waitcnt vmcnt(0)
; __device__ __forceinline__ float bf_lo(unsigned w) { return __uint_as_float(w << 16); }
; __device__ __forceinline__ float bf_hi(unsigned w) { return __uint_as_float(w & 0xffff0000u); }
; __device__ __forceinline__ float fast_sigmoid(float x) { return __builtin_amdgcn_rcpf(1.0f + __builtin_amdgcn_exp2f(-x * LOG2E)); }
;     __device__ __forceinline__ void operator()(const f32x4 (&acc)[2][2][4][2], const Unit& u, int wr, int wc, int fr, int fq) const {
;     ...
;         for (int it = 0; it < 8; ++it) { const int ai = it >> 2, m = it & 3, sc = it % RD;
;             if (it + RD - 1 < 8) RES_LOAD((it + RD - 1) % RD, it + RD - 1);
;             asm volatile("" ::: "memory");
;             const int row = row0 + ai * HALF + m * 16; const size_t ro = (size_t)row * DM + col0;
;             float rs = 1.0f; if (MODE == 1) rs = __builtin_amdgcn_rsqf(ss_fix(rsb[sc]) * (1.0f / DM) + EPS);
;             float sq = 0.f;
; #pragma unroll
;             for (int bj = 0; bj < 2; ++bj) { const size_t off = ro + bj * HALF;
;                 f32x4 v0 = acc[ai][bj][m][0], v1 = acc[ai][bj][m][1];
;                 if (MODE == 1) { const u32x4 pw = pbuf[sc][bj];
;                     v0[0] = fast_sigmoid(rs * v0[0]) * bf_lo(pw.x); v0[1] = fast_sigmoid(rs * v0[1]) * bf_hi(pw.x); v0[2] = fast_sigmoid(rs * v0[2]) * bf_lo(pw.y); v0[3] = fast_sigmoid(rs * v0[3]) * bf_hi(pw.y);
;                     v1[0] = fast_sigmoid(rs * v1[0]) * bf_lo(pw.z); v1[1] = fast_sigmoid(rs * v1[1]) * bf_hi(pw.z); v1[2] = fast_sigmoid(rs * v1[2]) * bf_lo(pw.w); v1[3] = fast_sigmoid(rs * v1[3]) * bf_hi(pw.w); }
;                 f32x4 h0, h1;
;                 if (IN16) { const u32x4 hw = hraw[sc][bj]; h0 = (f32x4){bf_lo(hw.x), bf_hi(hw.x), bf_lo(hw.y), bf_hi(hw.y)}; h1 = (f32x4){bf_lo(hw.z), bf_hi(hw.z), bf_lo(hw.w), bf_hi(hw.w)}; }
;                 else { h0 = hbuf[sc][2 * bj]; h1 = hbuf[sc][2 * bj + 1]; }
;                 const f32x4 o0 = h0 + v0, o1 = h1 + v1;
;                 if (OUT32) { *(f32x4*)(hout + off) = o0; *(f32x4*)(hout + off + 4) = o1; }
;                 if (hb) { u32x4 w; w.x = pk_bf16(o0[0], o0[1]); w.y = pk_bf16(o0[2], o0[3]); w.z = pk_bf16(o1[0], o1[1]); w.w = pk_bf16(o1[2], o1[3]); *(u32x4*)(hb + off) = w; }
;                 sq += ((o0[0] * o0[0] + o0[1] * o0[1]) + (o0[2] * o0[2] + o0[3] * o0[3])) + ((o1[0] * o1[0] + o1[1] * o1[1]) + (o1[2] * o1[2] + o1[3] * o1[3])); }
	v_cvt_f32_u32_e32 v86, v206
	v_lshlrev_b64 v[80:81], 11, v[128:129]
	v_lshl_add_u64 v[80:81], v[80:81], 0, v[176:177]
	v_lshlrev_b64 v[84:85], 1, v[80:81]
	v_mul_f32_e32 v86, 0x3b800000, v86
	v_fmamk_f32 v86, v86, 0x3a000000, v196
	v_rsq_f32_e32 v138, v86
	v_lshl_add_u64 v[80:81], s[6:7], 0, v[84:85]
	global_load_dwordx4 v[88:91], v[80:81], off
	v_mul_f32_e32 v72, v72, v138
	v_mul_f32_e32 v72, 0xbfb8aa3b, v72
	v_mul_f32_e32 v73, v73, v138
	v_exp_f32_e32 v72, v72
	v_mul_f32_e32 v73, 0xbfb8aa3b, v73
	v_exp_f32_e32 v73, v73
	v_lshl_add_u64 v[80:81], s[10:11], 0, v[84:85]
	v_or_b32_e32 v84, 0x100, v84
	global_load_dwordx4 v[92:95], v[80:81], off
	v_lshl_add_u64 v[80:81], s[6:7], 0, v[84:85]
	v_lshl_add_u64 v[84:85], s[10:11], 0, v[84:85]
	v_add_f32_e32 v72, 1.0, v72
	global_load_dwordx4 v[80:83], v[80:81], off
	s_nop 0
	global_load_dwordx4 v[84:87], v[84:85], off
	s_nop 0
	global_load_dword v139, v[180:181], off offset:576
	v_rcp_f32_e32 v132, v72
	v_add_f32_e32 v72, 1.0, v73
	v_rcp_f32_e32 v133, v72
	v_mul_f32_e32 v72, v74, v138
	v_mul_f32_e32 v76, v76, v138
	v_mul_f32_e32 v77, v77, v138
	v_mul_f32_e32 v78, v78, v138
	v_mul_f32_e32 v79, v79, v138
	v_mul_f32_e32 v72, 0xbfb8aa3b, v72
	v_mul_f32_e32 v73, v75, v138
	v_mul_f32_e32 v76, 0xbfb8aa3b, v76
	v_mul_f32_e32 v77, 0xbfb8aa3b, v77
	v_mul_f32_e32 v78, 0xbfb8aa3b, v78
	v_mul_f32_e32 v79, 0xbfb8aa3b, v79
	v_exp_f32_e32 v72, v72
	v_mul_f32_e32 v73, 0xbfb8aa3b, v73
	v_exp_f32_e32 v76, v76
	v_exp_f32_e32 v77, v77
	v_exp_f32_e32 v78, v78
	v_exp_f32_e32 v79, v79
	v_exp_f32_e32 v73, v73
	v_add_f32_e32 v72, 1.0, v72
	v_mul_f32_e32 v64, v64, v138
	v_add_f32_e32 v76, 1.0, v76
	v_add_f32_e32 v77, 1.0, v77
	v_add_f32_e32 v78, 1.0, v78
	v_add_f32_e32 v79, 1.0, v79
	v_rcp_f32_e32 v136, v72
	v_add_f32_e32 v72, 1.0, v73
	v_mul_f32_e32 v64, 0xbfb8aa3b, v64
	v_mul_f32_e32 v65, v65, v138
	v_rcp_f32_e32 v76, v76
	v_rcp_f32_e32 v77, v77
	v_rcp_f32_e32 v78, v78
	v_rcp_f32_e32 v79, v79
	v_rcp_f32_e32 v137, v72
	v_exp_f32_e32 v64, v64
	v_mul_f32_e32 v65, 0xbfb8aa3b, v65
	v_exp_f32_e32 v65, v65
	v_lshlrev_b32_e32 v130, 16, v124
	v_and_b32_e32 v131, 0xffff0000, v124
	v_lshlrev_b32_e32 v124, 16, v125
	v_and_b32_e32 v125, 0xffff0000, v125
	v_lshlrev_b32_e32 v134, 16, v126
	v_and_b32_e32 v135, 0xffff0000, v126
	v_lshlrev_b32_e32 v126, 16, v127
	v_and_b32_e32 v127, 0xffff0000, v127
	v_lshlrev_b32_e32 v72, 16, v120
	v_and_b32_e32 v73, 0xffff0000, v120
	v_lshlrev_b32_e32 v74, 16, v121
	v_and_b32_e32 v75, 0xffff0000, v121
	v_lshlrev_b32_e32 v120, 16, v122
	v_and_b32_e32 v121, 0xffff0000, v122
	v_lshlrev_b32_e32 v122, 16, v123
	v_and_b32_e32 v123, 0xffff0000, v123
	v_pk_fma_f32 v[74:75], v[78:79], v[124:125], v[74:75]
	v_pk_fma_f32 v[72:73], v[76:77], v[130:131], v[72:73]
	v_pk_fma_f32 v[78:79], v[136:137], v[126:127], v[122:123]
	v_pk_fma_f32 v[76:77], v[132:133], v[134:135], v[120:121]
	v_lshl_add_u64 v[120:121], v[184:185], 2, s[4:5]
	v_add_f32_e32 v64, 1.0, v64
	global_store_dwordx4 v[120:121], v[76:79], off offset:16
	v_mul_f32_e32 v68, v68, v138
	v_mul_f32_e32 v69, v69, v138
	v_rcp_f32_e32 v76, v64
	v_add_f32_e32 v64, 1.0, v65
	v_rcp_f32_e32 v77, v64
	v_mul_f32_e32 v64, v66, v138
	v_mul_f32_e32 v70, v70, v138
	v_mul_f32_e32 v71, v71, v138
	v_mul_f32_e32 v64, 0xbfb8aa3b, v64
	v_mul_f32_e32 v65, v67, v138
	v_mul_f32_e32 v68, 0xbfb8aa3b, v68
	v_mul_f32_e32 v69, 0xbfb8aa3b, v69
	v_mul_f32_e32 v70, 0xbfb8aa3b, v70
	v_mul_f32_e32 v71, 0xbfb8aa3b, v71
	v_exp_f32_e32 v64, v64
	v_mul_f32_e32 v65, 0xbfb8aa3b, v65
	v_exp_f32_e32 v68, v68
	v_exp_f32_e32 v69, v69
	v_exp_f32_e32 v70, v70
	v_exp_f32_e32 v71, v71
	v_exp_f32_e32 v65, v65
	v_add_f32_e32 v64, 1.0, v64
	global_store_dwordx4 v[120:121], v[72:75], off
	v_add_f32_e32 v68, 1.0, v68
	v_add_f32_e32 v69, 1.0, v69
	v_lshlrev_b32_e32 v72, 16, v116
	v_and_b32_e32 v73, 0xffff0000, v116
	v_add_f32_e32 v70, 1.0, v70
	v_add_f32_e32 v71, 1.0, v71
	v_rcp_f32_e32 v116, v64
	v_add_f32_e32 v64, 1.0, v65
	v_rcp_f32_e32 v68, v68
	v_rcp_f32_e32 v69, v69
	v_rcp_f32_e32 v70, v70
	v_rcp_f32_e32 v71, v71
	v_lshlrev_b32_e32 v74, 16, v117
	v_and_b32_e32 v75, 0xffff0000, v117
	v_rcp_f32_e32 v117, v64
	v_lshlrev_b32_e32 v78, 16, v118
	v_and_b32_e32 v79, 0xffff0000, v118
	v_lshlrev_b32_e32 v118, 16, v119
	v_and_b32_e32 v119, 0xffff0000, v119
	v_lshlrev_b32_e32 v64, 16, v112
	v_and_b32_e32 v65, 0xffff0000, v112
	v_lshlrev_b32_e32 v66, 16, v113
	v_and_b32_e32 v67, 0xffff0000, v113
	v_lshlrev_b32_e32 v112, 16, v114
	v_and_b32_e32 v113, 0xffff0000, v114
	v_lshlrev_b32_e32 v114, 16, v115
	v_and_b32_e32 v115, 0xffff0000, v115
	v_pk_fma_f32 v[66:67], v[70:71], v[74:75], v[66:67]
	v_pk_fma_f32 v[64:65], v[68:69], v[72:73], v[64:65]
	v_pk_fma_f32 v[70:71], v[116:117], v[118:119], v[114:115]
	v_pk_fma_f32 v[68:69], v[76:77], v[78:79], v[112:113]
	global_store_dwordx4 v[120:121], v[64:67], off offset:512
	global_store_dwordx4 v[120:121], v[68:71], off offset:528
	v_add_u32_e32 v114, 0xa0, v178
	v_ashrrev_i32_e32 v115, 31, v114
	v_cvt_f32_u32_e32 v70, v155
	v_lshlrev_b64 v[64:65], 11, v[114:115]
	v_lshl_add_u64 v[114:115], v[114:115], 2, s[8:9]
	v_mul_f32_e32 v70, 0x3b800000, v70
	v_fmamk_f32 v70, v70, 0x3a000000, v196
	v_rsq_f32_e32 v122, v70
	global_load_dword v123, v[114:115], off
	v_lshl_add_u64 v[112:113], v[64:65], 0, v[176:177]
	v_lshlrev_b64 v[68:69], 1, v[112:113]
	v_mul_f32_e32 v56, v56, v122
	v_mul_f32_e32 v56, 0xbfb8aa3b, v56
	v_mul_f32_e32 v57, v57, v122
	v_exp_f32_e32 v56, v56
	v_mul_f32_e32 v57, 0xbfb8aa3b, v57
	v_exp_f32_e32 v57, v57
	v_mul_f32_e32 v60, v60, v122
	v_add_f32_e32 v56, 1.0, v56
	v_rcp_f32_e32 v116, v56
	v_add_f32_e32 v56, 1.0, v57
	v_rcp_f32_e32 v117, v56
	v_mul_f32_e32 v56, v58, v122
; __device__ __forceinline__ float bf_lo(unsigned w) { return __uint_as_float(w << 16); }
; __device__ __forceinline__ float bf_hi(unsigned w) { return __uint_as_float(w & 0xffff0000u); }
; __device__ __forceinline__ float fast_sigmoid(float x) { return __builtin_amdgcn_rcpf(1.0f + __builtin_amdgcn_exp2f(-x * LOG2E)); }
;     __device__ __forceinline__ void operator()(const f32x4 (&acc)[2][2][4][2], const Unit& u, int wr, int wc, int fr, int fq) const {
;     ...
;         for (int it = 0; it < 8; ++it) { const int ai = it >> 2, m = it & 3, sc = it % RD;
;             if (it + RD - 1 < 8) RES_LOAD((it + RD - 1) % RD, it + RD - 1);
;             asm volatile("" ::: "memory");
;             const int row = row0 + ai * HALF + m * 16; const size_t ro = (size_t)row * DM + col0;
;             float rs = 1.0f; if (MODE == 1) rs = __builtin_amdgcn_rsqf(ss_fix(rsb[sc]) * (1.0f / DM) + EPS);
;             float sq = 0.f;
; #pragma unroll
;             for (int bj = 0; bj < 2; ++bj) { const size_t off = ro + bj * HALF;
;                 f32x4 v0 = acc[ai][bj][m][0], v1 = acc[ai][bj][m][1];
;                 if (MODE == 1) { const u32x4 pw = pbuf[sc][bj];
;                     v0[0] = fast_sigmoid(rs * v0[0]) * bf_lo(pw.x); v0[1] = fast_sigmoid(rs * v0[1]) * bf_hi(pw.x); v0[2] = fast_sigmoid(rs * v0[2]) * bf_lo(pw.y); v0[3] = fast_sigmoid(rs * v0[3]) * bf_hi(pw.y);
;                     v1[0] = fast_sigmoid(rs * v1[0]) * bf_lo(pw.z); v1[1] = fast_sigmoid(rs * v1[1]) * bf_hi(pw.z); v1[2] = fast_sigmoid(rs * v1[2]) * bf_lo(pw.w); v1[3] = fast_sigmoid(rs * v1[3]) * bf_hi(pw.w); }
;                 f32x4 h0, h1;
;                 if (IN16) { const u32x4 hw = hraw[sc][bj]; h0 = (f32x4){bf_lo(hw.x), bf_hi(hw.x), bf_lo(hw.y), bf_hi(hw.y)}; h1 = (f32x4){bf_lo(hw.z), bf_hi(hw.z), bf_lo(hw.w), bf_hi(hw.w)}; }
;                 else { h0 = hbuf[sc][2 * bj]; h1 = hbuf[sc][2 * bj + 1]; }
;                 const f32x4 o0 = h0 + v0, o1 = h1 + v1;
;                 if (OUT32) { *(f32x4*)(hout + off) = o0; *(f32x4*)(hout + off + 4) = o1; }
;                 if (hb) { u32x4 w; w.x = pk_bf16(o0[0], o0[1]); w.y = pk_bf16(o0[2], o0[3]); w.z = pk_bf16(o1[0], o1[1]); w.w = pk_bf16(o1[2], o1[3]); *(u32x4*)(hb + off) = w; }
;                 sq += ((o0[0] * o0[0] + o0[1] * o0[1]) + (o0[2] * o0[2] + o0[3] * o0[3])) + ((o1[0] * o1[0] + o1[1] * o1[1]) + (o1[2] * o1[2] + o1[3] * o1[3])); }
	v_mul_f32_e32 v61, v61, v122
	v_mul_f32_e32 v62, v62, v122
	v_mul_f32_e32 v63, v63, v122
	v_mul_f32_e32 v56, 0xbfb8aa3b, v56
	v_mul_f32_e32 v57, v59, v122
	v_mul_f32_e32 v60, 0xbfb8aa3b, v60
	v_mul_f32_e32 v61, 0xbfb8aa3b, v61
	v_mul_f32_e32 v62, 0xbfb8aa3b, v62
	v_mul_f32_e32 v63, 0xbfb8aa3b, v63
	v_exp_f32_e32 v56, v56
	v_mul_f32_e32 v57, 0xbfb8aa3b, v57
	v_exp_f32_e32 v60, v60
	v_exp_f32_e32 v61, v61
	v_exp_f32_e32 v62, v62
	v_exp_f32_e32 v63, v63
	v_exp_f32_e32 v57, v57
	v_add_f32_e32 v56, 1.0, v56
	v_mul_f32_e32 v48, v48, v122
	v_add_f32_e32 v60, 1.0, v60
	v_add_f32_e32 v61, 1.0, v61
	v_add_f32_e32 v62, 1.0, v62
	v_add_f32_e32 v63, 1.0, v63
	v_rcp_f32_e32 v120, v56
	v_add_f32_e32 v56, 1.0, v57
	v_mul_f32_e32 v48, 0xbfb8aa3b, v48
	v_mul_f32_e32 v49, v49, v122
	v_rcp_f32_e32 v60, v60
	v_rcp_f32_e32 v61, v61
	v_rcp_f32_e32 v62, v62
	v_rcp_f32_e32 v63, v63
	v_rcp_f32_e32 v121, v56
	v_exp_f32_e32 v48, v48
	v_mul_f32_e32 v49, 0xbfb8aa3b, v49
	v_exp_f32_e32 v49, v49
	v_lshl_add_u64 v[64:65], s[6:7], 0, v[68:69]
	global_load_dwordx4 v[72:75], v[64:65], off
	v_lshl_add_u64 v[64:65], s[10:11], 0, v[68:69]
	v_or_b32_e32 v68, 0x100, v68
	v_lshlrev_b32_e32 v114, 16, v108
	v_and_b32_e32 v115, 0xffff0000, v108
	v_lshlrev_b32_e32 v108, 16, v109
	v_and_b32_e32 v109, 0xffff0000, v109
	v_lshlrev_b32_e32 v118, 16, v110
	v_and_b32_e32 v119, 0xffff0000, v110
	v_lshlrev_b32_e32 v110, 16, v111
	v_and_b32_e32 v111, 0xffff0000, v111
	v_lshlrev_b32_e32 v56, 16, v104
	v_and_b32_e32 v57, 0xffff0000, v104
	v_lshlrev_b32_e32 v58, 16, v105
	v_and_b32_e32 v59, 0xffff0000, v105
	v_lshlrev_b32_e32 v104, 16, v106
	v_and_b32_e32 v105, 0xffff0000, v106
	v_lshlrev_b32_e32 v106, 16, v107
	v_and_b32_e32 v107, 0xffff0000, v107
	global_load_dwordx4 v[76:79], v[64:65], off
	v_lshl_add_u64 v[64:65], s[6:7], 0, v[68:69]
	v_lshl_add_u64 v[68:69], s[10:11], 0, v[68:69]
	v_pk_fma_f32 v[58:59], v[62:63], v[108:109], v[58:59]
	v_pk_fma_f32 v[56:57], v[60:61], v[114:115], v[56:57]
	v_pk_fma_f32 v[62:63], v[120:121], v[110:111], v[106:107]
	v_pk_fma_f32 v[60:61], v[116:117], v[118:119], v[104:105]
	v_lshl_add_u64 v[104:105], v[144:145], 2, s[4:5]
	v_add_f32_e32 v48, 1.0, v48
	global_load_dwordx4 v[64:67], v[64:65], off
	v_mul_f32_e32 v52, v52, v122
	global_load_dwordx4 v[68:71], v[68:69], off
	global_store_dwordx4 v[104:105], v[60:63], off offset:16
	v_mul_f32_e32 v53, v53, v122
	v_mul_f32_e32 v54, v54, v122
	v_rcp_f32_e32 v60, v48
	v_add_f32_e32 v48, 1.0, v49
	v_rcp_f32_e32 v61, v48
	v_mul_f32_e32 v48, v50, v122
	v_mul_f32_e32 v55, v55, v122
	v_mul_f32_e32 v48, 0xbfb8aa3b, v48
	v_mul_f32_e32 v49, v51, v122
	v_mul_f32_e32 v52, 0xbfb8aa3b, v52
	v_mul_f32_e32 v53, 0xbfb8aa3b, v53
	v_mul_f32_e32 v54, 0xbfb8aa3b, v54
	v_mul_f32_e32 v55, 0xbfb8aa3b, v55
	v_exp_f32_e32 v48, v48
	v_mul_f32_e32 v49, 0xbfb8aa3b, v49
	v_exp_f32_e32 v52, v52
	v_exp_f32_e32 v53, v53
	v_exp_f32_e32 v54, v54
	v_exp_f32_e32 v55, v55
	v_exp_f32_e32 v49, v49
	v_add_f32_e32 v48, 1.0, v48
	global_store_dwordx4 v[104:105], v[56:59], off
	v_add_f32_e32 v52, 1.0, v52
	v_add_f32_e32 v53, 1.0, v53
	v_lshlrev_b32_e32 v56, 16, v100
	v_and_b32_e32 v57, 0xffff0000, v100
	v_add_f32_e32 v54, 1.0, v54
	v_add_f32_e32 v55, 1.0, v55
	v_rcp_f32_e32 v100, v48
	v_add_f32_e32 v48, 1.0, v49
	v_rcp_f32_e32 v52, v52
	v_rcp_f32_e32 v53, v53
	v_rcp_f32_e32 v54, v54
	v_rcp_f32_e32 v55, v55
	v_lshlrev_b32_e32 v58, 16, v101
	v_and_b32_e32 v59, 0xffff0000, v101
	v_rcp_f32_e32 v101, v48
	v_lshlrev_b32_e32 v62, 16, v102
	v_and_b32_e32 v63, 0xffff0000, v102
	v_lshlrev_b32_e32 v102, 16, v103
	v_and_b32_e32 v103, 0xffff0000, v103
	v_lshlrev_b32_e32 v48, 16, v96
	v_and_b32_e32 v49, 0xffff0000, v96
	v_lshlrev_b32_e32 v50, 16, v97
	v_and_b32_e32 v51, 0xffff0000, v97
	v_lshlrev_b32_e32 v96, 16, v98
	v_and_b32_e32 v97, 0xffff0000, v98
	v_lshlrev_b32_e32 v98, 16, v99
	v_and_b32_e32 v99, 0xffff0000, v99
	v_pk_fma_f32 v[50:51], v[54:55], v[58:59], v[50:51]
	v_pk_fma_f32 v[48:49], v[52:53], v[56:57], v[48:49]
	v_pk_fma_f32 v[54:55], v[100:101], v[102:103], v[98:99]
	v_add_u32_e32 v98, 0xb0, v178
	v_pk_fma_f32 v[52:53], v[60:61], v[62:63], v[96:97]
	global_store_dwordx4 v[104:105], v[48:51], off offset:512
	global_store_dwordx4 v[104:105], v[52:55], off offset:528
	v_ashrrev_i32_e32 v99, 31, v98
	v_lshlrev_b64 v[48:49], 11, v[98:99]
	v_lshl_add_u64 v[98:99], v[98:99], 2, s[8:9]
	global_load_dword v107, v[98:99], off
	s_waitcnt vmcnt(0)
; __device__ __forceinline__ float bf_lo(unsigned w) { return __uint_as_float(w << 16); }
; __device__ __forceinline__ float bf_hi(unsigned w) { return __uint_as_float(w & 0xffff0000u); }
; __device__ __forceinline__ float fast_sigmoid(float x) { return __builtin_amdgcn_rcpf(1.0f + __builtin_amdgcn_exp2f(-x * LOG2E)); }
;     __device__ __forceinline__ void operator()(const f32x4 (&acc)[2][2][4][2], const Unit& u, int wr, int wc, int fr, int fq) const {
;     ...
;         for (int it = 0; it < 8; ++it) { const int ai = it >> 2, m = it & 3, sc = it % RD;
;             if (it + RD - 1 < 8) RES_LOAD((it + RD - 1) % RD, it + RD - 1);
;             asm volatile("" ::: "memory");
;             const int row = row0 + ai * HALF + m * 16; const size_t ro = (size_t)row * DM + col0;
;             float rs = 1.0f; if (MODE == 1) rs = __builtin_amdgcn_rsqf(ss_fix(rsb[sc]) * (1.0f / DM) + EPS);
;             float sq = 0.f;
; #pragma unroll
;             for (int bj = 0; bj < 2; ++bj) { const size_t off = ro + bj * HALF;
;                 f32x4 v0 = acc[ai][bj][m][0], v1 = acc[ai][bj][m][1];
;                 if (MODE == 1) { const u32x4 pw = pbuf[sc][bj];
;                     v0[0] = fast_sigmoid(rs * v0[0]) * bf_lo(pw.x); v0[1] = fast_sigmoid(rs * v0[1]) * bf_hi(pw.x); v0[2] = fast_sigmoid(rs * v0[2]) * bf_lo(pw.y); v0[3] = fast_sigmoid(rs * v0[3]) * bf_hi(pw.y);
;                     v1[0] = fast_sigmoid(rs * v1[0]) * bf_lo(pw.z); v1[1] = fast_sigmoid(rs * v1[1]) * bf_hi(pw.z); v1[2] = fast_sigmoid(rs * v1[2]) * bf_lo(pw.w); v1[3] = fast_sigmoid(rs * v1[3]) * bf_hi(pw.w); }
;                 f32x4 h0, h1;
;                 if (IN16) { const u32x4 hw = hraw[sc][bj]; h0 = (f32x4){bf_lo(hw.x), bf_hi(hw.x), bf_lo(hw.y), bf_hi(hw.y)}; h1 = (f32x4){bf_lo(hw.z), bf_hi(hw.z), bf_lo(hw.w), bf_hi(hw.w)}; }
;                 else { h0 = hbuf[sc][2 * bj]; h1 = hbuf[sc][2 * bj + 1]; }
;                 const f32x4 o0 = h0 + v0, o1 = h1 + v1;
;                 if (OUT32) { *(f32x4*)(hout + off) = o0; *(f32x4*)(hout + off + 4) = o1; }
;                 if (hb) { u32x4 w; w.x = pk_bf16(o0[0], o0[1]); w.y = pk_bf16(o0[2], o0[3]); w.z = pk_bf16(o1[0], o1[1]); w.w = pk_bf16(o1[2], o1[3]); *(u32x4*)(hb + off) = w; }
;                 sq += ((o0[0] * o0[0] + o0[1] * o0[1]) + (o0[2] * o0[2] + o0[3] * o0[3])) + ((o1[0] * o1[0] + o1[1] * o1[1]) + (o1[2] * o1[2] + o1[3] * o1[3])); }
	v_cvt_f32_u32_e32 v54, v139
	v_lshl_add_u64 v[96:97], v[48:49], 0, v[176:177]
	v_lshlrev_b64 v[52:53], 1, v[96:97]
	v_lshl_add_u64 v[48:49], s[6:7], 0, v[52:53]
	v_mul_f32_e32 v54, 0x3b800000, v54
	v_fmamk_f32 v54, v54, 0x3a000000, v196
	v_rsq_f32_e32 v106, v54
	global_load_dwordx4 v[56:59], v[48:49], off
	v_lshl_add_u64 v[48:49], s[10:11], 0, v[52:53]
	global_load_dwordx4 v[60:63], v[48:49], off
	v_mul_f32_e32 v40, v40, v106
	v_mul_f32_e32 v40, 0xbfb8aa3b, v40
	v_mul_f32_e32 v41, v41, v106
	v_exp_f32_e32 v40, v40
	v_mul_f32_e32 v41, 0xbfb8aa3b, v41
	v_exp_f32_e32 v41, v41
	v_mul_f32_e32 v44, v44, v106
	v_add_f32_e32 v40, 1.0, v40
	v_mul_f32_e32 v45, v45, v106
	v_rcp_f32_e32 v100, v40
	v_add_f32_e32 v40, 1.0, v41
	v_mul_f32_e32 v44, 0xbfb8aa3b, v44
	v_mul_f32_e32 v45, 0xbfb8aa3b, v45
	v_rcp_f32_e32 v101, v40
	v_mul_f32_e32 v40, v42, v106
	v_exp_f32_e32 v44, v44
	v_exp_f32_e32 v45, v45
	v_mul_f32_e32 v46, v46, v106
	v_mul_f32_e32 v47, v47, v106
	v_mul_f32_e32 v40, 0xbfb8aa3b, v40
	v_mul_f32_e32 v41, v43, v106
	v_mul_f32_e32 v46, 0xbfb8aa3b, v46
	v_mul_f32_e32 v47, 0xbfb8aa3b, v47
	v_exp_f32_e32 v40, v40
	v_mul_f32_e32 v41, 0xbfb8aa3b, v41
	v_exp_f32_e32 v46, v46
	v_exp_f32_e32 v47, v47
	v_exp_f32_e32 v41, v41
	v_add_f32_e32 v44, 1.0, v44
	v_add_f32_e32 v45, 1.0, v45
	v_rcp_f32_e32 v44, v44
	v_rcp_f32_e32 v45, v45
	v_add_f32_e32 v40, 1.0, v40
	v_mul_f32_e32 v32, v32, v106
	v_add_f32_e32 v46, 1.0, v46
	v_add_f32_e32 v47, 1.0, v47
	v_rcp_f32_e32 v104, v40
	v_add_f32_e32 v40, 1.0, v41
	v_mul_f32_e32 v32, 0xbfb8aa3b, v32
	v_mul_f32_e32 v33, v33, v106
	v_rcp_f32_e32 v46, v46
	v_rcp_f32_e32 v47, v47
	v_rcp_f32_e32 v105, v40
	v_mul_f32_e32 v38, v38, v106
	v_mul_f32_e32 v39, v39, v106
	v_exp_f32_e32 v32, v32
	v_mul_f32_e32 v33, 0xbfb8aa3b, v33
	v_lshlrev_b32_e32 v98, 16, v92
	v_and_b32_e32 v99, 0xffff0000, v92
	v_lshlrev_b32_e32 v102, 16, v94
	v_and_b32_e32 v103, 0xffff0000, v94
	v_lshlrev_b32_e32 v40, 16, v88
	v_and_b32_e32 v41, 0xffff0000, v88
	v_lshlrev_b32_e32 v42, 16, v89
	v_and_b32_e32 v43, 0xffff0000, v89
	v_lshlrev_b32_e32 v88, 16, v90
	v_and_b32_e32 v89, 0xffff0000, v90
	v_mul_f32_e32 v38, 0xbfb8aa3b, v38
	v_mul_f32_e32 v39, 0xbfb8aa3b, v39
	v_exp_f32_e32 v33, v33
	v_pk_fma_f32 v[40:41], v[44:45], v[98:99], v[40:41]
	v_pk_fma_f32 v[44:45], v[100:101], v[102:103], v[88:89]
	v_lshlrev_b64 v[88:89], 13, v[128:129]
	v_exp_f32_e32 v38, v38
	v_exp_f32_e32 v39, v39
	v_or_b32_e32 v52, 0x100, v52
	v_lshlrev_b32_e32 v92, 16, v93
	v_and_b32_e32 v93, 0xffff0000, v93
	v_lshlrev_b32_e32 v94, 16, v95
	v_and_b32_e32 v95, 0xffff0000, v95
	v_lshlrev_b32_e32 v90, 16, v91
	v_and_b32_e32 v91, 0xffff0000, v91
	v_lshl_add_u64 v[88:89], s[4:5], 0, v[88:89]
	v_lshl_add_u64 v[48:49], s[6:7], 0, v[52:53]
	v_lshl_add_u64 v[52:53], s[10:11], 0, v[52:53]
	v_pk_fma_f32 v[42:43], v[46:47], v[92:93], v[42:43]
	v_pk_fma_f32 v[46:47], v[104:105], v[94:95], v[90:91]
	v_lshl_add_u64 v[88:89], v[176:177], 2, v[88:89]
	v_mul_f32_e32 v36, v36, v106
	v_mul_f32_e32 v37, v37, v106
	v_add_f32_e32 v32, 1.0, v32
	global_load_dwordx4 v[48:51], v[48:49], off
	v_mul_f32_e32 v36, 0xbfb8aa3b, v36
	global_load_dwordx4 v[52:55], v[52:53], off
	v_mul_f32_e32 v37, 0xbfb8aa3b, v37
	global_store_dwordx4 v[88:89], v[44:47], off offset:16
	v_exp_f32_e32 v36, v36
	v_exp_f32_e32 v37, v37
	v_rcp_f32_e32 v44, v32
	v_add_f32_e32 v32, 1.0, v33
	v_add_f32_e32 v38, 1.0, v38
	v_add_f32_e32 v39, 1.0, v39
	v_rcp_f32_e32 v45, v32
	v_mul_f32_e32 v32, v34, v106
	v_rcp_f32_e32 v38, v38
	v_rcp_f32_e32 v39, v39
	v_mul_f32_e32 v32, 0xbfb8aa3b, v32
	v_mul_f32_e32 v33, v35, v106
	v_exp_f32_e32 v32, v32
	v_mul_f32_e32 v33, 0xbfb8aa3b, v33
	v_exp_f32_e32 v33, v33
	global_store_dwordx4 v[88:89], v[40:43], off
	v_add_f32_e32 v36, 1.0, v36
	v_add_f32_e32 v37, 1.0, v37
	v_lshlrev_b32_e32 v42, 16, v85
	v_and_b32_e32 v43, 0xffff0000, v85
	v_lshlrev_b32_e32 v34, 16, v81
	v_and_b32_e32 v35, 0xffff0000, v81
	v_rcp_f32_e32 v36, v36
	v_rcp_f32_e32 v37, v37
	v_pk_fma_f32 v[34:35], v[38:39], v[42:43], v[34:35]
	v_cvt_f32_u32_e32 v42, v123
	v_add_f32_e32 v32, 1.0, v32
	v_lshlrev_b32_e32 v40, 16, v84
	v_and_b32_e32 v41, 0xffff0000, v84
	v_rcp_f32_e32 v84, v32
	v_add_f32_e32 v32, 1.0, v33
	v_rcp_f32_e32 v85, v32
	v_lshlrev_b32_e32 v32, 16, v80
	v_and_b32_e32 v33, 0xffff0000, v80
	v_pk_fma_f32 v[32:33], v[36:37], v[40:41], v[32:33]
	v_mul_f32_e32 v40, 0x3b800000, v42
	v_lshlrev_b32_e32 v46, 16, v86
	v_and_b32_e32 v47, 0xffff0000, v86
	v_lshlrev_b32_e32 v80, 16, v82
	v_and_b32_e32 v81, 0xffff0000, v82
	v_fmamk_f32 v40, v40, 0x3a000000, v196
	v_pk_fma_f32 v[36:37], v[44:45], v[46:47], v[80:81]
	v_rsq_f32_e32 v80, v40
	v_lshlrev_b32_e32 v86, 16, v87
	v_and_b32_e32 v87, 0xffff0000, v87
	v_lshlrev_b32_e32 v82, 16, v83
	v_mul_f32_e32 v24, v24, v80
	v_mul_f32_e32 v24, 0xbfb8aa3b, v24
	v_mul_f32_e32 v25, v25, v80
	v_exp_f32_e32 v24, v24
	v_mul_f32_e32 v25, 0xbfb8aa3b, v25
	v_exp_f32_e32 v25, v25
	v_and_b32_e32 v83, 0xffff0000, v83
	v_add_f32_e32 v24, 1.0, v24
	v_pk_fma_f32 v[38:39], v[84:85], v[86:87], v[82:83]
	global_store_dwordx4 v[88:89], v[32:35], off offset:512
	global_store_dwordx4 v[88:89], v[36:39], off offset:528
	v_mul_f32_e32 v28, v28, v80
	v_mul_f32_e32 v29, v29, v80
	v_rcp_f32_e32 v36, v24
	v_add_f32_e32 v24, 1.0, v25
	v_rcp_f32_e32 v37, v24
	v_mul_f32_e32 v24, v26, v80
	v_mul_f32_e32 v30, v30, v80
	v_mul_f32_e32 v31, v31, v80
	v_mul_f32_e32 v24, 0xbfb8aa3b, v24
	v_mul_f32_e32 v25, v27, v80
	v_mul_f32_e32 v28, 0xbfb8aa3b, v28
	v_mul_f32_e32 v29, 0xbfb8aa3b, v29
	v_mul_f32_e32 v30, 0xbfb8aa3b, v30
	v_mul_f32_e32 v31, 0xbfb8aa3b, v31
	v_exp_f32_e32 v24, v24
	v_mul_f32_e32 v25, 0xbfb8aa3b, v25
	v_exp_f32_e32 v28, v28
; __device__ __forceinline__ float bf_lo(unsigned w) { return __uint_as_float(w << 16); }
; __device__ __forceinline__ float bf_hi(unsigned w) { return __uint_as_float(w & 0xffff0000u); }
; __device__ __forceinline__ float fast_sigmoid(float x) { return __builtin_amdgcn_rcpf(1.0f + __builtin_amdgcn_exp2f(-x * LOG2E)); }
;     __device__ __forceinline__ void operator()(const f32x4 (&acc)[2][2][4][2], const Unit& u, int wr, int wc, int fr, int fq) const {
;     ...
;         for (int it = 0; it < 8; ++it) { const int ai = it >> 2, m = it & 3, sc = it % RD;
;             if (it + RD - 1 < 8) RES_LOAD((it + RD - 1) % RD, it + RD - 1);
;             asm volatile("" ::: "memory");
;             const int row = row0 + ai * HALF + m * 16; const size_t ro = (size_t)row * DM + col0;
;             float rs = 1.0f; if (MODE == 1) rs = __builtin_amdgcn_rsqf(ss_fix(rsb[sc]) * (1.0f / DM) + EPS);
;             float sq = 0.f;
; #pragma unroll
;             for (int bj = 0; bj < 2; ++bj) { const size_t off = ro + bj * HALF;
;                 f32x4 v0 = acc[ai][bj][m][0], v1 = acc[ai][bj][m][1];
;                 if (MODE == 1) { const u32x4 pw = pbuf[sc][bj];
;                     v0[0] = fast_sigmoid(rs * v0[0]) * bf_lo(pw.x); v0[1] = fast_sigmoid(rs * v0[1]) * bf_hi(pw.x); v0[2] = fast_sigmoid(rs * v0[2]) * bf_lo(pw.y); v0[3] = fast_sigmoid(rs * v0[3]) * bf_hi(pw.y);
;                     v1[0] = fast_sigmoid(rs * v1[0]) * bf_lo(pw.z); v1[1] = fast_sigmoid(rs * v1[1]) * bf_hi(pw.z); v1[2] = fast_sigmoid(rs * v1[2]) * bf_lo(pw.w); v1[3] = fast_sigmoid(rs * v1[3]) * bf_hi(pw.w); }
;                 f32x4 h0, h1;
;                 if (IN16) { const u32x4 hw = hraw[sc][bj]; h0 = (f32x4){bf_lo(hw.x), bf_hi(hw.x), bf_lo(hw.y), bf_hi(hw.y)}; h1 = (f32x4){bf_lo(hw.z), bf_hi(hw.z), bf_lo(hw.w), bf_hi(hw.w)}; }
;                 else { h0 = hbuf[sc][2 * bj]; h1 = hbuf[sc][2 * bj + 1]; }
;                 const f32x4 o0 = h0 + v0, o1 = h1 + v1;
;                 if (OUT32) { *(f32x4*)(hout + off) = o0; *(f32x4*)(hout + off + 4) = o1; }
;                 if (hb) { u32x4 w; w.x = pk_bf16(o0[0], o0[1]); w.y = pk_bf16(o0[2], o0[3]); w.z = pk_bf16(o1[0], o1[1]); w.w = pk_bf16(o1[2], o1[3]); *(u32x4*)(hb + off) = w; }
;                 sq += ((o0[0] * o0[0] + o0[1] * o0[1]) + (o0[2] * o0[2] + o0[3] * o0[3])) + ((o1[0] * o1[0] + o1[1] * o1[1]) + (o1[2] * o1[2] + o1[3] * o1[3])); }
	v_exp_f32_e32 v29, v29
	v_exp_f32_e32 v30, v30
	v_exp_f32_e32 v31, v31
	v_exp_f32_e32 v25, v25
	v_add_f32_e32 v24, 1.0, v24
	v_mul_f32_e32 v16, v16, v80
	v_add_f32_e32 v28, 1.0, v28
	v_add_f32_e32 v29, 1.0, v29
	v_add_f32_e32 v30, 1.0, v30
	v_add_f32_e32 v31, 1.0, v31
	v_rcp_f32_e32 v40, v24
	v_add_f32_e32 v24, 1.0, v25
	v_mul_f32_e32 v16, 0xbfb8aa3b, v16
	v_mul_f32_e32 v17, v17, v80
	v_rcp_f32_e32 v28, v28
	v_rcp_f32_e32 v29, v29
	v_rcp_f32_e32 v30, v30
	v_rcp_f32_e32 v31, v31
	v_rcp_f32_e32 v41, v24
	v_exp_f32_e32 v16, v16
	v_mul_f32_e32 v17, 0xbfb8aa3b, v17
	v_mul_f32_e32 v22, v22, v80
	v_mul_f32_e32 v23, v23, v80
	v_exp_f32_e32 v17, v17
	v_mul_f32_e32 v22, 0xbfb8aa3b, v22
	v_mul_f32_e32 v23, 0xbfb8aa3b, v23
	v_lshlrev_b32_e32 v32, 16, v76
	v_and_b32_e32 v33, 0xffff0000, v76
	v_lshlrev_b32_e32 v34, 16, v77
	v_and_b32_e32 v35, 0xffff0000, v77
	v_lshlrev_b32_e32 v38, 16, v78
	v_and_b32_e32 v39, 0xffff0000, v78
	v_lshlrev_b32_e32 v42, 16, v79
	v_and_b32_e32 v43, 0xffff0000, v79
	v_lshlrev_b32_e32 v24, 16, v72
	v_and_b32_e32 v25, 0xffff0000, v72
	v_lshlrev_b32_e32 v26, 16, v73
	v_and_b32_e32 v27, 0xffff0000, v73
	v_lshlrev_b32_e32 v44, 16, v74
	v_and_b32_e32 v45, 0xffff0000, v74
	v_lshlrev_b32_e32 v46, 16, v75
	v_and_b32_e32 v47, 0xffff0000, v75
	v_exp_f32_e32 v22, v22
	v_exp_f32_e32 v23, v23
	v_pk_fma_f32 v[26:27], v[30:31], v[34:35], v[26:27]
	v_pk_fma_f32 v[24:25], v[28:29], v[32:33], v[24:25]
	v_pk_fma_f32 v[30:31], v[40:41], v[42:43], v[46:47]
	v_pk_fma_f32 v[28:29], v[36:37], v[38:39], v[44:45]
	v_lshl_add_u64 v[32:33], v[112:113], 2, s[4:5]
	v_add_f32_e32 v16, 1.0, v16
	v_mul_f32_e32 v20, v20, v80
	v_mul_f32_e32 v21, v21, v80
	global_store_dwordx4 v[32:33], v[28:31], off offset:16
	v_mul_f32_e32 v20, 0xbfb8aa3b, v20
	v_mul_f32_e32 v21, 0xbfb8aa3b, v21
	v_rcp_f32_e32 v28, v16
	v_add_f32_e32 v16, 1.0, v17
	v_rcp_f32_e32 v29, v16
	v_mul_f32_e32 v16, v18, v80
	v_exp_f32_e32 v20, v20
	v_exp_f32_e32 v21, v21
	v_add_f32_e32 v22, 1.0, v22
	v_add_f32_e32 v23, 1.0, v23
	v_mul_f32_e32 v16, 0xbfb8aa3b, v16
	v_mul_f32_e32 v17, v19, v80
	v_rcp_f32_e32 v22, v22
	v_rcp_f32_e32 v23, v23
	v_exp_f32_e32 v16, v16
	v_mul_f32_e32 v17, 0xbfb8aa3b, v17
	v_exp_f32_e32 v17, v17
	global_store_dwordx4 v[32:33], v[24:27], off
	v_add_f32_e32 v20, 1.0, v20
	v_add_f32_e32 v21, 1.0, v21
	v_lshlrev_b32_e32 v26, 16, v69
	v_and_b32_e32 v27, 0xffff0000, v69
	v_lshlrev_b32_e32 v18, 16, v65
	v_and_b32_e32 v19, 0xffff0000, v65
	v_rcp_f32_e32 v20, v20
	v_rcp_f32_e32 v21, v21
	v_add_f32_e32 v16, 1.0, v16
	v_pk_fma_f32 v[18:19], v[22:23], v[26:27], v[18:19]
	v_cvt_f32_u32_e32 v26, v107
	v_rcp_f32_e32 v34, v16
	v_add_f32_e32 v16, 1.0, v17
	v_rcp_f32_e32 v35, v16
	v_lshlrev_b32_e32 v24, 16, v68
	v_and_b32_e32 v25, 0xffff0000, v68
	v_lshlrev_b32_e32 v16, 16, v64
	v_and_b32_e32 v17, 0xffff0000, v64
	v_pk_fma_f32 v[16:17], v[20:21], v[24:25], v[16:17]
	v_mul_f32_e32 v24, 0x3b800000, v26
	v_lshlrev_b32_e32 v36, 16, v71
	v_and_b32_e32 v37, 0xffff0000, v71
	v_lshlrev_b32_e32 v40, 16, v67
	v_and_b32_e32 v41, 0xffff0000, v67
	v_fmamk_f32 v24, v24, 0x3a000000, v196
	v_pk_fma_f32 v[22:23], v[34:35], v[36:37], v[40:41]
	v_rsq_f32_e32 v34, v24
	v_lshlrev_b32_e32 v30, 16, v70
	v_and_b32_e32 v31, 0xffff0000, v70
	v_lshlrev_b32_e32 v38, 16, v66
	v_mul_f32_e32 v8, v8, v34
	v_mul_f32_e32 v8, 0xbfb8aa3b, v8
	v_mul_f32_e32 v9, v9, v34
	v_exp_f32_e32 v8, v8
	v_mul_f32_e32 v9, 0xbfb8aa3b, v9
	v_exp_f32_e32 v9, v9
	v_and_b32_e32 v39, 0xffff0000, v66
	v_pk_fma_f32 v[20:21], v[28:29], v[30:31], v[38:39]
	v_add_f32_e32 v8, 1.0, v8
	global_store_dwordx4 v[32:33], v[16:19], off offset:512
	global_store_dwordx4 v[32:33], v[20:23], off offset:528
	v_mul_f32_e32 v12, v12, v34
	v_mul_f32_e32 v13, v13, v34
	v_rcp_f32_e32 v20, v8
	v_add_f32_e32 v8, 1.0, v9
	v_rcp_f32_e32 v21, v8
	v_mul_f32_e32 v8, v10, v34
	v_mul_f32_e32 v14, v14, v34
	v_mul_f32_e32 v15, v15, v34
	v_mul_f32_e32 v8, 0xbfb8aa3b, v8
	v_mul_f32_e32 v9, v11, v34
	v_mul_f32_e32 v12, 0xbfb8aa3b, v12
	v_mul_f32_e32 v13, 0xbfb8aa3b, v13
	v_mul_f32_e32 v14, 0xbfb8aa3b, v14
	v_mul_f32_e32 v15, 0xbfb8aa3b, v15
	v_exp_f32_e32 v8, v8
	v_mul_f32_e32 v9, 0xbfb8aa3b, v9
	v_exp_f32_e32 v12, v12
	v_exp_f32_e32 v13, v13
	v_exp_f32_e32 v14, v14
	v_exp_f32_e32 v15, v15
	v_exp_f32_e32 v9, v9
	v_add_f32_e32 v8, 1.0, v8
	v_mul_f32_e32 v0, v0, v34
	v_add_f32_e32 v12, 1.0, v12
	v_add_f32_e32 v13, 1.0, v13
	v_add_f32_e32 v14, 1.0, v14
	v_add_f32_e32 v15, 1.0, v15
	v_rcp_f32_e32 v24, v8
	v_add_f32_e32 v8, 1.0, v9
	v_mul_f32_e32 v0, 0xbfb8aa3b, v0
	v_mul_f32_e32 v1, v1, v34
	v_rcp_f32_e32 v12, v12
	v_rcp_f32_e32 v13, v13
	v_rcp_f32_e32 v14, v14
	v_rcp_f32_e32 v15, v15
	v_rcp_f32_e32 v25, v8
	v_exp_f32_e32 v0, v0
	v_mul_f32_e32 v1, 0xbfb8aa3b, v1
	v_exp_f32_e32 v1, v1
	s_waitcnt vmcnt(0)
; __device__ __forceinline__ float bf_lo(unsigned w) { return __uint_as_float(w << 16); }
;     __device__ __forceinline__ void operator()(const f32x4 (&acc)[2][2][4][2], const Unit& u, int wr, int wc, int fr, int fq) const {
;     ...
;         for (int it = 0; it < 8; ++it) { const int ai = it >> 2, m = it & 3, sc = it % RD;
;             if (it + RD - 1 < 8) RES_LOAD((it + RD - 1) % RD, it + RD - 1);
;             asm volatile("" ::: "memory");
;             const int row = row0 + ai * HALF + m * 16; const size_t ro = (size_t)row * DM + col0;
;             float rs = 1.0f; if (MODE == 1) rs = __builtin_amdgcn_rsqf(ss_fix(rsb[sc]) * (1.0f / DM) + EPS);
;             float sq = 0.f;
; #pragma unroll
;             for (int bj = 0; bj < 2; ++bj) { const size_t off = ro + bj * HALF;
;                 f32x4 v0 = acc[ai][bj][m][0], v1 = acc[ai][bj][m][1];
;                 if (MODE == 1) { const u32x4 pw = pbuf[sc][bj];
;                     v0[0] = fast_sigmoid(rs * v0[0]) * bf_lo(pw.x); v0[1] = fast_sigmoid(rs * v0[1]) * bf_hi(pw.x); v0[2] = fast_sigmoid(rs * v0[2]) * bf_lo(pw.y); v0[3] = fast_sigmoid(rs * v0[3]) * bf_hi(pw.y);
;                     v1[0] = fast_sigmoid(rs * v1[0]) * bf_lo(pw.z); v1[1] = fast_sigmoid(rs * v1[1]) * bf_hi(pw.z); v1[2] = fast_sigmoid(rs * v1[2]) * bf_lo(pw.w); v1[3] = fast_sigmoid(rs * v1[3]) * bf_hi(pw.w); }
;                 f32x4 h0, h1;
;                 if (IN16) { const u32x4 hw = hraw[sc][bj]; h0 = (f32x4){bf_lo(hw.x), bf_hi(hw.x), bf_lo(hw.y), bf_hi(hw.y)}; h1 = (f32x4){bf_lo(hw.z), bf_hi(hw.z), bf_lo(hw.w), bf_hi(hw.w)}; }
;                 else { h0 = hbuf[sc][2 * bj]; h1 = hbuf[sc][2 * bj + 1]; }
;                 const f32x4 o0 = h0 + v0, o1 = h1 + v1;
;                 if (OUT32) { *(f32x4*)(hout + off) = o0; *(f32x4*)(hout + off + 4) = o1; }
;                 if (hb) { u32x4 w; w.x = pk_bf16(o0[0], o0[1]); w.y = pk_bf16(o0[2], o0[3]); w.z = pk_bf16(o1[0], o1[1]); w.w = pk_bf16(o1[2], o1[3]); *(u32x4*)(hb + off) = w; }
;                 sq += ((o0[0] * o0[0] + o0[1] * o0[1]) + (o0[2] * o0[2] + o0[3] * o0[3])) + ((o1[0] * o1[0] + o1[1] * o1[1]) + (o1[2] * o1[2] + o1[3] * o1[3])); }
;             if (ss_out) { sq += __shfl_xor(sq, 16); sq += __shfl_xor(sq, 32); if (fq == 0) atomicAdd((unsigned*)(ss_out + row), ss_enc(sq)); }
;             asm volatile("" ::: "memory"); }
	v_lshlrev_b32_e32 v16, 16, v60
	v_and_b32_e32 v17, 0xffff0000, v60
	v_lshlrev_b32_e32 v18, 16, v61
	v_and_b32_e32 v19, 0xffff0000, v61
	v_lshlrev_b32_e32 v22, 16, v62
	v_and_b32_e32 v23, 0xffff0000, v62
	v_lshlrev_b32_e32 v26, 16, v63
	v_and_b32_e32 v27, 0xffff0000, v63
	v_lshlrev_b32_e32 v8, 16, v56
	v_and_b32_e32 v9, 0xffff0000, v56
	v_lshlrev_b32_e32 v10, 16, v57
	v_and_b32_e32 v11, 0xffff0000, v57
	v_lshlrev_b32_e32 v28, 16, v58
	v_and_b32_e32 v29, 0xffff0000, v58
	v_lshlrev_b32_e32 v30, 16, v59
	v_and_b32_e32 v31, 0xffff0000, v59
	v_pk_fma_f32 v[10:11], v[14:15], v[18:19], v[10:11]
	v_pk_fma_f32 v[8:9], v[12:13], v[16:17], v[8:9]
	v_pk_fma_f32 v[14:15], v[24:25], v[26:27], v[30:31]
	v_pk_fma_f32 v[12:13], v[20:21], v[22:23], v[28:29]
	v_lshl_add_u64 v[16:17], v[96:97], 2, s[4:5]
	v_add_f32_e32 v0, 1.0, v0
	global_store_dwordx4 v[16:17], v[12:15], off offset:16
	v_mul_f32_e32 v4, v4, v34
	v_mul_f32_e32 v5, v5, v34
	v_rcp_f32_e32 v12, v0
	v_add_f32_e32 v0, 1.0, v1
	v_mul_f32_e32 v6, v6, v34
	v_mul_f32_e32 v7, v7, v34
	v_rcp_f32_e32 v13, v0
	v_mul_f32_e32 v0, v2, v34
	v_mul_f32_e32 v4, 0xbfb8aa3b, v4
	v_mul_f32_e32 v5, 0xbfb8aa3b, v5
	v_mul_f32_e32 v6, 0xbfb8aa3b, v6
	v_mul_f32_e32 v7, 0xbfb8aa3b, v7
	v_mul_f32_e32 v0, 0xbfb8aa3b, v0
	v_mul_f32_e32 v1, v3, v34
	v_exp_f32_e32 v4, v4
	v_exp_f32_e32 v5, v5
	v_exp_f32_e32 v6, v6
	v_exp_f32_e32 v7, v7
	v_exp_f32_e32 v0, v0
	v_mul_f32_e32 v1, 0xbfb8aa3b, v1
	v_exp_f32_e32 v1, v1
	v_add_f32_e32 v4, 1.0, v4
	v_add_f32_e32 v5, 1.0, v5
	v_add_f32_e32 v6, 1.0, v6
	v_add_f32_e32 v7, 1.0, v7
	v_add_f32_e32 v0, 1.0, v0
	v_rcp_f32_e32 v4, v4
	v_rcp_f32_e32 v5, v5
	v_rcp_f32_e32 v6, v6
	v_rcp_f32_e32 v7, v7
	v_rcp_f32_e32 v18, v0
	v_add_f32_e32 v0, 1.0, v1
	v_rcp_f32_e32 v19, v0
	global_store_dwordx4 v[16:17], v[8:11], off
	v_lshlrev_b32_e32 v0, 16, v48
	v_and_b32_e32 v1, 0xffff0000, v48
	v_lshlrev_b32_e32 v8, 16, v52
	v_and_b32_e32 v9, 0xffff0000, v52
	v_lshlrev_b32_e32 v10, 16, v53
	v_and_b32_e32 v11, 0xffff0000, v53
	v_lshlrev_b32_e32 v2, 16, v49
	v_and_b32_e32 v3, 0xffff0000, v49
	v_lshlrev_b32_e32 v14, 16, v54
	v_and_b32_e32 v15, 0xffff0000, v54
	v_lshlrev_b32_e32 v20, 16, v55
	v_and_b32_e32 v21, 0xffff0000, v55
	v_lshlrev_b32_e32 v22, 16, v50
	v_and_b32_e32 v23, 0xffff0000, v50
	v_lshlrev_b32_e32 v24, 16, v51
	v_and_b32_e32 v25, 0xffff0000, v51
	v_pk_fma_f32 v[2:3], v[6:7], v[10:11], v[2:3]
	v_pk_fma_f32 v[0:1], v[4:5], v[8:9], v[0:1]
	v_pk_fma_f32 v[6:7], v[18:19], v[20:21], v[24:25]
	v_pk_fma_f32 v[4:5], v[12:13], v[14:15], v[22:23]
	global_store_dwordx4 v[16:17], v[0:3], off offset:512
	global_store_dwordx4 v[16:17], v[4:7], off offset:528
	s_cbranch_vccz .LBB0_1846
	s_waitcnt vmcnt(0)
	s_cmpk_gt_u32 s33, 0xff
	s_cbranch_scc1 .LBB0_1857
	s_barrier
